# stack9 with per-phase s_setprio flips replaced by one static s_setprio 1 for waves 4-7 in the GEMM phases
# speedup vs baseline: 1.0021x; 1.0021x over previous
; DEVI int tid_() { int t = threadIdx.x; asm volatile("" : "+v"(t)); return t; }
; #define PG8_STAGE(bufoff, gbase, voff) do { _Pragma("unroll") for (int _i = 0; _i < 2; ++_i) \
;         __builtin_amdgcn_global_load_lds((const unsigned*)((const char*)(gbase) + (voff)[_i]), (LAS unsigned*)(lds + (bufoff) + ldsw + _i * 8192), 16, 0, 0); } while (0)
; #define PG8_BAR __builtin_amdgcn_s_barrier()
; template <class Epi, class Sched>
; DEVI void gemm_phase(LAS unsigned char* lds, const Gemm g, const Sched& S, const Epi& E) {
;     const int tid = tid_(), wid = __builtin_amdgcn_readfirstlane(tid >> 6), lane = tid & 63, wr = wid >> 2, wc = wid & 3, fr = lane & 15, fq = lane >> 4;
;     const int K = g.K, nt = K / BK;
;     unsigned voffA[2], voffB[2];
; #pragma unroll
;     for (int i = 0; i < 2; ++i) { int R, C; stage_rc(tid * 16 + i * 8192, R, C); const int Rb = Epi::PERM ? ((R & ~31) + perm32(R & 31)) : R;
;         voffA[i] = (unsigned)(R * K + C) * 2u; voffB[i] = (unsigned)(Rb * K + C) * 2u; }
;     const size_t kstep = (size_t)(BK * 2);
;     const size_t hstep = (size_t)HALF * K * 2;
;     const size_t tstep = 2 * hstep;
;     const unsigned ldsw = (unsigned)wid * 1024u;
;     const int aoff = lds_byte(wr * 64 + fr, fq * 8), boff = lds_byte(wc * 32 + fr, fq * 8);
;     ...
;     Unit cur, nxt; int ui = 0;
;     if (!S.next(0, cur)) return;
;     f32x4 acc[2][2][4][2];
; #pragma unroll
;     for (int a = 0; a < 2; ++a)
; #pragma unroll
;         for (int b = 0; b < 2; ++b)
; #pragma unroll
;             for (int m = 0; m < 4; ++m)
; #pragma unroll
;                 for (int n = 0; n < 2; ++n) acc[a][b][m][n] = (f32x4){0.f, 0.f, 0.f, 0.f};
;     bf16x8 At[4][2], B0[2][2], B1[2][2];
;     const char* cA = (const char*)g.A + (size_t)cur.pm * tstep; const char* cB = (const char*)g.Bt + (size_t)cur.pn * tstep;
;     S.a_ready(cur);
;     PG8_STAGE(PG8_SB(0, 0), cB, voffB); PG8_STAGE(PG8_SB(0, 1), cB + hstep, voffB); PG8_STAGE(PG8_SA(0, 0), cA, voffA); PG8_STAGE(PG8_SA(0, 1), cA + hstep, voffA);
;     if (wr == 1) PG8_BAR;
.LBB0_130:
	s_or_b64 exec, exec, s[0:1]
	s_mov_b64 s[0:1], s[96:97]
	s_mov_b32 s30, s89
	v_readlane_b32 s31, v249, 0
	v_mov_b32_e32 v8, v242
	s_barrier
	v_readfirstlane_b32 s98, v242
	s_nop 3
	s_cmpk_lt_u32 s98, 0x100
	s_cbranch_scc1 .Lsprio_sp1
	s_setprio 1
.Lsprio_sp1:
	s_cmpk_gt_i32 s31, 0x2ff
	v_readfirstlane_b32 s13, v8
	s_cbranch_scc1 .LBB0_146
	v_lshlrev_b32_e32 v0, 4, v8
	v_add_u32_e32 v1, 0x2000, v0
	s_waitcnt vmcnt(0)
	v_ashrrev_i32_e32 v2, 31, v1
	v_lshrrev_b32_e32 v2, 22, v2
	v_add_u32_e32 v2, v1, v2
	v_ashrrev_i32_e32 v9, 10, v2
	v_mul_i32_i24_e32 v2, 0x400, v9
	v_sub_u32_e32 v1, v1, v2
	v_lshrrev_b32_e32 v2, 4, v1
	v_bitop3_b32 v1, v2, v1, 32 bitop3:0x6c
	v_ashrrev_i32_e32 v2, 31, v1
	v_lshrrev_b32_e32 v2, 26, v2
	v_add_u32_e32 v2, v1, v2
	v_lshlrev_b32_e32 v3, 3, v9
	v_ashrrev_i32_e32 v10, 6, v2
	v_and_b32_e32 v3, -16, v3
	v_add_u32_e32 v3, v10, v3
	v_and_b32_e32 v4, 3, v10
	s_mov_b32 s2, 0x1fffe0
	v_lshrrev_b32_e32 v5, 2, v3
	v_lshlrev_b32_e32 v6, 1, v3
	v_and_b32_e32 v2, 0xc0, v2
	v_and_or_b32 v4, v3, s2, v4
	v_and_b32_e32 v5, 4, v5
	v_and_b32_e32 v6, 24, v6
	v_sub_u32_e32 v1, v1, v2
	v_mov_b32_e32 v2, 1
	v_or3_b32 v4, v4, v5, v6
	v_lshlrev_b32_e32 v5, 5, v9
	v_ashrrev_i16_sdwa v1, v2, sext(v1) dst_sel:DWORD dst_unused:UNUSED_PAD src0_sel:DWORD src1_sel:BYTE_0
	v_and_b32_e32 v5, 32, v5
	v_bfe_i32 v11, v1, 0, 16
	v_add_lshl_u32 v1, v5, v11, 1
	v_lshl_add_u32 v160, v4, 11, v1
	v_lshl_add_u32 v162, v3, 11, v1
	v_bfe_i32 v1, v8, 27, 1
	v_lshrrev_b32_e32 v1, 22, v1
	v_add_u32_e32 v1, v0, v1
	v_and_b32_e32 v1, 0xfffffc00, v1
	v_sub_u32_e32 v0, v0, v1
	v_lshrrev_b32_e32 v1, 4, v0
	v_bitop3_b32 v1, v1, v0, 32 bitop3:0x6c
	v_ashrrev_i32_e32 v0, 31, v0
	v_lshrrev_b32_e32 v0, 26, v0
	v_add_u32_e32 v0, v1, v0
	v_ashrrev_i32_e32 v12, 6, v0
	v_ashrrev_i32_e32 v0, 31, v8
	v_lshrrev_b32_e32 v0, 26, v0
	v_add_u32_e32 v0, v8, v0
	s_add_u32 s33, s0, 0x1000000
	v_ashrrev_i32_e32 v13, 6, v0
	s_addc_u32 s34, s1, 0
	v_lshlrev_b32_e32 v0, 3, v13
	s_add_u32 s35, s0, 0x6800000
	v_and_b32_e32 v0, -16, v0
	s_addc_u32 s36, s1, 0
	v_add_u32_e32 v0, v12, v0
	v_and_b32_e32 v3, 3, v12
	s_ashr_i32 s38, s31, 31
	v_and_or_b32 v3, v0, s2, v3
	s_lshr_b32 s2, s38, 29
	s_add_i32 s2, s31, s2
	s_ashr_i32 s10, s13, 6
	s_ashr_i32 s3, s2, 3
	s_and_b32 s2, s2, -8
	s_ashr_i32 s14, s13, 8
	s_lshl_b32 s37, s10, 10
	s_sub_i32 s2, s31, s2
	s_cmp_lt_i32 s2, 0
	s_movk_i32 s39, 0x61
	s_cselect_b32 s4, s39, 0x60
	s_mul_i32 s2, s4, s2
	s_add_i32 s2, s2, s3
	s_mul_hi_i32 s3, s2, 0x2aaaaaab
	s_lshr_b32 s4, s3, 31
	s_ashr_i32 s3, s3, 3
	s_add_i32 s3, s3, s4
	s_lshl_b32 s4, s3, 3
	s_mul_i32 s3, s3, 48
	s_sub_i32 s2, s2, s3
	s_bfe_i32 s3, s2, 0x80000
	s_bfe_u32 s3, s3, 0x3000c
	s_add_i32 s3, s2, s3
	s_bfe_i32 s5, s3, 0x80000
	s_and_b32 s3, s3, 0xf8
	v_lshrrev_b32_e32 v4, 2, v0
	v_lshlrev_b32_e32 v5, 1, v0
	s_sub_i32 s2, s2, s3
	v_and_b32_e32 v4, 4, v4
	v_and_b32_e32 v5, 24, v5
	s_sext_i32_i16 s5, s5
	s_sext_i32_i8 s2, s2
	v_or3_b32 v3, v3, v4, v5
	v_mul_i32_i24_e32 v5, 64, v12
	s_lshr_b32 s12, s5, 3
	s_add_i32 s22, s4, s2
	v_sub_u32_e32 v1, v1, v5
	s_ashr_i32 s23, s22, 31
	s_bfe_i64 s[4:5], s[12:13], 0x100000
	v_lshlrev_b32_e32 v4, 5, v13
	v_ashrrev_i16_sdwa v1, v2, sext(v1) dst_sel:DWORD dst_unused:UNUSED_PAD src0_sel:DWORD src1_sel:BYTE_0
	s_lshl_b64 s[2:3], s[22:23], 19
	s_lshl_b64 s[4:5], s[4:5], 19
	v_and_b32_e32 v4, 32, v4
	v_bfe_i32 v14, v1, 0, 16
	s_add_u32 s24, s33, s4
	v_add_lshl_u32 v1, v4, v14, 1
	s_addc_u32 s25, s34, s5
	s_add_i32 s23, s37, 0
	v_lshl_add_u32 v164, v3, 11, v1
	s_add_i32 m0, s23, 0x10000
	v_lshl_add_u32 v166, v0, 11, v1
	global_load_lds_dwordx4 v164, s[24:25]
	s_add_i32 m0, s23, 0x12000
	s_add_u32 s4, s24, 0x40000
	global_load_lds_dwordx4 v160, s[24:25]
	s_addc_u32 s5, s25, 0
	s_add_i32 m0, s23, 0x14000
	v_mov_b32_e32 v165, 0
	global_load_lds_dwordx4 v164, s[4:5]
	s_add_i32 m0, s23, 0x16000
	s_add_u32 s26, s35, s2
	s_addc_u32 s27, s36, s3
	s_add_i32 s40, s23, 0x2000
	global_load_lds_dwordx4 v160, s[4:5]
	s_mov_b32 m0, s23
	s_add_u32 s2, s26, 0x40000
	global_load_lds_dwordx4 v166, s[26:27]
	s_mov_b32 m0, s40
	s_addc_u32 s3, s27, 0
	s_add_i32 s41, s23, 0x4000
	global_load_lds_dwordx4 v162, s[26:27]
	s_mov_b32 m0, s41
	s_add_i32 s42, s23, 0x6000
	global_load_lds_dwordx4 v166, s[2:3]
	s_mov_b32 m0, s42
	v_mov_b32_e32 v161, v165
	global_load_lds_dwordx4 v162, s[2:3]
	v_mov_b32_e32 v167, v165
	v_mov_b32_e32 v163, v165
	s_cmp_eq_u32 s14, 1
	s_mov_b32 s43, 0
	v_lshl_add_u64 v[6:7], s[24:25], 0, v[164:165]
	v_lshl_add_u64 v[4:5], s[24:25], 0, v[160:161]
	v_lshl_add_u64 v[0:1], s[26:27], 0, v[166:167]
	s_cselect_b64 s[2:3], -1, 0
	s_cmp_lg_u32 s14, 1
	v_lshl_add_u64 v[2:3], s[26:27], 0, v[162:163]
	s_cbranch_scc1 .LBB0_133
	s_barrier

; #define PG8_STAGE(bufoff, gbase, voff) do { _Pragma("unroll") for (int _i = 0; _i < 2; ++_i) \
;         __builtin_amdgcn_global_load_lds((const unsigned*)((const char*)(gbase) + (voff)[_i]), (LAS unsigned*)(lds + (bufoff) + ldsw + _i * 8192), 16, 0, 0); } while (0)
; #define PG8_LDA(dst, b, h) do { _Pragma("unroll") for (int m = 0; m < 4; ++m) _Pragma("unroll") for (int k = 0; k < 2; ++k) dst[m][k] = *(const LAS bf16x8*)(lds + PG8_SA(b, h) + aoff + m * 2048 + k * 1024); } while (0)
; #define PG8_LDB(dst, b, h) do { _Pragma("unroll") for (int n = 0; n < 2; ++n) _Pragma("unroll") for (int k = 0; k < 2; ++k) dst[n][k] = *(const LAS bf16x8*)(lds + PG8_SB(b, h) + boff + n * 2048 + k * 1024); } while (0)
; #define PG8_MMA(ai, bj, At, Bt) do { __builtin_amdgcn_s_setprio(1); _Pragma("unroll") for (int m = 0; m < 4; ++m) _Pragma("unroll") for (int n = 0; n < 2; ++n) _Pragma("unroll") for (int k = 0; k < 2; ++k) \
;         acc[ai][bj][m][n] = __builtin_amdgcn_mfma_f32_16x16x32_bf16(Bt[n][k], At[m][k], acc[ai][bj][m][n], 0, 0, 0); __builtin_amdgcn_s_setprio(0); } while (0)
; #define PG8_WAIT_V(n) asm volatile("s_waitcnt vmcnt(" #n ")" ::: "memory")
; #define PG8_WAIT_L(n) asm volatile("s_waitcnt lgkmcnt(" #n ")" ::: "memory")
; #define PG8_BAR __builtin_amdgcn_s_barrier()
; #define PG8_SCHED __builtin_amdgcn_sched_barrier(0)
; template <class Epi, class Sched>
; DEVI void gemm_phase(LAS unsigned char* lds, const Gemm g, const Sched& S, const Epi& E) {
;     ...
;             PG8_LDB(B0, 0, 0); PG8_LDB(B1, 0, 1); PG8_SCHED; PG8_LDA(At, 0, 0); PG8_STAGE(PG8_SA(1, 1), a1 + hstep, voffA);
;             PG8_WAIT_V(8); PG8_WAIT_L(0); PG8_BAR; PG8_MMA(0, 0, At, B0); PG8_MMA(0, 1, At, B1); PG8_BAR; PG8_SCHED;
;             PG8_LDA(At, 0, 1); PG8_STAGE(PG8_SB(0, 0), b2, voffB); PG8_STAGE(PG8_SB(0, 1), b2 + hstep, voffB); PG8_STAGE(PG8_SA(0, 0), a2, voffA);
;             PG8_WAIT_V(8); PG8_WAIT_L(0); PG8_BAR; PG8_MMA(1, 0, At, B0); PG8_MMA(1, 1, At, B1); PG8_BAR; PG8_SCHED;
.LBB0_139:
	ds_read_b128 v[128:131], v183
	ds_read_b128 v[132:135], v183 offset:1024
	ds_read_b128 v[136:139], v183 offset:2048
	ds_read_b128 v[140:143], v183 offset:3072
	ds_read_b128 v[144:147], v184
	ds_read_b128 v[148:151], v184 offset:1024
	ds_read_b128 v[152:155], v184 offset:2048
	ds_read_b128 v[156:159], v184 offset:3072
	s_add_u32 s26, s24, 0xfffc0080
	s_addc_u32 s27, s25, -1
	s_cmp_eq_u32 s59, 12
	s_cselect_b32 s29, s17, s27
	s_cselect_b32 s28, s55, s26
	s_cselect_b32 s27, s15, s58
	s_cselect_b32 s26, s56, s57
	v_lshl_add_u64 v[214:215], s[24:25], 0, v[170:171]
	s_add_i32 m0, s23, 0xc000
	ds_read_b128 v[176:179], v185
	ds_read_b128 v[186:189], v185 offset:1024
	ds_read_b128 v[190:193], v185 offset:2048
	ds_read_b128 v[194:197], v185 offset:3072
	ds_read_b128 v[198:201], v185 offset:4096
	ds_read_b128 v[202:205], v185 offset:5120
	ds_read_b128 v[206:209], v185 offset:6144
	ds_read_b128 v[210:213], v185 offset:7168
	global_load_lds_dwordx4 v[214:215], off
	v_lshl_add_u64 v[214:215], s[24:25], 0, v[168:169]
	s_add_i32 m0, s23, 0xe000
	s_nop 0
	global_load_lds_dwordx4 v[214:215], off
	s_waitcnt vmcnt(8)
	s_waitcnt lgkmcnt(0)
	s_barrier
	s_waitcnt lgkmcnt(0)
	v_mfma_f32_16x16x32_bf16 v[124:127], v[128:131], v[176:179], v[124:127]
	v_mfma_f32_16x16x32_bf16 v[120:123], v[136:139], v[176:179], v[120:123]
	v_mfma_f32_16x16x32_bf16 v[116:119], v[128:131], v[190:193], v[116:119]
	v_mfma_f32_16x16x32_bf16 v[112:115], v[136:139], v[190:193], v[112:115]
	v_mfma_f32_16x16x32_bf16 v[108:111], v[128:131], v[198:201], v[108:111]
	v_mfma_f32_16x16x32_bf16 v[88:91], v[136:139], v[198:201], v[88:91]
	v_mfma_f32_16x16x32_bf16 v[80:83], v[128:131], v[206:209], v[80:83]
	v_mfma_f32_16x16x32_bf16 v[72:75], v[136:139], v[206:209], v[72:75]
	v_mfma_f32_16x16x32_bf16 v[124:127], v[132:135], v[186:189], v[124:127]
	v_mfma_f32_16x16x32_bf16 v[120:123], v[140:143], v[186:189], v[120:123]
	v_mfma_f32_16x16x32_bf16 v[116:119], v[132:135], v[194:197], v[116:119]
	v_mfma_f32_16x16x32_bf16 v[112:115], v[140:143], v[194:197], v[112:115]
	v_mfma_f32_16x16x32_bf16 v[108:111], v[132:135], v[202:205], v[108:111]
	v_mfma_f32_16x16x32_bf16 v[88:91], v[140:143], v[202:205], v[88:91]
	v_mfma_f32_16x16x32_bf16 v[80:83], v[132:135], v[210:213], v[80:83]
	v_mfma_f32_16x16x32_bf16 v[72:75], v[140:143], v[210:213], v[72:75]
	v_mfma_f32_16x16x32_bf16 v[104:107], v[144:147], v[176:179], v[104:107]
	v_mfma_f32_16x16x32_bf16 v[100:103], v[152:155], v[176:179], v[100:103]
	v_mfma_f32_16x16x32_bf16 v[96:99], v[144:147], v[190:193], v[96:99]
	v_mfma_f32_16x16x32_bf16 v[92:95], v[152:155], v[190:193], v[92:95]
	v_mfma_f32_16x16x32_bf16 v[84:87], v[144:147], v[198:201], v[84:87]
	v_mfma_f32_16x16x32_bf16 v[76:79], v[152:155], v[198:201], v[76:79]
	v_mfma_f32_16x16x32_bf16 v[68:71], v[144:147], v[206:209], v[68:71]
	v_mfma_f32_16x16x32_bf16 v[64:67], v[152:155], v[206:209], v[64:67]
	v_mfma_f32_16x16x32_bf16 v[104:107], v[148:151], v[186:189], v[104:107]
	v_mfma_f32_16x16x32_bf16 v[100:103], v[156:159], v[186:189], v[100:103]
	v_mfma_f32_16x16x32_bf16 v[96:99], v[148:151], v[194:197], v[96:99]
	v_mfma_f32_16x16x32_bf16 v[92:95], v[156:159], v[194:197], v[92:95]
	v_mfma_f32_16x16x32_bf16 v[84:87], v[148:151], v[202:205], v[84:87]
	v_mfma_f32_16x16x32_bf16 v[76:79], v[156:159], v[202:205], v[76:79]
	v_mfma_f32_16x16x32_bf16 v[68:71], v[148:151], v[210:213], v[68:71]
	v_mfma_f32_16x16x32_bf16 v[64:67], v[156:159], v[210:213], v[64:67]
	s_barrier
	s_add_i32 s60, s51, s37
	v_lshl_add_u64 v[214:215], s[26:27], 0, v[164:165]
	s_mov_b32 m0, s60
	ds_read_b128 v[176:179], v185 offset:16384
	ds_read_b128 v[186:189], v185 offset:17408
	ds_read_b128 v[190:193], v185 offset:18432
	ds_read_b128 v[194:197], v185 offset:19456
	ds_read_b128 v[198:201], v185 offset:20480
	ds_read_b128 v[202:205], v185 offset:21504
	ds_read_b128 v[206:209], v185 offset:22528
	ds_read_b128 v[210:213], v185 offset:23552
	global_load_lds_dwordx4 v[214:215], off
	s_add_i32 m0, s60, 0x2000
	s_add_u32 s60, s26, 0x40000
	v_lshl_add_u64 v[216:217], s[26:27], 0, v[160:161]
	s_addc_u32 s61, s27, 0
	s_add_i32 s62, s52, s37
	global_load_lds_dwordx4 v[216:217], off
	v_lshl_add_u64 v[218:219], s[60:61], 0, v[164:165]
	s_mov_b32 m0, s62
	v_lshl_add_u64 v[220:221], s[28:29], 0, v[162:163]
	global_load_lds_dwordx4 v[218:219], off
	v_lshl_add_u64 v[218:219], s[60:61], 0, v[160:161]
	s_add_i32 m0, s62, 0x2000
	s_nop 0
	global_load_lds_dwordx4 v[218:219], off
	v_lshl_add_u64 v[218:219], s[28:29], 0, v[166:167]
	s_mov_b32 m0, s23
	s_nop 0
	global_load_lds_dwordx4 v[218:219], off
	s_mov_b32 m0, s40
	s_nop 0
	global_load_lds_dwordx4 v[220:221], off
	s_waitcnt vmcnt(8)
	s_waitcnt lgkmcnt(0)
	s_barrier
; #define PG8_STAGE(bufoff, gbase, voff) do { _Pragma("unroll") for (int _i = 0; _i < 2; ++_i) \
;         __builtin_amdgcn_global_load_lds((const unsigned*)((const char*)(gbase) + (voff)[_i]), (LAS unsigned*)(lds + (bufoff) + ldsw + _i * 8192), 16, 0, 0); } while (0)
; #define PG8_LDA(dst, b, h) do { _Pragma("unroll") for (int m = 0; m < 4; ++m) _Pragma("unroll") for (int k = 0; k < 2; ++k) dst[m][k] = *(const LAS bf16x8*)(lds + PG8_SA(b, h) + aoff + m * 2048 + k * 1024); } while (0)
; #define PG8_LDB(dst, b, h) do { _Pragma("unroll") for (int n = 0; n < 2; ++n) _Pragma("unroll") for (int k = 0; k < 2; ++k) dst[n][k] = *(const LAS bf16x8*)(lds + PG8_SB(b, h) + boff + n * 2048 + k * 1024); } while (0)
; #define PG8_MMA(ai, bj, At, Bt) do { __builtin_amdgcn_s_setprio(1); _Pragma("unroll") for (int m = 0; m < 4; ++m) _Pragma("unroll") for (int n = 0; n < 2; ++n) _Pragma("unroll") for (int k = 0; k < 2; ++k) \
;         acc[ai][bj][m][n] = __builtin_amdgcn_mfma_f32_16x16x32_bf16(Bt[n][k], At[m][k], acc[ai][bj][m][n], 0, 0, 0); __builtin_amdgcn_s_setprio(0); } while (0)
; #define PG8_WAIT_V(n) asm volatile("s_waitcnt vmcnt(" #n ")" ::: "memory")
; #define PG8_WAIT_L(n) asm volatile("s_waitcnt lgkmcnt(" #n ")" ::: "memory")
; #define PG8_BAR __builtin_amdgcn_s_barrier()
; #define PG8_SCHED __builtin_amdgcn_sched_barrier(0)
; template <class Epi, class Sched>
; DEVI void gemm_phase(LAS unsigned char* lds, const Gemm g, const Sched& S, const Epi& E) {
;     ...
;             PG8_WAIT_V(8); PG8_WAIT_L(0); PG8_BAR; PG8_MMA(1, 0, At, B0); PG8_MMA(1, 1, At, B1); PG8_BAR; PG8_SCHED;
;             PG8_LDB(B0, 1, 0); PG8_LDB(B1, 1, 1); PG8_SCHED; PG8_LDA(At, 1, 0); PG8_STAGE(PG8_SA(0, 1), a2 + hstep, voffA);
;             PG8_WAIT_V(8); PG8_WAIT_L(0); PG8_BAR; PG8_MMA(0, 0, At, B0); PG8_MMA(0, 1, At, B1); PG8_BAR; PG8_SCHED;
	s_waitcnt lgkmcnt(0)
	v_mfma_f32_16x16x32_bf16 v[60:63], v[128:131], v[176:179], v[60:63]
	v_mfma_f32_16x16x32_bf16 v[56:59], v[136:139], v[176:179], v[56:59]
	v_mfma_f32_16x16x32_bf16 v[48:51], v[128:131], v[190:193], v[48:51]
	v_mfma_f32_16x16x32_bf16 v[40:43], v[136:139], v[190:193], v[40:43]
	v_mfma_f32_16x16x32_bf16 v[32:35], v[128:131], v[198:201], v[32:35]
	v_mfma_f32_16x16x32_bf16 v[24:27], v[136:139], v[198:201], v[24:27]
	v_mfma_f32_16x16x32_bf16 v[16:19], v[128:131], v[206:209], v[16:19]
	v_mfma_f32_16x16x32_bf16 v[8:11], v[136:139], v[206:209], v[8:11]
	v_mfma_f32_16x16x32_bf16 v[60:63], v[132:135], v[186:189], v[60:63]
	v_mfma_f32_16x16x32_bf16 v[56:59], v[140:143], v[186:189], v[56:59]
	v_mfma_f32_16x16x32_bf16 v[48:51], v[132:135], v[194:197], v[48:51]
	v_mfma_f32_16x16x32_bf16 v[40:43], v[140:143], v[194:197], v[40:43]
	v_mfma_f32_16x16x32_bf16 v[32:35], v[132:135], v[202:205], v[32:35]
	v_mfma_f32_16x16x32_bf16 v[24:27], v[140:143], v[202:205], v[24:27]
	v_mfma_f32_16x16x32_bf16 v[16:19], v[132:135], v[210:213], v[16:19]
	v_mfma_f32_16x16x32_bf16 v[8:11], v[140:143], v[210:213], v[8:11]
	v_mfma_f32_16x16x32_bf16 v[52:55], v[144:147], v[176:179], v[52:55]
	v_mfma_f32_16x16x32_bf16 v[44:47], v[152:155], v[176:179], v[44:47]
	v_mfma_f32_16x16x32_bf16 v[36:39], v[144:147], v[190:193], v[36:39]
	v_mfma_f32_16x16x32_bf16 v[28:31], v[152:155], v[190:193], v[28:31]
	v_mfma_f32_16x16x32_bf16 v[20:23], v[144:147], v[198:201], v[20:23]
	v_mfma_f32_16x16x32_bf16 v[12:15], v[152:155], v[198:201], v[12:15]
	v_mfma_f32_16x16x32_bf16 v[4:7], v[144:147], v[206:209], v[4:7]
	v_mfma_f32_16x16x32_bf16 v[0:3], v[152:155], v[206:209], v[0:3]
	v_mfma_f32_16x16x32_bf16 v[52:55], v[148:151], v[186:189], v[52:55]
	v_mfma_f32_16x16x32_bf16 v[44:47], v[156:159], v[186:189], v[44:47]
	v_mfma_f32_16x16x32_bf16 v[36:39], v[148:151], v[194:197], v[36:39]
	v_mfma_f32_16x16x32_bf16 v[28:31], v[156:159], v[194:197], v[28:31]
	v_mfma_f32_16x16x32_bf16 v[20:23], v[148:151], v[202:205], v[20:23]
	v_mfma_f32_16x16x32_bf16 v[12:15], v[156:159], v[202:205], v[12:15]
	v_mfma_f32_16x16x32_bf16 v[4:7], v[148:151], v[210:213], v[4:7]
	v_mfma_f32_16x16x32_bf16 v[0:3], v[156:159], v[210:213], v[0:3]
	s_barrier
	s_add_i32 s60, 0, 0x18000
	s_add_i32 s61, 0, 0x1c000
	v_add_u32_e32 v140, s60, v181
	v_add_u32_e32 v156, s61, v181
	ds_read_b128 v[128:131], v140
	ds_read_b128 v[132:135], v140 offset:1024
	ds_read_b128 v[136:139], v140 offset:2048
	ds_read_b128 v[140:143], v140 offset:3072
	ds_read_b128 v[144:147], v156
	ds_read_b128 v[148:151], v156 offset:1024
	ds_read_b128 v[152:155], v156 offset:2048
	ds_read_b128 v[156:159], v156 offset:3072
	s_add_u32 s28, s28, 0x40000
	s_addc_u32 s29, s29, 0
	s_mov_b32 m0, s41
	v_lshl_add_u64 v[222:223], s[28:29], 0, v[166:167]
	ds_read_b128 v[176:179], v185 offset:32768
	ds_read_b128 v[186:189], v185 offset:33792
	ds_read_b128 v[190:193], v185 offset:34816
	ds_read_b128 v[194:197], v185 offset:35840
	ds_read_b128 v[198:201], v185 offset:36864
	ds_read_b128 v[202:205], v185 offset:37888
	ds_read_b128 v[206:209], v185 offset:38912
	ds_read_b128 v[210:213], v185 offset:39936
	global_load_lds_dwordx4 v[222:223], off
	v_lshl_add_u64 v[222:223], s[28:29], 0, v[162:163]
	s_mov_b32 m0, s42
	s_nop 0
	global_load_lds_dwordx4 v[222:223], off
	s_waitcnt vmcnt(8)
	s_waitcnt lgkmcnt(0)
	s_barrier
	s_waitcnt lgkmcnt(0)
	v_mfma_f32_16x16x32_bf16 v[124:127], v[128:131], v[176:179], v[124:127]
	v_mfma_f32_16x16x32_bf16 v[120:123], v[136:139], v[176:179], v[120:123]
	v_mfma_f32_16x16x32_bf16 v[116:119], v[128:131], v[190:193], v[116:119]
	v_mfma_f32_16x16x32_bf16 v[112:115], v[136:139], v[190:193], v[112:115]
	v_mfma_f32_16x16x32_bf16 v[108:111], v[128:131], v[198:201], v[108:111]
	v_mfma_f32_16x16x32_bf16 v[88:91], v[136:139], v[198:201], v[88:91]
	v_mfma_f32_16x16x32_bf16 v[80:83], v[128:131], v[206:209], v[80:83]
	v_mfma_f32_16x16x32_bf16 v[72:75], v[136:139], v[206:209], v[72:75]
	v_mfma_f32_16x16x32_bf16 v[124:127], v[132:135], v[186:189], v[124:127]
	v_mfma_f32_16x16x32_bf16 v[120:123], v[140:143], v[186:189], v[120:123]
	v_mfma_f32_16x16x32_bf16 v[116:119], v[132:135], v[194:197], v[116:119]
	v_mfma_f32_16x16x32_bf16 v[112:115], v[140:143], v[194:197], v[112:115]
	v_mfma_f32_16x16x32_bf16 v[108:111], v[132:135], v[202:205], v[108:111]
	v_mfma_f32_16x16x32_bf16 v[88:91], v[140:143], v[202:205], v[88:91]
	v_mfma_f32_16x16x32_bf16 v[80:83], v[132:135], v[210:213], v[80:83]
	v_mfma_f32_16x16x32_bf16 v[72:75], v[140:143], v[210:213], v[72:75]
	v_mfma_f32_16x16x32_bf16 v[104:107], v[144:147], v[176:179], v[104:107]
	v_mfma_f32_16x16x32_bf16 v[100:103], v[152:155], v[176:179], v[100:103]
	v_mfma_f32_16x16x32_bf16 v[96:99], v[144:147], v[190:193], v[96:99]
	v_mfma_f32_16x16x32_bf16 v[92:95], v[152:155], v[190:193], v[92:95]
	v_mfma_f32_16x16x32_bf16 v[84:87], v[144:147], v[198:201], v[84:87]
	v_mfma_f32_16x16x32_bf16 v[76:79], v[152:155], v[198:201], v[76:79]
	v_mfma_f32_16x16x32_bf16 v[68:71], v[144:147], v[206:209], v[68:71]
	v_mfma_f32_16x16x32_bf16 v[64:67], v[152:155], v[206:209], v[64:67]
	v_mfma_f32_16x16x32_bf16 v[104:107], v[148:151], v[186:189], v[104:107]
	v_mfma_f32_16x16x32_bf16 v[100:103], v[156:159], v[186:189], v[100:103]
	v_mfma_f32_16x16x32_bf16 v[96:99], v[148:151], v[194:197], v[96:99]
	v_mfma_f32_16x16x32_bf16 v[92:95], v[156:159], v[194:197], v[92:95]
	v_mfma_f32_16x16x32_bf16 v[84:87], v[148:151], v[202:205], v[84:87]
	v_mfma_f32_16x16x32_bf16 v[76:79], v[156:159], v[202:205], v[76:79]
	v_mfma_f32_16x16x32_bf16 v[68:71], v[148:151], v[210:213], v[68:71]
	v_mfma_f32_16x16x32_bf16 v[64:67], v[156:159], v[210:213], v[64:67]
	s_barrier
; #define PG8_STAGE(bufoff, gbase, voff) do { _Pragma("unroll") for (int _i = 0; _i < 2; ++_i) \
;         __builtin_amdgcn_global_load_lds((const unsigned*)((const char*)(gbase) + (voff)[_i]), (LAS unsigned*)(lds + (bufoff) + ldsw + _i * 8192), 16, 0, 0); } while (0)
; #define PG8_LDA(dst, b, h) do { _Pragma("unroll") for (int m = 0; m < 4; ++m) _Pragma("unroll") for (int k = 0; k < 2; ++k) dst[m][k] = *(const LAS bf16x8*)(lds + PG8_SA(b, h) + aoff + m * 2048 + k * 1024); } while (0)
; #define PG8_MMA(ai, bj, At, Bt) do { __builtin_amdgcn_s_setprio(1); _Pragma("unroll") for (int m = 0; m < 4; ++m) _Pragma("unroll") for (int n = 0; n < 2; ++n) _Pragma("unroll") for (int k = 0; k < 2; ++k) \
;         acc[ai][bj][m][n] = __builtin_amdgcn_mfma_f32_16x16x32_bf16(Bt[n][k], At[m][k], acc[ai][bj][m][n], 0, 0, 0); __builtin_amdgcn_s_setprio(0); } while (0)
; #define PG8_WAIT_V(n) asm volatile("s_waitcnt vmcnt(" #n ")" ::: "memory")
; #define PG8_WAIT_L(n) asm volatile("s_waitcnt lgkmcnt(" #n ")" ::: "memory")
; #define PG8_BAR __builtin_amdgcn_s_barrier()
; #define PG8_SCHED __builtin_amdgcn_sched_barrier(0)
; template <class Epi, class Sched>
; DEVI void gemm_phase(LAS unsigned char* lds, const Gemm g, const Sched& S, const Epi& E) {
;     ...
;             PG8_LDA(At, 1, 1); PG8_STAGE(PG8_SB(1, 0), b3, voffB); PG8_STAGE(PG8_SB(1, 1), b3 + hstep, voffB); PG8_STAGE(PG8_SA(1, 0), a3, voffA);
;             PG8_WAIT_V(8); PG8_WAIT_L(0); PG8_BAR; PG8_MMA(1, 0, At, B0); PG8_MMA(1, 1, At, B1); PG8_BAR; PG8_SCHED;
;         }
;         if (wr == 0) PG8_BAR;
	s_add_i32 s28, s60, s37
	v_lshl_add_u64 v[214:215], v[214:215], 0, s[10:11]
	s_mov_b32 m0, s28
	ds_read_b128 v[176:179], v185 offset:49152
	ds_read_b128 v[186:189], v185 offset:50176
	ds_read_b128 v[190:193], v185 offset:51200
	ds_read_b128 v[194:197], v185 offset:52224
	ds_read_b128 v[198:201], v185 offset:53248
	ds_read_b128 v[202:205], v185 offset:54272
	ds_read_b128 v[206:209], v185 offset:55296
	ds_read_b128 v[210:213], v185 offset:56320
	global_load_lds_dwordx4 v[214:215], off
	s_add_i32 m0, s28, 0x2000
	s_add_u32 s26, s26, 0x40080
	v_lshl_add_u64 v[214:215], v[216:217], 0, s[10:11]
	s_addc_u32 s27, s27, 0
	s_add_i32 s28, s61, s37
	global_load_lds_dwordx4 v[214:215], off
	v_lshl_add_u64 v[214:215], s[26:27], 0, v[164:165]
	s_mov_b32 m0, s28
	s_nop 0
	global_load_lds_dwordx4 v[214:215], off
	v_lshl_add_u64 v[214:215], s[26:27], 0, v[160:161]
	s_add_i32 m0, s28, 0x2000
	s_nop 0
	global_load_lds_dwordx4 v[214:215], off
	v_lshl_add_u64 v[214:215], v[218:219], 0, s[10:11]
	s_mov_b32 m0, s48
	s_nop 0
	global_load_lds_dwordx4 v[214:215], off
	v_lshl_add_u64 v[214:215], v[220:221], 0, s[10:11]
	s_mov_b32 m0, s49
	s_nop 0
	global_load_lds_dwordx4 v[214:215], off
	s_waitcnt vmcnt(8)
	s_waitcnt lgkmcnt(0)
	s_barrier
	s_waitcnt lgkmcnt(0)
	v_mfma_f32_16x16x32_bf16 v[60:63], v[128:131], v[176:179], v[60:63]
	v_mfma_f32_16x16x32_bf16 v[56:59], v[136:139], v[176:179], v[56:59]
	v_mfma_f32_16x16x32_bf16 v[48:51], v[128:131], v[190:193], v[48:51]
	v_mfma_f32_16x16x32_bf16 v[40:43], v[136:139], v[190:193], v[40:43]
	v_mfma_f32_16x16x32_bf16 v[32:35], v[128:131], v[198:201], v[32:35]
	v_mfma_f32_16x16x32_bf16 v[24:27], v[136:139], v[198:201], v[24:27]
	v_mfma_f32_16x16x32_bf16 v[16:19], v[128:131], v[206:209], v[16:19]
	v_mfma_f32_16x16x32_bf16 v[8:11], v[136:139], v[206:209], v[8:11]
	v_mfma_f32_16x16x32_bf16 v[60:63], v[132:135], v[186:189], v[60:63]
	v_mfma_f32_16x16x32_bf16 v[56:59], v[140:143], v[186:189], v[56:59]
	v_mfma_f32_16x16x32_bf16 v[48:51], v[132:135], v[194:197], v[48:51]
	v_mfma_f32_16x16x32_bf16 v[40:43], v[140:143], v[194:197], v[40:43]
	v_mfma_f32_16x16x32_bf16 v[32:35], v[132:135], v[202:205], v[32:35]
	v_mfma_f32_16x16x32_bf16 v[24:27], v[140:143], v[202:205], v[24:27]
	v_mfma_f32_16x16x32_bf16 v[16:19], v[132:135], v[210:213], v[16:19]
	v_mfma_f32_16x16x32_bf16 v[8:11], v[140:143], v[210:213], v[8:11]
	v_mfma_f32_16x16x32_bf16 v[52:55], v[144:147], v[176:179], v[52:55]
	v_mfma_f32_16x16x32_bf16 v[44:47], v[152:155], v[176:179], v[44:47]
	v_mfma_f32_16x16x32_bf16 v[36:39], v[144:147], v[190:193], v[36:39]
	v_mfma_f32_16x16x32_bf16 v[28:31], v[152:155], v[190:193], v[28:31]
	v_mfma_f32_16x16x32_bf16 v[20:23], v[144:147], v[198:201], v[20:23]
	v_mfma_f32_16x16x32_bf16 v[12:15], v[152:155], v[198:201], v[12:15]
	v_mfma_f32_16x16x32_bf16 v[4:7], v[144:147], v[206:209], v[4:7]
	v_mfma_f32_16x16x32_bf16 v[0:3], v[152:155], v[206:209], v[0:3]
	v_mfma_f32_16x16x32_bf16 v[52:55], v[148:151], v[186:189], v[52:55]
	v_mfma_f32_16x16x32_bf16 v[44:47], v[156:159], v[186:189], v[44:47]
	v_mfma_f32_16x16x32_bf16 v[36:39], v[148:151], v[194:197], v[36:39]
	v_mfma_f32_16x16x32_bf16 v[28:31], v[156:159], v[194:197], v[28:31]
	v_mfma_f32_16x16x32_bf16 v[20:23], v[148:151], v[202:205], v[20:23]
	v_mfma_f32_16x16x32_bf16 v[12:15], v[156:159], v[202:205], v[12:15]
	v_mfma_f32_16x16x32_bf16 v[4:7], v[148:151], v[210:213], v[4:7]
	v_mfma_f32_16x16x32_bf16 v[0:3], v[156:159], v[210:213], v[0:3]
	s_barrier
	s_add_i32 s59, s59, 2
	s_add_u32 s57, s57, 0x100
	s_addc_u32 s58, s58, 0
	s_add_u32 s24, s24, 0x100
	s_addc_u32 s25, s25, 0
	s_cmp_gt_u32 s59, 13
	s_cbranch_scc0 .LBB0_139
	s_and_b64 vcc, exec, s[12:13]
	s_cbranch_vccz .LBB0_142
	s_barrier

; #define LAS __attribute__((address_space(3)))
; #define PG8_WAIT_V(n) asm volatile("s_waitcnt vmcnt(" #n ")" ::: "memory")
; #define PG8_BAR __builtin_amdgcn_s_barrier()
; DEVI unsigned xb_xcc_id() { return (unsigned)__builtin_amdgcn_s_getreg((3 << 11) | 20) & 0xFu; }
; template <class Epi, class Sched>
; DEVI void gemm_phase(LAS unsigned char* lds, const Gemm g, const Sched& S, const Epi& E) {
;     ...
;     PG8_WAIT_V(0);
;     PG8_BAR;
; DEVI void xcd_barrier(unsigned* bar, volatile LAS unsigned* st) {
;     asm volatile("s_waitcnt vmcnt(0)" ::: "memory");
;     __syncthreads();
;     if (threadIdx.x == 0) {
;         const unsigned x = xb_xcc_id();
;         __builtin_amdgcn_s_waitcnt(0);
;         unsigned nloc = st[0], nx = st[1];
;         if (nloc == 0u) { xcd_barrier_complete(bar, x, nloc, nx); st[0] = nloc; st[1] = nx; }
.LBB0_146:
	s_waitcnt vmcnt(0)
	s_add_u32 s0, s96, 0x6fc000
	v_writelane_b32 v248, s0, 2
	s_addc_u32 s0, s97, 0
	v_writelane_b32 v248, s0, 3
	s_waitcnt lgkmcnt(0)
	s_setprio 0
	s_barrier
	s_mov_b64 s[0:1], exec
	v_readlane_b32 s2, v249, 53
	v_readlane_b32 s3, v249, 54
	s_and_b64 s[2:3], s[0:1], s[2:3]
	s_mov_b64 exec, s[2:3]
	s_cbranch_execz .LBB0_202
	s_add_i32 s3, 0, 0x26ff0
	v_mov_b32_e32 v0, s3
	s_getreg_b32 s2, hwreg(HW_REG_XCC_ID, 0, 4)
	s_waitcnt vmcnt(0) expcnt(0) lgkmcnt(0)
	ds_read_b32 v2, v0
	s_add_i32 s3, 0, 0x26ff4
	v_mov_b32_e32 v0, s3
	ds_read_b32 v0, v0
	s_and_b32 s33, s2, 15
	s_waitcnt lgkmcnt(1)
	v_cmp_ne_u32_e32 vcc, 0, v2
	s_cbranch_vccnz .LBB0_162
	s_add_u32 s2, s96, 0x6fc200
	s_addc_u32 s3, s97, 0
	s_add_u32 s4, s96, 0x6fc400
	s_addc_u32 s5, s97, 0
	s_add_u32 s6, s96, 0x6fc500
	s_addc_u32 s7, s97, 0
	s_add_u32 s8, s96, 0x6fc600
	s_addc_u32 s9, s97, 0
	s_add_u32 s10, s96, 0x6fc700
	s_addc_u32 s11, s97, 0
	s_add_u32 s12, s96, 0x6fc800
	s_addc_u32 s13, s97, 0
	s_add_u32 s14, s96, 0x6fc900
	s_addc_u32 s15, s97, 0
	s_add_u32 s16, s96, 0x6fca00
	s_addc_u32 s17, s97, 0
	s_add_u32 s18, s96, 0x6fcb00
	s_addc_u32 s19, s97, 0
	s_add_u32 s20, s96, 0x6fcc00
	s_addc_u32 s21, s97, 0
	s_add_u32 s22, s96, 0x6fcd00
	s_addc_u32 s23, s97, 0
	s_add_u32 s24, s96, 0x6fce00
	s_addc_u32 s25, s97, 0
	s_add_u32 s26, s96, 0x6fcf00
	s_addc_u32 s27, s97, 0
	s_add_u32 s28, s96, 0x6fd000
	s_addc_u32 s29, s97, 0
	s_add_u32 s30, s96, 0x6fd100
	s_addc_u32 s31, s97, 0
	s_add_u32 s34, s96, 0x6fd200
	s_addc_u32 s35, s97, 0
	s_add_u32 s36, s96, 0x6fd300
	s_addc_u32 s37, s97, 0
	s_mov_b32 s48, 1
	v_mov_b32_e32 v16, 0
	s_branch .LBB0_150

;     DEVI bool next(int i, Unit& u) const {
;         const long L = (long)i * G + c; if (L >= nwg) return false;
;         int wgid = (int)L; { const int q = nwg / NXCD, r = nwg % NXCD, xcd = wgid % NXCD, off = wgid / NXCD; wgid = (xcd < r ? xcd * (q + 1) : r * (q + 1) + (xcd - r) * q) + off; }
;         const int nig = WGM * nN, gid = wgid / nig, fm = gid * WGM, gsz = (nM - fm) < WGM ? (nM - fm) : WGM;
;         u.pm = fm + ((wgid % nig) % gsz); u.pn = (wgid % nig) / gsz; return true;
.LBB0_485:
	s_or_b64 exec, exec, s[0:1]
	s_mov_b64 s[6:7], s[96:97]
	s_mov_b32 s19, s89
	v_readlane_b32 s33, v249, 0
	s_waitcnt lgkmcnt(0)
	s_barrier
	v_readfirstlane_b32 s98, v242
	s_nop 3
	s_cmpk_lt_u32 s98, 0x100
	s_cbranch_scc1 .Lsprio_sp5
	s_setprio 1
.Lsprio_sp5:
	v_mov_b32_e32 v8, v242
	s_cmpk_lt_i32 s33, 0x200
	s_cselect_b64 s[2:3], -1, 0
	s_cmpk_gt_i32 s33, 0x1ff
	v_readfirstlane_b32 s4, v8
	s_cbranch_scc1 .LBB0_491
	s_ashr_i32 s0, s33, 31
	s_lshr_b32 s0, s0, 29
	s_add_i32 s9, s33, s0
	s_and_b32 s0, s9, -8
	s_sub_i32 s5, s33, s0
	s_cmp_gt_i32 s5, -1
	s_cbranch_scc0 .LBB0_488
	s_lshl_b32 s8, s5, 6
	s_ashr_i32 s0, s9, 3
	s_cbranch_execz .LBB0_489
	s_branch .LBB0_490

; #define PG8_STAGE(bufoff, gbase, voff) do { _Pragma("unroll") for (int _i = 0; _i < 2; ++_i) \
;         __builtin_amdgcn_global_load_lds((const unsigned*)((const char*)(gbase) + (voff)[_i]), (LAS unsigned*)(lds + (bufoff) + ldsw + _i * 8192), 16, 0, 0); } while (0)
; #define PG8_LDA(dst, b, h) do { _Pragma("unroll") for (int m = 0; m < 4; ++m) _Pragma("unroll") for (int k = 0; k < 2; ++k) dst[m][k] = *(const LAS bf16x8*)(lds + PG8_SA(b, h) + aoff + m * 2048 + k * 1024); } while (0)
; #define PG8_LDB(dst, b, h) do { _Pragma("unroll") for (int n = 0; n < 2; ++n) _Pragma("unroll") for (int k = 0; k < 2; ++k) dst[n][k] = *(const LAS bf16x8*)(lds + PG8_SB(b, h) + boff + n * 2048 + k * 1024); } while (0)
; #define PG8_MMA(ai, bj, At, Bt) do { __builtin_amdgcn_s_setprio(1); _Pragma("unroll") for (int m = 0; m < 4; ++m) _Pragma("unroll") for (int n = 0; n < 2; ++n) _Pragma("unroll") for (int k = 0; k < 2; ++k) \
;         acc[ai][bj][m][n] = __builtin_amdgcn_mfma_f32_16x16x32_bf16(Bt[n][k], At[m][k], acc[ai][bj][m][n], 0, 0, 0); __builtin_amdgcn_s_setprio(0); } while (0)
; #define PG8_WAIT_V(n) asm volatile("s_waitcnt vmcnt(" #n ")" ::: "memory")
; #define PG8_WAIT_L(n) asm volatile("s_waitcnt lgkmcnt(" #n ")" ::: "memory")
; #define PG8_BAR __builtin_amdgcn_s_barrier()
; #define PG8_SCHED __builtin_amdgcn_sched_barrier(0)
; template <class Epi, class Sched>
; DEVI void gemm_phase(LAS unsigned char* lds, const Gemm g, const Sched& S, const Epi& E) {
;     ...
;             PG8_LDB(B0, 0, 0); PG8_LDB(B1, 0, 1); PG8_SCHED; PG8_LDA(At, 0, 0); PG8_STAGE(PG8_SA(1, 1), a1 + hstep, voffA);
;             PG8_WAIT_V(8); PG8_WAIT_L(0); PG8_BAR; PG8_MMA(0, 0, At, B0); PG8_MMA(0, 1, At, B1); PG8_BAR; PG8_SCHED;
;             PG8_LDA(At, 0, 1); PG8_STAGE(PG8_SB(0, 0), b2, voffB); PG8_STAGE(PG8_SB(0, 1), b2 + hstep, voffB); PG8_STAGE(PG8_SA(0, 0), a2, voffA);
;             PG8_WAIT_V(8); PG8_WAIT_L(0); PG8_BAR; PG8_MMA(1, 0, At, B0); PG8_MMA(1, 1, At, B1); PG8_BAR; PG8_SCHED;
.LBB0_504:
	ds_read_b128 v[144:147], v159
	ds_read_b128 v[148:151], v159 offset:1024
	ds_read_b128 v[152:155], v159 offset:2048
	ds_read_b128 v[164:167], v159 offset:3072
	ds_read_b128 v[168:171], v160
	ds_read_b128 v[172:175], v160 offset:1024
	ds_read_b128 v[176:179], v160 offset:2048
	ds_read_b128 v[180:183], v160 offset:3072
	s_add_u32 s34, s30, 0xfffc0080
	s_addc_u32 s35, s31, -1
	s_cmp_eq_u32 s64, 12
	s_cselect_b32 s37, s1, s35
	s_cselect_b32 s36, s23, s34
	s_cselect_b32 s35, s21, s63
	s_cselect_b32 s34, s29, s62
	v_lshl_add_u64 v[216:217], s[30:31], 0, v[138:139]
	s_add_i32 m0, s43, 0xc000
	ds_read_b128 v[184:187], v161
	ds_read_b128 v[188:191], v161 offset:1024
	ds_read_b128 v[192:195], v161 offset:2048
	ds_read_b128 v[196:199], v161 offset:3072
	ds_read_b128 v[200:203], v161 offset:4096
	ds_read_b128 v[204:207], v161 offset:5120
	ds_read_b128 v[208:211], v161 offset:6144
	ds_read_b128 v[212:215], v161 offset:7168
	global_load_lds_dwordx4 v[216:217], off
	v_lshl_add_u64 v[216:217], s[30:31], 0, v[136:137]
	s_add_i32 m0, s43, 0xe000
	s_nop 0
	global_load_lds_dwordx4 v[216:217], off
	s_waitcnt vmcnt(8)
	s_waitcnt lgkmcnt(0)
	s_barrier
	s_waitcnt lgkmcnt(0)
	v_mfma_f32_16x16x32_bf16 v[124:127], v[144:147], v[184:187], v[124:127]
	v_mfma_f32_16x16x32_bf16 v[120:123], v[152:155], v[184:187], v[120:123]
	v_mfma_f32_16x16x32_bf16 v[108:111], v[144:147], v[192:195], v[108:111]
	v_mfma_f32_16x16x32_bf16 v[104:107], v[152:155], v[192:195], v[104:107]
	v_mfma_f32_16x16x32_bf16 v[92:95], v[144:147], v[200:203], v[92:95]
	v_mfma_f32_16x16x32_bf16 v[88:91], v[152:155], v[200:203], v[88:91]
	v_mfma_f32_16x16x32_bf16 v[76:79], v[144:147], v[208:211], v[76:79]
	v_mfma_f32_16x16x32_bf16 v[72:75], v[152:155], v[208:211], v[72:75]
	v_mfma_f32_16x16x32_bf16 v[124:127], v[148:151], v[188:191], v[124:127]
	v_mfma_f32_16x16x32_bf16 v[120:123], v[164:167], v[188:191], v[120:123]
	v_mfma_f32_16x16x32_bf16 v[108:111], v[148:151], v[196:199], v[108:111]
	v_mfma_f32_16x16x32_bf16 v[104:107], v[164:167], v[196:199], v[104:107]
	v_mfma_f32_16x16x32_bf16 v[92:95], v[148:151], v[204:207], v[92:95]
	v_mfma_f32_16x16x32_bf16 v[88:91], v[164:167], v[204:207], v[88:91]
	v_mfma_f32_16x16x32_bf16 v[76:79], v[148:151], v[212:215], v[76:79]
	v_mfma_f32_16x16x32_bf16 v[72:75], v[164:167], v[212:215], v[72:75]
	v_mfma_f32_16x16x32_bf16 v[116:119], v[168:171], v[184:187], v[116:119]
	v_mfma_f32_16x16x32_bf16 v[112:115], v[176:179], v[184:187], v[112:115]
	v_mfma_f32_16x16x32_bf16 v[100:103], v[168:171], v[192:195], v[100:103]
	v_mfma_f32_16x16x32_bf16 v[96:99], v[176:179], v[192:195], v[96:99]
	v_mfma_f32_16x16x32_bf16 v[84:87], v[168:171], v[200:203], v[84:87]
	v_mfma_f32_16x16x32_bf16 v[80:83], v[176:179], v[200:203], v[80:83]
	v_mfma_f32_16x16x32_bf16 v[68:71], v[168:171], v[208:211], v[68:71]
	v_mfma_f32_16x16x32_bf16 v[64:67], v[176:179], v[208:211], v[64:67]
	v_mfma_f32_16x16x32_bf16 v[116:119], v[172:175], v[188:191], v[116:119]
	v_mfma_f32_16x16x32_bf16 v[112:115], v[180:183], v[188:191], v[112:115]
	v_mfma_f32_16x16x32_bf16 v[100:103], v[172:175], v[196:199], v[100:103]
	v_mfma_f32_16x16x32_bf16 v[96:99], v[180:183], v[196:199], v[96:99]
	v_mfma_f32_16x16x32_bf16 v[84:87], v[172:175], v[204:207], v[84:87]
	v_mfma_f32_16x16x32_bf16 v[80:83], v[180:183], v[204:207], v[80:83]
	v_mfma_f32_16x16x32_bf16 v[68:71], v[172:175], v[212:215], v[68:71]
	v_mfma_f32_16x16x32_bf16 v[64:67], v[180:183], v[212:215], v[64:67]
	s_barrier
	s_add_i32 s65, s60, s42
	v_lshl_add_u64 v[216:217], s[34:35], 0, v[130:131]
	s_mov_b32 m0, s65
	ds_read_b128 v[184:187], v161 offset:16384
	ds_read_b128 v[188:191], v161 offset:17408
	ds_read_b128 v[192:195], v161 offset:18432
	ds_read_b128 v[196:199], v161 offset:19456
	ds_read_b128 v[200:203], v161 offset:20480
	ds_read_b128 v[204:207], v161 offset:21504
	ds_read_b128 v[208:211], v161 offset:22528
	ds_read_b128 v[212:215], v161 offset:23552
	global_load_lds_dwordx4 v[216:217], off
	s_add_i32 m0, s65, 0x2000
	s_add_u32 s68, s34, 0x40000
	v_lshl_add_u64 v[218:219], s[34:35], 0, v[134:135]
	s_addc_u32 s69, s35, 0
	s_add_i32 s65, s61, s42
	global_load_lds_dwordx4 v[218:219], off
	v_lshl_add_u64 v[220:221], s[68:69], 0, v[130:131]
	s_mov_b32 m0, s65
	v_lshl_add_u64 v[222:223], s[36:37], 0, v[132:133]
	global_load_lds_dwordx4 v[220:221], off
	v_lshl_add_u64 v[220:221], s[68:69], 0, v[134:135]
	s_add_i32 m0, s65, 0x2000
	s_nop 0
	global_load_lds_dwordx4 v[220:221], off
	v_lshl_add_u64 v[220:221], s[36:37], 0, v[128:129]
	s_mov_b32 m0, s43
	s_nop 0
	global_load_lds_dwordx4 v[220:221], off
	s_mov_b32 m0, s48
	s_nop 0
	global_load_lds_dwordx4 v[222:223], off
	s_waitcnt vmcnt(8)
	s_waitcnt lgkmcnt(0)
	s_barrier
; #define PG8_STAGE(bufoff, gbase, voff) do { _Pragma("unroll") for (int _i = 0; _i < 2; ++_i) \
;         __builtin_amdgcn_global_load_lds((const unsigned*)((const char*)(gbase) + (voff)[_i]), (LAS unsigned*)(lds + (bufoff) + ldsw + _i * 8192), 16, 0, 0); } while (0)
; #define PG8_LDA(dst, b, h) do { _Pragma("unroll") for (int m = 0; m < 4; ++m) _Pragma("unroll") for (int k = 0; k < 2; ++k) dst[m][k] = *(const LAS bf16x8*)(lds + PG8_SA(b, h) + aoff + m * 2048 + k * 1024); } while (0)
; #define PG8_LDB(dst, b, h) do { _Pragma("unroll") for (int n = 0; n < 2; ++n) _Pragma("unroll") for (int k = 0; k < 2; ++k) dst[n][k] = *(const LAS bf16x8*)(lds + PG8_SB(b, h) + boff + n * 2048 + k * 1024); } while (0)
; #define PG8_MMA(ai, bj, At, Bt) do { __builtin_amdgcn_s_setprio(1); _Pragma("unroll") for (int m = 0; m < 4; ++m) _Pragma("unroll") for (int n = 0; n < 2; ++n) _Pragma("unroll") for (int k = 0; k < 2; ++k) \
;         acc[ai][bj][m][n] = __builtin_amdgcn_mfma_f32_16x16x32_bf16(Bt[n][k], At[m][k], acc[ai][bj][m][n], 0, 0, 0); __builtin_amdgcn_s_setprio(0); } while (0)
; #define PG8_WAIT_V(n) asm volatile("s_waitcnt vmcnt(" #n ")" ::: "memory")
; #define PG8_WAIT_L(n) asm volatile("s_waitcnt lgkmcnt(" #n ")" ::: "memory")
; #define PG8_BAR __builtin_amdgcn_s_barrier()
; #define PG8_SCHED __builtin_amdgcn_sched_barrier(0)
; template <class Epi, class Sched>
; DEVI void gemm_phase(LAS unsigned char* lds, const Gemm g, const Sched& S, const Epi& E) {
;     ...
;             PG8_WAIT_V(8); PG8_WAIT_L(0); PG8_BAR; PG8_MMA(1, 0, At, B0); PG8_MMA(1, 1, At, B1); PG8_BAR; PG8_SCHED;
;             PG8_LDB(B0, 1, 0); PG8_LDB(B1, 1, 1); PG8_SCHED; PG8_LDA(At, 1, 0); PG8_STAGE(PG8_SA(0, 1), a2 + hstep, voffA);
;             PG8_WAIT_V(8); PG8_WAIT_L(0); PG8_BAR; PG8_MMA(0, 0, At, B0); PG8_MMA(0, 1, At, B1); PG8_BAR; PG8_SCHED;
	s_waitcnt lgkmcnt(0)
	v_mfma_f32_16x16x32_bf16 v[60:63], v[144:147], v[184:187], v[60:63]
	v_mfma_f32_16x16x32_bf16 v[56:59], v[152:155], v[184:187], v[56:59]
	v_mfma_f32_16x16x32_bf16 v[44:47], v[144:147], v[192:195], v[44:47]
	v_mfma_f32_16x16x32_bf16 v[40:43], v[152:155], v[192:195], v[40:43]
	v_mfma_f32_16x16x32_bf16 v[28:31], v[144:147], v[200:203], v[28:31]
	v_mfma_f32_16x16x32_bf16 v[24:27], v[152:155], v[200:203], v[24:27]
	v_mfma_f32_16x16x32_bf16 v[12:15], v[144:147], v[208:211], v[12:15]
	v_mfma_f32_16x16x32_bf16 v[8:11], v[152:155], v[208:211], v[8:11]
	v_mfma_f32_16x16x32_bf16 v[60:63], v[148:151], v[188:191], v[60:63]
	v_mfma_f32_16x16x32_bf16 v[56:59], v[164:167], v[188:191], v[56:59]
	v_mfma_f32_16x16x32_bf16 v[44:47], v[148:151], v[196:199], v[44:47]
	v_mfma_f32_16x16x32_bf16 v[40:43], v[164:167], v[196:199], v[40:43]
	v_mfma_f32_16x16x32_bf16 v[28:31], v[148:151], v[204:207], v[28:31]
	v_mfma_f32_16x16x32_bf16 v[24:27], v[164:167], v[204:207], v[24:27]
	v_mfma_f32_16x16x32_bf16 v[12:15], v[148:151], v[212:215], v[12:15]
	v_mfma_f32_16x16x32_bf16 v[8:11], v[164:167], v[212:215], v[8:11]
	v_mfma_f32_16x16x32_bf16 v[52:55], v[168:171], v[184:187], v[52:55]
	v_mfma_f32_16x16x32_bf16 v[48:51], v[176:179], v[184:187], v[48:51]
	v_mfma_f32_16x16x32_bf16 v[36:39], v[168:171], v[192:195], v[36:39]
	v_mfma_f32_16x16x32_bf16 v[32:35], v[176:179], v[192:195], v[32:35]
	v_mfma_f32_16x16x32_bf16 v[20:23], v[168:171], v[200:203], v[20:23]
	v_mfma_f32_16x16x32_bf16 v[16:19], v[176:179], v[200:203], v[16:19]
	v_mfma_f32_16x16x32_bf16 v[4:7], v[168:171], v[208:211], v[4:7]
	v_mfma_f32_16x16x32_bf16 v[0:3], v[176:179], v[208:211], v[0:3]
	v_mfma_f32_16x16x32_bf16 v[52:55], v[172:175], v[188:191], v[52:55]
	v_mfma_f32_16x16x32_bf16 v[48:51], v[180:183], v[188:191], v[48:51]
	v_mfma_f32_16x16x32_bf16 v[36:39], v[172:175], v[196:199], v[36:39]
	v_mfma_f32_16x16x32_bf16 v[32:35], v[180:183], v[196:199], v[32:35]
	v_mfma_f32_16x16x32_bf16 v[20:23], v[172:175], v[204:207], v[20:23]
	v_mfma_f32_16x16x32_bf16 v[16:19], v[180:183], v[204:207], v[16:19]
	v_mfma_f32_16x16x32_bf16 v[4:7], v[172:175], v[212:215], v[4:7]
	v_mfma_f32_16x16x32_bf16 v[0:3], v[180:183], v[212:215], v[0:3]
	s_barrier
	s_add_i32 s65, 0, 0x18000
	v_add_u32_e32 v163, s65, v157
	s_add_i32 s68, 0, 0x1c000
	ds_read_b128 v[144:147], v163
	ds_read_b128 v[148:151], v163 offset:1024
	ds_read_b128 v[152:155], v163 offset:2048
	ds_read_b128 v[164:167], v163 offset:3072
	v_add_u32_e32 v163, s68, v157
	ds_read_b128 v[168:171], v163
	ds_read_b128 v[172:175], v163 offset:1024
	ds_read_b128 v[176:179], v163 offset:2048
	ds_read_b128 v[180:183], v163 offset:3072
	s_add_u32 s36, s36, 0x40000
	s_addc_u32 s37, s37, 0
	s_mov_b32 m0, s49
	v_lshl_add_u64 v[224:225], s[36:37], 0, v[128:129]
	ds_read_b128 v[184:187], v161 offset:32768
	ds_read_b128 v[188:191], v161 offset:33792
	ds_read_b128 v[192:195], v161 offset:34816
	ds_read_b128 v[196:199], v161 offset:35840
	ds_read_b128 v[200:203], v161 offset:36864
	ds_read_b128 v[204:207], v161 offset:37888
	ds_read_b128 v[208:211], v161 offset:38912
	ds_read_b128 v[212:215], v161 offset:39936
	global_load_lds_dwordx4 v[224:225], off
	v_lshl_add_u64 v[224:225], s[36:37], 0, v[132:133]
	s_mov_b32 m0, s50
	s_nop 0
	global_load_lds_dwordx4 v[224:225], off
	s_waitcnt vmcnt(8)
	s_waitcnt lgkmcnt(0)
	s_barrier
	s_waitcnt lgkmcnt(0)
	v_mfma_f32_16x16x32_bf16 v[124:127], v[144:147], v[184:187], v[124:127]
	v_mfma_f32_16x16x32_bf16 v[120:123], v[152:155], v[184:187], v[120:123]
	v_mfma_f32_16x16x32_bf16 v[108:111], v[144:147], v[192:195], v[108:111]
	v_mfma_f32_16x16x32_bf16 v[104:107], v[152:155], v[192:195], v[104:107]
	v_mfma_f32_16x16x32_bf16 v[92:95], v[144:147], v[200:203], v[92:95]
	v_mfma_f32_16x16x32_bf16 v[88:91], v[152:155], v[200:203], v[88:91]
	v_mfma_f32_16x16x32_bf16 v[76:79], v[144:147], v[208:211], v[76:79]
	v_mfma_f32_16x16x32_bf16 v[72:75], v[152:155], v[208:211], v[72:75]
	v_mfma_f32_16x16x32_bf16 v[124:127], v[148:151], v[188:191], v[124:127]
	v_mfma_f32_16x16x32_bf16 v[120:123], v[164:167], v[188:191], v[120:123]
	v_mfma_f32_16x16x32_bf16 v[108:111], v[148:151], v[196:199], v[108:111]
	v_mfma_f32_16x16x32_bf16 v[104:107], v[164:167], v[196:199], v[104:107]
	v_mfma_f32_16x16x32_bf16 v[92:95], v[148:151], v[204:207], v[92:95]
	v_mfma_f32_16x16x32_bf16 v[88:91], v[164:167], v[204:207], v[88:91]
	v_mfma_f32_16x16x32_bf16 v[76:79], v[148:151], v[212:215], v[76:79]
	v_mfma_f32_16x16x32_bf16 v[72:75], v[164:167], v[212:215], v[72:75]
	v_mfma_f32_16x16x32_bf16 v[116:119], v[168:171], v[184:187], v[116:119]
	v_mfma_f32_16x16x32_bf16 v[112:115], v[176:179], v[184:187], v[112:115]
	v_mfma_f32_16x16x32_bf16 v[100:103], v[168:171], v[192:195], v[100:103]
	v_mfma_f32_16x16x32_bf16 v[96:99], v[176:179], v[192:195], v[96:99]
	v_mfma_f32_16x16x32_bf16 v[84:87], v[168:171], v[200:203], v[84:87]
	v_mfma_f32_16x16x32_bf16 v[80:83], v[176:179], v[200:203], v[80:83]
	v_mfma_f32_16x16x32_bf16 v[68:71], v[168:171], v[208:211], v[68:71]
	v_mfma_f32_16x16x32_bf16 v[64:67], v[176:179], v[208:211], v[64:67]
	v_mfma_f32_16x16x32_bf16 v[116:119], v[172:175], v[188:191], v[116:119]
	v_mfma_f32_16x16x32_bf16 v[112:115], v[180:183], v[188:191], v[112:115]
	v_mfma_f32_16x16x32_bf16 v[100:103], v[172:175], v[196:199], v[100:103]
	v_mfma_f32_16x16x32_bf16 v[96:99], v[180:183], v[196:199], v[96:99]
	v_mfma_f32_16x16x32_bf16 v[84:87], v[172:175], v[204:207], v[84:87]
	v_mfma_f32_16x16x32_bf16 v[80:83], v[180:183], v[204:207], v[80:83]
	v_mfma_f32_16x16x32_bf16 v[68:71], v[172:175], v[212:215], v[68:71]
	v_mfma_f32_16x16x32_bf16 v[64:67], v[180:183], v[212:215], v[64:67]
	s_barrier
; #define PG8_STAGE(bufoff, gbase, voff) do { _Pragma("unroll") for (int _i = 0; _i < 2; ++_i) \
;         __builtin_amdgcn_global_load_lds((const unsigned*)((const char*)(gbase) + (voff)[_i]), (LAS unsigned*)(lds + (bufoff) + ldsw + _i * 8192), 16, 0, 0); } while (0)
; #define PG8_LDA(dst, b, h) do { _Pragma("unroll") for (int m = 0; m < 4; ++m) _Pragma("unroll") for (int k = 0; k < 2; ++k) dst[m][k] = *(const LAS bf16x8*)(lds + PG8_SA(b, h) + aoff + m * 2048 + k * 1024); } while (0)
; #define PG8_MMA(ai, bj, At, Bt) do { __builtin_amdgcn_s_setprio(1); _Pragma("unroll") for (int m = 0; m < 4; ++m) _Pragma("unroll") for (int n = 0; n < 2; ++n) _Pragma("unroll") for (int k = 0; k < 2; ++k) \
;         acc[ai][bj][m][n] = __builtin_amdgcn_mfma_f32_16x16x32_bf16(Bt[n][k], At[m][k], acc[ai][bj][m][n], 0, 0, 0); __builtin_amdgcn_s_setprio(0); } while (0)
; #define PG8_WAIT_V(n) asm volatile("s_waitcnt vmcnt(" #n ")" ::: "memory")
; #define PG8_WAIT_L(n) asm volatile("s_waitcnt lgkmcnt(" #n ")" ::: "memory")
; #define PG8_BAR __builtin_amdgcn_s_barrier()
; #define PG8_SCHED __builtin_amdgcn_sched_barrier(0)
; template <class Epi, class Sched>
; DEVI void gemm_phase(LAS unsigned char* lds, const Gemm g, const Sched& S, const Epi& E) {
;     ...
;             PG8_LDA(At, 1, 1); PG8_STAGE(PG8_SB(1, 0), b3, voffB); PG8_STAGE(PG8_SB(1, 1), b3 + hstep, voffB); PG8_STAGE(PG8_SA(1, 0), a3, voffA);
;             PG8_WAIT_V(8); PG8_WAIT_L(0); PG8_BAR; PG8_MMA(1, 0, At, B0); PG8_MMA(1, 1, At, B1); PG8_BAR; PG8_SCHED;
;         }
;         if (wr == 0) PG8_BAR;
	s_add_i32 s36, s65, s42
	v_lshl_add_u64 v[216:217], v[216:217], 0, s[12:13]
	s_mov_b32 m0, s36
	ds_read_b128 v[184:187], v161 offset:49152
	ds_read_b128 v[188:191], v161 offset:50176
	ds_read_b128 v[192:195], v161 offset:51200
	ds_read_b128 v[196:199], v161 offset:52224
	ds_read_b128 v[200:203], v161 offset:53248
	ds_read_b128 v[204:207], v161 offset:54272
	ds_read_b128 v[208:211], v161 offset:55296
	ds_read_b128 v[212:215], v161 offset:56320
	global_load_lds_dwordx4 v[216:217], off
	s_add_i32 m0, s36, 0x2000
	s_add_u32 s34, s34, 0x40080
	v_lshl_add_u64 v[216:217], v[218:219], 0, s[12:13]
	s_addc_u32 s35, s35, 0
	s_add_i32 s36, s68, s42
	global_load_lds_dwordx4 v[216:217], off
	v_lshl_add_u64 v[216:217], s[34:35], 0, v[130:131]
	s_mov_b32 m0, s36
	s_nop 0
	global_load_lds_dwordx4 v[216:217], off
	v_lshl_add_u64 v[216:217], s[34:35], 0, v[134:135]
	s_add_i32 m0, s36, 0x2000
	s_nop 0
	global_load_lds_dwordx4 v[216:217], off
	v_lshl_add_u64 v[216:217], v[220:221], 0, s[12:13]
	s_mov_b32 m0, s56
	s_nop 0
	global_load_lds_dwordx4 v[216:217], off
	v_lshl_add_u64 v[216:217], v[222:223], 0, s[12:13]
	s_mov_b32 m0, s57
	s_nop 0
	global_load_lds_dwordx4 v[216:217], off
	s_waitcnt vmcnt(8)
	s_waitcnt lgkmcnt(0)
	s_barrier
	s_waitcnt lgkmcnt(0)
	v_mfma_f32_16x16x32_bf16 v[60:63], v[144:147], v[184:187], v[60:63]
	v_mfma_f32_16x16x32_bf16 v[56:59], v[152:155], v[184:187], v[56:59]
	v_mfma_f32_16x16x32_bf16 v[44:47], v[144:147], v[192:195], v[44:47]
	v_mfma_f32_16x16x32_bf16 v[40:43], v[152:155], v[192:195], v[40:43]
	v_mfma_f32_16x16x32_bf16 v[28:31], v[144:147], v[200:203], v[28:31]
	v_mfma_f32_16x16x32_bf16 v[24:27], v[152:155], v[200:203], v[24:27]
	v_mfma_f32_16x16x32_bf16 v[12:15], v[144:147], v[208:211], v[12:15]
	v_mfma_f32_16x16x32_bf16 v[8:11], v[152:155], v[208:211], v[8:11]
	v_mfma_f32_16x16x32_bf16 v[60:63], v[148:151], v[188:191], v[60:63]
	v_mfma_f32_16x16x32_bf16 v[56:59], v[164:167], v[188:191], v[56:59]
	v_mfma_f32_16x16x32_bf16 v[44:47], v[148:151], v[196:199], v[44:47]
	v_mfma_f32_16x16x32_bf16 v[40:43], v[164:167], v[196:199], v[40:43]
	v_mfma_f32_16x16x32_bf16 v[28:31], v[148:151], v[204:207], v[28:31]
	v_mfma_f32_16x16x32_bf16 v[24:27], v[164:167], v[204:207], v[24:27]
	v_mfma_f32_16x16x32_bf16 v[12:15], v[148:151], v[212:215], v[12:15]
	v_mfma_f32_16x16x32_bf16 v[8:11], v[164:167], v[212:215], v[8:11]
	v_mfma_f32_16x16x32_bf16 v[52:55], v[168:171], v[184:187], v[52:55]
	v_mfma_f32_16x16x32_bf16 v[48:51], v[176:179], v[184:187], v[48:51]
	v_mfma_f32_16x16x32_bf16 v[36:39], v[168:171], v[192:195], v[36:39]
	v_mfma_f32_16x16x32_bf16 v[32:35], v[176:179], v[192:195], v[32:35]
	v_mfma_f32_16x16x32_bf16 v[20:23], v[168:171], v[200:203], v[20:23]
	v_mfma_f32_16x16x32_bf16 v[16:19], v[176:179], v[200:203], v[16:19]
	v_mfma_f32_16x16x32_bf16 v[4:7], v[168:171], v[208:211], v[4:7]
	v_mfma_f32_16x16x32_bf16 v[0:3], v[176:179], v[208:211], v[0:3]
	v_mfma_f32_16x16x32_bf16 v[52:55], v[172:175], v[188:191], v[52:55]
	v_mfma_f32_16x16x32_bf16 v[48:51], v[180:183], v[188:191], v[48:51]
	v_mfma_f32_16x16x32_bf16 v[36:39], v[172:175], v[196:199], v[36:39]
	v_mfma_f32_16x16x32_bf16 v[32:35], v[180:183], v[196:199], v[32:35]
	v_mfma_f32_16x16x32_bf16 v[20:23], v[172:175], v[204:207], v[20:23]
	v_mfma_f32_16x16x32_bf16 v[16:19], v[180:183], v[204:207], v[16:19]
	v_mfma_f32_16x16x32_bf16 v[4:7], v[172:175], v[212:215], v[4:7]
	v_mfma_f32_16x16x32_bf16 v[0:3], v[180:183], v[212:215], v[0:3]
	s_barrier
	s_add_i32 s64, s64, 2
	s_add_u32 s62, s62, 0x100
	s_addc_u32 s63, s63, 0
	s_add_u32 s30, s30, 0x100
	s_addc_u32 s31, s31, 0
	s_cmp_gt_u32 s64, 13
	s_cbranch_scc0 .LBB0_504
	s_and_b64 vcc, exec, s[14:15]
	s_cbranch_vccz .LBB0_507
	s_barrier

; #define LAS __attribute__((address_space(3)))
; #define PG8_WAIT_V(n) asm volatile("s_waitcnt vmcnt(" #n ")" ::: "memory")
; #define PG8_BAR __builtin_amdgcn_s_barrier()
; DEVI unsigned xb_xcc_id() { return (unsigned)__builtin_amdgcn_s_getreg((3 << 11) | 20) & 0xFu; }
; template <class Epi, class Sched>
; DEVI void gemm_phase(LAS unsigned char* lds, const Gemm g, const Sched& S, const Epi& E) {
;     ...
;     PG8_WAIT_V(0);
;     PG8_BAR;
; DEVI void xcd_barrier(unsigned* bar, volatile LAS unsigned* st) {
;     asm volatile("s_waitcnt vmcnt(0)" ::: "memory");
;     __syncthreads();
;     if (threadIdx.x == 0) {
;         const unsigned x = xb_xcc_id();
;         __builtin_amdgcn_s_waitcnt(0);
;         unsigned nloc = st[0], nx = st[1];
;         if (nloc == 0u) { xcd_barrier_complete(bar, x, nloc, nx); st[0] = nloc; st[1] = nx; }
.LBB0_591:
	s_waitcnt vmcnt(0)
	s_waitcnt lgkmcnt(0)
	s_setprio 0
	s_barrier
	s_mov_b64 s[0:1], exec
	v_readlane_b32 s2, v249, 53
	v_readlane_b32 s3, v249, 54
	s_and_b64 s[2:3], s[0:1], s[2:3]
	s_mov_b64 exec, s[2:3]
	s_cbranch_execz .LBB0_643
	s_add_i32 s3, 0, 0x26ff0
	v_mov_b32_e32 v0, s3
	s_getreg_b32 s2, hwreg(HW_REG_XCC_ID, 0, 4)
	s_waitcnt vmcnt(0) expcnt(0) lgkmcnt(0)
	ds_read_b32 v2, v0
	s_add_i32 s3, 0, 0x26ff4
	v_mov_b32_e32 v0, s3
	ds_read_b32 v0, v0
	s_and_b32 s33, s2, 15
	s_waitcnt lgkmcnt(1)
	v_cmp_ne_u32_e32 vcc, 0, v2
	s_cbranch_vccnz .LBB0_607
	s_add_u32 s2, s96, 0x6fc200
	s_addc_u32 s3, s97, 0
	s_add_u32 s4, s96, 0x6fc400
	s_addc_u32 s5, s97, 0
	s_add_u32 s6, s96, 0x6fc500
	s_addc_u32 s7, s97, 0
	s_add_u32 s8, s96, 0x6fc600
	s_addc_u32 s9, s97, 0
	s_add_u32 s10, s96, 0x6fc700
	s_addc_u32 s11, s97, 0
	s_add_u32 s12, s96, 0x6fc800
	s_addc_u32 s13, s97, 0
	s_add_u32 s14, s96, 0x6fc900
	s_addc_u32 s15, s97, 0
	s_add_u32 s16, s96, 0x6fca00
	s_addc_u32 s17, s97, 0
	s_add_u32 s18, s96, 0x6fcb00
	s_addc_u32 s19, s97, 0
	s_add_u32 s20, s96, 0x6fcc00
	s_addc_u32 s21, s97, 0
	s_add_u32 s22, s96, 0x6fcd00
	s_addc_u32 s23, s97, 0
	s_add_u32 s24, s96, 0x6fce00
	s_addc_u32 s25, s97, 0
	s_add_u32 s26, s96, 0x6fcf00
	s_addc_u32 s27, s97, 0
	s_add_u32 s28, s96, 0x6fd000
	s_addc_u32 s29, s97, 0
	s_add_u32 s30, s96, 0x6fd100
	s_addc_u32 s31, s97, 0
	s_add_u32 s34, s96, 0x6fd200
	s_addc_u32 s35, s97, 0
	s_add_u32 s36, s96, 0x6fd300
	s_addc_u32 s37, s97, 0
	s_mov_b32 s48, 1
	v_mov_b32_e32 v16, 0
	s_branch .LBB0_595

;     DEVI bool next(int i, Unit& u) const {
;         const long L = (long)i * G + c; if (L >= nwg) return false;
;         int wgid = (int)L; { const int q = nwg / NXCD, r = nwg % NXCD, xcd = wgid % NXCD, off = wgid / NXCD; wgid = (xcd < r ? xcd * (q + 1) : r * (q + 1) + (xcd - r) * q) + off; }
;         const int nig = WGM * nN, gid = wgid / nig, fm = gid * WGM, gsz = (nM - fm) < WGM ? (nM - fm) : WGM;
;         u.pm = fm + ((wgid % nig) % gsz); u.pn = (wgid % nig) / gsz; return true;
.LBB0_643:
	s_or_b64 exec, exec, s[0:1]
	s_mov_b64 s[44:45], s[96:97]
	s_mov_b32 s33, s89
	v_readlane_b32 s39, v249, 0
	s_waitcnt lgkmcnt(0)
	s_barrier
	v_readfirstlane_b32 s98, v242
	s_nop 3
	s_cmpk_lt_u32 s98, 0x100
	s_cbranch_scc1 .Lsprio_sp6
	s_setprio 1
.Lsprio_sp6:
	v_mov_b32_e32 v14, v242
	s_cmpk_lt_i32 s39, 0xb00
	s_cselect_b64 s[2:3], -1, 0
	s_mov_b32 s83, s39
	s_cmpk_gt_i32 s39, 0xaff
	v_readfirstlane_b32 s4, v14
	s_cbranch_scc1 .LBB0_645
	s_ashr_i32 s0, s83, 31
	s_lshr_b32 s0, s0, 29
	s_add_i32 s0, s83, s0
	s_ashr_i32 s1, s0, 3
	s_and_b32 s0, s0, -8
	s_sub_i32 s0, s83, s0
	s_cmp_lt_i32 s0, 0
	s_movk_i32 s5, 0x161
	s_cselect_b32 s5, s5, 0x160
	s_mul_i32 s0, s5, s0
	s_add_i32 s0, s0, s1
	s_mul_hi_i32 s1, s0, 0x2e8ba2e9
	s_lshr_b32 s5, s1, 31
	s_ashr_i32 s1, s1, 5
	s_add_i32 s1, s1, s5
	s_lshl_b32 s5, s1, 3
	s_mulk_i32 s1, 0xb0
	s_sub_i32 s0, s0, s1
	s_bfe_u32 s1, s0, 0x3001c
	s_add_i32 s1, s0, s1
	s_sext_i32_i16 s6, s1
	s_and_b32 s1, s1, 0xfff8
	s_sub_i32 s0, s0, s1
	s_sext_i32_i16 s0, s0
	s_add_i32 s0, s5, s0
	s_ashr_i32 s68, s6, 3

; #define PG8_STAGE(bufoff, gbase, voff) do { _Pragma("unroll") for (int _i = 0; _i < 2; ++_i) \
;         __builtin_amdgcn_global_load_lds((const unsigned*)((const char*)(gbase) + (voff)[_i]), (LAS unsigned*)(lds + (bufoff) + ldsw + _i * 8192), 16, 0, 0); } while (0)
; #define PG8_LDA(dst, b, h) do { _Pragma("unroll") for (int m = 0; m < 4; ++m) _Pragma("unroll") for (int k = 0; k < 2; ++k) dst[m][k] = *(const LAS bf16x8*)(lds + PG8_SA(b, h) + aoff + m * 2048 + k * 1024); } while (0)
; #define PG8_LDB(dst, b, h) do { _Pragma("unroll") for (int n = 0; n < 2; ++n) _Pragma("unroll") for (int k = 0; k < 2; ++k) dst[n][k] = *(const LAS bf16x8*)(lds + PG8_SB(b, h) + boff + n * 2048 + k * 1024); } while (0)
; #define PG8_MMA(ai, bj, At, Bt) do { __builtin_amdgcn_s_setprio(1); _Pragma("unroll") for (int m = 0; m < 4; ++m) _Pragma("unroll") for (int n = 0; n < 2; ++n) _Pragma("unroll") for (int k = 0; k < 2; ++k) \
;         acc[ai][bj][m][n] = __builtin_amdgcn_mfma_f32_16x16x32_bf16(Bt[n][k], At[m][k], acc[ai][bj][m][n], 0, 0, 0); __builtin_amdgcn_s_setprio(0); } while (0)
; #define PG8_WAIT_V(n) asm volatile("s_waitcnt vmcnt(" #n ")" ::: "memory")
; #define PG8_WAIT_L(n) asm volatile("s_waitcnt lgkmcnt(" #n ")" ::: "memory")
; #define PG8_BAR __builtin_amdgcn_s_barrier()
; #define PG8_SCHED __builtin_amdgcn_sched_barrier(0)
; template <class Epi, class Sched>
; DEVI void gemm_phase(LAS unsigned char* lds, const Gemm g, const Sched& S, const Epi& E) {
;     ...
;             PG8_LDB(B0, 0, 0); PG8_LDB(B1, 0, 1); PG8_SCHED; PG8_LDA(At, 0, 0); PG8_STAGE(PG8_SA(1, 1), a1 + hstep, voffA);
;             PG8_WAIT_V(8); PG8_WAIT_L(0); PG8_BAR; PG8_MMA(0, 0, At, B0); PG8_MMA(0, 1, At, B1); PG8_BAR; PG8_SCHED;
;             PG8_LDA(At, 0, 1); PG8_STAGE(PG8_SB(0, 0), b2, voffB); PG8_STAGE(PG8_SB(0, 1), b2 + hstep, voffB); PG8_STAGE(PG8_SA(0, 0), a2, voffA);
;             PG8_WAIT_V(8); PG8_WAIT_L(0); PG8_BAR; PG8_MMA(1, 0, At, B0); PG8_MMA(1, 1, At, B1); PG8_BAR; PG8_SCHED;
.LBB0_654:
	ds_read_b128 v[124:127], v245
	ds_read_b128 v[128:131], v245 offset:1024
	ds_read_b128 v[132:135], v245 offset:2048
	ds_read_b128 v[136:139], v245 offset:3072
	ds_read_b128 v[140:143], v246
	ds_read_b128 v[144:147], v246 offset:1024
	ds_read_b128 v[152:155], v246 offset:2048
	ds_read_b128 v[156:159], v246 offset:3072
	s_add_u32 s28, s72, 0xfffc0080
	s_addc_u32 s29, s73, -1
	s_cmp_eq_u32 s76, 12
	s_cselect_b32 s51, s1, s29
	s_cselect_b32 s50, s43, s28
	s_cselect_b32 s49, s41, s58
	s_cselect_b32 s48, vcc_lo, vcc_hi
	v_lshl_add_u64 v[212:213], s[72:73], 0, v[178:179]
	s_add_i32 m0, s63, 0xc000
	ds_read_b128 v[160:163], v247
	ds_read_b128 v[184:187], v247 offset:1024
	ds_read_b128 v[188:191], v247 offset:2048
	ds_read_b128 v[192:195], v247 offset:3072
	ds_read_b128 v[196:199], v247 offset:4096
	ds_read_b128 v[200:203], v247 offset:5120
	ds_read_b128 v[204:207], v247 offset:6144
	ds_read_b128 v[208:211], v247 offset:7168
	global_load_lds_dwordx4 v[212:213], off
	v_lshl_add_u64 v[212:213], s[72:73], 0, v[176:177]
	s_add_i32 m0, s63, 0xe000
	s_nop 0
	global_load_lds_dwordx4 v[212:213], off
	s_waitcnt vmcnt(8)
	s_waitcnt lgkmcnt(0)
	s_barrier
	s_waitcnt lgkmcnt(0)
	v_mfma_f32_16x16x32_bf16 v[148:151], v[124:127], v[160:163], v[148:151]
	v_mfma_f32_16x16x32_bf16 v[60:63], v[132:135], v[160:163], v[60:63]
	v_mfma_f32_16x16x32_bf16 v[116:119], v[124:127], v[188:191], v[116:119]
	v_mfma_f32_16x16x32_bf16 v[52:55], v[132:135], v[188:191], v[52:55]
	v_mfma_f32_16x16x32_bf16 v[108:111], v[124:127], v[196:199], v[108:111]
	v_mfma_f32_16x16x32_bf16 v[44:47], v[132:135], v[196:199], v[44:47]
	v_mfma_f32_16x16x32_bf16 v[100:103], v[124:127], v[204:207], v[100:103]
	v_mfma_f32_16x16x32_bf16 v[36:39], v[132:135], v[204:207], v[36:39]
	v_mfma_f32_16x16x32_bf16 v[148:151], v[128:131], v[184:187], v[148:151]
	v_mfma_f32_16x16x32_bf16 v[60:63], v[136:139], v[184:187], v[60:63]
	v_mfma_f32_16x16x32_bf16 v[116:119], v[128:131], v[192:195], v[116:119]
	v_mfma_f32_16x16x32_bf16 v[52:55], v[136:139], v[192:195], v[52:55]
	v_mfma_f32_16x16x32_bf16 v[108:111], v[128:131], v[200:203], v[108:111]
	v_mfma_f32_16x16x32_bf16 v[44:47], v[136:139], v[200:203], v[44:47]
	v_mfma_f32_16x16x32_bf16 v[100:103], v[128:131], v[208:211], v[100:103]
	v_mfma_f32_16x16x32_bf16 v[36:39], v[136:139], v[208:211], v[36:39]
	v_mfma_f32_16x16x32_bf16 v[120:123], v[140:143], v[160:163], v[120:123]
	v_mfma_f32_16x16x32_bf16 v[56:59], v[152:155], v[160:163], v[56:59]
	v_mfma_f32_16x16x32_bf16 v[112:115], v[140:143], v[188:191], v[112:115]
	v_mfma_f32_16x16x32_bf16 v[48:51], v[152:155], v[188:191], v[48:51]
	v_mfma_f32_16x16x32_bf16 v[104:107], v[140:143], v[196:199], v[104:107]
	v_mfma_f32_16x16x32_bf16 v[40:43], v[152:155], v[196:199], v[40:43]
	v_mfma_f32_16x16x32_bf16 v[96:99], v[140:143], v[204:207], v[96:99]
	v_mfma_f32_16x16x32_bf16 v[32:35], v[152:155], v[204:207], v[32:35]
	v_mfma_f32_16x16x32_bf16 v[120:123], v[144:147], v[184:187], v[120:123]
	v_mfma_f32_16x16x32_bf16 v[56:59], v[156:159], v[184:187], v[56:59]
	v_mfma_f32_16x16x32_bf16 v[112:115], v[144:147], v[192:195], v[112:115]
	v_mfma_f32_16x16x32_bf16 v[48:51], v[156:159], v[192:195], v[48:51]
	v_mfma_f32_16x16x32_bf16 v[104:107], v[144:147], v[200:203], v[104:107]
	v_mfma_f32_16x16x32_bf16 v[40:43], v[156:159], v[200:203], v[40:43]
	v_mfma_f32_16x16x32_bf16 v[96:99], v[144:147], v[208:211], v[96:99]
	v_mfma_f32_16x16x32_bf16 v[32:35], v[156:159], v[208:211], v[32:35]
	s_barrier
	s_add_i32 s28, s88, s62
	v_lshl_add_u64 v[212:213], s[48:49], 0, v[166:167]
	s_mov_b32 m0, s28
	ds_read_b128 v[160:163], v247 offset:16384
	ds_read_b128 v[184:187], v247 offset:17408
	ds_read_b128 v[188:191], v247 offset:18432
	ds_read_b128 v[192:195], v247 offset:19456
	ds_read_b128 v[196:199], v247 offset:20480
	ds_read_b128 v[200:203], v247 offset:21504
	ds_read_b128 v[204:207], v247 offset:22528
	ds_read_b128 v[208:211], v247 offset:23552
	global_load_lds_dwordx4 v[212:213], off
	s_add_i32 m0, s28, 0x2000
	s_add_u32 s28, s48, 0x40000
	v_lshl_add_u64 v[214:215], s[48:49], 0, v[170:171]
	s_addc_u32 s29, s49, 0
	s_add_i32 s77, s89, s62
	global_load_lds_dwordx4 v[214:215], off
	v_lshl_add_u64 v[216:217], s[28:29], 0, v[166:167]
	s_mov_b32 m0, s77
	v_lshl_add_u64 v[218:219], s[50:51], 0, v[168:169]
	global_load_lds_dwordx4 v[216:217], off
	v_lshl_add_u64 v[216:217], s[28:29], 0, v[170:171]
	s_add_i32 m0, s77, 0x2000
	s_nop 0
	global_load_lds_dwordx4 v[216:217], off
	v_lshl_add_u64 v[216:217], s[50:51], 0, v[164:165]
	s_mov_b32 m0, s63
	s_nop 0
	global_load_lds_dwordx4 v[216:217], off
	s_mov_b32 m0, s69
	s_nop 0
	global_load_lds_dwordx4 v[218:219], off
	s_waitcnt vmcnt(8)
	s_waitcnt lgkmcnt(0)
	s_barrier
; #define PG8_STAGE(bufoff, gbase, voff) do { _Pragma("unroll") for (int _i = 0; _i < 2; ++_i) \
;         __builtin_amdgcn_global_load_lds((const unsigned*)((const char*)(gbase) + (voff)[_i]), (LAS unsigned*)(lds + (bufoff) + ldsw + _i * 8192), 16, 0, 0); } while (0)
; #define PG8_LDA(dst, b, h) do { _Pragma("unroll") for (int m = 0; m < 4; ++m) _Pragma("unroll") for (int k = 0; k < 2; ++k) dst[m][k] = *(const LAS bf16x8*)(lds + PG8_SA(b, h) + aoff + m * 2048 + k * 1024); } while (0)
; #define PG8_LDB(dst, b, h) do { _Pragma("unroll") for (int n = 0; n < 2; ++n) _Pragma("unroll") for (int k = 0; k < 2; ++k) dst[n][k] = *(const LAS bf16x8*)(lds + PG8_SB(b, h) + boff + n * 2048 + k * 1024); } while (0)
; #define PG8_MMA(ai, bj, At, Bt) do { __builtin_amdgcn_s_setprio(1); _Pragma("unroll") for (int m = 0; m < 4; ++m) _Pragma("unroll") for (int n = 0; n < 2; ++n) _Pragma("unroll") for (int k = 0; k < 2; ++k) \
;         acc[ai][bj][m][n] = __builtin_amdgcn_mfma_f32_16x16x32_bf16(Bt[n][k], At[m][k], acc[ai][bj][m][n], 0, 0, 0); __builtin_amdgcn_s_setprio(0); } while (0)
; #define PG8_WAIT_V(n) asm volatile("s_waitcnt vmcnt(" #n ")" ::: "memory")
; #define PG8_WAIT_L(n) asm volatile("s_waitcnt lgkmcnt(" #n ")" ::: "memory")
; #define PG8_BAR __builtin_amdgcn_s_barrier()
; #define PG8_SCHED __builtin_amdgcn_sched_barrier(0)
; template <class Epi, class Sched>
; DEVI void gemm_phase(LAS unsigned char* lds, const Gemm g, const Sched& S, const Epi& E) {
;     ...
;             PG8_WAIT_V(8); PG8_WAIT_L(0); PG8_BAR; PG8_MMA(1, 0, At, B0); PG8_MMA(1, 1, At, B1); PG8_BAR; PG8_SCHED;
;             PG8_LDB(B0, 1, 0); PG8_LDB(B1, 1, 1); PG8_SCHED; PG8_LDA(At, 1, 0); PG8_STAGE(PG8_SA(0, 1), a2 + hstep, voffA);
;             PG8_WAIT_V(8); PG8_WAIT_L(0); PG8_BAR; PG8_MMA(0, 0, At, B0); PG8_MMA(0, 1, At, B1); PG8_BAR; PG8_SCHED;
	s_waitcnt lgkmcnt(0)
	v_mfma_f32_16x16x32_bf16 v[92:95], v[124:127], v[160:163], v[92:95]
	v_mfma_f32_16x16x32_bf16 v[28:31], v[132:135], v[160:163], v[28:31]
	v_mfma_f32_16x16x32_bf16 v[84:87], v[124:127], v[188:191], v[84:87]
	v_mfma_f32_16x16x32_bf16 v[20:23], v[132:135], v[188:191], v[20:23]
	v_mfma_f32_16x16x32_bf16 v[76:79], v[124:127], v[196:199], v[76:79]
	v_mfma_f32_16x16x32_bf16 v[12:15], v[132:135], v[196:199], v[12:15]
	v_mfma_f32_16x16x32_bf16 v[68:71], v[124:127], v[204:207], v[68:71]
	v_mfma_f32_16x16x32_bf16 v[4:7], v[132:135], v[204:207], v[4:7]
	v_mfma_f32_16x16x32_bf16 v[92:95], v[128:131], v[184:187], v[92:95]
	v_mfma_f32_16x16x32_bf16 v[28:31], v[136:139], v[184:187], v[28:31]
	v_mfma_f32_16x16x32_bf16 v[84:87], v[128:131], v[192:195], v[84:87]
	v_mfma_f32_16x16x32_bf16 v[20:23], v[136:139], v[192:195], v[20:23]
	v_mfma_f32_16x16x32_bf16 v[76:79], v[128:131], v[200:203], v[76:79]
	v_mfma_f32_16x16x32_bf16 v[12:15], v[136:139], v[200:203], v[12:15]
	v_mfma_f32_16x16x32_bf16 v[68:71], v[128:131], v[208:211], v[68:71]
	v_mfma_f32_16x16x32_bf16 v[4:7], v[136:139], v[208:211], v[4:7]
	v_mfma_f32_16x16x32_bf16 v[88:91], v[140:143], v[160:163], v[88:91]
	v_mfma_f32_16x16x32_bf16 v[24:27], v[152:155], v[160:163], v[24:27]
	v_mfma_f32_16x16x32_bf16 v[80:83], v[140:143], v[188:191], v[80:83]
	v_mfma_f32_16x16x32_bf16 v[16:19], v[152:155], v[188:191], v[16:19]
	v_mfma_f32_16x16x32_bf16 v[72:75], v[140:143], v[196:199], v[72:75]
	v_mfma_f32_16x16x32_bf16 v[8:11], v[152:155], v[196:199], v[8:11]
	v_mfma_f32_16x16x32_bf16 v[64:67], v[140:143], v[204:207], v[64:67]
	v_mfma_f32_16x16x32_bf16 v[0:3], v[152:155], v[204:207], v[0:3]
	v_mfma_f32_16x16x32_bf16 v[88:91], v[144:147], v[184:187], v[88:91]
	v_mfma_f32_16x16x32_bf16 v[24:27], v[156:159], v[184:187], v[24:27]
	v_mfma_f32_16x16x32_bf16 v[80:83], v[144:147], v[192:195], v[80:83]
	v_mfma_f32_16x16x32_bf16 v[16:19], v[156:159], v[192:195], v[16:19]
	v_mfma_f32_16x16x32_bf16 v[72:75], v[144:147], v[200:203], v[72:75]
	v_mfma_f32_16x16x32_bf16 v[8:11], v[156:159], v[200:203], v[8:11]
	v_mfma_f32_16x16x32_bf16 v[64:67], v[144:147], v[208:211], v[64:67]
	v_mfma_f32_16x16x32_bf16 v[0:3], v[156:159], v[208:211], v[0:3]
	s_barrier
	s_add_i32 s77, 0, 0x18000
	s_add_i32 s59, 0, 0x1c000
	v_add_u32_e32 v136, s77, v173
	v_add_u32_e32 v156, s59, v173
	ds_read_b128 v[124:127], v136
	ds_read_b128 v[128:131], v136 offset:1024
	ds_read_b128 v[132:135], v136 offset:2048
	ds_read_b128 v[136:139], v136 offset:3072
	ds_read_b128 v[140:143], v156
	ds_read_b128 v[144:147], v156 offset:1024
	ds_read_b128 v[152:155], v156 offset:2048
	ds_read_b128 v[156:159], v156 offset:3072
	s_add_u32 s28, s50, 0x40000
	s_addc_u32 s29, s51, 0
	s_mov_b32 m0, s80
	v_lshl_add_u64 v[220:221], s[28:29], 0, v[164:165]
	ds_read_b128 v[160:163], v247 offset:32768
	ds_read_b128 v[184:187], v247 offset:33792
	ds_read_b128 v[188:191], v247 offset:34816
	ds_read_b128 v[192:195], v247 offset:35840
	ds_read_b128 v[196:199], v247 offset:36864
	ds_read_b128 v[200:203], v247 offset:37888
	ds_read_b128 v[204:207], v247 offset:38912
	ds_read_b128 v[208:211], v247 offset:39936
	global_load_lds_dwordx4 v[220:221], off
	v_lshl_add_u64 v[220:221], s[28:29], 0, v[168:169]
	s_mov_b32 m0, s81
	s_nop 0
	global_load_lds_dwordx4 v[220:221], off
	s_waitcnt vmcnt(8)
	s_waitcnt lgkmcnt(0)
	s_barrier
	s_waitcnt lgkmcnt(0)
	v_mfma_f32_16x16x32_bf16 v[148:151], v[124:127], v[160:163], v[148:151]
	v_mfma_f32_16x16x32_bf16 v[60:63], v[132:135], v[160:163], v[60:63]
	v_mfma_f32_16x16x32_bf16 v[116:119], v[124:127], v[188:191], v[116:119]
	v_mfma_f32_16x16x32_bf16 v[52:55], v[132:135], v[188:191], v[52:55]
	v_mfma_f32_16x16x32_bf16 v[108:111], v[124:127], v[196:199], v[108:111]
	v_mfma_f32_16x16x32_bf16 v[44:47], v[132:135], v[196:199], v[44:47]
	v_mfma_f32_16x16x32_bf16 v[100:103], v[124:127], v[204:207], v[100:103]
	v_mfma_f32_16x16x32_bf16 v[36:39], v[132:135], v[204:207], v[36:39]
	v_mfma_f32_16x16x32_bf16 v[148:151], v[128:131], v[184:187], v[148:151]
	v_mfma_f32_16x16x32_bf16 v[60:63], v[136:139], v[184:187], v[60:63]
	v_mfma_f32_16x16x32_bf16 v[116:119], v[128:131], v[192:195], v[116:119]
	v_mfma_f32_16x16x32_bf16 v[52:55], v[136:139], v[192:195], v[52:55]
	v_mfma_f32_16x16x32_bf16 v[108:111], v[128:131], v[200:203], v[108:111]
	v_mfma_f32_16x16x32_bf16 v[44:47], v[136:139], v[200:203], v[44:47]
	v_mfma_f32_16x16x32_bf16 v[100:103], v[128:131], v[208:211], v[100:103]
	v_mfma_f32_16x16x32_bf16 v[36:39], v[136:139], v[208:211], v[36:39]
	v_mfma_f32_16x16x32_bf16 v[120:123], v[140:143], v[160:163], v[120:123]
	v_mfma_f32_16x16x32_bf16 v[56:59], v[152:155], v[160:163], v[56:59]
	v_mfma_f32_16x16x32_bf16 v[112:115], v[140:143], v[188:191], v[112:115]
	v_mfma_f32_16x16x32_bf16 v[48:51], v[152:155], v[188:191], v[48:51]
	v_mfma_f32_16x16x32_bf16 v[104:107], v[140:143], v[196:199], v[104:107]
	v_mfma_f32_16x16x32_bf16 v[40:43], v[152:155], v[196:199], v[40:43]
	v_mfma_f32_16x16x32_bf16 v[96:99], v[140:143], v[204:207], v[96:99]
	v_mfma_f32_16x16x32_bf16 v[32:35], v[152:155], v[204:207], v[32:35]
	v_mfma_f32_16x16x32_bf16 v[120:123], v[144:147], v[184:187], v[120:123]
	v_mfma_f32_16x16x32_bf16 v[56:59], v[156:159], v[184:187], v[56:59]
	v_mfma_f32_16x16x32_bf16 v[112:115], v[144:147], v[192:195], v[112:115]
	v_mfma_f32_16x16x32_bf16 v[48:51], v[156:159], v[192:195], v[48:51]
	v_mfma_f32_16x16x32_bf16 v[104:107], v[144:147], v[200:203], v[104:107]
	v_mfma_f32_16x16x32_bf16 v[40:43], v[156:159], v[200:203], v[40:43]
	v_mfma_f32_16x16x32_bf16 v[96:99], v[144:147], v[208:211], v[96:99]
	v_mfma_f32_16x16x32_bf16 v[32:35], v[156:159], v[208:211], v[32:35]
	s_barrier
; #define PG8_STAGE(bufoff, gbase, voff) do { _Pragma("unroll") for (int _i = 0; _i < 2; ++_i) \
;         __builtin_amdgcn_global_load_lds((const unsigned*)((const char*)(gbase) + (voff)[_i]), (LAS unsigned*)(lds + (bufoff) + ldsw + _i * 8192), 16, 0, 0); } while (0)
; #define PG8_LDA(dst, b, h) do { _Pragma("unroll") for (int m = 0; m < 4; ++m) _Pragma("unroll") for (int k = 0; k < 2; ++k) dst[m][k] = *(const LAS bf16x8*)(lds + PG8_SA(b, h) + aoff + m * 2048 + k * 1024); } while (0)
; #define PG8_MMA(ai, bj, At, Bt) do { __builtin_amdgcn_s_setprio(1); _Pragma("unroll") for (int m = 0; m < 4; ++m) _Pragma("unroll") for (int n = 0; n < 2; ++n) _Pragma("unroll") for (int k = 0; k < 2; ++k) \
;         acc[ai][bj][m][n] = __builtin_amdgcn_mfma_f32_16x16x32_bf16(Bt[n][k], At[m][k], acc[ai][bj][m][n], 0, 0, 0); __builtin_amdgcn_s_setprio(0); } while (0)
; #define PG8_WAIT_V(n) asm volatile("s_waitcnt vmcnt(" #n ")" ::: "memory")
; #define PG8_WAIT_L(n) asm volatile("s_waitcnt lgkmcnt(" #n ")" ::: "memory")
; #define PG8_BAR __builtin_amdgcn_s_barrier()
; #define PG8_SCHED __builtin_amdgcn_sched_barrier(0)
; template <class Epi, class Sched>
; DEVI void gemm_phase(LAS unsigned char* lds, const Gemm g, const Sched& S, const Epi& E) {
;     ...
;             PG8_LDA(At, 1, 1); PG8_STAGE(PG8_SB(1, 0), b3, voffB); PG8_STAGE(PG8_SB(1, 1), b3 + hstep, voffB); PG8_STAGE(PG8_SA(1, 0), a3, voffA);
;             PG8_WAIT_V(8); PG8_WAIT_L(0); PG8_BAR; PG8_MMA(1, 0, At, B0); PG8_MMA(1, 1, At, B1); PG8_BAR; PG8_SCHED;
;         }
;         if (wr == 0) PG8_BAR;
	s_add_i32 s28, s77, s62
	v_lshl_add_u64 v[212:213], v[212:213], 0, s[26:27]
	s_mov_b32 m0, s28
	ds_read_b128 v[160:163], v247 offset:49152
	ds_read_b128 v[184:187], v247 offset:50176
	ds_read_b128 v[188:191], v247 offset:51200
	ds_read_b128 v[192:195], v247 offset:52224
	ds_read_b128 v[196:199], v247 offset:53248
	ds_read_b128 v[200:203], v247 offset:54272
	ds_read_b128 v[204:207], v247 offset:55296
	ds_read_b128 v[208:211], v247 offset:56320
	global_load_lds_dwordx4 v[212:213], off
	s_add_i32 m0, s28, 0x2000
	s_add_u32 s28, s48, 0x40080
	v_lshl_add_u64 v[212:213], v[214:215], 0, s[26:27]
	s_addc_u32 s29, s49, 0
	s_add_i32 s48, s59, s62
	global_load_lds_dwordx4 v[212:213], off
	v_lshl_add_u64 v[212:213], s[28:29], 0, v[166:167]
	s_mov_b32 m0, s48
	s_nop 0
	global_load_lds_dwordx4 v[212:213], off
	v_lshl_add_u64 v[212:213], s[28:29], 0, v[170:171]
	s_add_i32 m0, s48, 0x2000
	s_nop 0
	global_load_lds_dwordx4 v[212:213], off
	v_lshl_add_u64 v[212:213], v[216:217], 0, s[26:27]
	s_mov_b32 m0, s84
	s_nop 0
	global_load_lds_dwordx4 v[212:213], off
	v_lshl_add_u64 v[212:213], v[218:219], 0, s[26:27]
	s_mov_b32 m0, s85
	s_nop 0
	global_load_lds_dwordx4 v[212:213], off
	s_waitcnt vmcnt(8)
	s_waitcnt lgkmcnt(0)
	s_barrier
	s_waitcnt lgkmcnt(0)
	v_mfma_f32_16x16x32_bf16 v[92:95], v[124:127], v[160:163], v[92:95]
	v_mfma_f32_16x16x32_bf16 v[28:31], v[132:135], v[160:163], v[28:31]
	v_mfma_f32_16x16x32_bf16 v[84:87], v[124:127], v[188:191], v[84:87]
	v_mfma_f32_16x16x32_bf16 v[20:23], v[132:135], v[188:191], v[20:23]
	v_mfma_f32_16x16x32_bf16 v[76:79], v[124:127], v[196:199], v[76:79]
	v_mfma_f32_16x16x32_bf16 v[12:15], v[132:135], v[196:199], v[12:15]
	v_mfma_f32_16x16x32_bf16 v[68:71], v[124:127], v[204:207], v[68:71]
	v_mfma_f32_16x16x32_bf16 v[4:7], v[132:135], v[204:207], v[4:7]
	v_mfma_f32_16x16x32_bf16 v[92:95], v[128:131], v[184:187], v[92:95]
	v_mfma_f32_16x16x32_bf16 v[28:31], v[136:139], v[184:187], v[28:31]
	v_mfma_f32_16x16x32_bf16 v[84:87], v[128:131], v[192:195], v[84:87]
	v_mfma_f32_16x16x32_bf16 v[20:23], v[136:139], v[192:195], v[20:23]
	v_mfma_f32_16x16x32_bf16 v[76:79], v[128:131], v[200:203], v[76:79]
	v_mfma_f32_16x16x32_bf16 v[12:15], v[136:139], v[200:203], v[12:15]
	v_mfma_f32_16x16x32_bf16 v[68:71], v[128:131], v[208:211], v[68:71]
	v_mfma_f32_16x16x32_bf16 v[4:7], v[136:139], v[208:211], v[4:7]
	v_mfma_f32_16x16x32_bf16 v[88:91], v[140:143], v[160:163], v[88:91]
	v_mfma_f32_16x16x32_bf16 v[24:27], v[152:155], v[160:163], v[24:27]
	v_mfma_f32_16x16x32_bf16 v[80:83], v[140:143], v[188:191], v[80:83]
	v_mfma_f32_16x16x32_bf16 v[16:19], v[152:155], v[188:191], v[16:19]
	v_mfma_f32_16x16x32_bf16 v[72:75], v[140:143], v[196:199], v[72:75]
	v_mfma_f32_16x16x32_bf16 v[8:11], v[152:155], v[196:199], v[8:11]
	v_mfma_f32_16x16x32_bf16 v[64:67], v[140:143], v[204:207], v[64:67]
	v_mfma_f32_16x16x32_bf16 v[0:3], v[152:155], v[204:207], v[0:3]
	v_mfma_f32_16x16x32_bf16 v[88:91], v[144:147], v[184:187], v[88:91]
	v_mfma_f32_16x16x32_bf16 v[24:27], v[156:159], v[184:187], v[24:27]
	v_mfma_f32_16x16x32_bf16 v[80:83], v[144:147], v[192:195], v[80:83]
	v_mfma_f32_16x16x32_bf16 v[16:19], v[156:159], v[192:195], v[16:19]
	v_mfma_f32_16x16x32_bf16 v[72:75], v[144:147], v[200:203], v[72:75]
	v_mfma_f32_16x16x32_bf16 v[8:11], v[156:159], v[200:203], v[8:11]
	v_mfma_f32_16x16x32_bf16 v[64:67], v[144:147], v[208:211], v[64:67]
	v_mfma_f32_16x16x32_bf16 v[0:3], v[156:159], v[208:211], v[0:3]
	s_barrier
	s_add_i32 s76, s76, 2
	s_add_u32 vcc_hi, vcc_hi, 0x100
	s_addc_u32 s58, s58, 0
	s_add_u32 s72, s72, 0x100
	s_addc_u32 s73, s73, 0
	s_cmp_gt_u32 s76, 13
	s_cbranch_scc0 .LBB0_654
	v_readlane_b32 s8, v248, 0
	v_readlane_b32 s9, v248, 1
	s_and_b64 vcc, exec, s[8:9]
	s_cbranch_vccz .LBB0_657
	s_barrier

; #define LAS __attribute__((address_space(3)))
; #define PG8_WAIT_V(n) asm volatile("s_waitcnt vmcnt(" #n ")" ::: "memory")
; #define PG8_BAR __builtin_amdgcn_s_barrier()
; DEVI unsigned xb_xcc_id() { return (unsigned)__builtin_amdgcn_s_getreg((3 << 11) | 20) & 0xFu; }
; template <class Epi, class Sched>
; DEVI void gemm_phase(LAS unsigned char* lds, const Gemm g, const Sched& S, const Epi& E) {
;     ...
;     PG8_WAIT_V(0);
;     PG8_BAR;
; DEVI void xcd_barrier(unsigned* bar, volatile LAS unsigned* st) {
;     asm volatile("s_waitcnt vmcnt(0)" ::: "memory");
;     __syncthreads();
;     if (threadIdx.x == 0) {
;         const unsigned x = xb_xcc_id();
;         __builtin_amdgcn_s_waitcnt(0);
;         unsigned nloc = st[0], nx = st[1];
;         if (nloc == 0u) { xcd_barrier_complete(bar, x, nloc, nx); st[0] = nloc; st[1] = nx; }
.LBB0_701:
	s_waitcnt vmcnt(0)
	s_waitcnt lgkmcnt(0)
	s_setprio 0
	s_barrier
	s_mov_b64 s[0:1], exec
	v_readlane_b32 s2, v249, 53
	v_readlane_b32 s3, v249, 54
	v_readlane_b32 s44, v249, 59
	s_and_b64 s[2:3], s[0:1], s[2:3]
	v_readlane_b32 s45, v249, 60
	v_readlane_b32 s46, v249, 61
	v_readlane_b32 s47, v249, 62
	s_mov_b64 exec, s[2:3]
	s_cbranch_execz .LBB0_753
	s_add_i32 s3, 0, 0x26ff0
	v_mov_b32_e32 v0, s3
	s_getreg_b32 s2, hwreg(HW_REG_XCC_ID, 0, 4)
	s_waitcnt vmcnt(0) expcnt(0) lgkmcnt(0)
	ds_read_b32 v2, v0
	s_add_i32 s3, 0, 0x26ff4
	v_mov_b32_e32 v0, s3
	ds_read_b32 v0, v0
	s_and_b32 s33, s2, 15
	s_waitcnt lgkmcnt(1)
	v_cmp_ne_u32_e32 vcc, 0, v2
	s_cbranch_vccnz .LBB0_717
	s_add_u32 s2, s96, 0x6fc200
	s_addc_u32 s3, s97, 0
	s_add_u32 s4, s96, 0x6fc400
	s_addc_u32 s5, s97, 0
	s_add_u32 s6, s96, 0x6fc500
	s_addc_u32 s7, s97, 0
	s_add_u32 s8, s96, 0x6fc600
	s_addc_u32 s9, s97, 0
	s_add_u32 s10, s96, 0x6fc700
	s_addc_u32 s11, s97, 0
	s_add_u32 s12, s96, 0x6fc800
	s_addc_u32 s13, s97, 0
	s_add_u32 s14, s96, 0x6fc900
	s_addc_u32 s15, s97, 0
	s_add_u32 s16, s96, 0x6fca00
	s_addc_u32 s17, s97, 0
	s_add_u32 s18, s96, 0x6fcb00
	s_addc_u32 s19, s97, 0
	s_add_u32 s20, s96, 0x6fcc00
	s_addc_u32 s21, s97, 0
	s_add_u32 s22, s96, 0x6fcd00
	s_addc_u32 s23, s97, 0
	s_add_u32 s24, s96, 0x6fce00
	s_addc_u32 s25, s97, 0
	s_add_u32 s26, s96, 0x6fcf00
	s_addc_u32 s27, s97, 0
	s_add_u32 s28, s96, 0x6fd000
	s_addc_u32 s29, s97, 0
	s_add_u32 s30, s96, 0x6fd100
	s_addc_u32 s31, s97, 0
	s_add_u32 s34, s96, 0x6fd200
	s_addc_u32 s35, s97, 0
	s_add_u32 s36, s96, 0x6fd300
	s_addc_u32 s37, s97, 0
	s_mov_b32 s48, 1
	v_mov_b32_e32 v16, 0
	s_branch .LBB0_705

; DEVI int bid_() { int t = blockIdx.x; asm volatile("" : "+s"(t)); return t; }
; DEVI int gdim_() { int t = gridDim.x; asm volatile("" : "+s"(t)); return t; }
; template <int PH>
; DEVI void run_phase(const Params& p, unsigned char* smem) {
;     ...
;             pg8::Gemm g{(const bf16_t*)(ws + WS_H), wbase + (size_t)16 * MiB / 2, MROWS, DM, DFF}; pg8::StaticOrder S; S.init(MROWS, DM, gdim_(), bid_());
;             pg8::Unit u;
;             for (int i = 0; S.next(i, u); ++i) ffn_fixup_panel(u.pm, (bf16_t*)(ws + WS_H), p.in[28] + (size_t)l * 3 * DFF, p.in[29] + (size_t)l * DFF, (const float*)(ws + WS_TAIL), (const float*)(ws + WS_HPG), (const float*)(ws + WS_HUP));
.LBB0_753:
	s_or_b64 exec, exec, s[0:1]
	s_mov_b64 s[8:9], s[96:97]
	s_waitcnt lgkmcnt(0)
	s_barrier
	v_readfirstlane_b32 s98, v242
	s_nop 3
	s_cmpk_lt_u32 s98, 0x100
	s_cbranch_scc1 .Lsprio_sp7
	s_setprio 1
.Lsprio_sp7:
	s_add_u32 s10, s8, 0x10a00000
	s_mov_b32 s25, s89
	v_readlane_b32 s27, v249, 0
	s_addc_u32 s11, s9, 0
	s_ashr_i32 s33, s25, 31
	s_ashr_i32 s38, s27, 31
	s_add_u32 s0, s8, 0xa800000
	s_addc_u32 s1, s9, 0
	s_add_u32 s2, s8, 0xb300000
	s_addc_u32 s3, s9, 0
	v_readlane_b32 s56, v249, 37
	s_add_u32 s4, s8, 0xbe00000
	v_readlane_b32 s57, v249, 38
	v_readlane_b32 s58, v249, 39
	v_readlane_b32 s59, v249, 40
	v_readlane_b32 s64, v249, 45
	v_readlane_b32 s65, v249, 46
	s_addc_u32 s5, s9, 0
	v_readlane_b32 s66, v249, 47
	v_readlane_b32 s67, v249, 48
	s_mov_b64 s[56:57], s[64:65]
	s_add_u32 s6, s56, 0x2c00
	s_addc_u32 s7, s57, 0
	s_mov_b32 s20, 0
	v_mov_b64_e32 v[20:21], 0x1ff
	s_movk_i32 s21, 0x1600
	s_mov_b32 s22, 0x2e8ba2e9
	s_movk_i32 s23, 0x2c00
	s_movk_i32 s24, 0x5800
	s_movk_i32 s26, 0x13ff
	v_mov_b32_e32 v28, 0
	v_readlane_b32 s60, v249, 41
	v_readlane_b32 s61, v249, 42
	v_readlane_b32 s62, v249, 43
	v_readlane_b32 s63, v249, 44
	v_readlane_b32 s68, v249, 49
	v_readlane_b32 s69, v249, 50
	v_readlane_b32 s70, v249, 51
	v_readlane_b32 s71, v249, 52
	s_mov_b64 s[58:59], s[66:67]
	s_branch .LBB0_756

; #define PG8_STAGE(bufoff, gbase, voff) do { _Pragma("unroll") for (int _i = 0; _i < 2; ++_i) \
;         __builtin_amdgcn_global_load_lds((const unsigned*)((const char*)(gbase) + (voff)[_i]), (LAS unsigned*)(lds + (bufoff) + ldsw + _i * 8192), 16, 0, 0); } while (0)
; #define PG8_LDA(dst, b, h) do { _Pragma("unroll") for (int m = 0; m < 4; ++m) _Pragma("unroll") for (int k = 0; k < 2; ++k) dst[m][k] = *(const LAS bf16x8*)(lds + PG8_SA(b, h) + aoff + m * 2048 + k * 1024); } while (0)
; #define PG8_LDB(dst, b, h) do { _Pragma("unroll") for (int n = 0; n < 2; ++n) _Pragma("unroll") for (int k = 0; k < 2; ++k) dst[n][k] = *(const LAS bf16x8*)(lds + PG8_SB(b, h) + boff + n * 2048 + k * 1024); } while (0)
; #define PG8_MMA(ai, bj, At, Bt) do { __builtin_amdgcn_s_setprio(1); _Pragma("unroll") for (int m = 0; m < 4; ++m) _Pragma("unroll") for (int n = 0; n < 2; ++n) _Pragma("unroll") for (int k = 0; k < 2; ++k) \
;         acc[ai][bj][m][n] = __builtin_amdgcn_mfma_f32_16x16x32_bf16(Bt[n][k], At[m][k], acc[ai][bj][m][n], 0, 0, 0); __builtin_amdgcn_s_setprio(0); } while (0)
; #define PG8_WAIT_V(n) asm volatile("s_waitcnt vmcnt(" #n ")" ::: "memory")
; #define PG8_WAIT_L(n) asm volatile("s_waitcnt lgkmcnt(" #n ")" ::: "memory")
; #define PG8_BAR __builtin_amdgcn_s_barrier()
; #define PG8_SCHED __builtin_amdgcn_sched_barrier(0)
; template <class Epi, class Sched>
; DEVI void gemm_phase(LAS unsigned char* lds, const Gemm g, const Sched& S, const Epi& E) {
;     ...
;             PG8_LDB(B0, 0, 0); PG8_LDB(B1, 0, 1); PG8_SCHED; PG8_LDA(At, 0, 0); PG8_STAGE(PG8_SA(1, 1), a1 + hstep, voffA);
;             PG8_WAIT_V(8); PG8_WAIT_L(0); PG8_BAR; PG8_MMA(0, 0, At, B0); PG8_MMA(0, 1, At, B1); PG8_BAR; PG8_SCHED;
;             PG8_LDA(At, 0, 1); PG8_STAGE(PG8_SB(0, 0), b2, voffB); PG8_STAGE(PG8_SB(0, 1), b2 + hstep, voffB); PG8_STAGE(PG8_SA(0, 0), a2, voffA);
;             PG8_WAIT_V(8); PG8_WAIT_L(0); PG8_BAR; PG8_MMA(1, 0, At, B0); PG8_MMA(1, 1, At, B1); PG8_BAR; PG8_SCHED;
.LBB0_793:
	ds_read_b128 v[128:131], v171
	ds_read_b128 v[132:135], v171 offset:1024
	ds_read_b128 v[152:155], v171 offset:2048
	ds_read_b128 v[156:159], v171 offset:3072
	ds_read_b128 v[160:163], v172
	ds_read_b128 v[164:167], v172 offset:1024
	ds_read_b128 v[176:179], v172 offset:2048
	ds_read_b128 v[180:183], v172 offset:3072
	s_add_u32 s30, s6, 0x100
	s_addc_u32 s31, s7, 0
	s_cmp_eq_u32 s68, 40
	s_cselect_b32 s37, s1, s31
	s_cselect_b32 s36, s0, s30
	s_cselect_b32 s35, s29, s65
	s_cselect_b32 s34, s28, s64
	v_lshl_add_u64 v[216:217], s[6:7], 0, v[146:147]
	s_add_i32 m0, s42, 0xc000
	ds_read_b128 v[184:187], v173
	ds_read_b128 v[188:191], v173 offset:1024
	ds_read_b128 v[192:195], v173 offset:2048
	ds_read_b128 v[196:199], v173 offset:3072
	ds_read_b128 v[200:203], v173 offset:4096
	ds_read_b128 v[204:207], v173 offset:5120
	ds_read_b128 v[208:211], v173 offset:6144
	ds_read_b128 v[212:215], v173 offset:7168
	global_load_lds_dwordx4 v[216:217], off
	v_lshl_add_u64 v[216:217], s[6:7], 0, v[144:145]
	s_add_i32 m0, s42, 0xe000
	s_nop 0
	global_load_lds_dwordx4 v[216:217], off
	s_waitcnt vmcnt(8)
	s_waitcnt lgkmcnt(0)
	s_barrier
	s_waitcnt lgkmcnt(0)
	v_mfma_f32_16x16x32_bf16 v[124:127], v[128:131], v[184:187], v[124:127]
	v_mfma_f32_16x16x32_bf16 v[120:123], v[152:155], v[184:187], v[120:123]
	v_mfma_f32_16x16x32_bf16 v[108:111], v[128:131], v[192:195], v[108:111]
	v_mfma_f32_16x16x32_bf16 v[104:107], v[152:155], v[192:195], v[104:107]
	v_mfma_f32_16x16x32_bf16 v[92:95], v[128:131], v[200:203], v[92:95]
	v_mfma_f32_16x16x32_bf16 v[88:91], v[152:155], v[200:203], v[88:91]
	v_mfma_f32_16x16x32_bf16 v[76:79], v[128:131], v[208:211], v[76:79]
	v_mfma_f32_16x16x32_bf16 v[72:75], v[152:155], v[208:211], v[72:75]
	v_mfma_f32_16x16x32_bf16 v[124:127], v[132:135], v[188:191], v[124:127]
	v_mfma_f32_16x16x32_bf16 v[120:123], v[156:159], v[188:191], v[120:123]
	v_mfma_f32_16x16x32_bf16 v[108:111], v[132:135], v[196:199], v[108:111]
	v_mfma_f32_16x16x32_bf16 v[104:107], v[156:159], v[196:199], v[104:107]
	v_mfma_f32_16x16x32_bf16 v[92:95], v[132:135], v[204:207], v[92:95]
	v_mfma_f32_16x16x32_bf16 v[88:91], v[156:159], v[204:207], v[88:91]
	v_mfma_f32_16x16x32_bf16 v[76:79], v[132:135], v[212:215], v[76:79]
	v_mfma_f32_16x16x32_bf16 v[72:75], v[156:159], v[212:215], v[72:75]
	v_mfma_f32_16x16x32_bf16 v[116:119], v[160:163], v[184:187], v[116:119]
	v_mfma_f32_16x16x32_bf16 v[112:115], v[176:179], v[184:187], v[112:115]
	v_mfma_f32_16x16x32_bf16 v[100:103], v[160:163], v[192:195], v[100:103]
	v_mfma_f32_16x16x32_bf16 v[96:99], v[176:179], v[192:195], v[96:99]
	v_mfma_f32_16x16x32_bf16 v[84:87], v[160:163], v[200:203], v[84:87]
	v_mfma_f32_16x16x32_bf16 v[80:83], v[176:179], v[200:203], v[80:83]
	v_mfma_f32_16x16x32_bf16 v[68:71], v[160:163], v[208:211], v[68:71]
	v_mfma_f32_16x16x32_bf16 v[64:67], v[176:179], v[208:211], v[64:67]
	v_mfma_f32_16x16x32_bf16 v[116:119], v[164:167], v[188:191], v[116:119]
	v_mfma_f32_16x16x32_bf16 v[112:115], v[180:183], v[188:191], v[112:115]
	v_mfma_f32_16x16x32_bf16 v[100:103], v[164:167], v[196:199], v[100:103]
	v_mfma_f32_16x16x32_bf16 v[96:99], v[180:183], v[196:199], v[96:99]
	v_mfma_f32_16x16x32_bf16 v[84:87], v[164:167], v[204:207], v[84:87]
	v_mfma_f32_16x16x32_bf16 v[80:83], v[180:183], v[204:207], v[80:83]
	v_mfma_f32_16x16x32_bf16 v[68:71], v[164:167], v[212:215], v[68:71]
	v_mfma_f32_16x16x32_bf16 v[64:67], v[180:183], v[212:215], v[64:67]
	s_barrier
	s_add_i32 s6, s57, s41
	v_lshl_add_u64 v[216:217], s[34:35], 0, v[138:139]
	s_mov_b32 m0, s6
	ds_read_b128 v[184:187], v173 offset:16384
	ds_read_b128 v[188:191], v173 offset:17408
	ds_read_b128 v[192:195], v173 offset:18432
	ds_read_b128 v[196:199], v173 offset:19456
	ds_read_b128 v[200:203], v173 offset:20480
	ds_read_b128 v[204:207], v173 offset:21504
	ds_read_b128 v[208:211], v173 offset:22528
	ds_read_b128 v[212:215], v173 offset:23552
	global_load_lds_dwordx4 v[216:217], off
	s_add_i32 m0, s6, 0x2000
	s_add_u32 s6, s34, 0xb0000
	v_lshl_add_u64 v[218:219], s[34:35], 0, v[142:143]
	s_addc_u32 s7, s35, 0
	s_add_i32 s69, s58, s41
	global_load_lds_dwordx4 v[218:219], off
	v_lshl_add_u64 v[220:221], s[6:7], 0, v[138:139]
	s_mov_b32 m0, s69
	v_lshl_add_u64 v[222:223], s[36:37], 0, v[140:141]
	global_load_lds_dwordx4 v[220:221], off
	v_lshl_add_u64 v[220:221], s[6:7], 0, v[142:143]
	s_add_i32 m0, s69, 0x2000
	s_nop 0
	global_load_lds_dwordx4 v[220:221], off
	v_lshl_add_u64 v[220:221], s[36:37], 0, v[136:137]
	s_mov_b32 m0, s42
	s_nop 0
	global_load_lds_dwordx4 v[220:221], off
	s_mov_b32 m0, s43
	s_nop 0
	global_load_lds_dwordx4 v[222:223], off
	s_waitcnt vmcnt(8)
	s_waitcnt lgkmcnt(0)
	s_barrier
; #define PG8_STAGE(bufoff, gbase, voff) do { _Pragma("unroll") for (int _i = 0; _i < 2; ++_i) \
;         __builtin_amdgcn_global_load_lds((const unsigned*)((const char*)(gbase) + (voff)[_i]), (LAS unsigned*)(lds + (bufoff) + ldsw + _i * 8192), 16, 0, 0); } while (0)
; #define PG8_LDA(dst, b, h) do { _Pragma("unroll") for (int m = 0; m < 4; ++m) _Pragma("unroll") for (int k = 0; k < 2; ++k) dst[m][k] = *(const LAS bf16x8*)(lds + PG8_SA(b, h) + aoff + m * 2048 + k * 1024); } while (0)
; #define PG8_LDB(dst, b, h) do { _Pragma("unroll") for (int n = 0; n < 2; ++n) _Pragma("unroll") for (int k = 0; k < 2; ++k) dst[n][k] = *(const LAS bf16x8*)(lds + PG8_SB(b, h) + boff + n * 2048 + k * 1024); } while (0)
; #define PG8_MMA(ai, bj, At, Bt) do { __builtin_amdgcn_s_setprio(1); _Pragma("unroll") for (int m = 0; m < 4; ++m) _Pragma("unroll") for (int n = 0; n < 2; ++n) _Pragma("unroll") for (int k = 0; k < 2; ++k) \
;         acc[ai][bj][m][n] = __builtin_amdgcn_mfma_f32_16x16x32_bf16(Bt[n][k], At[m][k], acc[ai][bj][m][n], 0, 0, 0); __builtin_amdgcn_s_setprio(0); } while (0)
; #define PG8_WAIT_V(n) asm volatile("s_waitcnt vmcnt(" #n ")" ::: "memory")
; #define PG8_WAIT_L(n) asm volatile("s_waitcnt lgkmcnt(" #n ")" ::: "memory")
; #define PG8_BAR __builtin_amdgcn_s_barrier()
; #define PG8_SCHED __builtin_amdgcn_sched_barrier(0)
; template <class Epi, class Sched>
; DEVI void gemm_phase(LAS unsigned char* lds, const Gemm g, const Sched& S, const Epi& E) {
;     ...
;             PG8_WAIT_V(8); PG8_WAIT_L(0); PG8_BAR; PG8_MMA(1, 0, At, B0); PG8_MMA(1, 1, At, B1); PG8_BAR; PG8_SCHED;
;             PG8_LDB(B0, 1, 0); PG8_LDB(B1, 1, 1); PG8_SCHED; PG8_LDA(At, 1, 0); PG8_STAGE(PG8_SA(0, 1), a2 + hstep, voffA);
;             PG8_WAIT_V(8); PG8_WAIT_L(0); PG8_BAR; PG8_MMA(0, 0, At, B0); PG8_MMA(0, 1, At, B1); PG8_BAR; PG8_SCHED;
	s_waitcnt lgkmcnt(0)
	v_mfma_f32_16x16x32_bf16 v[60:63], v[128:131], v[184:187], v[60:63]
	v_mfma_f32_16x16x32_bf16 v[56:59], v[152:155], v[184:187], v[56:59]
	v_mfma_f32_16x16x32_bf16 v[44:47], v[128:131], v[192:195], v[44:47]
	v_mfma_f32_16x16x32_bf16 v[40:43], v[152:155], v[192:195], v[40:43]
	v_mfma_f32_16x16x32_bf16 v[28:31], v[128:131], v[200:203], v[28:31]
	v_mfma_f32_16x16x32_bf16 v[24:27], v[152:155], v[200:203], v[24:27]
	v_mfma_f32_16x16x32_bf16 v[12:15], v[128:131], v[208:211], v[12:15]
	v_mfma_f32_16x16x32_bf16 v[8:11], v[152:155], v[208:211], v[8:11]
	v_mfma_f32_16x16x32_bf16 v[60:63], v[132:135], v[188:191], v[60:63]
	v_mfma_f32_16x16x32_bf16 v[56:59], v[156:159], v[188:191], v[56:59]
	v_mfma_f32_16x16x32_bf16 v[44:47], v[132:135], v[196:199], v[44:47]
	v_mfma_f32_16x16x32_bf16 v[40:43], v[156:159], v[196:199], v[40:43]
	v_mfma_f32_16x16x32_bf16 v[28:31], v[132:135], v[204:207], v[28:31]
	v_mfma_f32_16x16x32_bf16 v[24:27], v[156:159], v[204:207], v[24:27]
	v_mfma_f32_16x16x32_bf16 v[12:15], v[132:135], v[212:215], v[12:15]
	v_mfma_f32_16x16x32_bf16 v[8:11], v[156:159], v[212:215], v[8:11]
	v_mfma_f32_16x16x32_bf16 v[52:55], v[160:163], v[184:187], v[52:55]
	v_mfma_f32_16x16x32_bf16 v[48:51], v[176:179], v[184:187], v[48:51]
	v_mfma_f32_16x16x32_bf16 v[36:39], v[160:163], v[192:195], v[36:39]
	v_mfma_f32_16x16x32_bf16 v[32:35], v[176:179], v[192:195], v[32:35]
	v_mfma_f32_16x16x32_bf16 v[20:23], v[160:163], v[200:203], v[20:23]
	v_mfma_f32_16x16x32_bf16 v[16:19], v[176:179], v[200:203], v[16:19]
	v_mfma_f32_16x16x32_bf16 v[4:7], v[160:163], v[208:211], v[4:7]
	v_mfma_f32_16x16x32_bf16 v[0:3], v[176:179], v[208:211], v[0:3]
	v_mfma_f32_16x16x32_bf16 v[52:55], v[164:167], v[188:191], v[52:55]
	v_mfma_f32_16x16x32_bf16 v[48:51], v[180:183], v[188:191], v[48:51]
	v_mfma_f32_16x16x32_bf16 v[36:39], v[164:167], v[196:199], v[36:39]
	v_mfma_f32_16x16x32_bf16 v[32:35], v[180:183], v[196:199], v[32:35]
	v_mfma_f32_16x16x32_bf16 v[20:23], v[164:167], v[204:207], v[20:23]
	v_mfma_f32_16x16x32_bf16 v[16:19], v[180:183], v[204:207], v[16:19]
	v_mfma_f32_16x16x32_bf16 v[4:7], v[164:167], v[212:215], v[4:7]
	v_mfma_f32_16x16x32_bf16 v[0:3], v[180:183], v[212:215], v[0:3]
	s_barrier
	s_add_i32 s69, 0, 0x18000
	s_add_i32 s72, 0, 0x1c000
	v_add_u32_e32 v156, s69, v169
	v_add_u32_e32 v175, s72, v169
	ds_read_b128 v[128:131], v156
	ds_read_b128 v[132:135], v156 offset:1024
	ds_read_b128 v[152:155], v156 offset:2048
	ds_read_b128 v[156:159], v156 offset:3072
	ds_read_b128 v[160:163], v175
	ds_read_b128 v[164:167], v175 offset:1024
	ds_read_b128 v[176:179], v175 offset:2048
	ds_read_b128 v[180:183], v175 offset:3072
	s_add_u32 s6, s36, 0xb0000
	s_addc_u32 s7, s37, 0
	s_mov_b32 m0, s48
	v_lshl_add_u64 v[224:225], s[6:7], 0, v[136:137]
	ds_read_b128 v[184:187], v173 offset:32768
	ds_read_b128 v[188:191], v173 offset:33792
	ds_read_b128 v[192:195], v173 offset:34816
	ds_read_b128 v[196:199], v173 offset:35840
	ds_read_b128 v[200:203], v173 offset:36864
	ds_read_b128 v[204:207], v173 offset:37888
	ds_read_b128 v[208:211], v173 offset:38912
	ds_read_b128 v[212:215], v173 offset:39936
	global_load_lds_dwordx4 v[224:225], off
	v_lshl_add_u64 v[224:225], s[6:7], 0, v[140:141]
	s_mov_b32 m0, s49
	s_nop 0
	global_load_lds_dwordx4 v[224:225], off
	s_waitcnt vmcnt(8)
	s_waitcnt lgkmcnt(0)
	s_barrier
	s_waitcnt lgkmcnt(0)
	v_mfma_f32_16x16x32_bf16 v[124:127], v[128:131], v[184:187], v[124:127]
	v_mfma_f32_16x16x32_bf16 v[120:123], v[152:155], v[184:187], v[120:123]
	v_mfma_f32_16x16x32_bf16 v[108:111], v[128:131], v[192:195], v[108:111]
	v_mfma_f32_16x16x32_bf16 v[104:107], v[152:155], v[192:195], v[104:107]
	v_mfma_f32_16x16x32_bf16 v[92:95], v[128:131], v[200:203], v[92:95]
	v_mfma_f32_16x16x32_bf16 v[88:91], v[152:155], v[200:203], v[88:91]
	v_mfma_f32_16x16x32_bf16 v[76:79], v[128:131], v[208:211], v[76:79]
	v_mfma_f32_16x16x32_bf16 v[72:75], v[152:155], v[208:211], v[72:75]
	v_mfma_f32_16x16x32_bf16 v[124:127], v[132:135], v[188:191], v[124:127]
	v_mfma_f32_16x16x32_bf16 v[120:123], v[156:159], v[188:191], v[120:123]
	v_mfma_f32_16x16x32_bf16 v[108:111], v[132:135], v[196:199], v[108:111]
	v_mfma_f32_16x16x32_bf16 v[104:107], v[156:159], v[196:199], v[104:107]
	v_mfma_f32_16x16x32_bf16 v[92:95], v[132:135], v[204:207], v[92:95]
	v_mfma_f32_16x16x32_bf16 v[88:91], v[156:159], v[204:207], v[88:91]
	v_mfma_f32_16x16x32_bf16 v[76:79], v[132:135], v[212:215], v[76:79]
	v_mfma_f32_16x16x32_bf16 v[72:75], v[156:159], v[212:215], v[72:75]
	v_mfma_f32_16x16x32_bf16 v[116:119], v[160:163], v[184:187], v[116:119]
	v_mfma_f32_16x16x32_bf16 v[112:115], v[176:179], v[184:187], v[112:115]
	v_mfma_f32_16x16x32_bf16 v[100:103], v[160:163], v[192:195], v[100:103]
	v_mfma_f32_16x16x32_bf16 v[96:99], v[176:179], v[192:195], v[96:99]
	v_mfma_f32_16x16x32_bf16 v[84:87], v[160:163], v[200:203], v[84:87]
	v_mfma_f32_16x16x32_bf16 v[80:83], v[176:179], v[200:203], v[80:83]
	v_mfma_f32_16x16x32_bf16 v[68:71], v[160:163], v[208:211], v[68:71]
	v_mfma_f32_16x16x32_bf16 v[64:67], v[176:179], v[208:211], v[64:67]
	v_mfma_f32_16x16x32_bf16 v[116:119], v[164:167], v[188:191], v[116:119]
	v_mfma_f32_16x16x32_bf16 v[112:115], v[180:183], v[188:191], v[112:115]
	v_mfma_f32_16x16x32_bf16 v[100:103], v[164:167], v[196:199], v[100:103]
	v_mfma_f32_16x16x32_bf16 v[96:99], v[180:183], v[196:199], v[96:99]
	v_mfma_f32_16x16x32_bf16 v[84:87], v[164:167], v[204:207], v[84:87]
	v_mfma_f32_16x16x32_bf16 v[80:83], v[180:183], v[204:207], v[80:83]
	v_mfma_f32_16x16x32_bf16 v[68:71], v[164:167], v[212:215], v[68:71]
	v_mfma_f32_16x16x32_bf16 v[64:67], v[180:183], v[212:215], v[64:67]
	s_barrier
; #define PG8_STAGE(bufoff, gbase, voff) do { _Pragma("unroll") for (int _i = 0; _i < 2; ++_i) \
;         __builtin_amdgcn_global_load_lds((const unsigned*)((const char*)(gbase) + (voff)[_i]), (LAS unsigned*)(lds + (bufoff) + ldsw + _i * 8192), 16, 0, 0); } while (0)
; #define PG8_LDA(dst, b, h) do { _Pragma("unroll") for (int m = 0; m < 4; ++m) _Pragma("unroll") for (int k = 0; k < 2; ++k) dst[m][k] = *(const LAS bf16x8*)(lds + PG8_SA(b, h) + aoff + m * 2048 + k * 1024); } while (0)
; #define PG8_MMA(ai, bj, At, Bt) do { __builtin_amdgcn_s_setprio(1); _Pragma("unroll") for (int m = 0; m < 4; ++m) _Pragma("unroll") for (int n = 0; n < 2; ++n) _Pragma("unroll") for (int k = 0; k < 2; ++k) \
;         acc[ai][bj][m][n] = __builtin_amdgcn_mfma_f32_16x16x32_bf16(Bt[n][k], At[m][k], acc[ai][bj][m][n], 0, 0, 0); __builtin_amdgcn_s_setprio(0); } while (0)
; #define PG8_WAIT_V(n) asm volatile("s_waitcnt vmcnt(" #n ")" ::: "memory")
; #define PG8_WAIT_L(n) asm volatile("s_waitcnt lgkmcnt(" #n ")" ::: "memory")
; #define PG8_BAR __builtin_amdgcn_s_barrier()
; #define PG8_SCHED __builtin_amdgcn_sched_barrier(0)
; template <class Epi, class Sched>
; DEVI void gemm_phase(LAS unsigned char* lds, const Gemm g, const Sched& S, const Epi& E) {
;     ...
;             PG8_LDA(At, 1, 1); PG8_STAGE(PG8_SB(1, 0), b3, voffB); PG8_STAGE(PG8_SB(1, 1), b3 + hstep, voffB); PG8_STAGE(PG8_SA(1, 0), a3, voffA);
;             PG8_WAIT_V(8); PG8_WAIT_L(0); PG8_BAR; PG8_MMA(1, 0, At, B0); PG8_MMA(1, 1, At, B1); PG8_BAR; PG8_SCHED;
;         }
;         if (wr == 0) PG8_BAR;
	s_add_i32 s6, s69, s41
	v_lshl_add_u64 v[216:217], v[216:217], 0, s[18:19]
	s_mov_b32 m0, s6
	ds_read_b128 v[184:187], v173 offset:49152
	ds_read_b128 v[188:191], v173 offset:50176
	ds_read_b128 v[192:195], v173 offset:51200
	ds_read_b128 v[196:199], v173 offset:52224
	ds_read_b128 v[200:203], v173 offset:53248
	ds_read_b128 v[204:207], v173 offset:54272
	ds_read_b128 v[208:211], v173 offset:55296
	ds_read_b128 v[212:215], v173 offset:56320
	global_load_lds_dwordx4 v[216:217], off
	s_add_i32 m0, s6, 0x2000
	s_add_u32 s6, s34, 0xb0080
	v_lshl_add_u64 v[216:217], v[218:219], 0, s[18:19]
	s_addc_u32 s7, s35, 0
	s_add_i32 s34, s72, s41
	global_load_lds_dwordx4 v[216:217], off
	v_lshl_add_u64 v[216:217], s[6:7], 0, v[138:139]
	s_mov_b32 m0, s34
	s_nop 0
	global_load_lds_dwordx4 v[216:217], off
	v_lshl_add_u64 v[216:217], s[6:7], 0, v[142:143]
	s_add_i32 m0, s34, 0x2000
	s_nop 0
	global_load_lds_dwordx4 v[216:217], off
	v_lshl_add_u64 v[216:217], v[220:221], 0, s[18:19]
	s_mov_b32 m0, s51
	s_nop 0
	global_load_lds_dwordx4 v[216:217], off
	v_lshl_add_u64 v[216:217], v[222:223], 0, s[18:19]
	s_mov_b32 m0, s56
	s_nop 0
	global_load_lds_dwordx4 v[216:217], off
	s_waitcnt vmcnt(8)
	s_waitcnt lgkmcnt(0)
	s_barrier
	s_waitcnt lgkmcnt(0)
	v_mfma_f32_16x16x32_bf16 v[60:63], v[128:131], v[184:187], v[60:63]
	v_mfma_f32_16x16x32_bf16 v[56:59], v[152:155], v[184:187], v[56:59]
	v_mfma_f32_16x16x32_bf16 v[44:47], v[128:131], v[192:195], v[44:47]
	v_mfma_f32_16x16x32_bf16 v[40:43], v[152:155], v[192:195], v[40:43]
	v_mfma_f32_16x16x32_bf16 v[28:31], v[128:131], v[200:203], v[28:31]
	v_mfma_f32_16x16x32_bf16 v[24:27], v[152:155], v[200:203], v[24:27]
	v_mfma_f32_16x16x32_bf16 v[12:15], v[128:131], v[208:211], v[12:15]
	v_mfma_f32_16x16x32_bf16 v[8:11], v[152:155], v[208:211], v[8:11]
	v_mfma_f32_16x16x32_bf16 v[60:63], v[132:135], v[188:191], v[60:63]
	v_mfma_f32_16x16x32_bf16 v[56:59], v[156:159], v[188:191], v[56:59]
	v_mfma_f32_16x16x32_bf16 v[44:47], v[132:135], v[196:199], v[44:47]
	v_mfma_f32_16x16x32_bf16 v[40:43], v[156:159], v[196:199], v[40:43]
	v_mfma_f32_16x16x32_bf16 v[28:31], v[132:135], v[204:207], v[28:31]
	v_mfma_f32_16x16x32_bf16 v[24:27], v[156:159], v[204:207], v[24:27]
	v_mfma_f32_16x16x32_bf16 v[12:15], v[132:135], v[212:215], v[12:15]
	v_mfma_f32_16x16x32_bf16 v[8:11], v[156:159], v[212:215], v[8:11]
	v_mfma_f32_16x16x32_bf16 v[52:55], v[160:163], v[184:187], v[52:55]
	v_mfma_f32_16x16x32_bf16 v[48:51], v[176:179], v[184:187], v[48:51]
	v_mfma_f32_16x16x32_bf16 v[36:39], v[160:163], v[192:195], v[36:39]
	v_mfma_f32_16x16x32_bf16 v[32:35], v[176:179], v[192:195], v[32:35]
	v_mfma_f32_16x16x32_bf16 v[20:23], v[160:163], v[200:203], v[20:23]
	v_mfma_f32_16x16x32_bf16 v[16:19], v[176:179], v[200:203], v[16:19]
	v_mfma_f32_16x16x32_bf16 v[4:7], v[160:163], v[208:211], v[4:7]
	v_mfma_f32_16x16x32_bf16 v[0:3], v[176:179], v[208:211], v[0:3]
	v_mfma_f32_16x16x32_bf16 v[52:55], v[164:167], v[188:191], v[52:55]
	v_mfma_f32_16x16x32_bf16 v[48:51], v[180:183], v[188:191], v[48:51]
	v_mfma_f32_16x16x32_bf16 v[36:39], v[164:167], v[196:199], v[36:39]
	v_mfma_f32_16x16x32_bf16 v[32:35], v[180:183], v[196:199], v[32:35]
	v_mfma_f32_16x16x32_bf16 v[20:23], v[164:167], v[204:207], v[20:23]
	v_mfma_f32_16x16x32_bf16 v[16:19], v[180:183], v[204:207], v[16:19]
	v_mfma_f32_16x16x32_bf16 v[4:7], v[164:167], v[212:215], v[4:7]
	v_mfma_f32_16x16x32_bf16 v[0:3], v[180:183], v[212:215], v[0:3]
	s_barrier
	s_add_i32 s68, s68, 2
	s_add_u32 s64, s64, 0x100
	s_addc_u32 s65, s65, 0
	s_cmp_gt_u32 s68, 41
	s_mov_b64 s[6:7], s[30:31]
	s_cbranch_scc0 .LBB0_793
	s_and_b64 vcc, exec, s[20:21]
	s_cbranch_vccz .LBB0_796
	s_barrier

; DEVI int tid_() { int t = threadIdx.x; asm volatile("" : "+v"(t)); return t; }
; #define PG8_STAGE(bufoff, gbase, voff) do { _Pragma("unroll") for (int _i = 0; _i < 2; ++_i) \
;         __builtin_amdgcn_global_load_lds((const unsigned*)((const char*)(gbase) + (voff)[_i]), (LAS unsigned*)(lds + (bufoff) + ldsw + _i * 8192), 16, 0, 0); } while (0)
; #define PG8_BAR __builtin_amdgcn_s_barrier()
; template <class Epi, class Sched>
; DEVI void gemm_phase(LAS unsigned char* lds, const Gemm g, const Sched& S, const Epi& E) {
;     const int tid = tid_(), wid = __builtin_amdgcn_readfirstlane(tid >> 6), lane = tid & 63, wr = wid >> 2, wc = wid & 3, fr = lane & 15, fq = lane >> 4;
;     const int K = g.K, nt = K / BK;
;     unsigned voffA[2], voffB[2];
; #pragma unroll
;     for (int i = 0; i < 2; ++i) { int R, C; stage_rc(tid * 16 + i * 8192, R, C); const int Rb = Epi::PERM ? ((R & ~31) + perm32(R & 31)) : R;
;         voffA[i] = (unsigned)(R * K + C) * 2u; voffB[i] = (unsigned)(Rb * K + C) * 2u; }
;     const size_t kstep = (size_t)(BK * 2);
;     const size_t hstep = (size_t)HALF * K * 2;
;     const size_t tstep = 2 * hstep;
;     const unsigned ldsw = (unsigned)wid * 1024u;
;     const int aoff = lds_byte(wr * 64 + fr, fq * 8), boff = lds_byte(wc * 32 + fr, fq * 8);
;     ...
;     Unit cur, nxt; int ui = 0;
;     if (!S.next(0, cur)) return;
;     f32x4 acc[2][2][4][2];
; #pragma unroll
;     for (int a = 0; a < 2; ++a)
; #pragma unroll
;         for (int b = 0; b < 2; ++b)
; #pragma unroll
;             for (int m = 0; m < 4; ++m)
; #pragma unroll
;                 for (int n = 0; n < 2; ++n) acc[a][b][m][n] = (f32x4){0.f, 0.f, 0.f, 0.f};
;     bf16x8 At[4][2], B0[2][2], B1[2][2];
;     const char* cA = (const char*)g.A + (size_t)cur.pm * tstep; const char* cB = (const char*)g.Bt + (size_t)cur.pn * tstep;
;     S.a_ready(cur);
;     PG8_STAGE(PG8_SB(0, 0), cB, voffB); PG8_STAGE(PG8_SB(0, 1), cB + hstep, voffB); PG8_STAGE(PG8_SA(0, 0), cA, voffA); PG8_STAGE(PG8_SA(0, 1), cA + hstep, voffA);
;     if (wr == 1) PG8_BAR;
.LBB0_956:
	s_or_b64 exec, exec, s[0:1]
	s_mov_b64 s[0:1], s[96:97]
	s_mov_b32 s17, s89
	v_readlane_b32 s33, v249, 0
	v_mov_b32_e32 v8, v242
	s_waitcnt lgkmcnt(0)
	s_barrier
	v_readfirstlane_b32 s98, v242
	s_nop 3
	s_cmpk_lt_u32 s98, 0x100
	s_cbranch_scc1 .Lsprio_sp8
	s_setprio 1
.Lsprio_sp8:
	s_cmpk_gt_i32 s33, 0x2ff
	v_readfirstlane_b32 s15, v8
	s_cbranch_scc1 .LBB0_972
	v_lshlrev_b32_e32 v0, 4, v8
	v_add_u32_e32 v1, 0x2000, v0
	v_ashrrev_i32_e32 v2, 31, v1
	v_lshrrev_b32_e32 v2, 22, v2
	v_add_u32_e32 v2, v1, v2
	v_ashrrev_i32_e32 v9, 10, v2
	v_mul_i32_i24_e32 v2, 0x400, v9
	v_sub_u32_e32 v1, v1, v2
	v_lshrrev_b32_e32 v2, 4, v1
	v_bitop3_b32 v1, v2, v1, 32 bitop3:0x6c
	v_ashrrev_i32_e32 v2, 31, v1
	v_lshrrev_b32_e32 v2, 26, v2
	v_add_u32_e32 v2, v1, v2
	v_lshlrev_b32_e32 v3, 3, v9
	v_ashrrev_i32_e32 v10, 6, v2
	v_and_b32_e32 v3, -16, v3
	v_add_u32_e32 v3, v10, v3
	v_and_b32_e32 v4, 3, v10
	s_mov_b32 s2, 0x1fffe0
	v_lshrrev_b32_e32 v5, 2, v3
	v_lshlrev_b32_e32 v6, 1, v3
	v_and_b32_e32 v2, 0xc0, v2
	v_and_or_b32 v4, v3, s2, v4
	v_and_b32_e32 v5, 4, v5
	v_and_b32_e32 v6, 24, v6
	v_sub_u32_e32 v1, v1, v2
	v_mov_b32_e32 v2, 1
	v_or3_b32 v4, v4, v5, v6
	v_lshlrev_b32_e32 v5, 5, v9
	v_ashrrev_i16_sdwa v1, v2, sext(v1) dst_sel:DWORD dst_unused:UNUSED_PAD src0_sel:DWORD src1_sel:BYTE_0
	v_and_b32_e32 v5, 32, v5
	v_bfe_i32 v11, v1, 0, 16
	v_add_lshl_u32 v1, v5, v11, 1
	v_lshl_add_u32 v160, v4, 11, v1
	v_lshl_add_u32 v162, v3, 11, v1
	v_bfe_i32 v1, v8, 27, 1
	v_lshrrev_b32_e32 v1, 22, v1
	v_add_u32_e32 v1, v0, v1
	v_and_b32_e32 v1, 0xfffffc00, v1
	v_sub_u32_e32 v0, v0, v1
	v_lshrrev_b32_e32 v1, 4, v0
	v_bitop3_b32 v1, v1, v0, 32 bitop3:0x6c
	v_ashrrev_i32_e32 v0, 31, v0
	v_lshrrev_b32_e32 v0, 26, v0
	v_add_u32_e32 v0, v1, v0
	v_ashrrev_i32_e32 v12, 6, v0
	v_ashrrev_i32_e32 v0, 31, v8
	v_lshrrev_b32_e32 v0, 26, v0
	v_add_u32_e32 v0, v8, v0
	s_add_u32 s36, s0, 0x2600000
	v_ashrrev_i32_e32 v13, 6, v0
	s_addc_u32 s37, s1, 0
	v_lshlrev_b32_e32 v0, 3, v13
	s_add_u32 s38, s0, 0x6800000
	v_and_b32_e32 v0, -16, v0
	s_addc_u32 s39, s1, 0
	v_add_u32_e32 v0, v12, v0
	v_and_b32_e32 v3, 3, v12
	s_ashr_i32 s41, s33, 31
	v_and_or_b32 v3, v0, s2, v3
	s_lshr_b32 s2, s41, 29
	s_add_i32 s2, s33, s2
	s_ashr_i32 s12, s15, 6
	s_ashr_i32 s3, s2, 3
	s_and_b32 s2, s2, -8
	s_ashr_i32 s16, s15, 8
	s_lshl_b32 s40, s12, 10
	s_sub_i32 s2, s33, s2
	s_cmp_lt_i32 s2, 0
	s_movk_i32 s42, 0x61
	s_cselect_b32 s4, s42, 0x60
	s_mul_i32 s2, s4, s2
	s_add_i32 s2, s2, s3
	s_mul_hi_i32 s3, s2, 0x2aaaaaab
	s_lshr_b32 s4, s3, 31
	s_ashr_i32 s3, s3, 3
	s_add_i32 s3, s3, s4
	s_lshl_b32 s4, s3, 3
	s_mul_i32 s3, s3, 48
	s_sub_i32 s2, s2, s3
	s_bfe_i32 s3, s2, 0x80000
	s_bfe_u32 s3, s3, 0x3000c
	s_add_i32 s3, s2, s3
	s_bfe_i32 s5, s3, 0x80000
	s_and_b32 s3, s3, 0xf8
	v_lshrrev_b32_e32 v4, 2, v0
	v_lshlrev_b32_e32 v5, 1, v0
	s_sub_i32 s2, s2, s3
	v_and_b32_e32 v4, 4, v4
	v_and_b32_e32 v5, 24, v5
	s_sext_i32_i16 s5, s5
	s_sext_i32_i8 s2, s2
	v_or3_b32 v3, v3, v4, v5
	v_mul_i32_i24_e32 v5, 64, v12
	s_lshr_b32 s14, s5, 3
	s_add_i32 s26, s4, s2
	v_sub_u32_e32 v1, v1, v5
	s_ashr_i32 s27, s26, 31
	s_bfe_i64 s[4:5], s[14:15], 0x100000
	v_lshlrev_b32_e32 v4, 5, v13
	v_ashrrev_i16_sdwa v1, v2, sext(v1) dst_sel:DWORD dst_unused:UNUSED_PAD src0_sel:DWORD src1_sel:BYTE_0
	s_lshl_b64 s[2:3], s[26:27], 19
	s_lshl_b64 s[4:5], s[4:5], 19
	v_and_b32_e32 v4, 32, v4
	v_bfe_i32 v14, v1, 0, 16
	s_add_u32 s28, s36, s4
	v_add_lshl_u32 v1, v4, v14, 1
	s_addc_u32 s29, s37, s5
	s_add_i32 s27, s40, 0
	v_lshl_add_u32 v164, v3, 11, v1
	s_add_i32 m0, s27, 0x10000
	v_lshl_add_u32 v166, v0, 11, v1
	global_load_lds_dwordx4 v164, s[28:29]
	s_add_i32 m0, s27, 0x12000
	s_add_u32 s4, s28, 0x40000
	global_load_lds_dwordx4 v160, s[28:29]
	s_addc_u32 s5, s29, 0
	s_add_i32 m0, s27, 0x14000
	v_mov_b32_e32 v165, 0
	global_load_lds_dwordx4 v164, s[4:5]
	s_add_i32 m0, s27, 0x16000
	s_add_u32 s30, s38, s2
	s_addc_u32 s31, s39, s3
	s_add_i32 s43, s27, 0x2000
	global_load_lds_dwordx4 v160, s[4:5]
	s_mov_b32 m0, s27
	s_add_u32 s2, s30, 0x40000
	global_load_lds_dwordx4 v166, s[30:31]
	s_mov_b32 m0, s43
	s_addc_u32 s3, s31, 0
	s_add_i32 s48, s27, 0x4000
	global_load_lds_dwordx4 v162, s[30:31]
	s_mov_b32 m0, s48
	s_add_i32 s49, s27, 0x6000
	global_load_lds_dwordx4 v166, s[2:3]
	s_mov_b32 m0, s49
	v_mov_b32_e32 v161, v165
	global_load_lds_dwordx4 v162, s[2:3]
	v_mov_b32_e32 v167, v165
	v_mov_b32_e32 v163, v165
	s_cmp_eq_u32 s16, 1
	s_mov_b32 s50, 0
	v_lshl_add_u64 v[6:7], s[28:29], 0, v[164:165]
	v_lshl_add_u64 v[4:5], s[28:29], 0, v[160:161]
	v_lshl_add_u64 v[0:1], s[30:31], 0, v[166:167]
	s_cselect_b64 s[2:3], -1, 0
	s_cmp_lg_u32 s16, 1
	v_lshl_add_u64 v[2:3], s[30:31], 0, v[162:163]
	s_cbranch_scc1 .LBB0_959
	s_barrier

; #define PG8_STAGE(bufoff, gbase, voff) do { _Pragma("unroll") for (int _i = 0; _i < 2; ++_i) \
;         __builtin_amdgcn_global_load_lds((const unsigned*)((const char*)(gbase) + (voff)[_i]), (LAS unsigned*)(lds + (bufoff) + ldsw + _i * 8192), 16, 0, 0); } while (0)
; #define PG8_LDA(dst, b, h) do { _Pragma("unroll") for (int m = 0; m < 4; ++m) _Pragma("unroll") for (int k = 0; k < 2; ++k) dst[m][k] = *(const LAS bf16x8*)(lds + PG8_SA(b, h) + aoff + m * 2048 + k * 1024); } while (0)
; #define PG8_LDB(dst, b, h) do { _Pragma("unroll") for (int n = 0; n < 2; ++n) _Pragma("unroll") for (int k = 0; k < 2; ++k) dst[n][k] = *(const LAS bf16x8*)(lds + PG8_SB(b, h) + boff + n * 2048 + k * 1024); } while (0)
; #define PG8_MMA(ai, bj, At, Bt) do { __builtin_amdgcn_s_setprio(1); _Pragma("unroll") for (int m = 0; m < 4; ++m) _Pragma("unroll") for (int n = 0; n < 2; ++n) _Pragma("unroll") for (int k = 0; k < 2; ++k) \
;         acc[ai][bj][m][n] = __builtin_amdgcn_mfma_f32_16x16x32_bf16(Bt[n][k], At[m][k], acc[ai][bj][m][n], 0, 0, 0); __builtin_amdgcn_s_setprio(0); } while (0)
; #define PG8_WAIT_V(n) asm volatile("s_waitcnt vmcnt(" #n ")" ::: "memory")
; #define PG8_WAIT_L(n) asm volatile("s_waitcnt lgkmcnt(" #n ")" ::: "memory")
; #define PG8_BAR __builtin_amdgcn_s_barrier()
; #define PG8_SCHED __builtin_amdgcn_sched_barrier(0)
; template <class Epi, class Sched>
; DEVI void gemm_phase(LAS unsigned char* lds, const Gemm g, const Sched& S, const Epi& E) {
;     ...
;             PG8_LDB(B0, 0, 0); PG8_LDB(B1, 0, 1); PG8_SCHED; PG8_LDA(At, 0, 0); PG8_STAGE(PG8_SA(1, 1), a1 + hstep, voffA);
;             PG8_WAIT_V(8); PG8_WAIT_L(0); PG8_BAR; PG8_MMA(0, 0, At, B0); PG8_MMA(0, 1, At, B1); PG8_BAR; PG8_SCHED;
;             PG8_LDA(At, 0, 1); PG8_STAGE(PG8_SB(0, 0), b2, voffB); PG8_STAGE(PG8_SB(0, 1), b2 + hstep, voffB); PG8_STAGE(PG8_SA(0, 0), a2, voffA);
;             PG8_WAIT_V(8); PG8_WAIT_L(0); PG8_BAR; PG8_MMA(1, 0, At, B0); PG8_MMA(1, 1, At, B1); PG8_BAR; PG8_SCHED;
.LBB0_965:
	ds_read_b128 v[112:115], v185
	ds_read_b128 v[116:119], v185 offset:1024
	ds_read_b128 v[120:123], v185 offset:2048
	ds_read_b128 v[124:127], v185 offset:3072
	ds_read_b128 v[128:131], v186
	ds_read_b128 v[132:135], v186 offset:1024
	ds_read_b128 v[136:139], v186 offset:2048
	ds_read_b128 v[140:143], v186 offset:3072
	s_add_u32 s30, s28, 0xfffc0080
	s_addc_u32 s31, s29, -1
	s_cmp_eq_u32 s69, 12
	s_cselect_b32 s35, s21, s31
	s_cselect_b32 s34, s63, s30
	s_cselect_b32 s31, s19, s68
	s_cselect_b32 s30, s64, s65
	v_lshl_add_u64 v[180:181], s[28:29], 0, v[170:171]
	s_add_i32 m0, s27, 0xc000
	ds_read_b128 v[176:179], v187
	ds_read_b128 v[188:191], v187 offset:1024
	ds_read_b128 v[192:195], v187 offset:2048
	ds_read_b128 v[196:199], v187 offset:3072
	ds_read_b128 v[200:203], v187 offset:4096
	ds_read_b128 v[204:207], v187 offset:5120
	ds_read_b128 v[208:211], v187 offset:6144
	ds_read_b128 v[212:215], v187 offset:7168
	global_load_lds_dwordx4 v[180:181], off
	v_lshl_add_u64 v[180:181], s[28:29], 0, v[168:169]
	s_add_i32 m0, s27, 0xe000
	s_nop 0
	global_load_lds_dwordx4 v[180:181], off
	s_waitcnt vmcnt(8)
	s_waitcnt lgkmcnt(0)
	s_barrier
	s_waitcnt lgkmcnt(0)
	v_mfma_f32_16x16x32_bf16 v[156:159], v[112:115], v[176:179], v[156:159]
	v_mfma_f32_16x16x32_bf16 v[152:155], v[120:123], v[176:179], v[152:155]
	v_mfma_f32_16x16x32_bf16 v[108:111], v[112:115], v[192:195], v[108:111]
	v_mfma_f32_16x16x32_bf16 v[104:107], v[120:123], v[192:195], v[104:107]
	v_mfma_f32_16x16x32_bf16 v[92:95], v[112:115], v[200:203], v[92:95]
	v_mfma_f32_16x16x32_bf16 v[88:91], v[120:123], v[200:203], v[88:91]
	v_mfma_f32_16x16x32_bf16 v[76:79], v[112:115], v[208:211], v[76:79]
	v_mfma_f32_16x16x32_bf16 v[72:75], v[120:123], v[208:211], v[72:75]
	v_mfma_f32_16x16x32_bf16 v[156:159], v[116:119], v[188:191], v[156:159]
	v_mfma_f32_16x16x32_bf16 v[152:155], v[124:127], v[188:191], v[152:155]
	v_mfma_f32_16x16x32_bf16 v[108:111], v[116:119], v[196:199], v[108:111]
	v_mfma_f32_16x16x32_bf16 v[104:107], v[124:127], v[196:199], v[104:107]
	v_mfma_f32_16x16x32_bf16 v[92:95], v[116:119], v[204:207], v[92:95]
	v_mfma_f32_16x16x32_bf16 v[88:91], v[124:127], v[204:207], v[88:91]
	v_mfma_f32_16x16x32_bf16 v[76:79], v[116:119], v[212:215], v[76:79]
	v_mfma_f32_16x16x32_bf16 v[72:75], v[124:127], v[212:215], v[72:75]
	v_mfma_f32_16x16x32_bf16 v[148:151], v[128:131], v[176:179], v[148:151]
	v_mfma_f32_16x16x32_bf16 v[144:147], v[136:139], v[176:179], v[144:147]
	v_mfma_f32_16x16x32_bf16 v[100:103], v[128:131], v[192:195], v[100:103]
	v_mfma_f32_16x16x32_bf16 v[96:99], v[136:139], v[192:195], v[96:99]
	v_mfma_f32_16x16x32_bf16 v[84:87], v[128:131], v[200:203], v[84:87]
	v_mfma_f32_16x16x32_bf16 v[80:83], v[136:139], v[200:203], v[80:83]
	v_mfma_f32_16x16x32_bf16 v[68:71], v[128:131], v[208:211], v[68:71]
	v_mfma_f32_16x16x32_bf16 v[64:67], v[136:139], v[208:211], v[64:67]
	v_mfma_f32_16x16x32_bf16 v[148:151], v[132:135], v[188:191], v[148:151]
	v_mfma_f32_16x16x32_bf16 v[144:147], v[140:143], v[188:191], v[144:147]
	v_mfma_f32_16x16x32_bf16 v[100:103], v[132:135], v[196:199], v[100:103]
	v_mfma_f32_16x16x32_bf16 v[96:99], v[140:143], v[196:199], v[96:99]
	v_mfma_f32_16x16x32_bf16 v[84:87], v[132:135], v[204:207], v[84:87]
	v_mfma_f32_16x16x32_bf16 v[80:83], v[140:143], v[204:207], v[80:83]
	v_mfma_f32_16x16x32_bf16 v[68:71], v[132:135], v[212:215], v[68:71]
	v_mfma_f32_16x16x32_bf16 v[64:67], v[140:143], v[212:215], v[64:67]
	s_barrier
	s_add_i32 s72, s58, s40
	v_lshl_add_u64 v[180:181], s[30:31], 0, v[164:165]
	s_mov_b32 m0, s72
	ds_read_b128 v[176:179], v187 offset:16384
	ds_read_b128 v[188:191], v187 offset:17408
	ds_read_b128 v[192:195], v187 offset:18432
	ds_read_b128 v[196:199], v187 offset:19456
	ds_read_b128 v[200:203], v187 offset:20480
	ds_read_b128 v[204:207], v187 offset:21504
	ds_read_b128 v[208:211], v187 offset:22528
	ds_read_b128 v[212:215], v187 offset:23552
	global_load_lds_dwordx4 v[180:181], off
	s_add_i32 m0, s72, 0x2000
	s_add_u32 s72, s30, 0x40000
	v_lshl_add_u64 v[216:217], s[30:31], 0, v[160:161]
	s_addc_u32 s73, s31, 0
	s_add_i32 s76, s59, s40
	global_load_lds_dwordx4 v[216:217], off
	v_lshl_add_u64 v[218:219], s[72:73], 0, v[164:165]
	s_mov_b32 m0, s76
	v_lshl_add_u64 v[220:221], s[34:35], 0, v[162:163]
	global_load_lds_dwordx4 v[218:219], off
	v_lshl_add_u64 v[218:219], s[72:73], 0, v[160:161]
	s_add_i32 m0, s76, 0x2000
	s_nop 0
	global_load_lds_dwordx4 v[218:219], off
	v_lshl_add_u64 v[218:219], s[34:35], 0, v[166:167]
	s_mov_b32 m0, s27
	s_nop 0
	global_load_lds_dwordx4 v[218:219], off
	s_mov_b32 m0, s43
	s_nop 0
	global_load_lds_dwordx4 v[220:221], off
	s_waitcnt vmcnt(8)
	s_waitcnt lgkmcnt(0)
	s_barrier
; #define PG8_STAGE(bufoff, gbase, voff) do { _Pragma("unroll") for (int _i = 0; _i < 2; ++_i) \
;         __builtin_amdgcn_global_load_lds((const unsigned*)((const char*)(gbase) + (voff)[_i]), (LAS unsigned*)(lds + (bufoff) + ldsw + _i * 8192), 16, 0, 0); } while (0)
; #define PG8_LDA(dst, b, h) do { _Pragma("unroll") for (int m = 0; m < 4; ++m) _Pragma("unroll") for (int k = 0; k < 2; ++k) dst[m][k] = *(const LAS bf16x8*)(lds + PG8_SA(b, h) + aoff + m * 2048 + k * 1024); } while (0)
; #define PG8_LDB(dst, b, h) do { _Pragma("unroll") for (int n = 0; n < 2; ++n) _Pragma("unroll") for (int k = 0; k < 2; ++k) dst[n][k] = *(const LAS bf16x8*)(lds + PG8_SB(b, h) + boff + n * 2048 + k * 1024); } while (0)
; #define PG8_MMA(ai, bj, At, Bt) do { __builtin_amdgcn_s_setprio(1); _Pragma("unroll") for (int m = 0; m < 4; ++m) _Pragma("unroll") for (int n = 0; n < 2; ++n) _Pragma("unroll") for (int k = 0; k < 2; ++k) \
;         acc[ai][bj][m][n] = __builtin_amdgcn_mfma_f32_16x16x32_bf16(Bt[n][k], At[m][k], acc[ai][bj][m][n], 0, 0, 0); __builtin_amdgcn_s_setprio(0); } while (0)
; #define PG8_WAIT_V(n) asm volatile("s_waitcnt vmcnt(" #n ")" ::: "memory")
; #define PG8_WAIT_L(n) asm volatile("s_waitcnt lgkmcnt(" #n ")" ::: "memory")
; #define PG8_BAR __builtin_amdgcn_s_barrier()
; #define PG8_SCHED __builtin_amdgcn_sched_barrier(0)
; template <class Epi, class Sched>
; DEVI void gemm_phase(LAS unsigned char* lds, const Gemm g, const Sched& S, const Epi& E) {
;     ...
;             PG8_WAIT_V(8); PG8_WAIT_L(0); PG8_BAR; PG8_MMA(1, 0, At, B0); PG8_MMA(1, 1, At, B1); PG8_BAR; PG8_SCHED;
;             PG8_LDB(B0, 1, 0); PG8_LDB(B1, 1, 1); PG8_SCHED; PG8_LDA(At, 1, 0); PG8_STAGE(PG8_SA(0, 1), a2 + hstep, voffA);
;             PG8_WAIT_V(8); PG8_WAIT_L(0); PG8_BAR; PG8_MMA(0, 0, At, B0); PG8_MMA(0, 1, At, B1); PG8_BAR; PG8_SCHED;
	s_waitcnt lgkmcnt(0)
	v_mfma_f32_16x16x32_bf16 v[60:63], v[112:115], v[176:179], v[60:63]
	v_mfma_f32_16x16x32_bf16 v[56:59], v[120:123], v[176:179], v[56:59]
	v_mfma_f32_16x16x32_bf16 v[44:47], v[112:115], v[192:195], v[44:47]
	v_mfma_f32_16x16x32_bf16 v[40:43], v[120:123], v[192:195], v[40:43]
	v_mfma_f32_16x16x32_bf16 v[28:31], v[112:115], v[200:203], v[28:31]
	v_mfma_f32_16x16x32_bf16 v[24:27], v[120:123], v[200:203], v[24:27]
	v_mfma_f32_16x16x32_bf16 v[12:15], v[112:115], v[208:211], v[12:15]
	v_mfma_f32_16x16x32_bf16 v[8:11], v[120:123], v[208:211], v[8:11]
	v_mfma_f32_16x16x32_bf16 v[60:63], v[116:119], v[188:191], v[60:63]
	v_mfma_f32_16x16x32_bf16 v[56:59], v[124:127], v[188:191], v[56:59]
	v_mfma_f32_16x16x32_bf16 v[44:47], v[116:119], v[196:199], v[44:47]
	v_mfma_f32_16x16x32_bf16 v[40:43], v[124:127], v[196:199], v[40:43]
	v_mfma_f32_16x16x32_bf16 v[28:31], v[116:119], v[204:207], v[28:31]
	v_mfma_f32_16x16x32_bf16 v[24:27], v[124:127], v[204:207], v[24:27]
	v_mfma_f32_16x16x32_bf16 v[12:15], v[116:119], v[212:215], v[12:15]
	v_mfma_f32_16x16x32_bf16 v[8:11], v[124:127], v[212:215], v[8:11]
	v_mfma_f32_16x16x32_bf16 v[52:55], v[128:131], v[176:179], v[52:55]
	v_mfma_f32_16x16x32_bf16 v[48:51], v[136:139], v[176:179], v[48:51]
	v_mfma_f32_16x16x32_bf16 v[36:39], v[128:131], v[192:195], v[36:39]
	v_mfma_f32_16x16x32_bf16 v[32:35], v[136:139], v[192:195], v[32:35]
	v_mfma_f32_16x16x32_bf16 v[20:23], v[128:131], v[200:203], v[20:23]
	v_mfma_f32_16x16x32_bf16 v[16:19], v[136:139], v[200:203], v[16:19]
	v_mfma_f32_16x16x32_bf16 v[4:7], v[128:131], v[208:211], v[4:7]
	v_mfma_f32_16x16x32_bf16 v[0:3], v[136:139], v[208:211], v[0:3]
	v_mfma_f32_16x16x32_bf16 v[52:55], v[132:135], v[188:191], v[52:55]
	v_mfma_f32_16x16x32_bf16 v[48:51], v[140:143], v[188:191], v[48:51]
	v_mfma_f32_16x16x32_bf16 v[36:39], v[132:135], v[196:199], v[36:39]
	v_mfma_f32_16x16x32_bf16 v[32:35], v[140:143], v[196:199], v[32:35]
	v_mfma_f32_16x16x32_bf16 v[20:23], v[132:135], v[204:207], v[20:23]
	v_mfma_f32_16x16x32_bf16 v[16:19], v[140:143], v[204:207], v[16:19]
	v_mfma_f32_16x16x32_bf16 v[4:7], v[132:135], v[212:215], v[4:7]
	v_mfma_f32_16x16x32_bf16 v[0:3], v[140:143], v[212:215], v[0:3]
	s_barrier
	s_add_i32 s72, 0, 0x18000
	s_add_i32 s73, 0, 0x1c000
	v_add_u32_e32 v124, s72, v183
	v_add_u32_e32 v140, s73, v183
	ds_read_b128 v[112:115], v124
	ds_read_b128 v[116:119], v124 offset:1024
	ds_read_b128 v[120:123], v124 offset:2048
	ds_read_b128 v[124:127], v124 offset:3072
	ds_read_b128 v[128:131], v140
	ds_read_b128 v[132:135], v140 offset:1024
	ds_read_b128 v[136:139], v140 offset:2048
	ds_read_b128 v[140:143], v140 offset:3072
	s_add_u32 s34, s34, 0x40000
	s_addc_u32 s35, s35, 0
	s_mov_b32 m0, s48
	v_lshl_add_u64 v[222:223], s[34:35], 0, v[166:167]
	ds_read_b128 v[176:179], v187 offset:32768
	ds_read_b128 v[188:191], v187 offset:33792
	ds_read_b128 v[192:195], v187 offset:34816
	ds_read_b128 v[196:199], v187 offset:35840
	ds_read_b128 v[200:203], v187 offset:36864
	ds_read_b128 v[204:207], v187 offset:37888
	ds_read_b128 v[208:211], v187 offset:38912
	ds_read_b128 v[212:215], v187 offset:39936
	global_load_lds_dwordx4 v[222:223], off
	v_lshl_add_u64 v[222:223], s[34:35], 0, v[162:163]
	s_mov_b32 m0, s49
	s_nop 0
	global_load_lds_dwordx4 v[222:223], off
	s_waitcnt vmcnt(8)
	s_waitcnt lgkmcnt(0)
	s_barrier
	s_waitcnt lgkmcnt(0)
	v_mfma_f32_16x16x32_bf16 v[156:159], v[112:115], v[176:179], v[156:159]
	v_mfma_f32_16x16x32_bf16 v[152:155], v[120:123], v[176:179], v[152:155]
	v_mfma_f32_16x16x32_bf16 v[108:111], v[112:115], v[192:195], v[108:111]
	v_mfma_f32_16x16x32_bf16 v[104:107], v[120:123], v[192:195], v[104:107]
	v_mfma_f32_16x16x32_bf16 v[92:95], v[112:115], v[200:203], v[92:95]
	v_mfma_f32_16x16x32_bf16 v[88:91], v[120:123], v[200:203], v[88:91]
	v_mfma_f32_16x16x32_bf16 v[76:79], v[112:115], v[208:211], v[76:79]
	v_mfma_f32_16x16x32_bf16 v[72:75], v[120:123], v[208:211], v[72:75]
	v_mfma_f32_16x16x32_bf16 v[156:159], v[116:119], v[188:191], v[156:159]
	v_mfma_f32_16x16x32_bf16 v[152:155], v[124:127], v[188:191], v[152:155]
	v_mfma_f32_16x16x32_bf16 v[108:111], v[116:119], v[196:199], v[108:111]
	v_mfma_f32_16x16x32_bf16 v[104:107], v[124:127], v[196:199], v[104:107]
	v_mfma_f32_16x16x32_bf16 v[92:95], v[116:119], v[204:207], v[92:95]
	v_mfma_f32_16x16x32_bf16 v[88:91], v[124:127], v[204:207], v[88:91]
	v_mfma_f32_16x16x32_bf16 v[76:79], v[116:119], v[212:215], v[76:79]
	v_mfma_f32_16x16x32_bf16 v[72:75], v[124:127], v[212:215], v[72:75]
	v_mfma_f32_16x16x32_bf16 v[148:151], v[128:131], v[176:179], v[148:151]
	v_mfma_f32_16x16x32_bf16 v[144:147], v[136:139], v[176:179], v[144:147]
	v_mfma_f32_16x16x32_bf16 v[100:103], v[128:131], v[192:195], v[100:103]
	v_mfma_f32_16x16x32_bf16 v[96:99], v[136:139], v[192:195], v[96:99]
	v_mfma_f32_16x16x32_bf16 v[84:87], v[128:131], v[200:203], v[84:87]
	v_mfma_f32_16x16x32_bf16 v[80:83], v[136:139], v[200:203], v[80:83]
	v_mfma_f32_16x16x32_bf16 v[68:71], v[128:131], v[208:211], v[68:71]
	v_mfma_f32_16x16x32_bf16 v[64:67], v[136:139], v[208:211], v[64:67]
	v_mfma_f32_16x16x32_bf16 v[148:151], v[132:135], v[188:191], v[148:151]
	v_mfma_f32_16x16x32_bf16 v[144:147], v[140:143], v[188:191], v[144:147]
	v_mfma_f32_16x16x32_bf16 v[100:103], v[132:135], v[196:199], v[100:103]
	v_mfma_f32_16x16x32_bf16 v[96:99], v[140:143], v[196:199], v[96:99]
	v_mfma_f32_16x16x32_bf16 v[84:87], v[132:135], v[204:207], v[84:87]
	v_mfma_f32_16x16x32_bf16 v[80:83], v[140:143], v[204:207], v[80:83]
	v_mfma_f32_16x16x32_bf16 v[68:71], v[132:135], v[212:215], v[68:71]
	v_mfma_f32_16x16x32_bf16 v[64:67], v[140:143], v[212:215], v[64:67]
	s_barrier
; #define PG8_STAGE(bufoff, gbase, voff) do { _Pragma("unroll") for (int _i = 0; _i < 2; ++_i) \
;         __builtin_amdgcn_global_load_lds((const unsigned*)((const char*)(gbase) + (voff)[_i]), (LAS unsigned*)(lds + (bufoff) + ldsw + _i * 8192), 16, 0, 0); } while (0)
; #define PG8_LDA(dst, b, h) do { _Pragma("unroll") for (int m = 0; m < 4; ++m) _Pragma("unroll") for (int k = 0; k < 2; ++k) dst[m][k] = *(const LAS bf16x8*)(lds + PG8_SA(b, h) + aoff + m * 2048 + k * 1024); } while (0)
; #define PG8_MMA(ai, bj, At, Bt) do { __builtin_amdgcn_s_setprio(1); _Pragma("unroll") for (int m = 0; m < 4; ++m) _Pragma("unroll") for (int n = 0; n < 2; ++n) _Pragma("unroll") for (int k = 0; k < 2; ++k) \
;         acc[ai][bj][m][n] = __builtin_amdgcn_mfma_f32_16x16x32_bf16(Bt[n][k], At[m][k], acc[ai][bj][m][n], 0, 0, 0); __builtin_amdgcn_s_setprio(0); } while (0)
; #define PG8_WAIT_V(n) asm volatile("s_waitcnt vmcnt(" #n ")" ::: "memory")
; #define PG8_WAIT_L(n) asm volatile("s_waitcnt lgkmcnt(" #n ")" ::: "memory")
; #define PG8_BAR __builtin_amdgcn_s_barrier()
; #define PG8_SCHED __builtin_amdgcn_sched_barrier(0)
; template <class Epi, class Sched>
; DEVI void gemm_phase(LAS unsigned char* lds, const Gemm g, const Sched& S, const Epi& E) {
;     ...
;             PG8_LDA(At, 1, 1); PG8_STAGE(PG8_SB(1, 0), b3, voffB); PG8_STAGE(PG8_SB(1, 1), b3 + hstep, voffB); PG8_STAGE(PG8_SA(1, 0), a3, voffA);
;             PG8_WAIT_V(8); PG8_WAIT_L(0); PG8_BAR; PG8_MMA(1, 0, At, B0); PG8_MMA(1, 1, At, B1); PG8_BAR; PG8_SCHED;
;         }
;         if (wr == 0) PG8_BAR;
	s_add_i32 s34, s72, s40
	v_lshl_add_u64 v[180:181], v[180:181], 0, s[12:13]
	s_mov_b32 m0, s34
	ds_read_b128 v[176:179], v187 offset:49152
	ds_read_b128 v[188:191], v187 offset:50176
	ds_read_b128 v[192:195], v187 offset:51200
	ds_read_b128 v[196:199], v187 offset:52224
	ds_read_b128 v[200:203], v187 offset:53248
	ds_read_b128 v[204:207], v187 offset:54272
	ds_read_b128 v[208:211], v187 offset:55296
	ds_read_b128 v[212:215], v187 offset:56320
	global_load_lds_dwordx4 v[180:181], off
	s_add_i32 m0, s34, 0x2000
	s_add_u32 s30, s30, 0x40080
	v_lshl_add_u64 v[180:181], v[216:217], 0, s[12:13]
	s_addc_u32 s31, s31, 0
	s_add_i32 s34, s73, s40
	global_load_lds_dwordx4 v[180:181], off
	v_lshl_add_u64 v[180:181], s[30:31], 0, v[164:165]
	s_mov_b32 m0, s34
	s_nop 0
	global_load_lds_dwordx4 v[180:181], off
	v_lshl_add_u64 v[180:181], s[30:31], 0, v[160:161]
	s_add_i32 m0, s34, 0x2000
	s_nop 0
	global_load_lds_dwordx4 v[180:181], off
	v_lshl_add_u64 v[180:181], v[218:219], 0, s[12:13]
	s_mov_b32 m0, s51
	s_nop 0
	global_load_lds_dwordx4 v[180:181], off
	v_lshl_add_u64 v[180:181], v[220:221], 0, s[12:13]
	s_mov_b32 m0, s56
	s_nop 0
	global_load_lds_dwordx4 v[180:181], off
	s_waitcnt vmcnt(8)
	s_waitcnt lgkmcnt(0)
	s_barrier
	s_waitcnt lgkmcnt(0)
	v_mfma_f32_16x16x32_bf16 v[60:63], v[112:115], v[176:179], v[60:63]
	v_mfma_f32_16x16x32_bf16 v[56:59], v[120:123], v[176:179], v[56:59]
	v_mfma_f32_16x16x32_bf16 v[44:47], v[112:115], v[192:195], v[44:47]
	v_mfma_f32_16x16x32_bf16 v[40:43], v[120:123], v[192:195], v[40:43]
	v_mfma_f32_16x16x32_bf16 v[28:31], v[112:115], v[200:203], v[28:31]
	v_mfma_f32_16x16x32_bf16 v[24:27], v[120:123], v[200:203], v[24:27]
	v_mfma_f32_16x16x32_bf16 v[12:15], v[112:115], v[208:211], v[12:15]
	v_mfma_f32_16x16x32_bf16 v[8:11], v[120:123], v[208:211], v[8:11]
	v_mfma_f32_16x16x32_bf16 v[60:63], v[116:119], v[188:191], v[60:63]
	v_mfma_f32_16x16x32_bf16 v[56:59], v[124:127], v[188:191], v[56:59]
	v_mfma_f32_16x16x32_bf16 v[44:47], v[116:119], v[196:199], v[44:47]
	v_mfma_f32_16x16x32_bf16 v[40:43], v[124:127], v[196:199], v[40:43]
	v_mfma_f32_16x16x32_bf16 v[28:31], v[116:119], v[204:207], v[28:31]
	v_mfma_f32_16x16x32_bf16 v[24:27], v[124:127], v[204:207], v[24:27]
	v_mfma_f32_16x16x32_bf16 v[12:15], v[116:119], v[212:215], v[12:15]
	v_mfma_f32_16x16x32_bf16 v[8:11], v[124:127], v[212:215], v[8:11]
	v_mfma_f32_16x16x32_bf16 v[52:55], v[128:131], v[176:179], v[52:55]
	v_mfma_f32_16x16x32_bf16 v[48:51], v[136:139], v[176:179], v[48:51]
	v_mfma_f32_16x16x32_bf16 v[36:39], v[128:131], v[192:195], v[36:39]
	v_mfma_f32_16x16x32_bf16 v[32:35], v[136:139], v[192:195], v[32:35]
	v_mfma_f32_16x16x32_bf16 v[20:23], v[128:131], v[200:203], v[20:23]
	v_mfma_f32_16x16x32_bf16 v[16:19], v[136:139], v[200:203], v[16:19]
	v_mfma_f32_16x16x32_bf16 v[4:7], v[128:131], v[208:211], v[4:7]
	v_mfma_f32_16x16x32_bf16 v[0:3], v[136:139], v[208:211], v[0:3]
	v_mfma_f32_16x16x32_bf16 v[52:55], v[132:135], v[188:191], v[52:55]
	v_mfma_f32_16x16x32_bf16 v[48:51], v[140:143], v[188:191], v[48:51]
	v_mfma_f32_16x16x32_bf16 v[36:39], v[132:135], v[196:199], v[36:39]
	v_mfma_f32_16x16x32_bf16 v[32:35], v[140:143], v[196:199], v[32:35]
	v_mfma_f32_16x16x32_bf16 v[20:23], v[132:135], v[204:207], v[20:23]
	v_mfma_f32_16x16x32_bf16 v[16:19], v[140:143], v[204:207], v[16:19]
	v_mfma_f32_16x16x32_bf16 v[4:7], v[132:135], v[212:215], v[4:7]
	v_mfma_f32_16x16x32_bf16 v[0:3], v[140:143], v[212:215], v[0:3]
	s_barrier
	s_add_i32 s69, s69, 2
	s_add_u32 s65, s65, 0x100
	s_addc_u32 s68, s68, 0
	s_add_u32 s28, s28, 0x100
	s_addc_u32 s29, s29, 0
	s_cmp_gt_u32 s69, 13
	s_cbranch_scc0 .LBB0_965
	s_and_b64 vcc, exec, s[14:15]
	s_cbranch_vccz .LBB0_968
	s_barrier

;     DEVI bool next(int i, Unit& u) const {
;         const long L = (long)i * G + c; if (L >= nwg) return false;
;         int wgid = (int)L; { const int q = nwg / NXCD, r = nwg % NXCD, xcd = wgid % NXCD, off = wgid / NXCD; wgid = (xcd < r ? xcd * (q + 1) : r * (q + 1) + (xcd - r) * q) + off; }
;         const int nig = WGM * nN, gid = wgid / nig, fm = gid * WGM, gsz = (nM - fm) < WGM ? (nM - fm) : WGM;
;         u.pm = fm + ((wgid % nig) % gsz); u.pn = (wgid % nig) / gsz; return true;
.LBB0_1307:
	s_or_b64 exec, exec, s[0:1]
	s_mov_b64 s[2:3], s[96:97]
	s_mov_b32 s19, s89
	v_readlane_b32 s21, v249, 0
	s_waitcnt lgkmcnt(0)
	s_barrier
	v_readfirstlane_b32 s98, v242
	s_nop 3
	s_cmpk_lt_u32 s98, 0x100
	s_cbranch_scc1 .Lsprio_sp12
	s_setprio 1
.Lsprio_sp12:
	v_mov_b32_e32 v8, v242
	s_cmpk_lt_i32 s21, 0x200
	s_cselect_b64 s[0:1], -1, 0
	s_cmpk_gt_i32 s21, 0x1ff
	v_readfirstlane_b32 s16, v8
	s_cbranch_scc1 .LBB0_1313
	s_ashr_i32 s4, s21, 31
	s_lshr_b32 s4, s4, 29
	s_add_i32 s8, s21, s4
	s_and_b32 s4, s8, -8
	s_sub_i32 s6, s21, s4
	s_cmp_gt_i32 s6, -1
	s_cbranch_scc0 .LBB0_1310
	s_lshl_b32 s7, s6, 6
	s_ashr_i32 s4, s8, 3
	s_cbranch_execz .LBB0_1311
	s_branch .LBB0_1312

; #define PG8_STAGE(bufoff, gbase, voff) do { _Pragma("unroll") for (int _i = 0; _i < 2; ++_i) \
;         __builtin_amdgcn_global_load_lds((const unsigned*)((const char*)(gbase) + (voff)[_i]), (LAS unsigned*)(lds + (bufoff) + ldsw + _i * 8192), 16, 0, 0); } while (0)
; #define PG8_LDA(dst, b, h) do { _Pragma("unroll") for (int m = 0; m < 4; ++m) _Pragma("unroll") for (int k = 0; k < 2; ++k) dst[m][k] = *(const LAS bf16x8*)(lds + PG8_SA(b, h) + aoff + m * 2048 + k * 1024); } while (0)
; #define PG8_LDB(dst, b, h) do { _Pragma("unroll") for (int n = 0; n < 2; ++n) _Pragma("unroll") for (int k = 0; k < 2; ++k) dst[n][k] = *(const LAS bf16x8*)(lds + PG8_SB(b, h) + boff + n * 2048 + k * 1024); } while (0)
; #define PG8_MMA(ai, bj, At, Bt) do { __builtin_amdgcn_s_setprio(1); _Pragma("unroll") for (int m = 0; m < 4; ++m) _Pragma("unroll") for (int n = 0; n < 2; ++n) _Pragma("unroll") for (int k = 0; k < 2; ++k) \
;         acc[ai][bj][m][n] = __builtin_amdgcn_mfma_f32_16x16x32_bf16(Bt[n][k], At[m][k], acc[ai][bj][m][n], 0, 0, 0); __builtin_amdgcn_s_setprio(0); } while (0)
; #define PG8_WAIT_V(n) asm volatile("s_waitcnt vmcnt(" #n ")" ::: "memory")
; #define PG8_WAIT_L(n) asm volatile("s_waitcnt lgkmcnt(" #n ")" ::: "memory")
; #define PG8_BAR __builtin_amdgcn_s_barrier()
; #define PG8_SCHED __builtin_amdgcn_sched_barrier(0)
; template <class Epi, class Sched>
; DEVI void gemm_phase(LAS unsigned char* lds, const Gemm g, const Sched& S, const Epi& E) {
;     ...
;             PG8_LDB(B0, 0, 0); PG8_LDB(B1, 0, 1); PG8_SCHED; PG8_LDA(At, 0, 0); PG8_STAGE(PG8_SA(1, 1), a1 + hstep, voffA);
;             PG8_WAIT_V(8); PG8_WAIT_L(0); PG8_BAR; PG8_MMA(0, 0, At, B0); PG8_MMA(0, 1, At, B1); PG8_BAR; PG8_SCHED;
;             PG8_LDA(At, 0, 1); PG8_STAGE(PG8_SB(0, 0), b2, voffB); PG8_STAGE(PG8_SB(0, 1), b2 + hstep, voffB); PG8_STAGE(PG8_SA(0, 0), a2, voffA);
;             PG8_WAIT_V(8); PG8_WAIT_L(0); PG8_BAR; PG8_MMA(1, 0, At, B0); PG8_MMA(1, 1, At, B1); PG8_BAR; PG8_SCHED;
.LBB0_1326:
	ds_read_b128 v[144:147], v165
	ds_read_b128 v[148:151], v165 offset:1024
	ds_read_b128 v[152:155], v165 offset:2048
	ds_read_b128 v[156:159], v165 offset:3072
	ds_read_b128 v[170:173], v166
	ds_read_b128 v[174:177], v166 offset:1024
	ds_read_b128 v[178:181], v166 offset:2048
	ds_read_b128 v[182:185], v166 offset:3072
	s_add_u32 s38, s36, 0xfffc0080
	s_addc_u32 s39, s37, -1
	s_cmp_eq_u32 s72, 12
	s_cselect_b32 s41, s25, s39
	s_cselect_b32 s40, s31, s38
	s_cselect_b32 s39, s23, s69
	s_cselect_b32 s38, s65, s68
	v_lshl_add_u64 v[160:161], s[36:37], 0, v[138:139]
	s_add_i32 m0, s35, 0xc000
	ds_read_b128 v[186:189], v167
	ds_read_b128 v[190:193], v167 offset:1024
	ds_read_b128 v[194:197], v167 offset:2048
	ds_read_b128 v[198:201], v167 offset:3072
	ds_read_b128 v[202:205], v167 offset:4096
	ds_read_b128 v[206:209], v167 offset:5120
	ds_read_b128 v[210:213], v167 offset:6144
	ds_read_b128 v[214:217], v167 offset:7168
	global_load_lds_dwordx4 v[160:161], off
	v_lshl_add_u64 v[160:161], s[36:37], 0, v[136:137]
	s_add_i32 m0, s35, 0xe000
	s_nop 0
	global_load_lds_dwordx4 v[160:161], off
	s_waitcnt vmcnt(8)
	s_waitcnt lgkmcnt(0)
	s_barrier
	s_waitcnt lgkmcnt(0)
	v_mfma_f32_16x16x32_bf16 v[124:127], v[144:147], v[186:189], v[124:127]
	v_mfma_f32_16x16x32_bf16 v[120:123], v[152:155], v[186:189], v[120:123]
	v_mfma_f32_16x16x32_bf16 v[108:111], v[144:147], v[194:197], v[108:111]
	v_mfma_f32_16x16x32_bf16 v[104:107], v[152:155], v[194:197], v[104:107]
	v_mfma_f32_16x16x32_bf16 v[92:95], v[144:147], v[202:205], v[92:95]
	v_mfma_f32_16x16x32_bf16 v[88:91], v[152:155], v[202:205], v[88:91]
	v_mfma_f32_16x16x32_bf16 v[76:79], v[144:147], v[210:213], v[76:79]
	v_mfma_f32_16x16x32_bf16 v[72:75], v[152:155], v[210:213], v[72:75]
	v_mfma_f32_16x16x32_bf16 v[124:127], v[148:151], v[190:193], v[124:127]
	v_mfma_f32_16x16x32_bf16 v[120:123], v[156:159], v[190:193], v[120:123]
	v_mfma_f32_16x16x32_bf16 v[108:111], v[148:151], v[198:201], v[108:111]
	v_mfma_f32_16x16x32_bf16 v[104:107], v[156:159], v[198:201], v[104:107]
	v_mfma_f32_16x16x32_bf16 v[92:95], v[148:151], v[206:209], v[92:95]
	v_mfma_f32_16x16x32_bf16 v[88:91], v[156:159], v[206:209], v[88:91]
	v_mfma_f32_16x16x32_bf16 v[76:79], v[148:151], v[214:217], v[76:79]
	v_mfma_f32_16x16x32_bf16 v[72:75], v[156:159], v[214:217], v[72:75]
	v_mfma_f32_16x16x32_bf16 v[116:119], v[170:173], v[186:189], v[116:119]
	v_mfma_f32_16x16x32_bf16 v[112:115], v[178:181], v[186:189], v[112:115]
	v_mfma_f32_16x16x32_bf16 v[100:103], v[170:173], v[194:197], v[100:103]
	v_mfma_f32_16x16x32_bf16 v[96:99], v[178:181], v[194:197], v[96:99]
	v_mfma_f32_16x16x32_bf16 v[84:87], v[170:173], v[202:205], v[84:87]
	v_mfma_f32_16x16x32_bf16 v[80:83], v[178:181], v[202:205], v[80:83]
	v_mfma_f32_16x16x32_bf16 v[68:71], v[170:173], v[210:213], v[68:71]
	v_mfma_f32_16x16x32_bf16 v[64:67], v[178:181], v[210:213], v[64:67]
	v_mfma_f32_16x16x32_bf16 v[116:119], v[174:177], v[190:193], v[116:119]
	v_mfma_f32_16x16x32_bf16 v[112:115], v[182:185], v[190:193], v[112:115]
	v_mfma_f32_16x16x32_bf16 v[100:103], v[174:177], v[198:201], v[100:103]
	v_mfma_f32_16x16x32_bf16 v[96:99], v[182:185], v[198:201], v[96:99]
	v_mfma_f32_16x16x32_bf16 v[84:87], v[174:177], v[206:209], v[84:87]
	v_mfma_f32_16x16x32_bf16 v[80:83], v[182:185], v[206:209], v[80:83]
	v_mfma_f32_16x16x32_bf16 v[68:71], v[174:177], v[214:217], v[68:71]
	v_mfma_f32_16x16x32_bf16 v[64:67], v[182:185], v[214:217], v[64:67]
	s_barrier
	s_add_i32 s73, s62, s49
	v_lshl_add_u64 v[160:161], s[38:39], 0, v[130:131]
	s_mov_b32 m0, s73
	ds_read_b128 v[186:189], v167 offset:16384
	ds_read_b128 v[190:193], v167 offset:17408
	ds_read_b128 v[194:197], v167 offset:18432
	ds_read_b128 v[198:201], v167 offset:19456
	ds_read_b128 v[202:205], v167 offset:20480
	ds_read_b128 v[206:209], v167 offset:21504
	ds_read_b128 v[210:213], v167 offset:22528
	ds_read_b128 v[214:217], v167 offset:23552
	global_load_lds_dwordx4 v[160:161], off
	s_add_i32 m0, s73, 0x2000
	s_add_u32 s76, s38, 0x40000
	v_lshl_add_u64 v[218:219], s[38:39], 0, v[134:135]
	s_addc_u32 s77, s39, 0
	s_add_i32 s73, s63, s49
	global_load_lds_dwordx4 v[218:219], off
	v_lshl_add_u64 v[220:221], s[76:77], 0, v[130:131]
	s_mov_b32 m0, s73
	v_lshl_add_u64 v[222:223], s[40:41], 0, v[132:133]
	global_load_lds_dwordx4 v[220:221], off
	v_lshl_add_u64 v[220:221], s[76:77], 0, v[134:135]
	s_add_i32 m0, s73, 0x2000
	s_nop 0
	global_load_lds_dwordx4 v[220:221], off
	v_lshl_add_u64 v[220:221], s[40:41], 0, v[128:129]
	s_mov_b32 m0, s35
	s_nop 0
	global_load_lds_dwordx4 v[220:221], off
	s_mov_b32 m0, s50
	s_nop 0
	global_load_lds_dwordx4 v[222:223], off
	s_waitcnt vmcnt(8)
	s_waitcnt lgkmcnt(0)
	s_barrier
; #define PG8_STAGE(bufoff, gbase, voff) do { _Pragma("unroll") for (int _i = 0; _i < 2; ++_i) \
;         __builtin_amdgcn_global_load_lds((const unsigned*)((const char*)(gbase) + (voff)[_i]), (LAS unsigned*)(lds + (bufoff) + ldsw + _i * 8192), 16, 0, 0); } while (0)
; #define PG8_LDA(dst, b, h) do { _Pragma("unroll") for (int m = 0; m < 4; ++m) _Pragma("unroll") for (int k = 0; k < 2; ++k) dst[m][k] = *(const LAS bf16x8*)(lds + PG8_SA(b, h) + aoff + m * 2048 + k * 1024); } while (0)
; #define PG8_LDB(dst, b, h) do { _Pragma("unroll") for (int n = 0; n < 2; ++n) _Pragma("unroll") for (int k = 0; k < 2; ++k) dst[n][k] = *(const LAS bf16x8*)(lds + PG8_SB(b, h) + boff + n * 2048 + k * 1024); } while (0)
; #define PG8_MMA(ai, bj, At, Bt) do { __builtin_amdgcn_s_setprio(1); _Pragma("unroll") for (int m = 0; m < 4; ++m) _Pragma("unroll") for (int n = 0; n < 2; ++n) _Pragma("unroll") for (int k = 0; k < 2; ++k) \
;         acc[ai][bj][m][n] = __builtin_amdgcn_mfma_f32_16x16x32_bf16(Bt[n][k], At[m][k], acc[ai][bj][m][n], 0, 0, 0); __builtin_amdgcn_s_setprio(0); } while (0)
; #define PG8_WAIT_V(n) asm volatile("s_waitcnt vmcnt(" #n ")" ::: "memory")
; #define PG8_WAIT_L(n) asm volatile("s_waitcnt lgkmcnt(" #n ")" ::: "memory")
; #define PG8_BAR __builtin_amdgcn_s_barrier()
; #define PG8_SCHED __builtin_amdgcn_sched_barrier(0)
; template <class Epi, class Sched>
; DEVI void gemm_phase(LAS unsigned char* lds, const Gemm g, const Sched& S, const Epi& E) {
;     ...
;             PG8_WAIT_V(8); PG8_WAIT_L(0); PG8_BAR; PG8_MMA(1, 0, At, B0); PG8_MMA(1, 1, At, B1); PG8_BAR; PG8_SCHED;
;             PG8_LDB(B0, 1, 0); PG8_LDB(B1, 1, 1); PG8_SCHED; PG8_LDA(At, 1, 0); PG8_STAGE(PG8_SA(0, 1), a2 + hstep, voffA);
;             PG8_WAIT_V(8); PG8_WAIT_L(0); PG8_BAR; PG8_MMA(0, 0, At, B0); PG8_MMA(0, 1, At, B1); PG8_BAR; PG8_SCHED;
	s_waitcnt lgkmcnt(0)
	v_mfma_f32_16x16x32_bf16 v[60:63], v[144:147], v[186:189], v[60:63]
	v_mfma_f32_16x16x32_bf16 v[56:59], v[152:155], v[186:189], v[56:59]
	v_mfma_f32_16x16x32_bf16 v[44:47], v[144:147], v[194:197], v[44:47]
	v_mfma_f32_16x16x32_bf16 v[40:43], v[152:155], v[194:197], v[40:43]
	v_mfma_f32_16x16x32_bf16 v[28:31], v[144:147], v[202:205], v[28:31]
	v_mfma_f32_16x16x32_bf16 v[24:27], v[152:155], v[202:205], v[24:27]
	v_mfma_f32_16x16x32_bf16 v[12:15], v[144:147], v[210:213], v[12:15]
	v_mfma_f32_16x16x32_bf16 v[8:11], v[152:155], v[210:213], v[8:11]
	v_mfma_f32_16x16x32_bf16 v[60:63], v[148:151], v[190:193], v[60:63]
	v_mfma_f32_16x16x32_bf16 v[56:59], v[156:159], v[190:193], v[56:59]
	v_mfma_f32_16x16x32_bf16 v[44:47], v[148:151], v[198:201], v[44:47]
	v_mfma_f32_16x16x32_bf16 v[40:43], v[156:159], v[198:201], v[40:43]
	v_mfma_f32_16x16x32_bf16 v[28:31], v[148:151], v[206:209], v[28:31]
	v_mfma_f32_16x16x32_bf16 v[24:27], v[156:159], v[206:209], v[24:27]
	v_mfma_f32_16x16x32_bf16 v[12:15], v[148:151], v[214:217], v[12:15]
	v_mfma_f32_16x16x32_bf16 v[8:11], v[156:159], v[214:217], v[8:11]
	v_mfma_f32_16x16x32_bf16 v[52:55], v[170:173], v[186:189], v[52:55]
	v_mfma_f32_16x16x32_bf16 v[48:51], v[178:181], v[186:189], v[48:51]
	v_mfma_f32_16x16x32_bf16 v[36:39], v[170:173], v[194:197], v[36:39]
	v_mfma_f32_16x16x32_bf16 v[32:35], v[178:181], v[194:197], v[32:35]
	v_mfma_f32_16x16x32_bf16 v[20:23], v[170:173], v[202:205], v[20:23]
	v_mfma_f32_16x16x32_bf16 v[16:19], v[178:181], v[202:205], v[16:19]
	v_mfma_f32_16x16x32_bf16 v[4:7], v[170:173], v[210:213], v[4:7]
	v_mfma_f32_16x16x32_bf16 v[0:3], v[178:181], v[210:213], v[0:3]
	v_mfma_f32_16x16x32_bf16 v[52:55], v[174:177], v[190:193], v[52:55]
	v_mfma_f32_16x16x32_bf16 v[48:51], v[182:185], v[190:193], v[48:51]
	v_mfma_f32_16x16x32_bf16 v[36:39], v[174:177], v[198:201], v[36:39]
	v_mfma_f32_16x16x32_bf16 v[32:35], v[182:185], v[198:201], v[32:35]
	v_mfma_f32_16x16x32_bf16 v[20:23], v[174:177], v[206:209], v[20:23]
	v_mfma_f32_16x16x32_bf16 v[16:19], v[182:185], v[206:209], v[16:19]
	v_mfma_f32_16x16x32_bf16 v[4:7], v[174:177], v[214:217], v[4:7]
	v_mfma_f32_16x16x32_bf16 v[0:3], v[182:185], v[214:217], v[0:3]
	s_barrier
	s_add_i32 s73, 0, 0x18000
	s_add_i32 s76, 0, 0x1c000
	v_add_u32_e32 v156, s73, v163
	v_add_u32_e32 v169, s76, v163
	ds_read_b128 v[144:147], v156
	ds_read_b128 v[148:151], v156 offset:1024
	ds_read_b128 v[152:155], v156 offset:2048
	ds_read_b128 v[156:159], v156 offset:3072
	ds_read_b128 v[170:173], v169
	ds_read_b128 v[174:177], v169 offset:1024
	ds_read_b128 v[178:181], v169 offset:2048
	ds_read_b128 v[182:185], v169 offset:3072
	s_add_u32 s40, s40, 0x40000
	s_addc_u32 s41, s41, 0
	s_mov_b32 m0, s51
	v_lshl_add_u64 v[224:225], s[40:41], 0, v[128:129]
	ds_read_b128 v[186:189], v167 offset:32768
	ds_read_b128 v[190:193], v167 offset:33792
	ds_read_b128 v[194:197], v167 offset:34816
	ds_read_b128 v[198:201], v167 offset:35840
	ds_read_b128 v[202:205], v167 offset:36864
	ds_read_b128 v[206:209], v167 offset:37888
	ds_read_b128 v[210:213], v167 offset:38912
	ds_read_b128 v[214:217], v167 offset:39936
	global_load_lds_dwordx4 v[224:225], off
	v_lshl_add_u64 v[224:225], s[40:41], 0, v[132:133]
	s_mov_b32 m0, s56
	s_nop 0
	global_load_lds_dwordx4 v[224:225], off
	s_waitcnt vmcnt(8)
	s_waitcnt lgkmcnt(0)
	s_barrier
	s_waitcnt lgkmcnt(0)
	v_mfma_f32_16x16x32_bf16 v[124:127], v[144:147], v[186:189], v[124:127]
	v_mfma_f32_16x16x32_bf16 v[120:123], v[152:155], v[186:189], v[120:123]
	v_mfma_f32_16x16x32_bf16 v[108:111], v[144:147], v[194:197], v[108:111]
	v_mfma_f32_16x16x32_bf16 v[104:107], v[152:155], v[194:197], v[104:107]
	v_mfma_f32_16x16x32_bf16 v[92:95], v[144:147], v[202:205], v[92:95]
	v_mfma_f32_16x16x32_bf16 v[88:91], v[152:155], v[202:205], v[88:91]
	v_mfma_f32_16x16x32_bf16 v[76:79], v[144:147], v[210:213], v[76:79]
	v_mfma_f32_16x16x32_bf16 v[72:75], v[152:155], v[210:213], v[72:75]
	v_mfma_f32_16x16x32_bf16 v[124:127], v[148:151], v[190:193], v[124:127]
	v_mfma_f32_16x16x32_bf16 v[120:123], v[156:159], v[190:193], v[120:123]
	v_mfma_f32_16x16x32_bf16 v[108:111], v[148:151], v[198:201], v[108:111]
	v_mfma_f32_16x16x32_bf16 v[104:107], v[156:159], v[198:201], v[104:107]
	v_mfma_f32_16x16x32_bf16 v[92:95], v[148:151], v[206:209], v[92:95]
	v_mfma_f32_16x16x32_bf16 v[88:91], v[156:159], v[206:209], v[88:91]
	v_mfma_f32_16x16x32_bf16 v[76:79], v[148:151], v[214:217], v[76:79]
	v_mfma_f32_16x16x32_bf16 v[72:75], v[156:159], v[214:217], v[72:75]
	v_mfma_f32_16x16x32_bf16 v[116:119], v[170:173], v[186:189], v[116:119]
	v_mfma_f32_16x16x32_bf16 v[112:115], v[178:181], v[186:189], v[112:115]
	v_mfma_f32_16x16x32_bf16 v[100:103], v[170:173], v[194:197], v[100:103]
	v_mfma_f32_16x16x32_bf16 v[96:99], v[178:181], v[194:197], v[96:99]
	v_mfma_f32_16x16x32_bf16 v[84:87], v[170:173], v[202:205], v[84:87]
	v_mfma_f32_16x16x32_bf16 v[80:83], v[178:181], v[202:205], v[80:83]
	v_mfma_f32_16x16x32_bf16 v[68:71], v[170:173], v[210:213], v[68:71]
	v_mfma_f32_16x16x32_bf16 v[64:67], v[178:181], v[210:213], v[64:67]
	v_mfma_f32_16x16x32_bf16 v[116:119], v[174:177], v[190:193], v[116:119]
	v_mfma_f32_16x16x32_bf16 v[112:115], v[182:185], v[190:193], v[112:115]
	v_mfma_f32_16x16x32_bf16 v[100:103], v[174:177], v[198:201], v[100:103]
	v_mfma_f32_16x16x32_bf16 v[96:99], v[182:185], v[198:201], v[96:99]
	v_mfma_f32_16x16x32_bf16 v[84:87], v[174:177], v[206:209], v[84:87]
	v_mfma_f32_16x16x32_bf16 v[80:83], v[182:185], v[206:209], v[80:83]
	v_mfma_f32_16x16x32_bf16 v[68:71], v[174:177], v[214:217], v[68:71]
	v_mfma_f32_16x16x32_bf16 v[64:67], v[182:185], v[214:217], v[64:67]
	s_barrier
; #define PG8_STAGE(bufoff, gbase, voff) do { _Pragma("unroll") for (int _i = 0; _i < 2; ++_i) \
;         __builtin_amdgcn_global_load_lds((const unsigned*)((const char*)(gbase) + (voff)[_i]), (LAS unsigned*)(lds + (bufoff) + ldsw + _i * 8192), 16, 0, 0); } while (0)
; #define PG8_LDA(dst, b, h) do { _Pragma("unroll") for (int m = 0; m < 4; ++m) _Pragma("unroll") for (int k = 0; k < 2; ++k) dst[m][k] = *(const LAS bf16x8*)(lds + PG8_SA(b, h) + aoff + m * 2048 + k * 1024); } while (0)
; #define PG8_MMA(ai, bj, At, Bt) do { __builtin_amdgcn_s_setprio(1); _Pragma("unroll") for (int m = 0; m < 4; ++m) _Pragma("unroll") for (int n = 0; n < 2; ++n) _Pragma("unroll") for (int k = 0; k < 2; ++k) \
;         acc[ai][bj][m][n] = __builtin_amdgcn_mfma_f32_16x16x32_bf16(Bt[n][k], At[m][k], acc[ai][bj][m][n], 0, 0, 0); __builtin_amdgcn_s_setprio(0); } while (0)
; #define PG8_WAIT_V(n) asm volatile("s_waitcnt vmcnt(" #n ")" ::: "memory")
; #define PG8_WAIT_L(n) asm volatile("s_waitcnt lgkmcnt(" #n ")" ::: "memory")
; #define PG8_BAR __builtin_amdgcn_s_barrier()
; #define PG8_SCHED __builtin_amdgcn_sched_barrier(0)
; template <class Epi, class Sched>
; DEVI void gemm_phase(LAS unsigned char* lds, const Gemm g, const Sched& S, const Epi& E) {
;     ...
;             PG8_LDA(At, 1, 1); PG8_STAGE(PG8_SB(1, 0), b3, voffB); PG8_STAGE(PG8_SB(1, 1), b3 + hstep, voffB); PG8_STAGE(PG8_SA(1, 0), a3, voffA);
;             PG8_WAIT_V(8); PG8_WAIT_L(0); PG8_BAR; PG8_MMA(1, 0, At, B0); PG8_MMA(1, 1, At, B1); PG8_BAR; PG8_SCHED;
;         }
;         if (wr == 0) PG8_BAR;
	s_add_i32 s40, s73, s49
	v_lshl_add_u64 v[160:161], v[160:161], 0, s[14:15]
	s_mov_b32 m0, s40
	ds_read_b128 v[186:189], v167 offset:49152
	ds_read_b128 v[190:193], v167 offset:50176
	ds_read_b128 v[194:197], v167 offset:51200
	ds_read_b128 v[198:201], v167 offset:52224
	ds_read_b128 v[202:205], v167 offset:53248
	ds_read_b128 v[206:209], v167 offset:54272
	ds_read_b128 v[210:213], v167 offset:55296
	ds_read_b128 v[214:217], v167 offset:56320
	global_load_lds_dwordx4 v[160:161], off
	s_add_i32 m0, s40, 0x2000
	s_add_u32 s38, s38, 0x40080
	v_lshl_add_u64 v[160:161], v[218:219], 0, s[14:15]
	s_addc_u32 s39, s39, 0
	s_add_i32 s40, s76, s49
	global_load_lds_dwordx4 v[160:161], off
	v_lshl_add_u64 v[160:161], s[38:39], 0, v[130:131]
	s_mov_b32 m0, s40
	s_nop 0
	global_load_lds_dwordx4 v[160:161], off
	v_lshl_add_u64 v[160:161], s[38:39], 0, v[134:135]
	s_add_i32 m0, s40, 0x2000
	s_nop 0
	global_load_lds_dwordx4 v[160:161], off
	v_lshl_add_u64 v[160:161], v[220:221], 0, s[14:15]
	s_mov_b32 m0, s58
	s_nop 0
	global_load_lds_dwordx4 v[160:161], off
	v_lshl_add_u64 v[160:161], v[222:223], 0, s[14:15]
	s_mov_b32 m0, s59
	s_nop 0
	global_load_lds_dwordx4 v[160:161], off
	s_waitcnt vmcnt(8)
	s_waitcnt lgkmcnt(0)
	s_barrier
	s_waitcnt lgkmcnt(0)
	v_mfma_f32_16x16x32_bf16 v[60:63], v[144:147], v[186:189], v[60:63]
	v_mfma_f32_16x16x32_bf16 v[56:59], v[152:155], v[186:189], v[56:59]
	v_mfma_f32_16x16x32_bf16 v[44:47], v[144:147], v[194:197], v[44:47]
	v_mfma_f32_16x16x32_bf16 v[40:43], v[152:155], v[194:197], v[40:43]
	v_mfma_f32_16x16x32_bf16 v[28:31], v[144:147], v[202:205], v[28:31]
	v_mfma_f32_16x16x32_bf16 v[24:27], v[152:155], v[202:205], v[24:27]
	v_mfma_f32_16x16x32_bf16 v[12:15], v[144:147], v[210:213], v[12:15]
	v_mfma_f32_16x16x32_bf16 v[8:11], v[152:155], v[210:213], v[8:11]
	v_mfma_f32_16x16x32_bf16 v[60:63], v[148:151], v[190:193], v[60:63]
	v_mfma_f32_16x16x32_bf16 v[56:59], v[156:159], v[190:193], v[56:59]
	v_mfma_f32_16x16x32_bf16 v[44:47], v[148:151], v[198:201], v[44:47]
	v_mfma_f32_16x16x32_bf16 v[40:43], v[156:159], v[198:201], v[40:43]
	v_mfma_f32_16x16x32_bf16 v[28:31], v[148:151], v[206:209], v[28:31]
	v_mfma_f32_16x16x32_bf16 v[24:27], v[156:159], v[206:209], v[24:27]
	v_mfma_f32_16x16x32_bf16 v[12:15], v[148:151], v[214:217], v[12:15]
	v_mfma_f32_16x16x32_bf16 v[8:11], v[156:159], v[214:217], v[8:11]
	v_mfma_f32_16x16x32_bf16 v[52:55], v[170:173], v[186:189], v[52:55]
	v_mfma_f32_16x16x32_bf16 v[48:51], v[178:181], v[186:189], v[48:51]
	v_mfma_f32_16x16x32_bf16 v[36:39], v[170:173], v[194:197], v[36:39]
	v_mfma_f32_16x16x32_bf16 v[32:35], v[178:181], v[194:197], v[32:35]
	v_mfma_f32_16x16x32_bf16 v[20:23], v[170:173], v[202:205], v[20:23]
	v_mfma_f32_16x16x32_bf16 v[16:19], v[178:181], v[202:205], v[16:19]
	v_mfma_f32_16x16x32_bf16 v[4:7], v[170:173], v[210:213], v[4:7]
	v_mfma_f32_16x16x32_bf16 v[0:3], v[178:181], v[210:213], v[0:3]
	v_mfma_f32_16x16x32_bf16 v[52:55], v[174:177], v[190:193], v[52:55]
	v_mfma_f32_16x16x32_bf16 v[48:51], v[182:185], v[190:193], v[48:51]
	v_mfma_f32_16x16x32_bf16 v[36:39], v[174:177], v[198:201], v[36:39]
	v_mfma_f32_16x16x32_bf16 v[32:35], v[182:185], v[198:201], v[32:35]
	v_mfma_f32_16x16x32_bf16 v[20:23], v[174:177], v[206:209], v[20:23]
	v_mfma_f32_16x16x32_bf16 v[16:19], v[182:185], v[206:209], v[16:19]
	v_mfma_f32_16x16x32_bf16 v[4:7], v[174:177], v[214:217], v[4:7]
	v_mfma_f32_16x16x32_bf16 v[0:3], v[182:185], v[214:217], v[0:3]
	s_barrier
	s_add_i32 s72, s72, 2
	s_add_u32 s68, s68, 0x100
	s_addc_u32 s69, s69, 0
	s_add_u32 s36, s36, 0x100
	s_addc_u32 s37, s37, 0
	s_cmp_gt_u32 s72, 13
	s_cbranch_scc0 .LBB0_1326
	s_and_b64 vcc, exec, s[16:17]
	s_cbranch_vccz .LBB0_1329
	s_barrier

; DEVI int bid_() { int t = blockIdx.x; asm volatile("" : "+s"(t)); return t; }
; DEVI int gdim_() { int t = gridDim.x; asm volatile("" : "+s"(t)); return t; }
;     DEVI bool next(int i, Unit& u) const {
;         const long L = (long)i * G + c; if (L >= nwg) return false;
;         int wgid = (int)L; { const int q = nwg / NXCD, r = nwg % NXCD, xcd = wgid % NXCD, off = wgid / NXCD; wgid = (xcd < r ? xcd * (q + 1) : r * (q + 1) + (xcd - r) * q) + off; }
;         const int nig = WGM * nN, gid = wgid / nig, fm = gid * WGM, gsz = (nM - fm) < WGM ? (nM - fm) : WGM;
;         u.pm = fm + ((wgid % nig) % gsz); u.pn = (wgid % nig) / gsz; return true;
; template <int PH>
; DEVI void run_phase(const Params& p, unsigned char* smem) {
;     ...
;             pg8::Gemm g{(const bf16_t*)(ws + WS_ZB), wbase + (size_t)5 * MiB / 2, MROWS, 2 * DFF, DM}; pg8::StaticOrder S; S.init(MROWS, 2 * DFF, gdim_(), bid_());
;             EpiFfn E{(bf16_t*)(ws + WS_H), stA, vec + 3072, vec + 3072 + 5632, p.in[28] + (size_t)l * 3 * DFF, p.in[29] + (size_t)l * DFF, (float*)(ws + WS_TAIL), (float*)(ws + WS_HPG), (float*)(ws + WS_HUP)};
;             pg8::gemm_phase<EpiFfn, pg8::StaticOrder>(lds, g, S, E);
.LBB0_1401:
	s_or_b64 exec, exec, s[0:1]
	v_readlane_b32 s39, v249, 0
	s_mov_b64 s[2:3], s[96:97]
	s_mov_b32 s33, s89
	s_mov_b32 s66, s39
	s_waitcnt lgkmcnt(0)
	s_barrier
	v_readfirstlane_b32 s98, v242
	s_nop 3
	s_cmpk_lt_u32 s98, 0x100
	s_cbranch_scc1 .Lsprio_sp13
	s_setprio 1
.Lsprio_sp13:
	v_mov_b32_e32 v12, v242
	s_cmpk_lt_i32 s66, 0xb00
	s_cselect_b64 s[4:5], -1, 0
	s_cmpk_gt_i32 s66, 0xaff
	v_readfirstlane_b32 s6, v12
	s_cbranch_scc1 .LBB0_1403
	s_ashr_i32 s0, s66, 31
	s_lshr_b32 s0, s0, 29
	s_add_i32 s0, s66, s0
	s_ashr_i32 s1, s0, 3
	s_and_b32 s0, s0, -8
	s_sub_i32 s0, s66, s0
	s_cmp_lt_i32 s0, 0
	s_movk_i32 s7, 0x161
	s_cselect_b32 s7, s7, 0x160
	s_mul_i32 s0, s7, s0
	s_add_i32 s0, s0, s1
	s_mul_hi_i32 s1, s0, 0x2e8ba2e9
	s_lshr_b32 s7, s1, 31
	s_ashr_i32 s1, s1, 5
	s_add_i32 s1, s1, s7
	s_lshl_b32 s7, s1, 3
	s_mulk_i32 s1, 0xb0
	s_sub_i32 s0, s0, s1
	s_bfe_u32 s1, s0, 0x3001c
	s_add_i32 s1, s0, s1
	s_sext_i32_i16 s8, s1
	s_and_b32 s1, s1, 0xfff8
	s_sub_i32 s0, s0, s1
	s_sext_i32_i16 s0, s0
	s_add_i32 s72, s7, s0
	s_ashr_i32 s68, s8, 3

; #define PG8_STAGE(bufoff, gbase, voff) do { _Pragma("unroll") for (int _i = 0; _i < 2; ++_i) \
;         __builtin_amdgcn_global_load_lds((const unsigned*)((const char*)(gbase) + (voff)[_i]), (LAS unsigned*)(lds + (bufoff) + ldsw + _i * 8192), 16, 0, 0); } while (0)
; #define PG8_LDA(dst, b, h) do { _Pragma("unroll") for (int m = 0; m < 4; ++m) _Pragma("unroll") for (int k = 0; k < 2; ++k) dst[m][k] = *(const LAS bf16x8*)(lds + PG8_SA(b, h) + aoff + m * 2048 + k * 1024); } while (0)
; #define PG8_LDB(dst, b, h) do { _Pragma("unroll") for (int n = 0; n < 2; ++n) _Pragma("unroll") for (int k = 0; k < 2; ++k) dst[n][k] = *(const LAS bf16x8*)(lds + PG8_SB(b, h) + boff + n * 2048 + k * 1024); } while (0)
; #define PG8_MMA(ai, bj, At, Bt) do { __builtin_amdgcn_s_setprio(1); _Pragma("unroll") for (int m = 0; m < 4; ++m) _Pragma("unroll") for (int n = 0; n < 2; ++n) _Pragma("unroll") for (int k = 0; k < 2; ++k) \
;         acc[ai][bj][m][n] = __builtin_amdgcn_mfma_f32_16x16x32_bf16(Bt[n][k], At[m][k], acc[ai][bj][m][n], 0, 0, 0); __builtin_amdgcn_s_setprio(0); } while (0)
; #define PG8_WAIT_V(n) asm volatile("s_waitcnt vmcnt(" #n ")" ::: "memory")
; #define PG8_WAIT_L(n) asm volatile("s_waitcnt lgkmcnt(" #n ")" ::: "memory")
; #define PG8_BAR __builtin_amdgcn_s_barrier()
; #define PG8_SCHED __builtin_amdgcn_sched_barrier(0)
; template <class Epi, class Sched>
; DEVI void gemm_phase(LAS unsigned char* lds, const Gemm g, const Sched& S, const Epi& E) {
;     ...
;         for (int t = 0; t < nt; t += 2) {
;             const bool last = (t == nt - 2);
;             const char* a1 = cA + (size_t)(t + 1) * kstep;
;             const char* a2 = last ? nA : cA + (size_t)(t + 2) * kstep; const char* b2 = last ? nB : cB + (size_t)(t + 2) * kstep;
;             const char* a3 = a2 + kstep; const char* b3 = b2 + kstep;
;             if (last && has_next) S.a_ready(nxt);
;             PG8_LDB(B0, 0, 0); PG8_LDB(B1, 0, 1); PG8_SCHED; PG8_LDA(At, 0, 0); PG8_STAGE(PG8_SA(1, 1), a1 + hstep, voffA);
;             PG8_WAIT_V(8); PG8_WAIT_L(0); PG8_BAR; PG8_MMA(0, 0, At, B0); PG8_MMA(0, 1, At, B1); PG8_BAR; PG8_SCHED;
;             PG8_LDA(At, 0, 1); PG8_STAGE(PG8_SB(0, 0), b2, voffB); PG8_STAGE(PG8_SB(0, 1), b2 + hstep, voffB); PG8_STAGE(PG8_SA(0, 0), a2, voffA);
;             PG8_WAIT_V(8); PG8_WAIT_L(0); PG8_BAR; PG8_MMA(1, 0, At, B0); PG8_MMA(1, 1, At, B1); PG8_BAR; PG8_SCHED;
.LBB0_1412:
	ds_read_b128 v[96:99], v227
	ds_read_b128 v[100:103], v227 offset:1024
	ds_read_b128 v[104:107], v227 offset:2048
	ds_read_b128 v[108:111], v227 offset:3072
	ds_read_b128 v[112:115], v228
	ds_read_b128 v[116:119], v228 offset:1024
	ds_read_b128 v[120:123], v228 offset:2048
	ds_read_b128 v[124:127], v228 offset:3072
	s_add_u32 s30, s76, 0xfffc0080
	s_addc_u32 s31, s77, -1
	s_cmp_eq_u32 s80, 12
	s_cselect_b32 s51, s43, s31
	s_cselect_b32 s50, vcc_lo, s30
	s_cselect_b32 s49, s41, s85
	s_cselect_b32 s48, vcc_hi, s59
	v_lshl_add_u64 v[212:213], s[76:77], 0, v[178:179]
	s_add_i32 m0, s69, 0xc000
	ds_read_b128 v[160:163], v229
	ds_read_b128 v[184:187], v229 offset:1024
	ds_read_b128 v[188:191], v229 offset:2048
	ds_read_b128 v[192:195], v229 offset:3072
	ds_read_b128 v[196:199], v229 offset:4096
	ds_read_b128 v[200:203], v229 offset:5120
	ds_read_b128 v[204:207], v229 offset:6144
	ds_read_b128 v[208:211], v229 offset:7168
	global_load_lds_dwordx4 v[212:213], off
	v_lshl_add_u64 v[212:213], s[76:77], 0, v[176:177]
	s_add_i32 m0, s69, 0xe000
	s_nop 0
	global_load_lds_dwordx4 v[212:213], off
	s_waitcnt vmcnt(8)
	s_waitcnt lgkmcnt(0)
	s_barrier
	s_waitcnt lgkmcnt(0)
	v_mfma_f32_16x16x32_bf16 v[156:159], v[96:99], v[160:163], v[156:159]
	v_mfma_f32_16x16x32_bf16 v[60:63], v[104:107], v[160:163], v[60:63]
	v_mfma_f32_16x16x32_bf16 v[148:151], v[96:99], v[188:191], v[148:151]
	v_mfma_f32_16x16x32_bf16 v[52:55], v[104:107], v[188:191], v[52:55]
	v_mfma_f32_16x16x32_bf16 v[140:143], v[96:99], v[196:199], v[140:143]
	v_mfma_f32_16x16x32_bf16 v[44:47], v[104:107], v[196:199], v[44:47]
	v_mfma_f32_16x16x32_bf16 v[132:135], v[96:99], v[204:207], v[132:135]
	v_mfma_f32_16x16x32_bf16 v[36:39], v[104:107], v[204:207], v[36:39]
	v_mfma_f32_16x16x32_bf16 v[156:159], v[100:103], v[184:187], v[156:159]
	v_mfma_f32_16x16x32_bf16 v[60:63], v[108:111], v[184:187], v[60:63]
	v_mfma_f32_16x16x32_bf16 v[148:151], v[100:103], v[192:195], v[148:151]
	v_mfma_f32_16x16x32_bf16 v[52:55], v[108:111], v[192:195], v[52:55]
	v_mfma_f32_16x16x32_bf16 v[140:143], v[100:103], v[200:203], v[140:143]
	v_mfma_f32_16x16x32_bf16 v[44:47], v[108:111], v[200:203], v[44:47]
	v_mfma_f32_16x16x32_bf16 v[132:135], v[100:103], v[208:211], v[132:135]
	v_mfma_f32_16x16x32_bf16 v[36:39], v[108:111], v[208:211], v[36:39]
	v_mfma_f32_16x16x32_bf16 v[152:155], v[112:115], v[160:163], v[152:155]
	v_mfma_f32_16x16x32_bf16 v[56:59], v[120:123], v[160:163], v[56:59]
	v_mfma_f32_16x16x32_bf16 v[144:147], v[112:115], v[188:191], v[144:147]
	v_mfma_f32_16x16x32_bf16 v[48:51], v[120:123], v[188:191], v[48:51]
	v_mfma_f32_16x16x32_bf16 v[136:139], v[112:115], v[196:199], v[136:139]
	v_mfma_f32_16x16x32_bf16 v[40:43], v[120:123], v[196:199], v[40:43]
	v_mfma_f32_16x16x32_bf16 v[128:131], v[112:115], v[204:207], v[128:131]
	v_mfma_f32_16x16x32_bf16 v[32:35], v[120:123], v[204:207], v[32:35]
	v_mfma_f32_16x16x32_bf16 v[152:155], v[116:119], v[184:187], v[152:155]
	v_mfma_f32_16x16x32_bf16 v[56:59], v[124:127], v[184:187], v[56:59]
	v_mfma_f32_16x16x32_bf16 v[144:147], v[116:119], v[192:195], v[144:147]
	v_mfma_f32_16x16x32_bf16 v[48:51], v[124:127], v[192:195], v[48:51]
	v_mfma_f32_16x16x32_bf16 v[136:139], v[116:119], v[200:203], v[136:139]
	v_mfma_f32_16x16x32_bf16 v[40:43], v[124:127], v[200:203], v[40:43]
	v_mfma_f32_16x16x32_bf16 v[128:131], v[116:119], v[208:211], v[128:131]
	v_mfma_f32_16x16x32_bf16 v[32:35], v[124:127], v[208:211], v[32:35]
	s_barrier
	s_add_i32 s30, s10, s63
	v_lshl_add_u64 v[212:213], s[48:49], 0, v[166:167]
	s_mov_b32 m0, s30
	ds_read_b128 v[160:163], v229 offset:16384
	ds_read_b128 v[184:187], v229 offset:17408
	ds_read_b128 v[188:191], v229 offset:18432
	ds_read_b128 v[192:195], v229 offset:19456
	ds_read_b128 v[196:199], v229 offset:20480
	ds_read_b128 v[200:203], v229 offset:21504
	ds_read_b128 v[204:207], v229 offset:22528
	ds_read_b128 v[208:211], v229 offset:23552
	global_load_lds_dwordx4 v[212:213], off
	s_add_i32 m0, s30, 0x2000
	s_add_u32 s30, s48, 0x40000
	v_lshl_add_u64 v[214:215], s[48:49], 0, v[170:171]
	s_addc_u32 s31, s49, 0
	s_add_i32 s81, s11, s63
	global_load_lds_dwordx4 v[214:215], off
	v_lshl_add_u64 v[216:217], s[30:31], 0, v[166:167]
	s_mov_b32 m0, s81
	v_lshl_add_u64 v[218:219], s[50:51], 0, v[168:169]
	global_load_lds_dwordx4 v[216:217], off
	v_lshl_add_u64 v[216:217], s[30:31], 0, v[170:171]
	s_add_i32 m0, s81, 0x2000
	s_nop 0
	global_load_lds_dwordx4 v[216:217], off
	v_lshl_add_u64 v[216:217], s[50:51], 0, v[164:165]
	s_mov_b32 m0, s69
	s_nop 0
	global_load_lds_dwordx4 v[216:217], off
	s_mov_b32 m0, s73
	s_nop 0
	global_load_lds_dwordx4 v[218:219], off
	s_waitcnt vmcnt(8)
	s_waitcnt lgkmcnt(0)
	s_barrier
; #define PG8_STAGE(bufoff, gbase, voff) do { _Pragma("unroll") for (int _i = 0; _i < 2; ++_i) \
;         __builtin_amdgcn_global_load_lds((const unsigned*)((const char*)(gbase) + (voff)[_i]), (LAS unsigned*)(lds + (bufoff) + ldsw + _i * 8192), 16, 0, 0); } while (0)
; #define PG8_LDA(dst, b, h) do { _Pragma("unroll") for (int m = 0; m < 4; ++m) _Pragma("unroll") for (int k = 0; k < 2; ++k) dst[m][k] = *(const LAS bf16x8*)(lds + PG8_SA(b, h) + aoff + m * 2048 + k * 1024); } while (0)
; #define PG8_LDB(dst, b, h) do { _Pragma("unroll") for (int n = 0; n < 2; ++n) _Pragma("unroll") for (int k = 0; k < 2; ++k) dst[n][k] = *(const LAS bf16x8*)(lds + PG8_SB(b, h) + boff + n * 2048 + k * 1024); } while (0)
; #define PG8_MMA(ai, bj, At, Bt) do { __builtin_amdgcn_s_setprio(1); _Pragma("unroll") for (int m = 0; m < 4; ++m) _Pragma("unroll") for (int n = 0; n < 2; ++n) _Pragma("unroll") for (int k = 0; k < 2; ++k) \
;         acc[ai][bj][m][n] = __builtin_amdgcn_mfma_f32_16x16x32_bf16(Bt[n][k], At[m][k], acc[ai][bj][m][n], 0, 0, 0); __builtin_amdgcn_s_setprio(0); } while (0)
; #define PG8_WAIT_V(n) asm volatile("s_waitcnt vmcnt(" #n ")" ::: "memory")
; #define PG8_WAIT_L(n) asm volatile("s_waitcnt lgkmcnt(" #n ")" ::: "memory")
; #define PG8_BAR __builtin_amdgcn_s_barrier()
; #define PG8_SCHED __builtin_amdgcn_sched_barrier(0)
; template <class Epi, class Sched>
; DEVI void gemm_phase(LAS unsigned char* lds, const Gemm g, const Sched& S, const Epi& E) {
;     ...
;             PG8_WAIT_V(8); PG8_WAIT_L(0); PG8_BAR; PG8_MMA(1, 0, At, B0); PG8_MMA(1, 1, At, B1); PG8_BAR; PG8_SCHED;
;             PG8_LDB(B0, 1, 0); PG8_LDB(B1, 1, 1); PG8_SCHED; PG8_LDA(At, 1, 0); PG8_STAGE(PG8_SA(0, 1), a2 + hstep, voffA);
;             PG8_WAIT_V(8); PG8_WAIT_L(0); PG8_BAR; PG8_MMA(0, 0, At, B0); PG8_MMA(0, 1, At, B1); PG8_BAR; PG8_SCHED;
	s_waitcnt lgkmcnt(0)
	v_mfma_f32_16x16x32_bf16 v[92:95], v[96:99], v[160:163], v[92:95]
	v_mfma_f32_16x16x32_bf16 v[28:31], v[104:107], v[160:163], v[28:31]
	v_mfma_f32_16x16x32_bf16 v[84:87], v[96:99], v[188:191], v[84:87]
	v_mfma_f32_16x16x32_bf16 v[20:23], v[104:107], v[188:191], v[20:23]
	v_mfma_f32_16x16x32_bf16 v[76:79], v[96:99], v[196:199], v[76:79]
	v_mfma_f32_16x16x32_bf16 v[12:15], v[104:107], v[196:199], v[12:15]
	v_mfma_f32_16x16x32_bf16 v[68:71], v[96:99], v[204:207], v[68:71]
	v_mfma_f32_16x16x32_bf16 v[4:7], v[104:107], v[204:207], v[4:7]
	v_mfma_f32_16x16x32_bf16 v[92:95], v[100:103], v[184:187], v[92:95]
	v_mfma_f32_16x16x32_bf16 v[28:31], v[108:111], v[184:187], v[28:31]
	v_mfma_f32_16x16x32_bf16 v[84:87], v[100:103], v[192:195], v[84:87]
	v_mfma_f32_16x16x32_bf16 v[20:23], v[108:111], v[192:195], v[20:23]
	v_mfma_f32_16x16x32_bf16 v[76:79], v[100:103], v[200:203], v[76:79]
	v_mfma_f32_16x16x32_bf16 v[12:15], v[108:111], v[200:203], v[12:15]
	v_mfma_f32_16x16x32_bf16 v[68:71], v[100:103], v[208:211], v[68:71]
	v_mfma_f32_16x16x32_bf16 v[4:7], v[108:111], v[208:211], v[4:7]
	v_mfma_f32_16x16x32_bf16 v[88:91], v[112:115], v[160:163], v[88:91]
	v_mfma_f32_16x16x32_bf16 v[24:27], v[120:123], v[160:163], v[24:27]
	v_mfma_f32_16x16x32_bf16 v[80:83], v[112:115], v[188:191], v[80:83]
	v_mfma_f32_16x16x32_bf16 v[16:19], v[120:123], v[188:191], v[16:19]
	v_mfma_f32_16x16x32_bf16 v[72:75], v[112:115], v[196:199], v[72:75]
	v_mfma_f32_16x16x32_bf16 v[8:11], v[120:123], v[196:199], v[8:11]
	v_mfma_f32_16x16x32_bf16 v[64:67], v[112:115], v[204:207], v[64:67]
	v_mfma_f32_16x16x32_bf16 v[0:3], v[120:123], v[204:207], v[0:3]
	v_mfma_f32_16x16x32_bf16 v[88:91], v[116:119], v[184:187], v[88:91]
	v_mfma_f32_16x16x32_bf16 v[24:27], v[124:127], v[184:187], v[24:27]
	v_mfma_f32_16x16x32_bf16 v[80:83], v[116:119], v[192:195], v[80:83]
	v_mfma_f32_16x16x32_bf16 v[16:19], v[124:127], v[192:195], v[16:19]
	v_mfma_f32_16x16x32_bf16 v[72:75], v[116:119], v[200:203], v[72:75]
	v_mfma_f32_16x16x32_bf16 v[8:11], v[124:127], v[200:203], v[8:11]
	v_mfma_f32_16x16x32_bf16 v[64:67], v[116:119], v[208:211], v[64:67]
	v_mfma_f32_16x16x32_bf16 v[0:3], v[124:127], v[208:211], v[0:3]
	s_barrier
	s_add_i32 s81, 0, 0x18000
	s_add_i32 s56, 0, 0x1c000
	v_add_u32_e32 v108, s81, v173
	v_add_u32_e32 v124, s56, v173
	ds_read_b128 v[96:99], v108
	ds_read_b128 v[100:103], v108 offset:1024
	ds_read_b128 v[104:107], v108 offset:2048
	ds_read_b128 v[108:111], v108 offset:3072
	ds_read_b128 v[112:115], v124
	ds_read_b128 v[116:119], v124 offset:1024
	ds_read_b128 v[120:123], v124 offset:2048
	ds_read_b128 v[124:127], v124 offset:3072
	s_add_u32 s30, s50, 0x40000
	s_addc_u32 s31, s51, 0
	s_mov_b32 m0, s82
	v_lshl_add_u64 v[220:221], s[30:31], 0, v[164:165]
	ds_read_b128 v[160:163], v229 offset:32768
	ds_read_b128 v[184:187], v229 offset:33792
	ds_read_b128 v[188:191], v229 offset:34816
	ds_read_b128 v[192:195], v229 offset:35840
	ds_read_b128 v[196:199], v229 offset:36864
	ds_read_b128 v[200:203], v229 offset:37888
	ds_read_b128 v[204:207], v229 offset:38912
	ds_read_b128 v[208:211], v229 offset:39936
	global_load_lds_dwordx4 v[220:221], off
	v_lshl_add_u64 v[220:221], s[30:31], 0, v[168:169]
	s_mov_b32 m0, s83
	s_nop 0
	global_load_lds_dwordx4 v[220:221], off
	s_waitcnt vmcnt(8)
	s_waitcnt lgkmcnt(0)
	s_barrier
	s_waitcnt lgkmcnt(0)
	v_mfma_f32_16x16x32_bf16 v[156:159], v[96:99], v[160:163], v[156:159]
	v_mfma_f32_16x16x32_bf16 v[60:63], v[104:107], v[160:163], v[60:63]
	v_mfma_f32_16x16x32_bf16 v[148:151], v[96:99], v[188:191], v[148:151]
	v_mfma_f32_16x16x32_bf16 v[52:55], v[104:107], v[188:191], v[52:55]
	v_mfma_f32_16x16x32_bf16 v[140:143], v[96:99], v[196:199], v[140:143]
	v_mfma_f32_16x16x32_bf16 v[44:47], v[104:107], v[196:199], v[44:47]
	v_mfma_f32_16x16x32_bf16 v[132:135], v[96:99], v[204:207], v[132:135]
	v_mfma_f32_16x16x32_bf16 v[36:39], v[104:107], v[204:207], v[36:39]
	v_mfma_f32_16x16x32_bf16 v[156:159], v[100:103], v[184:187], v[156:159]
	v_mfma_f32_16x16x32_bf16 v[60:63], v[108:111], v[184:187], v[60:63]
	v_mfma_f32_16x16x32_bf16 v[148:151], v[100:103], v[192:195], v[148:151]
	v_mfma_f32_16x16x32_bf16 v[52:55], v[108:111], v[192:195], v[52:55]
	v_mfma_f32_16x16x32_bf16 v[140:143], v[100:103], v[200:203], v[140:143]
	v_mfma_f32_16x16x32_bf16 v[44:47], v[108:111], v[200:203], v[44:47]
	v_mfma_f32_16x16x32_bf16 v[132:135], v[100:103], v[208:211], v[132:135]
	v_mfma_f32_16x16x32_bf16 v[36:39], v[108:111], v[208:211], v[36:39]
	v_mfma_f32_16x16x32_bf16 v[152:155], v[112:115], v[160:163], v[152:155]
	v_mfma_f32_16x16x32_bf16 v[56:59], v[120:123], v[160:163], v[56:59]
	v_mfma_f32_16x16x32_bf16 v[144:147], v[112:115], v[188:191], v[144:147]
	v_mfma_f32_16x16x32_bf16 v[48:51], v[120:123], v[188:191], v[48:51]
	v_mfma_f32_16x16x32_bf16 v[136:139], v[112:115], v[196:199], v[136:139]
	v_mfma_f32_16x16x32_bf16 v[40:43], v[120:123], v[196:199], v[40:43]
	v_mfma_f32_16x16x32_bf16 v[128:131], v[112:115], v[204:207], v[128:131]
	v_mfma_f32_16x16x32_bf16 v[32:35], v[120:123], v[204:207], v[32:35]
	v_mfma_f32_16x16x32_bf16 v[152:155], v[116:119], v[184:187], v[152:155]
	v_mfma_f32_16x16x32_bf16 v[56:59], v[124:127], v[184:187], v[56:59]
	v_mfma_f32_16x16x32_bf16 v[144:147], v[116:119], v[192:195], v[144:147]
	v_mfma_f32_16x16x32_bf16 v[48:51], v[124:127], v[192:195], v[48:51]
	v_mfma_f32_16x16x32_bf16 v[136:139], v[116:119], v[200:203], v[136:139]
	v_mfma_f32_16x16x32_bf16 v[40:43], v[124:127], v[200:203], v[40:43]
	v_mfma_f32_16x16x32_bf16 v[128:131], v[116:119], v[208:211], v[128:131]
	v_mfma_f32_16x16x32_bf16 v[32:35], v[124:127], v[208:211], v[32:35]
	s_barrier
; #define PG8_STAGE(bufoff, gbase, voff) do { _Pragma("unroll") for (int _i = 0; _i < 2; ++_i) \
;         __builtin_amdgcn_global_load_lds((const unsigned*)((const char*)(gbase) + (voff)[_i]), (LAS unsigned*)(lds + (bufoff) + ldsw + _i * 8192), 16, 0, 0); } while (0)
; #define PG8_LDA(dst, b, h) do { _Pragma("unroll") for (int m = 0; m < 4; ++m) _Pragma("unroll") for (int k = 0; k < 2; ++k) dst[m][k] = *(const LAS bf16x8*)(lds + PG8_SA(b, h) + aoff + m * 2048 + k * 1024); } while (0)
; #define PG8_MMA(ai, bj, At, Bt) do { __builtin_amdgcn_s_setprio(1); _Pragma("unroll") for (int m = 0; m < 4; ++m) _Pragma("unroll") for (int n = 0; n < 2; ++n) _Pragma("unroll") for (int k = 0; k < 2; ++k) \
;         acc[ai][bj][m][n] = __builtin_amdgcn_mfma_f32_16x16x32_bf16(Bt[n][k], At[m][k], acc[ai][bj][m][n], 0, 0, 0); __builtin_amdgcn_s_setprio(0); } while (0)
; #define PG8_WAIT_V(n) asm volatile("s_waitcnt vmcnt(" #n ")" ::: "memory")
; #define PG8_WAIT_L(n) asm volatile("s_waitcnt lgkmcnt(" #n ")" ::: "memory")
; #define PG8_BAR __builtin_amdgcn_s_barrier()
; #define PG8_SCHED __builtin_amdgcn_sched_barrier(0)
; template <class Epi, class Sched>
; DEVI void gemm_phase(LAS unsigned char* lds, const Gemm g, const Sched& S, const Epi& E) {
;     ...
;             PG8_LDA(At, 1, 1); PG8_STAGE(PG8_SB(1, 0), b3, voffB); PG8_STAGE(PG8_SB(1, 1), b3 + hstep, voffB); PG8_STAGE(PG8_SA(1, 0), a3, voffA);
;             PG8_WAIT_V(8); PG8_WAIT_L(0); PG8_BAR; PG8_MMA(1, 0, At, B0); PG8_MMA(1, 1, At, B1); PG8_BAR; PG8_SCHED;
;         }
;         if (wr == 0) PG8_BAR;
	s_add_i32 s30, s81, s63
	v_lshl_add_u64 v[212:213], v[212:213], 0, s[28:29]
	s_mov_b32 m0, s30
	ds_read_b128 v[160:163], v229 offset:49152
	ds_read_b128 v[184:187], v229 offset:50176
	ds_read_b128 v[188:191], v229 offset:51200
	ds_read_b128 v[192:195], v229 offset:52224
	ds_read_b128 v[196:199], v229 offset:53248
	ds_read_b128 v[200:203], v229 offset:54272
	ds_read_b128 v[204:207], v229 offset:55296
	ds_read_b128 v[208:211], v229 offset:56320
	global_load_lds_dwordx4 v[212:213], off
	s_add_i32 m0, s30, 0x2000
	s_add_u32 s30, s48, 0x40080
	v_lshl_add_u64 v[212:213], v[214:215], 0, s[28:29]
	s_addc_u32 s31, s49, 0
	s_add_i32 s48, s56, s63
	global_load_lds_dwordx4 v[212:213], off
	v_lshl_add_u64 v[212:213], s[30:31], 0, v[166:167]
	s_mov_b32 m0, s48
	s_nop 0
	global_load_lds_dwordx4 v[212:213], off
	v_lshl_add_u64 v[212:213], s[30:31], 0, v[170:171]
	s_add_i32 m0, s48, 0x2000
	s_nop 0
	global_load_lds_dwordx4 v[212:213], off
	v_lshl_add_u64 v[212:213], v[216:217], 0, s[28:29]
	s_mov_b32 m0, s86
	s_nop 0
	global_load_lds_dwordx4 v[212:213], off
	v_lshl_add_u64 v[212:213], v[218:219], 0, s[28:29]
	s_mov_b32 m0, s87
	s_nop 0
	global_load_lds_dwordx4 v[212:213], off
	s_waitcnt vmcnt(8)
	s_waitcnt lgkmcnt(0)
	s_barrier
	s_waitcnt lgkmcnt(0)
	v_mfma_f32_16x16x32_bf16 v[92:95], v[96:99], v[160:163], v[92:95]
	v_mfma_f32_16x16x32_bf16 v[28:31], v[104:107], v[160:163], v[28:31]
	v_mfma_f32_16x16x32_bf16 v[84:87], v[96:99], v[188:191], v[84:87]
	v_mfma_f32_16x16x32_bf16 v[20:23], v[104:107], v[188:191], v[20:23]
	v_mfma_f32_16x16x32_bf16 v[76:79], v[96:99], v[196:199], v[76:79]
	v_mfma_f32_16x16x32_bf16 v[12:15], v[104:107], v[196:199], v[12:15]
	v_mfma_f32_16x16x32_bf16 v[68:71], v[96:99], v[204:207], v[68:71]
	v_mfma_f32_16x16x32_bf16 v[4:7], v[104:107], v[204:207], v[4:7]
	v_mfma_f32_16x16x32_bf16 v[92:95], v[100:103], v[184:187], v[92:95]
	v_mfma_f32_16x16x32_bf16 v[28:31], v[108:111], v[184:187], v[28:31]
	v_mfma_f32_16x16x32_bf16 v[84:87], v[100:103], v[192:195], v[84:87]
	v_mfma_f32_16x16x32_bf16 v[20:23], v[108:111], v[192:195], v[20:23]
	v_mfma_f32_16x16x32_bf16 v[76:79], v[100:103], v[200:203], v[76:79]
	v_mfma_f32_16x16x32_bf16 v[12:15], v[108:111], v[200:203], v[12:15]
	v_mfma_f32_16x16x32_bf16 v[68:71], v[100:103], v[208:211], v[68:71]
	v_mfma_f32_16x16x32_bf16 v[4:7], v[108:111], v[208:211], v[4:7]
	v_mfma_f32_16x16x32_bf16 v[88:91], v[112:115], v[160:163], v[88:91]
	v_mfma_f32_16x16x32_bf16 v[24:27], v[120:123], v[160:163], v[24:27]
	v_mfma_f32_16x16x32_bf16 v[80:83], v[112:115], v[188:191], v[80:83]
	v_mfma_f32_16x16x32_bf16 v[16:19], v[120:123], v[188:191], v[16:19]
	v_mfma_f32_16x16x32_bf16 v[72:75], v[112:115], v[196:199], v[72:75]
	v_mfma_f32_16x16x32_bf16 v[8:11], v[120:123], v[196:199], v[8:11]
	v_mfma_f32_16x16x32_bf16 v[64:67], v[112:115], v[204:207], v[64:67]
	v_mfma_f32_16x16x32_bf16 v[0:3], v[120:123], v[204:207], v[0:3]
	v_mfma_f32_16x16x32_bf16 v[88:91], v[116:119], v[184:187], v[88:91]
	v_mfma_f32_16x16x32_bf16 v[24:27], v[124:127], v[184:187], v[24:27]
	v_mfma_f32_16x16x32_bf16 v[80:83], v[116:119], v[192:195], v[80:83]
	v_mfma_f32_16x16x32_bf16 v[16:19], v[124:127], v[192:195], v[16:19]
	v_mfma_f32_16x16x32_bf16 v[72:75], v[116:119], v[200:203], v[72:75]
	v_mfma_f32_16x16x32_bf16 v[8:11], v[124:127], v[200:203], v[8:11]
	v_mfma_f32_16x16x32_bf16 v[64:67], v[116:119], v[208:211], v[64:67]
	v_mfma_f32_16x16x32_bf16 v[0:3], v[124:127], v[208:211], v[0:3]
	s_barrier
	s_add_i32 s80, s80, 2
	s_add_u32 s59, s59, 0x100
	s_addc_u32 s85, s85, 0
	s_add_u32 s76, s76, 0x100
	s_addc_u32 s77, s77, 0
	s_cmp_gt_u32 s80, 13
	s_cbranch_scc0 .LBB0_1412
	s_and_b64 vcc, exec, s[46:47]
	s_cbranch_vccz .LBB0_1415
	s_barrier

; #define LAS __attribute__((address_space(3)))
; #define PG8_WAIT_V(n) asm volatile("s_waitcnt vmcnt(" #n ")" ::: "memory")
; #define PG8_BAR __builtin_amdgcn_s_barrier()
; DEVI unsigned xb_xcc_id() { return (unsigned)__builtin_amdgcn_s_getreg((3 << 11) | 20) & 0xFu; }
; template <class Epi, class Sched>
; DEVI void gemm_phase(LAS unsigned char* lds, const Gemm g, const Sched& S, const Epi& E) {
;     ...
;     PG8_WAIT_V(0);
;     PG8_BAR;
; DEVI void xcd_barrier(unsigned* bar, volatile LAS unsigned* st) {
;     asm volatile("s_waitcnt vmcnt(0)" ::: "memory");
;     __syncthreads();
;     if (threadIdx.x == 0) {
;         const unsigned x = xb_xcc_id();
;         __builtin_amdgcn_s_waitcnt(0);
;         unsigned nloc = st[0], nx = st[1];
;         if (nloc == 0u) { xcd_barrier_complete(bar, x, nloc, nx); st[0] = nloc; st[1] = nx; }
.LBB0_1443:
	s_waitcnt vmcnt(0)
	s_waitcnt lgkmcnt(0)
	s_setprio 0
	s_barrier
	s_mov_b64 s[2:3], exec
	v_readlane_b32 s4, v249, 53
	v_readlane_b32 s5, v249, 54
	s_and_b64 s[4:5], s[2:3], s[4:5]
	s_mov_b64 exec, s[4:5]
	s_cbranch_execz .LBB0_1495
	s_add_i32 s5, 0, 0x26ff0
	v_mov_b32_e32 v0, s5
	s_getreg_b32 s4, hwreg(HW_REG_XCC_ID, 0, 4)
	s_waitcnt vmcnt(0) expcnt(0) lgkmcnt(0)
	ds_read_b32 v2, v0
	s_add_i32 s5, 0, 0x26ff4
	v_mov_b32_e32 v0, s5
	ds_read_b32 v0, v0
	s_and_b32 s33, s4, 15
	s_waitcnt lgkmcnt(1)
	v_cmp_ne_u32_e32 vcc, 0, v2
	s_cbranch_vccnz .LBB0_1459
	s_add_u32 s4, s96, 0x6fc200
	s_addc_u32 s5, s97, 0
	s_add_u32 s6, s96, 0x6fc400
	s_addc_u32 s7, s97, 0
	s_add_u32 s8, s96, 0x6fc500
	s_addc_u32 s9, s97, 0
	s_add_u32 s10, s96, 0x6fc600
	s_addc_u32 s11, s97, 0
	s_add_u32 s12, s96, 0x6fc700
	s_addc_u32 s13, s97, 0
	s_add_u32 s14, s96, 0x6fc800
	s_addc_u32 s15, s97, 0
	s_add_u32 s16, s96, 0x6fc900
	s_addc_u32 s17, s97, 0
	s_add_u32 s18, s96, 0x6fca00
	s_addc_u32 s19, s97, 0
	s_add_u32 s20, s96, 0x6fcb00
	s_addc_u32 s21, s97, 0
	s_add_u32 s22, s96, 0x6fcc00
	s_addc_u32 s23, s97, 0
	s_add_u32 s24, s96, 0x6fcd00
	s_addc_u32 s25, s97, 0
	s_add_u32 s26, s96, 0x6fce00
	s_addc_u32 s27, s97, 0
	s_add_u32 s28, s96, 0x6fcf00
	s_addc_u32 s29, s97, 0
	s_add_u32 s30, s96, 0x6fd000
	s_addc_u32 s31, s97, 0
	s_add_u32 s34, s96, 0x6fd100
	s_addc_u32 s35, s97, 0
	s_add_u32 s36, s96, 0x6fd200
	s_addc_u32 s37, s97, 0
	s_add_u32 s38, s96, 0x6fd300
	s_addc_u32 s39, s97, 0
	s_mov_b32 s50, 1
	v_mov_b32_e32 v16, 0
	s_branch .LBB0_1447

; DEVI int tid_() { int t = threadIdx.x; asm volatile("" : "+v"(t)); return t; }
; DEVI int bid_() { int t = blockIdx.x; asm volatile("" : "+s"(t)); return t; }
; DEVI int gdim_() { int t = gridDim.x; asm volatile("" : "+s"(t)); return t; }
; DEVI void ffn_fixup_panel(int pm, bf16_t* H, const float* cw, const float* cb, const float* tailg, const float* headpg, const float* headup) {
;     for (int it = tid_(); it < 4 * 2 * (DFF / 4); it += 512) {
;         const int j = (it % (DFF / 4)) * 4, be = it / (DFF / 4), e = be & 1, blk = pm * 4 + (be >> 1);
;         const int row = blk * 64 + e, t = row & (SEQ - 1);
; template <int PH>
; DEVI void run_phase(const Params& p, unsigned char* smem) {
;     ...
;             pg8::Gemm g{(const bf16_t*)(ws + WS_H), wbase + (size_t)16 * MiB / 2, MROWS, DM, DFF}; pg8::StaticOrder S; S.init(MROWS, DM, gdim_(), bid_());
;             pg8::Unit u;
;             for (int i = 0; S.next(i, u); ++i) ffn_fixup_panel(u.pm, (bf16_t*)(ws + WS_H), p.in[28] + (size_t)l * 3 * DFF, p.in[29] + (size_t)l * DFF, (const float*)(ws + WS_TAIL), (const float*)(ws + WS_HPG), (const float*)(ws + WS_HUP));
.LBB0_1495:
	s_or_b64 exec, exec, s[2:3]
	s_mov_b64 s[2:3], s[96:97]
	s_waitcnt lgkmcnt(0)
	s_barrier
	v_readfirstlane_b32 s98, v242
	s_nop 3
	s_cmpk_lt_u32 s98, 0x100
	s_cbranch_scc1 .Lsprio_sp14
	s_setprio 1
.Lsprio_sp14:
	s_add_u32 s6, s2, 0x10a00000
	s_mov_b32 s25, s89
	v_readlane_b32 s27, v249, 0
	s_addc_u32 s7, s3, 0
	s_ashr_i32 s33, s25, 31
	s_ashr_i32 s40, s27, 31
	s_add_u32 s4, s2, 0xa800000
	s_addc_u32 s5, s3, 0
	s_add_u32 s8, s2, 0xb300000
	s_addc_u32 s9, s3, 0
	v_readlane_b32 s56, v249, 37
	s_add_u32 s10, s2, 0xbe00000
	v_readlane_b32 s64, v249, 45
	v_readlane_b32 s65, v249, 46
	s_addc_u32 s11, s3, 0
	v_readlane_b32 s66, v249, 47
	v_readlane_b32 s67, v249, 48
	s_mov_b64 s[44:45], s[64:65]
	s_mov_b64 s[46:47], s[66:67]
	s_add_u32 s12, s44, 0xb000
	s_addc_u32 s13, s45, 0
	v_readlane_b32 s44, v249, 59
	s_mov_b32 s22, 0
	v_mov_b64_e32 v[20:21], 0x1ff
	s_movk_i32 s23, 0x1600
	s_mov_b32 s24, 0x2e8ba2e9
	s_movk_i32 s26, 0x2c00
	s_movk_i32 s28, 0x5800
	s_movk_i32 s29, 0x13ff
	v_mov_b32_e32 v28, 0
	v_readlane_b32 s45, v249, 60
	v_readlane_b32 s46, v249, 61
	v_readlane_b32 s47, v249, 62
	v_readlane_b32 s57, v249, 38
	v_readlane_b32 s58, v249, 39
	v_readlane_b32 s59, v249, 40
	v_readlane_b32 s60, v249, 41
	v_readlane_b32 s61, v249, 42
	v_readlane_b32 s62, v249, 43
	v_readlane_b32 s63, v249, 44
	v_readlane_b32 s68, v249, 49
	v_readlane_b32 s69, v249, 50
	v_readlane_b32 s70, v249, 51
	v_readlane_b32 s71, v249, 52
	s_branch .LBB0_1498

; #define PG8_STAGE(bufoff, gbase, voff) do { _Pragma("unroll") for (int _i = 0; _i < 2; ++_i) \
;         __builtin_amdgcn_global_load_lds((const unsigned*)((const char*)(gbase) + (voff)[_i]), (LAS unsigned*)(lds + (bufoff) + ldsw + _i * 8192), 16, 0, 0); } while (0)
; #define PG8_LDA(dst, b, h) do { _Pragma("unroll") for (int m = 0; m < 4; ++m) _Pragma("unroll") for (int k = 0; k < 2; ++k) dst[m][k] = *(const LAS bf16x8*)(lds + PG8_SA(b, h) + aoff + m * 2048 + k * 1024); } while (0)
; #define PG8_LDB(dst, b, h) do { _Pragma("unroll") for (int n = 0; n < 2; ++n) _Pragma("unroll") for (int k = 0; k < 2; ++k) dst[n][k] = *(const LAS bf16x8*)(lds + PG8_SB(b, h) + boff + n * 2048 + k * 1024); } while (0)
; #define PG8_MMA(ai, bj, At, Bt) do { __builtin_amdgcn_s_setprio(1); _Pragma("unroll") for (int m = 0; m < 4; ++m) _Pragma("unroll") for (int n = 0; n < 2; ++n) _Pragma("unroll") for (int k = 0; k < 2; ++k) \
;         acc[ai][bj][m][n] = __builtin_amdgcn_mfma_f32_16x16x32_bf16(Bt[n][k], At[m][k], acc[ai][bj][m][n], 0, 0, 0); __builtin_amdgcn_s_setprio(0); } while (0)
; #define PG8_WAIT_V(n) asm volatile("s_waitcnt vmcnt(" #n ")" ::: "memory")
; #define PG8_WAIT_L(n) asm volatile("s_waitcnt lgkmcnt(" #n ")" ::: "memory")
; #define PG8_BAR __builtin_amdgcn_s_barrier()
; #define PG8_SCHED __builtin_amdgcn_sched_barrier(0)
; template <class Epi, class Sched>
; DEVI void gemm_phase(LAS unsigned char* lds, const Gemm g, const Sched& S, const Epi& E) {
;     ...
;         for (int t = 0; t < nt; t += 2) {
;             const bool last = (t == nt - 2);
;             const char* a1 = cA + (size_t)(t + 1) * kstep;
;             const char* a2 = last ? nA : cA + (size_t)(t + 2) * kstep; const char* b2 = last ? nB : cB + (size_t)(t + 2) * kstep;
;             const char* a3 = a2 + kstep; const char* b3 = b2 + kstep;
;             if (last && has_next) S.a_ready(nxt);
;             PG8_LDB(B0, 0, 0); PG8_LDB(B1, 0, 1); PG8_SCHED; PG8_LDA(At, 0, 0); PG8_STAGE(PG8_SA(1, 1), a1 + hstep, voffA);
;             PG8_WAIT_V(8); PG8_WAIT_L(0); PG8_BAR; PG8_MMA(0, 0, At, B0); PG8_MMA(0, 1, At, B1); PG8_BAR; PG8_SCHED;
;             PG8_LDA(At, 0, 1); PG8_STAGE(PG8_SB(0, 0), b2, voffB); PG8_STAGE(PG8_SB(0, 1), b2 + hstep, voffB); PG8_STAGE(PG8_SA(0, 0), a2, voffA);
;             PG8_WAIT_V(8); PG8_WAIT_L(0); PG8_BAR; PG8_MMA(1, 0, At, B0); PG8_MMA(1, 1, At, B1); PG8_BAR; PG8_SCHED;
.LBB0_1535:
	ds_read_b128 v[144:147], v165
	ds_read_b128 v[148:151], v165 offset:1024
	ds_read_b128 v[152:155], v165 offset:2048
	ds_read_b128 v[156:159], v165 offset:3072
	ds_read_b128 v[170:173], v166
	ds_read_b128 v[174:177], v166 offset:1024
	ds_read_b128 v[178:181], v166 offset:2048
	ds_read_b128 v[182:185], v166 offset:3072
	s_add_u32 s34, s30, 0x100
	s_addc_u32 s35, s31, 0
	s_cmp_eq_u32 s72, 40
	s_cselect_b32 s39, s1, s35
	s_cselect_b32 s38, s0, s34
	s_cselect_b32 s37, s29, s69
	s_cselect_b32 s36, s28, s68
	v_lshl_add_u64 v[160:161], s[30:31], 0, v[138:139]
	s_add_i32 m0, s48, 0xc000
	ds_read_b128 v[186:189], v167
	ds_read_b128 v[190:193], v167 offset:1024
	ds_read_b128 v[194:197], v167 offset:2048
	ds_read_b128 v[198:201], v167 offset:3072
	ds_read_b128 v[202:205], v167 offset:4096
	ds_read_b128 v[206:209], v167 offset:5120
	ds_read_b128 v[210:213], v167 offset:6144
	ds_read_b128 v[214:217], v167 offset:7168
	global_load_lds_dwordx4 v[160:161], off
	v_lshl_add_u64 v[160:161], s[30:31], 0, v[136:137]
	s_add_i32 m0, s48, 0xe000
	s_nop 0
	global_load_lds_dwordx4 v[160:161], off
	s_waitcnt vmcnt(8)
	s_waitcnt lgkmcnt(0)
	s_barrier
	s_waitcnt lgkmcnt(0)
	v_mfma_f32_16x16x32_bf16 v[124:127], v[144:147], v[186:189], v[124:127]
	v_mfma_f32_16x16x32_bf16 v[120:123], v[152:155], v[186:189], v[120:123]
	v_mfma_f32_16x16x32_bf16 v[108:111], v[144:147], v[194:197], v[108:111]
	v_mfma_f32_16x16x32_bf16 v[104:107], v[152:155], v[194:197], v[104:107]
	v_mfma_f32_16x16x32_bf16 v[92:95], v[144:147], v[202:205], v[92:95]
	v_mfma_f32_16x16x32_bf16 v[88:91], v[152:155], v[202:205], v[88:91]
	v_mfma_f32_16x16x32_bf16 v[76:79], v[144:147], v[210:213], v[76:79]
	v_mfma_f32_16x16x32_bf16 v[72:75], v[152:155], v[210:213], v[72:75]
	v_mfma_f32_16x16x32_bf16 v[124:127], v[148:151], v[190:193], v[124:127]
	v_mfma_f32_16x16x32_bf16 v[120:123], v[156:159], v[190:193], v[120:123]
	v_mfma_f32_16x16x32_bf16 v[108:111], v[148:151], v[198:201], v[108:111]
	v_mfma_f32_16x16x32_bf16 v[104:107], v[156:159], v[198:201], v[104:107]
	v_mfma_f32_16x16x32_bf16 v[92:95], v[148:151], v[206:209], v[92:95]
	v_mfma_f32_16x16x32_bf16 v[88:91], v[156:159], v[206:209], v[88:91]
	v_mfma_f32_16x16x32_bf16 v[76:79], v[148:151], v[214:217], v[76:79]
	v_mfma_f32_16x16x32_bf16 v[72:75], v[156:159], v[214:217], v[72:75]
	v_mfma_f32_16x16x32_bf16 v[116:119], v[170:173], v[186:189], v[116:119]
	v_mfma_f32_16x16x32_bf16 v[112:115], v[178:181], v[186:189], v[112:115]
	v_mfma_f32_16x16x32_bf16 v[100:103], v[170:173], v[194:197], v[100:103]
	v_mfma_f32_16x16x32_bf16 v[96:99], v[178:181], v[194:197], v[96:99]
	v_mfma_f32_16x16x32_bf16 v[84:87], v[170:173], v[202:205], v[84:87]
	v_mfma_f32_16x16x32_bf16 v[80:83], v[178:181], v[202:205], v[80:83]
	v_mfma_f32_16x16x32_bf16 v[68:71], v[170:173], v[210:213], v[68:71]
	v_mfma_f32_16x16x32_bf16 v[64:67], v[178:181], v[210:213], v[64:67]
	v_mfma_f32_16x16x32_bf16 v[116:119], v[174:177], v[190:193], v[116:119]
	v_mfma_f32_16x16x32_bf16 v[112:115], v[182:185], v[190:193], v[112:115]
	v_mfma_f32_16x16x32_bf16 v[100:103], v[174:177], v[198:201], v[100:103]
	v_mfma_f32_16x16x32_bf16 v[96:99], v[182:185], v[198:201], v[96:99]
	v_mfma_f32_16x16x32_bf16 v[84:87], v[174:177], v[206:209], v[84:87]
	v_mfma_f32_16x16x32_bf16 v[80:83], v[182:185], v[206:209], v[80:83]
	v_mfma_f32_16x16x32_bf16 v[68:71], v[174:177], v[214:217], v[68:71]
	v_mfma_f32_16x16x32_bf16 v[64:67], v[182:185], v[214:217], v[64:67]
	s_barrier
	s_add_i32 s30, s59, s43
	v_lshl_add_u64 v[160:161], s[36:37], 0, v[130:131]
	s_mov_b32 m0, s30
	ds_read_b128 v[186:189], v167 offset:16384
	ds_read_b128 v[190:193], v167 offset:17408
	ds_read_b128 v[194:197], v167 offset:18432
	ds_read_b128 v[198:201], v167 offset:19456
	ds_read_b128 v[202:205], v167 offset:20480
	ds_read_b128 v[206:209], v167 offset:21504
	ds_read_b128 v[210:213], v167 offset:22528
	ds_read_b128 v[214:217], v167 offset:23552
	global_load_lds_dwordx4 v[160:161], off
	s_add_i32 m0, s30, 0x2000
	s_add_u32 s30, s36, 0xb0000
	v_lshl_add_u64 v[218:219], s[36:37], 0, v[134:135]
	s_addc_u32 s31, s37, 0
	s_add_i32 s73, s60, s43
	global_load_lds_dwordx4 v[218:219], off
	v_lshl_add_u64 v[220:221], s[30:31], 0, v[130:131]
	s_mov_b32 m0, s73
	v_lshl_add_u64 v[222:223], s[38:39], 0, v[132:133]
	global_load_lds_dwordx4 v[220:221], off
	v_lshl_add_u64 v[220:221], s[30:31], 0, v[134:135]
	s_add_i32 m0, s73, 0x2000
	s_nop 0
	global_load_lds_dwordx4 v[220:221], off
	v_lshl_add_u64 v[220:221], s[38:39], 0, v[128:129]
	s_mov_b32 m0, s48
	s_nop 0
	global_load_lds_dwordx4 v[220:221], off
	s_mov_b32 m0, s49
	s_nop 0
	global_load_lds_dwordx4 v[222:223], off
	s_waitcnt vmcnt(8)
	s_waitcnt lgkmcnt(0)
	s_barrier
; #define PG8_STAGE(bufoff, gbase, voff) do { _Pragma("unroll") for (int _i = 0; _i < 2; ++_i) \
;         __builtin_amdgcn_global_load_lds((const unsigned*)((const char*)(gbase) + (voff)[_i]), (LAS unsigned*)(lds + (bufoff) + ldsw + _i * 8192), 16, 0, 0); } while (0)
; #define PG8_LDA(dst, b, h) do { _Pragma("unroll") for (int m = 0; m < 4; ++m) _Pragma("unroll") for (int k = 0; k < 2; ++k) dst[m][k] = *(const LAS bf16x8*)(lds + PG8_SA(b, h) + aoff + m * 2048 + k * 1024); } while (0)
; #define PG8_LDB(dst, b, h) do { _Pragma("unroll") for (int n = 0; n < 2; ++n) _Pragma("unroll") for (int k = 0; k < 2; ++k) dst[n][k] = *(const LAS bf16x8*)(lds + PG8_SB(b, h) + boff + n * 2048 + k * 1024); } while (0)
; #define PG8_MMA(ai, bj, At, Bt) do { __builtin_amdgcn_s_setprio(1); _Pragma("unroll") for (int m = 0; m < 4; ++m) _Pragma("unroll") for (int n = 0; n < 2; ++n) _Pragma("unroll") for (int k = 0; k < 2; ++k) \
;         acc[ai][bj][m][n] = __builtin_amdgcn_mfma_f32_16x16x32_bf16(Bt[n][k], At[m][k], acc[ai][bj][m][n], 0, 0, 0); __builtin_amdgcn_s_setprio(0); } while (0)
; #define PG8_WAIT_V(n) asm volatile("s_waitcnt vmcnt(" #n ")" ::: "memory")
; #define PG8_WAIT_L(n) asm volatile("s_waitcnt lgkmcnt(" #n ")" ::: "memory")
; #define PG8_BAR __builtin_amdgcn_s_barrier()
; #define PG8_SCHED __builtin_amdgcn_sched_barrier(0)
; template <class Epi, class Sched>
; DEVI void gemm_phase(LAS unsigned char* lds, const Gemm g, const Sched& S, const Epi& E) {
;     ...
;             PG8_WAIT_V(8); PG8_WAIT_L(0); PG8_BAR; PG8_MMA(1, 0, At, B0); PG8_MMA(1, 1, At, B1); PG8_BAR; PG8_SCHED;
;             PG8_LDB(B0, 1, 0); PG8_LDB(B1, 1, 1); PG8_SCHED; PG8_LDA(At, 1, 0); PG8_STAGE(PG8_SA(0, 1), a2 + hstep, voffA);
;             PG8_WAIT_V(8); PG8_WAIT_L(0); PG8_BAR; PG8_MMA(0, 0, At, B0); PG8_MMA(0, 1, At, B1); PG8_BAR; PG8_SCHED;
	s_waitcnt lgkmcnt(0)
	v_mfma_f32_16x16x32_bf16 v[60:63], v[144:147], v[186:189], v[60:63]
	v_mfma_f32_16x16x32_bf16 v[56:59], v[152:155], v[186:189], v[56:59]
	v_mfma_f32_16x16x32_bf16 v[44:47], v[144:147], v[194:197], v[44:47]
	v_mfma_f32_16x16x32_bf16 v[40:43], v[152:155], v[194:197], v[40:43]
	v_mfma_f32_16x16x32_bf16 v[28:31], v[144:147], v[202:205], v[28:31]
	v_mfma_f32_16x16x32_bf16 v[24:27], v[152:155], v[202:205], v[24:27]
	v_mfma_f32_16x16x32_bf16 v[12:15], v[144:147], v[210:213], v[12:15]
	v_mfma_f32_16x16x32_bf16 v[8:11], v[152:155], v[210:213], v[8:11]
	v_mfma_f32_16x16x32_bf16 v[60:63], v[148:151], v[190:193], v[60:63]
	v_mfma_f32_16x16x32_bf16 v[56:59], v[156:159], v[190:193], v[56:59]
	v_mfma_f32_16x16x32_bf16 v[44:47], v[148:151], v[198:201], v[44:47]
	v_mfma_f32_16x16x32_bf16 v[40:43], v[156:159], v[198:201], v[40:43]
	v_mfma_f32_16x16x32_bf16 v[28:31], v[148:151], v[206:209], v[28:31]
	v_mfma_f32_16x16x32_bf16 v[24:27], v[156:159], v[206:209], v[24:27]
	v_mfma_f32_16x16x32_bf16 v[12:15], v[148:151], v[214:217], v[12:15]
	v_mfma_f32_16x16x32_bf16 v[8:11], v[156:159], v[214:217], v[8:11]
	v_mfma_f32_16x16x32_bf16 v[52:55], v[170:173], v[186:189], v[52:55]
	v_mfma_f32_16x16x32_bf16 v[48:51], v[178:181], v[186:189], v[48:51]
	v_mfma_f32_16x16x32_bf16 v[36:39], v[170:173], v[194:197], v[36:39]
	v_mfma_f32_16x16x32_bf16 v[32:35], v[178:181], v[194:197], v[32:35]
	v_mfma_f32_16x16x32_bf16 v[20:23], v[170:173], v[202:205], v[20:23]
	v_mfma_f32_16x16x32_bf16 v[16:19], v[178:181], v[202:205], v[16:19]
	v_mfma_f32_16x16x32_bf16 v[4:7], v[170:173], v[210:213], v[4:7]
	v_mfma_f32_16x16x32_bf16 v[0:3], v[178:181], v[210:213], v[0:3]
	v_mfma_f32_16x16x32_bf16 v[52:55], v[174:177], v[190:193], v[52:55]
	v_mfma_f32_16x16x32_bf16 v[48:51], v[182:185], v[190:193], v[48:51]
	v_mfma_f32_16x16x32_bf16 v[36:39], v[174:177], v[198:201], v[36:39]
	v_mfma_f32_16x16x32_bf16 v[32:35], v[182:185], v[198:201], v[32:35]
	v_mfma_f32_16x16x32_bf16 v[20:23], v[174:177], v[206:209], v[20:23]
	v_mfma_f32_16x16x32_bf16 v[16:19], v[182:185], v[206:209], v[16:19]
	v_mfma_f32_16x16x32_bf16 v[4:7], v[174:177], v[214:217], v[4:7]
	v_mfma_f32_16x16x32_bf16 v[0:3], v[182:185], v[214:217], v[0:3]
	s_barrier
	s_add_i32 s73, 0, 0x18000
	s_add_i32 s76, 0, 0x1c000
	v_add_u32_e32 v156, s73, v163
	v_add_u32_e32 v169, s76, v163
	ds_read_b128 v[144:147], v156
	ds_read_b128 v[148:151], v156 offset:1024
	ds_read_b128 v[152:155], v156 offset:2048
	ds_read_b128 v[156:159], v156 offset:3072
	ds_read_b128 v[170:173], v169
	ds_read_b128 v[174:177], v169 offset:1024
	ds_read_b128 v[178:181], v169 offset:2048
	ds_read_b128 v[182:185], v169 offset:3072
	s_add_u32 s30, s38, 0xb0000
	s_addc_u32 s31, s39, 0
	s_mov_b32 m0, s50
	v_lshl_add_u64 v[224:225], s[30:31], 0, v[128:129]
	ds_read_b128 v[186:189], v167 offset:32768
	ds_read_b128 v[190:193], v167 offset:33792
	ds_read_b128 v[194:197], v167 offset:34816
	ds_read_b128 v[198:201], v167 offset:35840
	ds_read_b128 v[202:205], v167 offset:36864
	ds_read_b128 v[206:209], v167 offset:37888
	ds_read_b128 v[210:213], v167 offset:38912
	ds_read_b128 v[214:217], v167 offset:39936
	global_load_lds_dwordx4 v[224:225], off
	v_lshl_add_u64 v[224:225], s[30:31], 0, v[132:133]
	s_mov_b32 m0, s51
	s_nop 0
	global_load_lds_dwordx4 v[224:225], off
	s_waitcnt vmcnt(8)
	s_waitcnt lgkmcnt(0)
	s_barrier
	s_waitcnt lgkmcnt(0)
	v_mfma_f32_16x16x32_bf16 v[124:127], v[144:147], v[186:189], v[124:127]
	v_mfma_f32_16x16x32_bf16 v[120:123], v[152:155], v[186:189], v[120:123]
	v_mfma_f32_16x16x32_bf16 v[108:111], v[144:147], v[194:197], v[108:111]
	v_mfma_f32_16x16x32_bf16 v[104:107], v[152:155], v[194:197], v[104:107]
	v_mfma_f32_16x16x32_bf16 v[92:95], v[144:147], v[202:205], v[92:95]
	v_mfma_f32_16x16x32_bf16 v[88:91], v[152:155], v[202:205], v[88:91]
	v_mfma_f32_16x16x32_bf16 v[76:79], v[144:147], v[210:213], v[76:79]
	v_mfma_f32_16x16x32_bf16 v[72:75], v[152:155], v[210:213], v[72:75]
	v_mfma_f32_16x16x32_bf16 v[124:127], v[148:151], v[190:193], v[124:127]
	v_mfma_f32_16x16x32_bf16 v[120:123], v[156:159], v[190:193], v[120:123]
	v_mfma_f32_16x16x32_bf16 v[108:111], v[148:151], v[198:201], v[108:111]
	v_mfma_f32_16x16x32_bf16 v[104:107], v[156:159], v[198:201], v[104:107]
	v_mfma_f32_16x16x32_bf16 v[92:95], v[148:151], v[206:209], v[92:95]
	v_mfma_f32_16x16x32_bf16 v[88:91], v[156:159], v[206:209], v[88:91]
	v_mfma_f32_16x16x32_bf16 v[76:79], v[148:151], v[214:217], v[76:79]
	v_mfma_f32_16x16x32_bf16 v[72:75], v[156:159], v[214:217], v[72:75]
	v_mfma_f32_16x16x32_bf16 v[116:119], v[170:173], v[186:189], v[116:119]
	v_mfma_f32_16x16x32_bf16 v[112:115], v[178:181], v[186:189], v[112:115]
	v_mfma_f32_16x16x32_bf16 v[100:103], v[170:173], v[194:197], v[100:103]
	v_mfma_f32_16x16x32_bf16 v[96:99], v[178:181], v[194:197], v[96:99]
	v_mfma_f32_16x16x32_bf16 v[84:87], v[170:173], v[202:205], v[84:87]
	v_mfma_f32_16x16x32_bf16 v[80:83], v[178:181], v[202:205], v[80:83]
	v_mfma_f32_16x16x32_bf16 v[68:71], v[170:173], v[210:213], v[68:71]
	v_mfma_f32_16x16x32_bf16 v[64:67], v[178:181], v[210:213], v[64:67]
	v_mfma_f32_16x16x32_bf16 v[116:119], v[174:177], v[190:193], v[116:119]
	v_mfma_f32_16x16x32_bf16 v[112:115], v[182:185], v[190:193], v[112:115]
	v_mfma_f32_16x16x32_bf16 v[100:103], v[174:177], v[198:201], v[100:103]
	v_mfma_f32_16x16x32_bf16 v[96:99], v[182:185], v[198:201], v[96:99]
	v_mfma_f32_16x16x32_bf16 v[84:87], v[174:177], v[206:209], v[84:87]
	v_mfma_f32_16x16x32_bf16 v[80:83], v[182:185], v[206:209], v[80:83]
	v_mfma_f32_16x16x32_bf16 v[68:71], v[174:177], v[214:217], v[68:71]
	v_mfma_f32_16x16x32_bf16 v[64:67], v[182:185], v[214:217], v[64:67]
	s_barrier
; #define PG8_STAGE(bufoff, gbase, voff) do { _Pragma("unroll") for (int _i = 0; _i < 2; ++_i) \
;         __builtin_amdgcn_global_load_lds((const unsigned*)((const char*)(gbase) + (voff)[_i]), (LAS unsigned*)(lds + (bufoff) + ldsw + _i * 8192), 16, 0, 0); } while (0)
; #define PG8_LDA(dst, b, h) do { _Pragma("unroll") for (int m = 0; m < 4; ++m) _Pragma("unroll") for (int k = 0; k < 2; ++k) dst[m][k] = *(const LAS bf16x8*)(lds + PG8_SA(b, h) + aoff + m * 2048 + k * 1024); } while (0)
; #define PG8_MMA(ai, bj, At, Bt) do { __builtin_amdgcn_s_setprio(1); _Pragma("unroll") for (int m = 0; m < 4; ++m) _Pragma("unroll") for (int n = 0; n < 2; ++n) _Pragma("unroll") for (int k = 0; k < 2; ++k) \
;         acc[ai][bj][m][n] = __builtin_amdgcn_mfma_f32_16x16x32_bf16(Bt[n][k], At[m][k], acc[ai][bj][m][n], 0, 0, 0); __builtin_amdgcn_s_setprio(0); } while (0)
; #define PG8_WAIT_V(n) asm volatile("s_waitcnt vmcnt(" #n ")" ::: "memory")
; #define PG8_WAIT_L(n) asm volatile("s_waitcnt lgkmcnt(" #n ")" ::: "memory")
; #define PG8_BAR __builtin_amdgcn_s_barrier()
; #define PG8_SCHED __builtin_amdgcn_sched_barrier(0)
; template <class Epi, class Sched>
; DEVI void gemm_phase(LAS unsigned char* lds, const Gemm g, const Sched& S, const Epi& E) {
;     ...
;             PG8_LDA(At, 1, 1); PG8_STAGE(PG8_SB(1, 0), b3, voffB); PG8_STAGE(PG8_SB(1, 1), b3 + hstep, voffB); PG8_STAGE(PG8_SA(1, 0), a3, voffA);
;             PG8_WAIT_V(8); PG8_WAIT_L(0); PG8_BAR; PG8_MMA(1, 0, At, B0); PG8_MMA(1, 1, At, B1); PG8_BAR; PG8_SCHED;
;         }
;         if (wr == 0) PG8_BAR;
	s_add_i32 s30, s73, s43
	v_lshl_add_u64 v[160:161], v[160:161], 0, s[20:21]
	s_mov_b32 m0, s30
	ds_read_b128 v[186:189], v167 offset:49152
	ds_read_b128 v[190:193], v167 offset:50176
	ds_read_b128 v[194:197], v167 offset:51200
	ds_read_b128 v[198:201], v167 offset:52224
	ds_read_b128 v[202:205], v167 offset:53248
	ds_read_b128 v[206:209], v167 offset:54272
	ds_read_b128 v[210:213], v167 offset:55296
	ds_read_b128 v[214:217], v167 offset:56320
	global_load_lds_dwordx4 v[160:161], off
	s_add_i32 m0, s30, 0x2000
	s_add_u32 s30, s36, 0xb0080
	v_lshl_add_u64 v[160:161], v[218:219], 0, s[20:21]
	s_addc_u32 s31, s37, 0
	s_add_i32 s36, s76, s43
	global_load_lds_dwordx4 v[160:161], off
	v_lshl_add_u64 v[160:161], s[30:31], 0, v[130:131]
	s_mov_b32 m0, s36
	s_nop 0
	global_load_lds_dwordx4 v[160:161], off
	v_lshl_add_u64 v[160:161], s[30:31], 0, v[134:135]
	s_add_i32 m0, s36, 0x2000
	s_nop 0
	global_load_lds_dwordx4 v[160:161], off
	v_lshl_add_u64 v[160:161], v[220:221], 0, s[20:21]
	s_mov_b32 m0, s57
	s_nop 0
	global_load_lds_dwordx4 v[160:161], off
	v_lshl_add_u64 v[160:161], v[222:223], 0, s[20:21]
	s_mov_b32 m0, s58
	s_nop 0
	global_load_lds_dwordx4 v[160:161], off
	s_waitcnt vmcnt(8)
	s_waitcnt lgkmcnt(0)
	s_barrier
	s_waitcnt lgkmcnt(0)
	v_mfma_f32_16x16x32_bf16 v[60:63], v[144:147], v[186:189], v[60:63]
	v_mfma_f32_16x16x32_bf16 v[56:59], v[152:155], v[186:189], v[56:59]
	v_mfma_f32_16x16x32_bf16 v[44:47], v[144:147], v[194:197], v[44:47]
	v_mfma_f32_16x16x32_bf16 v[40:43], v[152:155], v[194:197], v[40:43]
	v_mfma_f32_16x16x32_bf16 v[28:31], v[144:147], v[202:205], v[28:31]
	v_mfma_f32_16x16x32_bf16 v[24:27], v[152:155], v[202:205], v[24:27]
	v_mfma_f32_16x16x32_bf16 v[12:15], v[144:147], v[210:213], v[12:15]
	v_mfma_f32_16x16x32_bf16 v[8:11], v[152:155], v[210:213], v[8:11]
	v_mfma_f32_16x16x32_bf16 v[60:63], v[148:151], v[190:193], v[60:63]
	v_mfma_f32_16x16x32_bf16 v[56:59], v[156:159], v[190:193], v[56:59]
	v_mfma_f32_16x16x32_bf16 v[44:47], v[148:151], v[198:201], v[44:47]
	v_mfma_f32_16x16x32_bf16 v[40:43], v[156:159], v[198:201], v[40:43]
	v_mfma_f32_16x16x32_bf16 v[28:31], v[148:151], v[206:209], v[28:31]
	v_mfma_f32_16x16x32_bf16 v[24:27], v[156:159], v[206:209], v[24:27]
	v_mfma_f32_16x16x32_bf16 v[12:15], v[148:151], v[214:217], v[12:15]
	v_mfma_f32_16x16x32_bf16 v[8:11], v[156:159], v[214:217], v[8:11]
	v_mfma_f32_16x16x32_bf16 v[52:55], v[170:173], v[186:189], v[52:55]
	v_mfma_f32_16x16x32_bf16 v[48:51], v[178:181], v[186:189], v[48:51]
	v_mfma_f32_16x16x32_bf16 v[36:39], v[170:173], v[194:197], v[36:39]
	v_mfma_f32_16x16x32_bf16 v[32:35], v[178:181], v[194:197], v[32:35]
	v_mfma_f32_16x16x32_bf16 v[20:23], v[170:173], v[202:205], v[20:23]
	v_mfma_f32_16x16x32_bf16 v[16:19], v[178:181], v[202:205], v[16:19]
	v_mfma_f32_16x16x32_bf16 v[4:7], v[170:173], v[210:213], v[4:7]
	v_mfma_f32_16x16x32_bf16 v[0:3], v[178:181], v[210:213], v[0:3]
	v_mfma_f32_16x16x32_bf16 v[52:55], v[174:177], v[190:193], v[52:55]
	v_mfma_f32_16x16x32_bf16 v[48:51], v[182:185], v[190:193], v[48:51]
	v_mfma_f32_16x16x32_bf16 v[36:39], v[174:177], v[198:201], v[36:39]
	v_mfma_f32_16x16x32_bf16 v[32:35], v[182:185], v[198:201], v[32:35]
	v_mfma_f32_16x16x32_bf16 v[20:23], v[174:177], v[206:209], v[20:23]
	v_mfma_f32_16x16x32_bf16 v[16:19], v[182:185], v[206:209], v[16:19]
	v_mfma_f32_16x16x32_bf16 v[4:7], v[174:177], v[214:217], v[4:7]
	v_mfma_f32_16x16x32_bf16 v[0:3], v[182:185], v[214:217], v[0:3]
	s_barrier
	s_add_i32 s72, s72, 2
	s_add_u32 s68, s68, 0x100
	s_addc_u32 s69, s69, 0
	s_cmp_gt_u32 s72, 41
	s_mov_b64 s[30:31], s[34:35]
	s_cbranch_scc0 .LBB0_1535
	s_and_b64 vcc, exec, s[22:23]
	s_cbranch_vccz .LBB0_1538
	s_barrier

; DEVI int tid_() { int t = threadIdx.x; asm volatile("" : "+v"(t)); return t; }
; #define PG8_STAGE(bufoff, gbase, voff) do { _Pragma("unroll") for (int _i = 0; _i < 2; ++_i) \
;         __builtin_amdgcn_global_load_lds((const unsigned*)((const char*)(gbase) + (voff)[_i]), (LAS unsigned*)(lds + (bufoff) + ldsw + _i * 8192), 16, 0, 0); } while (0)
; #define PG8_WAIT_V(n) asm volatile("s_waitcnt vmcnt(" #n ")" ::: "memory")
; #define PG8_BAR __builtin_amdgcn_s_barrier()
; template <class Epi, class Sched>
; DEVI void gemm_phase(LAS unsigned char* lds, const Gemm g, const Sched& S, const Epi& E) {
;     const int tid = tid_(), wid = __builtin_amdgcn_readfirstlane(tid >> 6), lane = tid & 63, wr = wid >> 2, wc = wid & 3, fr = lane & 15, fq = lane >> 4;
;     const int K = g.K, nt = K / BK;
;     unsigned voffA[2], voffB[2];
; #pragma unroll
;     for (int i = 0; i < 2; ++i) { int R, C; stage_rc(tid * 16 + i * 8192, R, C); const int Rb = Epi::PERM ? ((R & ~31) + perm32(R & 31)) : R;
;         voffA[i] = (unsigned)(R * K + C) * 2u; voffB[i] = (unsigned)(Rb * K + C) * 2u; }
;     const size_t kstep = (size_t)(BK * 2);
;     const size_t hstep = (size_t)HALF * K * 2;
;     const size_t tstep = 2 * hstep;
;     const unsigned ldsw = (unsigned)wid * 1024u;
;     const int aoff = lds_byte(wr * 64 + fr, fq * 8), boff = lds_byte(wc * 32 + fr, fq * 8);
;     ...
;     Unit cur, nxt; int ui = 0;
;     if (!S.next(0, cur)) return;
;     f32x4 acc[2][2][4][2];
; #pragma unroll
;     for (int a = 0; a < 2; ++a)
; #pragma unroll
;         for (int b = 0; b < 2; ++b)
; #pragma unroll
;             for (int m = 0; m < 4; ++m)
; #pragma unroll
;                 for (int n = 0; n < 2; ++n) acc[a][b][m][n] = (f32x4){0.f, 0.f, 0.f, 0.f};
;     bf16x8 At[4][2], B0[2][2], B1[2][2];
;     const char* cA = (const char*)g.A + (size_t)cur.pm * tstep; const char* cB = (const char*)g.Bt + (size_t)cur.pn * tstep;
;     S.a_ready(cur);
;     PG8_STAGE(PG8_SB(0, 0), cB, voffB); PG8_STAGE(PG8_SB(0, 1), cB + hstep, voffB); PG8_STAGE(PG8_SA(0, 0), cA, voffA); PG8_STAGE(PG8_SA(0, 1), cA + hstep, voffA);
;     if (wr == 1) PG8_BAR;
;     PG8_WAIT_V(2); PG8_BAR;
;     PG8_STAGE(PG8_SB(1, 0), cB + kstep, voffB); PG8_STAGE(PG8_SA(1, 0), cA + kstep, voffA); PG8_STAGE(PG8_SB(1, 1), cB + hstep + kstep, voffB);
;     PG8_WAIT_V(6); PG8_BAR;
.Lsprio_sp15:
	s_cmpk_gt_i32 s33, 0x2ff
	v_readfirstlane_b32 s15, v8
	s_cbranch_scc1 .LBB0_1626
	v_lshlrev_b32_e32 v0, 4, v8
	v_add_u32_e32 v1, 0x2000, v0
	v_ashrrev_i32_e32 v2, 31, v1
	v_lshrrev_b32_e32 v2, 22, v2
	v_add_u32_e32 v2, v1, v2
	v_ashrrev_i32_e32 v9, 10, v2
	v_mul_i32_i24_e32 v2, 0x400, v9
	v_sub_u32_e32 v1, v1, v2
	v_lshrrev_b32_e32 v2, 4, v1
	v_bitop3_b32 v1, v2, v1, 32 bitop3:0x6c
	v_ashrrev_i32_e32 v2, 31, v1
	v_lshrrev_b32_e32 v2, 26, v2
	v_add_u32_e32 v2, v1, v2
	v_lshlrev_b32_e32 v3, 3, v9
	v_ashrrev_i32_e32 v10, 6, v2
	v_and_b32_e32 v3, -16, v3
	v_add_u32_e32 v3, v10, v3
	v_and_b32_e32 v4, 3, v10
	s_mov_b32 s2, 0x1fffe0
	v_lshrrev_b32_e32 v5, 2, v3
	v_lshlrev_b32_e32 v6, 1, v3
	v_and_b32_e32 v2, 0xc0, v2
	v_and_or_b32 v4, v3, s2, v4
	v_and_b32_e32 v5, 4, v5
	v_and_b32_e32 v6, 24, v6
	v_sub_u32_e32 v1, v1, v2
	v_mov_b32_e32 v2, 1
	v_or3_b32 v4, v4, v5, v6
	v_lshlrev_b32_e32 v5, 5, v9
	v_ashrrev_i16_sdwa v1, v2, sext(v1) dst_sel:DWORD dst_unused:UNUSED_PAD src0_sel:DWORD src1_sel:BYTE_0
	v_and_b32_e32 v5, 32, v5
	v_bfe_i32 v11, v1, 0, 16
	v_add_lshl_u32 v1, v5, v11, 1
	v_lshl_add_u32 v160, v4, 11, v1
	v_lshl_add_u32 v162, v3, 11, v1
	v_bfe_i32 v1, v8, 27, 1
	v_lshrrev_b32_e32 v1, 22, v1
	v_add_u32_e32 v1, v0, v1
	v_and_b32_e32 v1, 0xfffffc00, v1
	v_sub_u32_e32 v0, v0, v1
	v_lshrrev_b32_e32 v1, 4, v0
	v_bitop3_b32 v1, v1, v0, 32 bitop3:0x6c
	v_ashrrev_i32_e32 v0, 31, v0
	v_lshrrev_b32_e32 v0, 26, v0
	v_add_u32_e32 v0, v1, v0
	v_ashrrev_i32_e32 v12, 6, v0
	v_ashrrev_i32_e32 v0, 31, v8
	v_lshrrev_b32_e32 v0, 26, v0
	v_add_u32_e32 v0, v8, v0
	s_add_u32 s36, s0, 0x3c00000
	v_ashrrev_i32_e32 v13, 6, v0
	s_addc_u32 s37, s1, 0
	v_lshlrev_b32_e32 v0, 3, v13
	s_add_u32 s38, s0, 0x6800000
	v_and_b32_e32 v0, -16, v0
	s_addc_u32 s39, s1, 0
	v_add_u32_e32 v0, v12, v0
	v_and_b32_e32 v3, 3, v12
	s_ashr_i32 s41, s33, 31
	v_and_or_b32 v3, v0, s2, v3
	s_lshr_b32 s2, s41, 29
	s_add_i32 s2, s33, s2
	s_ashr_i32 s12, s15, 6
	s_ashr_i32 s3, s2, 3
	s_and_b32 s2, s2, -8
	s_ashr_i32 s16, s15, 8
	s_lshl_b32 s40, s12, 10
	s_sub_i32 s2, s33, s2
	s_cmp_lt_i32 s2, 0
	s_movk_i32 s42, 0x61
	s_cselect_b32 s4, s42, 0x60
	s_mul_i32 s2, s4, s2
	s_add_i32 s2, s2, s3
	s_mul_hi_i32 s3, s2, 0x2aaaaaab
	s_lshr_b32 s4, s3, 31
	s_ashr_i32 s3, s3, 3
	s_add_i32 s3, s3, s4
	s_lshl_b32 s4, s3, 3
	s_mul_i32 s3, s3, 48
	s_sub_i32 s2, s2, s3
	s_bfe_i32 s3, s2, 0x80000
	s_bfe_u32 s3, s3, 0x3000c
	s_add_i32 s3, s2, s3
	s_bfe_i32 s5, s3, 0x80000
	s_and_b32 s3, s3, 0xf8
	v_lshrrev_b32_e32 v4, 2, v0
	v_lshlrev_b32_e32 v5, 1, v0
	s_sub_i32 s2, s2, s3
	v_and_b32_e32 v4, 4, v4
	v_and_b32_e32 v5, 24, v5
	s_sext_i32_i16 s5, s5
	s_sext_i32_i8 s2, s2
	v_or3_b32 v3, v3, v4, v5
	v_mul_i32_i24_e32 v5, 64, v12
	s_lshr_b32 s14, s5, 3
	s_add_i32 s26, s4, s2
	v_sub_u32_e32 v1, v1, v5
	s_ashr_i32 s27, s26, 31
	s_bfe_i64 s[4:5], s[14:15], 0x100000
	v_lshlrev_b32_e32 v4, 5, v13
	v_ashrrev_i16_sdwa v1, v2, sext(v1) dst_sel:DWORD dst_unused:UNUSED_PAD src0_sel:DWORD src1_sel:BYTE_0
	s_lshl_b64 s[2:3], s[26:27], 19
	s_lshl_b64 s[4:5], s[4:5], 19
	v_and_b32_e32 v4, 32, v4
	v_bfe_i32 v14, v1, 0, 16
	s_add_u32 s28, s36, s4
	v_add_lshl_u32 v1, v4, v14, 1
	s_addc_u32 s29, s37, s5
	s_add_i32 s27, s40, 0
	v_lshl_add_u32 v164, v3, 11, v1
	s_add_i32 m0, s27, 0x10000
	v_lshl_add_u32 v166, v0, 11, v1
	global_load_lds_dwordx4 v164, s[28:29]
	s_add_i32 m0, s27, 0x12000
	s_add_u32 s4, s28, 0x40000
	global_load_lds_dwordx4 v160, s[28:29]
	s_addc_u32 s5, s29, 0
	s_add_i32 m0, s27, 0x14000
	v_mov_b32_e32 v165, 0
	global_load_lds_dwordx4 v164, s[4:5]
	s_add_i32 m0, s27, 0x16000
	s_add_u32 s30, s38, s2
	s_addc_u32 s31, s39, s3
	s_add_i32 s43, s27, 0x2000
	global_load_lds_dwordx4 v160, s[4:5]
	s_mov_b32 m0, s27
	s_add_u32 s2, s30, 0x40000
	global_load_lds_dwordx4 v166, s[30:31]
	s_mov_b32 m0, s43
	s_addc_u32 s3, s31, 0
	s_add_i32 s48, s27, 0x4000
	global_load_lds_dwordx4 v162, s[30:31]
	s_mov_b32 m0, s48
	s_add_i32 s49, s27, 0x6000
	global_load_lds_dwordx4 v166, s[2:3]
	s_mov_b32 m0, s49
	v_mov_b32_e32 v161, v165
	global_load_lds_dwordx4 v162, s[2:3]
	v_mov_b32_e32 v167, v165
	v_mov_b32_e32 v163, v165
	s_cmp_eq_u32 s16, 1
	s_mov_b32 s50, 0
	v_lshl_add_u64 v[6:7], s[28:29], 0, v[164:165]
	v_lshl_add_u64 v[4:5], s[28:29], 0, v[160:161]
	v_lshl_add_u64 v[0:1], s[30:31], 0, v[166:167]
	s_cselect_b64 s[2:3], -1, 0
	s_cmp_lg_u32 s16, 1
	v_lshl_add_u64 v[2:3], s[30:31], 0, v[162:163]
	s_cbranch_scc1 .LBB0_1613
	s_barrier

; DEVI int bid_() { int t = blockIdx.x; asm volatile("" : "+s"(t)); return t; }
; DEVI int gdim_() { int t = gridDim.x; asm volatile("" : "+s"(t)); return t; }
;     DEVI bool next(int i, Unit& u) const {
;         const long L = (long)i * G + c; if (L >= nwg) return false;
;         int wgid = (int)L; { const int q = nwg / NXCD, r = nwg % NXCD, xcd = wgid % NXCD, off = wgid / NXCD; wgid = (xcd < r ? xcd * (q + 1) : r * (q + 1) + (xcd - r) * q) + off; }
;         const int nig = WGM * nN, gid = wgid / nig, fm = gid * WGM, gsz = (nM - fm) < WGM ? (nM - fm) : WGM;
;         u.pm = fm + ((wgid % nig) % gsz); u.pn = (wgid % nig) / gsz; return true;
; template <int PH>
; DEVI void run_phase(const Params& p, unsigned char* smem) {
;     ...
;             pg8::Gemm g{(const bf16_t*)(ws + WS_MIX), wbase + (size_t)3 * MiB / 2, MROWS, DM, DM}; pg8::StaticOrder S; S.init(MROWS, DM, gdim_(), bid_());
;             EpiRes E{l > 0 ? p.out : p.in[0], p.out, (bf16_t*)(ws + WS_ZB), stPrev, l > 0 ? p.in[31] + (size_t)lp * DM : nullptr, l > 0 ? p.in[32] + (size_t)lp * DM : nullptr, p.in[23] + (size_t)l * DM, stA};
;             pg8::gemm_phase<EpiRes, pg8::StaticOrder>(lds, g, S, E);
.LBB0_1961:
	s_or_b64 exec, exec, s[0:1]
	s_mov_b64 s[2:3], s[96:97]
	s_mov_b32 s23, s89
	v_readlane_b32 s25, v249, 0
	s_waitcnt lgkmcnt(0)
	s_barrier
	v_readfirstlane_b32 s98, v242
	s_nop 3
	s_cmpk_lt_u32 s98, 0x100
	s_cbranch_scc1 .Lsprio_sp19
	s_setprio 1
.Lsprio_sp19:
	v_mov_b32_e32 v8, v242
	s_cmpk_lt_i32 s25, 0x200
	s_cselect_b64 s[0:1], -1, 0
	s_cmpk_gt_i32 s25, 0x1ff
	v_readfirstlane_b32 s20, v8
	s_cbranch_scc1 .LBB0_1967
	s_ashr_i32 s4, s25, 31
	s_lshr_b32 s4, s4, 29
	s_add_i32 s8, s25, s4
	s_and_b32 s4, s8, -8
	s_sub_i32 s6, s25, s4
	s_cmp_gt_i32 s6, -1
	s_cbranch_scc0 .LBB0_1964
	s_lshl_b32 s7, s6, 6
	s_ashr_i32 s4, s8, 3
	s_cbranch_execz .LBB0_1965
	s_branch .LBB0_1966

; #define PG8_STAGE(bufoff, gbase, voff) do { _Pragma("unroll") for (int _i = 0; _i < 2; ++_i) \
;         __builtin_amdgcn_global_load_lds((const unsigned*)((const char*)(gbase) + (voff)[_i]), (LAS unsigned*)(lds + (bufoff) + ldsw + _i * 8192), 16, 0, 0); } while (0)
; #define PG8_LDA(dst, b, h) do { _Pragma("unroll") for (int m = 0; m < 4; ++m) _Pragma("unroll") for (int k = 0; k < 2; ++k) dst[m][k] = *(const LAS bf16x8*)(lds + PG8_SA(b, h) + aoff + m * 2048 + k * 1024); } while (0)
; #define PG8_LDB(dst, b, h) do { _Pragma("unroll") for (int n = 0; n < 2; ++n) _Pragma("unroll") for (int k = 0; k < 2; ++k) dst[n][k] = *(const LAS bf16x8*)(lds + PG8_SB(b, h) + boff + n * 2048 + k * 1024); } while (0)
; #define PG8_MMA(ai, bj, At, Bt) do { __builtin_amdgcn_s_setprio(1); _Pragma("unroll") for (int m = 0; m < 4; ++m) _Pragma("unroll") for (int n = 0; n < 2; ++n) _Pragma("unroll") for (int k = 0; k < 2; ++k) \
;         acc[ai][bj][m][n] = __builtin_amdgcn_mfma_f32_16x16x32_bf16(Bt[n][k], At[m][k], acc[ai][bj][m][n], 0, 0, 0); __builtin_amdgcn_s_setprio(0); } while (0)
; #define PG8_WAIT_V(n) asm volatile("s_waitcnt vmcnt(" #n ")" ::: "memory")
; #define PG8_WAIT_L(n) asm volatile("s_waitcnt lgkmcnt(" #n ")" ::: "memory")
; #define PG8_BAR __builtin_amdgcn_s_barrier()
; #define PG8_SCHED __builtin_amdgcn_sched_barrier(0)
; template <class Epi, class Sched>
; DEVI void gemm_phase(LAS unsigned char* lds, const Gemm g, const Sched& S, const Epi& E) {
;     ...
;         for (int t = 0; t < nt; t += 2) {
;             const bool last = (t == nt - 2);
;             const char* a1 = cA + (size_t)(t + 1) * kstep;
;             const char* a2 = last ? nA : cA + (size_t)(t + 2) * kstep; const char* b2 = last ? nB : cB + (size_t)(t + 2) * kstep;
;             const char* a3 = a2 + kstep; const char* b3 = b2 + kstep;
;             if (last && has_next) S.a_ready(nxt);
;             PG8_LDB(B0, 0, 0); PG8_LDB(B1, 0, 1); PG8_SCHED; PG8_LDA(At, 0, 0); PG8_STAGE(PG8_SA(1, 1), a1 + hstep, voffA);
;             PG8_WAIT_V(8); PG8_WAIT_L(0); PG8_BAR; PG8_MMA(0, 0, At, B0); PG8_MMA(0, 1, At, B1); PG8_BAR; PG8_SCHED;
;             PG8_LDA(At, 0, 1); PG8_STAGE(PG8_SB(0, 0), b2, voffB); PG8_STAGE(PG8_SB(0, 1), b2 + hstep, voffB); PG8_STAGE(PG8_SA(0, 0), a2, voffA);
;             PG8_WAIT_V(8); PG8_WAIT_L(0); PG8_BAR; PG8_MMA(1, 0, At, B0); PG8_MMA(1, 1, At, B1); PG8_BAR; PG8_SCHED;
.LBB0_1980:
	ds_read_b128 v[144:147], v171
	ds_read_b128 v[148:151], v171 offset:1024
	ds_read_b128 v[152:155], v171 offset:2048
	ds_read_b128 v[156:159], v171 offset:3072
	ds_read_b128 v[160:163], v172
	ds_read_b128 v[164:167], v172 offset:1024
	ds_read_b128 v[176:179], v172 offset:2048
	ds_read_b128 v[180:183], v172 offset:3072
	s_add_u32 s42, s40, 0xfffc0080
	s_addc_u32 s43, s41, -1
	s_cmp_eq_u32 s80, 12
	s_cselect_b32 s49, s29, s43
	s_cselect_b32 s48, s37, s42
	s_cselect_b32 s43, s27, s77
	s_cselect_b32 s42, s73, s76
	v_lshl_add_u64 v[216:217], s[40:41], 0, v[138:139]
	s_add_i32 m0, s39, 0xc000
	ds_read_b128 v[184:187], v173
	ds_read_b128 v[188:191], v173 offset:1024
	ds_read_b128 v[192:195], v173 offset:2048
	ds_read_b128 v[196:199], v173 offset:3072
	ds_read_b128 v[200:203], v173 offset:4096
	ds_read_b128 v[204:207], v173 offset:5120
	ds_read_b128 v[208:211], v173 offset:6144
	ds_read_b128 v[212:215], v173 offset:7168
	global_load_lds_dwordx4 v[216:217], off
	v_lshl_add_u64 v[216:217], s[40:41], 0, v[136:137]
	s_add_i32 m0, s39, 0xe000
	s_nop 0
	global_load_lds_dwordx4 v[216:217], off
	s_waitcnt vmcnt(8)
	s_waitcnt lgkmcnt(0)
	s_barrier
	s_waitcnt lgkmcnt(0)
	v_mfma_f32_16x16x32_bf16 v[124:127], v[144:147], v[184:187], v[124:127]
	v_mfma_f32_16x16x32_bf16 v[120:123], v[152:155], v[184:187], v[120:123]
	v_mfma_f32_16x16x32_bf16 v[108:111], v[144:147], v[192:195], v[108:111]
	v_mfma_f32_16x16x32_bf16 v[104:107], v[152:155], v[192:195], v[104:107]
	v_mfma_f32_16x16x32_bf16 v[92:95], v[144:147], v[200:203], v[92:95]
	v_mfma_f32_16x16x32_bf16 v[88:91], v[152:155], v[200:203], v[88:91]
	v_mfma_f32_16x16x32_bf16 v[76:79], v[144:147], v[208:211], v[76:79]
	v_mfma_f32_16x16x32_bf16 v[72:75], v[152:155], v[208:211], v[72:75]
	v_mfma_f32_16x16x32_bf16 v[124:127], v[148:151], v[188:191], v[124:127]
	v_mfma_f32_16x16x32_bf16 v[120:123], v[156:159], v[188:191], v[120:123]
	v_mfma_f32_16x16x32_bf16 v[108:111], v[148:151], v[196:199], v[108:111]
	v_mfma_f32_16x16x32_bf16 v[104:107], v[156:159], v[196:199], v[104:107]
	v_mfma_f32_16x16x32_bf16 v[92:95], v[148:151], v[204:207], v[92:95]
	v_mfma_f32_16x16x32_bf16 v[88:91], v[156:159], v[204:207], v[88:91]
	v_mfma_f32_16x16x32_bf16 v[76:79], v[148:151], v[212:215], v[76:79]
	v_mfma_f32_16x16x32_bf16 v[72:75], v[156:159], v[212:215], v[72:75]
	v_mfma_f32_16x16x32_bf16 v[116:119], v[160:163], v[184:187], v[116:119]
	v_mfma_f32_16x16x32_bf16 v[112:115], v[176:179], v[184:187], v[112:115]
	v_mfma_f32_16x16x32_bf16 v[100:103], v[160:163], v[192:195], v[100:103]
	v_mfma_f32_16x16x32_bf16 v[96:99], v[176:179], v[192:195], v[96:99]
	v_mfma_f32_16x16x32_bf16 v[84:87], v[160:163], v[200:203], v[84:87]
	v_mfma_f32_16x16x32_bf16 v[80:83], v[176:179], v[200:203], v[80:83]
	v_mfma_f32_16x16x32_bf16 v[68:71], v[160:163], v[208:211], v[68:71]
	v_mfma_f32_16x16x32_bf16 v[64:67], v[176:179], v[208:211], v[64:67]
	v_mfma_f32_16x16x32_bf16 v[116:119], v[164:167], v[188:191], v[116:119]
	v_mfma_f32_16x16x32_bf16 v[112:115], v[180:183], v[188:191], v[112:115]
	v_mfma_f32_16x16x32_bf16 v[100:103], v[164:167], v[196:199], v[100:103]
	v_mfma_f32_16x16x32_bf16 v[96:99], v[180:183], v[196:199], v[96:99]
	v_mfma_f32_16x16x32_bf16 v[84:87], v[164:167], v[204:207], v[84:87]
	v_mfma_f32_16x16x32_bf16 v[80:83], v[180:183], v[204:207], v[80:83]
	v_mfma_f32_16x16x32_bf16 v[68:71], v[164:167], v[212:215], v[68:71]
	v_mfma_f32_16x16x32_bf16 v[64:67], v[180:183], v[212:215], v[64:67]
	s_barrier
	s_add_i32 s81, s68, s57
	v_lshl_add_u64 v[216:217], s[42:43], 0, v[130:131]
	s_mov_b32 m0, s81
	ds_read_b128 v[184:187], v173 offset:16384
	ds_read_b128 v[188:191], v173 offset:17408
	ds_read_b128 v[192:195], v173 offset:18432
	ds_read_b128 v[196:199], v173 offset:19456
	ds_read_b128 v[200:203], v173 offset:20480
	ds_read_b128 v[204:207], v173 offset:21504
	ds_read_b128 v[208:211], v173 offset:22528
	ds_read_b128 v[212:215], v173 offset:23552
	global_load_lds_dwordx4 v[216:217], off
	s_add_i32 m0, s81, 0x2000
	s_add_u32 s82, s42, 0x40000
	v_lshl_add_u64 v[218:219], s[42:43], 0, v[134:135]
	s_addc_u32 s83, s43, 0
	s_add_i32 s81, s69, s57
	global_load_lds_dwordx4 v[218:219], off
	v_lshl_add_u64 v[220:221], s[82:83], 0, v[130:131]
	s_mov_b32 m0, s81
	v_lshl_add_u64 v[222:223], s[48:49], 0, v[132:133]
	global_load_lds_dwordx4 v[220:221], off
	v_lshl_add_u64 v[220:221], s[82:83], 0, v[134:135]
	s_add_i32 m0, s81, 0x2000
	s_nop 0
	global_load_lds_dwordx4 v[220:221], off
	v_lshl_add_u64 v[220:221], s[48:49], 0, v[128:129]
	s_mov_b32 m0, s39
	s_nop 0
	global_load_lds_dwordx4 v[220:221], off
	s_mov_b32 m0, s58
	s_nop 0
	global_load_lds_dwordx4 v[222:223], off
	s_waitcnt vmcnt(8)
	s_waitcnt lgkmcnt(0)
	s_barrier
; #define PG8_STAGE(bufoff, gbase, voff) do { _Pragma("unroll") for (int _i = 0; _i < 2; ++_i) \
;         __builtin_amdgcn_global_load_lds((const unsigned*)((const char*)(gbase) + (voff)[_i]), (LAS unsigned*)(lds + (bufoff) + ldsw + _i * 8192), 16, 0, 0); } while (0)
; #define PG8_LDA(dst, b, h) do { _Pragma("unroll") for (int m = 0; m < 4; ++m) _Pragma("unroll") for (int k = 0; k < 2; ++k) dst[m][k] = *(const LAS bf16x8*)(lds + PG8_SA(b, h) + aoff + m * 2048 + k * 1024); } while (0)
; #define PG8_LDB(dst, b, h) do { _Pragma("unroll") for (int n = 0; n < 2; ++n) _Pragma("unroll") for (int k = 0; k < 2; ++k) dst[n][k] = *(const LAS bf16x8*)(lds + PG8_SB(b, h) + boff + n * 2048 + k * 1024); } while (0)
; #define PG8_MMA(ai, bj, At, Bt) do { __builtin_amdgcn_s_setprio(1); _Pragma("unroll") for (int m = 0; m < 4; ++m) _Pragma("unroll") for (int n = 0; n < 2; ++n) _Pragma("unroll") for (int k = 0; k < 2; ++k) \
;         acc[ai][bj][m][n] = __builtin_amdgcn_mfma_f32_16x16x32_bf16(Bt[n][k], At[m][k], acc[ai][bj][m][n], 0, 0, 0); __builtin_amdgcn_s_setprio(0); } while (0)
; #define PG8_WAIT_V(n) asm volatile("s_waitcnt vmcnt(" #n ")" ::: "memory")
; #define PG8_WAIT_L(n) asm volatile("s_waitcnt lgkmcnt(" #n ")" ::: "memory")
; #define PG8_BAR __builtin_amdgcn_s_barrier()
; #define PG8_SCHED __builtin_amdgcn_sched_barrier(0)
; template <class Epi, class Sched>
; DEVI void gemm_phase(LAS unsigned char* lds, const Gemm g, const Sched& S, const Epi& E) {
;     ...
;             PG8_WAIT_V(8); PG8_WAIT_L(0); PG8_BAR; PG8_MMA(1, 0, At, B0); PG8_MMA(1, 1, At, B1); PG8_BAR; PG8_SCHED;
;             PG8_LDB(B0, 1, 0); PG8_LDB(B1, 1, 1); PG8_SCHED; PG8_LDA(At, 1, 0); PG8_STAGE(PG8_SA(0, 1), a2 + hstep, voffA);
;             PG8_WAIT_V(8); PG8_WAIT_L(0); PG8_BAR; PG8_MMA(0, 0, At, B0); PG8_MMA(0, 1, At, B1); PG8_BAR; PG8_SCHED;
	s_waitcnt lgkmcnt(0)
	v_mfma_f32_16x16x32_bf16 v[60:63], v[144:147], v[184:187], v[60:63]
	v_mfma_f32_16x16x32_bf16 v[56:59], v[152:155], v[184:187], v[56:59]
	v_mfma_f32_16x16x32_bf16 v[44:47], v[144:147], v[192:195], v[44:47]
	v_mfma_f32_16x16x32_bf16 v[40:43], v[152:155], v[192:195], v[40:43]
	v_mfma_f32_16x16x32_bf16 v[28:31], v[144:147], v[200:203], v[28:31]
	v_mfma_f32_16x16x32_bf16 v[24:27], v[152:155], v[200:203], v[24:27]
	v_mfma_f32_16x16x32_bf16 v[12:15], v[144:147], v[208:211], v[12:15]
	v_mfma_f32_16x16x32_bf16 v[8:11], v[152:155], v[208:211], v[8:11]
	v_mfma_f32_16x16x32_bf16 v[60:63], v[148:151], v[188:191], v[60:63]
	v_mfma_f32_16x16x32_bf16 v[56:59], v[156:159], v[188:191], v[56:59]
	v_mfma_f32_16x16x32_bf16 v[44:47], v[148:151], v[196:199], v[44:47]
	v_mfma_f32_16x16x32_bf16 v[40:43], v[156:159], v[196:199], v[40:43]
	v_mfma_f32_16x16x32_bf16 v[28:31], v[148:151], v[204:207], v[28:31]
	v_mfma_f32_16x16x32_bf16 v[24:27], v[156:159], v[204:207], v[24:27]
	v_mfma_f32_16x16x32_bf16 v[12:15], v[148:151], v[212:215], v[12:15]
	v_mfma_f32_16x16x32_bf16 v[8:11], v[156:159], v[212:215], v[8:11]
	v_mfma_f32_16x16x32_bf16 v[52:55], v[160:163], v[184:187], v[52:55]
	v_mfma_f32_16x16x32_bf16 v[48:51], v[176:179], v[184:187], v[48:51]
	v_mfma_f32_16x16x32_bf16 v[36:39], v[160:163], v[192:195], v[36:39]
	v_mfma_f32_16x16x32_bf16 v[32:35], v[176:179], v[192:195], v[32:35]
	v_mfma_f32_16x16x32_bf16 v[20:23], v[160:163], v[200:203], v[20:23]
	v_mfma_f32_16x16x32_bf16 v[16:19], v[176:179], v[200:203], v[16:19]
	v_mfma_f32_16x16x32_bf16 v[4:7], v[160:163], v[208:211], v[4:7]
	v_mfma_f32_16x16x32_bf16 v[0:3], v[176:179], v[208:211], v[0:3]
	v_mfma_f32_16x16x32_bf16 v[52:55], v[164:167], v[188:191], v[52:55]
	v_mfma_f32_16x16x32_bf16 v[48:51], v[180:183], v[188:191], v[48:51]
	v_mfma_f32_16x16x32_bf16 v[36:39], v[164:167], v[196:199], v[36:39]
	v_mfma_f32_16x16x32_bf16 v[32:35], v[180:183], v[196:199], v[32:35]
	v_mfma_f32_16x16x32_bf16 v[20:23], v[164:167], v[204:207], v[20:23]
	v_mfma_f32_16x16x32_bf16 v[16:19], v[180:183], v[204:207], v[16:19]
	v_mfma_f32_16x16x32_bf16 v[4:7], v[164:167], v[212:215], v[4:7]
	v_mfma_f32_16x16x32_bf16 v[0:3], v[180:183], v[212:215], v[0:3]
	s_barrier
	s_add_i32 s81, 0, 0x18000
	s_add_i32 s82, 0, 0x1c000
	v_add_u32_e32 v156, s81, v169
	v_add_u32_e32 v175, s82, v169
	ds_read_b128 v[144:147], v156
	ds_read_b128 v[148:151], v156 offset:1024
	ds_read_b128 v[152:155], v156 offset:2048
	ds_read_b128 v[156:159], v156 offset:3072
	ds_read_b128 v[160:163], v175
	ds_read_b128 v[164:167], v175 offset:1024
	ds_read_b128 v[176:179], v175 offset:2048
	ds_read_b128 v[180:183], v175 offset:3072
	s_add_u32 s48, s48, 0x40000
	s_addc_u32 s49, s49, 0
	s_mov_b32 m0, s59
	v_lshl_add_u64 v[224:225], s[48:49], 0, v[128:129]
	ds_read_b128 v[184:187], v173 offset:32768
	ds_read_b128 v[188:191], v173 offset:33792
	ds_read_b128 v[192:195], v173 offset:34816
	ds_read_b128 v[196:199], v173 offset:35840
	ds_read_b128 v[200:203], v173 offset:36864
	ds_read_b128 v[204:207], v173 offset:37888
	ds_read_b128 v[208:211], v173 offset:38912
	ds_read_b128 v[212:215], v173 offset:39936
	global_load_lds_dwordx4 v[224:225], off
	v_lshl_add_u64 v[224:225], s[48:49], 0, v[132:133]
	s_mov_b32 m0, s60
	s_nop 0
	global_load_lds_dwordx4 v[224:225], off
	s_waitcnt vmcnt(8)
	s_waitcnt lgkmcnt(0)
	s_barrier
	s_waitcnt lgkmcnt(0)
	v_mfma_f32_16x16x32_bf16 v[124:127], v[144:147], v[184:187], v[124:127]
	v_mfma_f32_16x16x32_bf16 v[120:123], v[152:155], v[184:187], v[120:123]
	v_mfma_f32_16x16x32_bf16 v[108:111], v[144:147], v[192:195], v[108:111]
	v_mfma_f32_16x16x32_bf16 v[104:107], v[152:155], v[192:195], v[104:107]
	v_mfma_f32_16x16x32_bf16 v[92:95], v[144:147], v[200:203], v[92:95]
	v_mfma_f32_16x16x32_bf16 v[88:91], v[152:155], v[200:203], v[88:91]
	v_mfma_f32_16x16x32_bf16 v[76:79], v[144:147], v[208:211], v[76:79]
	v_mfma_f32_16x16x32_bf16 v[72:75], v[152:155], v[208:211], v[72:75]
	v_mfma_f32_16x16x32_bf16 v[124:127], v[148:151], v[188:191], v[124:127]
	v_mfma_f32_16x16x32_bf16 v[120:123], v[156:159], v[188:191], v[120:123]
	v_mfma_f32_16x16x32_bf16 v[108:111], v[148:151], v[196:199], v[108:111]
	v_mfma_f32_16x16x32_bf16 v[104:107], v[156:159], v[196:199], v[104:107]
	v_mfma_f32_16x16x32_bf16 v[92:95], v[148:151], v[204:207], v[92:95]
	v_mfma_f32_16x16x32_bf16 v[88:91], v[156:159], v[204:207], v[88:91]
	v_mfma_f32_16x16x32_bf16 v[76:79], v[148:151], v[212:215], v[76:79]
	v_mfma_f32_16x16x32_bf16 v[72:75], v[156:159], v[212:215], v[72:75]
	v_mfma_f32_16x16x32_bf16 v[116:119], v[160:163], v[184:187], v[116:119]
	v_mfma_f32_16x16x32_bf16 v[112:115], v[176:179], v[184:187], v[112:115]
	v_mfma_f32_16x16x32_bf16 v[100:103], v[160:163], v[192:195], v[100:103]
	v_mfma_f32_16x16x32_bf16 v[96:99], v[176:179], v[192:195], v[96:99]
	v_mfma_f32_16x16x32_bf16 v[84:87], v[160:163], v[200:203], v[84:87]
	v_mfma_f32_16x16x32_bf16 v[80:83], v[176:179], v[200:203], v[80:83]
	v_mfma_f32_16x16x32_bf16 v[68:71], v[160:163], v[208:211], v[68:71]
	v_mfma_f32_16x16x32_bf16 v[64:67], v[176:179], v[208:211], v[64:67]
	v_mfma_f32_16x16x32_bf16 v[116:119], v[164:167], v[188:191], v[116:119]
	v_mfma_f32_16x16x32_bf16 v[112:115], v[180:183], v[188:191], v[112:115]
	v_mfma_f32_16x16x32_bf16 v[100:103], v[164:167], v[196:199], v[100:103]
	v_mfma_f32_16x16x32_bf16 v[96:99], v[180:183], v[196:199], v[96:99]
	v_mfma_f32_16x16x32_bf16 v[84:87], v[164:167], v[204:207], v[84:87]
	v_mfma_f32_16x16x32_bf16 v[80:83], v[180:183], v[204:207], v[80:83]
	v_mfma_f32_16x16x32_bf16 v[68:71], v[164:167], v[212:215], v[68:71]
	v_mfma_f32_16x16x32_bf16 v[64:67], v[180:183], v[212:215], v[64:67]
	s_barrier
; #define PG8_STAGE(bufoff, gbase, voff) do { _Pragma("unroll") for (int _i = 0; _i < 2; ++_i) \
;         __builtin_amdgcn_global_load_lds((const unsigned*)((const char*)(gbase) + (voff)[_i]), (LAS unsigned*)(lds + (bufoff) + ldsw + _i * 8192), 16, 0, 0); } while (0)
; #define PG8_LDA(dst, b, h) do { _Pragma("unroll") for (int m = 0; m < 4; ++m) _Pragma("unroll") for (int k = 0; k < 2; ++k) dst[m][k] = *(const LAS bf16x8*)(lds + PG8_SA(b, h) + aoff + m * 2048 + k * 1024); } while (0)
; #define PG8_MMA(ai, bj, At, Bt) do { __builtin_amdgcn_s_setprio(1); _Pragma("unroll") for (int m = 0; m < 4; ++m) _Pragma("unroll") for (int n = 0; n < 2; ++n) _Pragma("unroll") for (int k = 0; k < 2; ++k) \
;         acc[ai][bj][m][n] = __builtin_amdgcn_mfma_f32_16x16x32_bf16(Bt[n][k], At[m][k], acc[ai][bj][m][n], 0, 0, 0); __builtin_amdgcn_s_setprio(0); } while (0)
; #define PG8_WAIT_V(n) asm volatile("s_waitcnt vmcnt(" #n ")" ::: "memory")
; #define PG8_WAIT_L(n) asm volatile("s_waitcnt lgkmcnt(" #n ")" ::: "memory")
; #define PG8_BAR __builtin_amdgcn_s_barrier()
; #define PG8_SCHED __builtin_amdgcn_sched_barrier(0)
; template <class Epi, class Sched>
; DEVI void gemm_phase(LAS unsigned char* lds, const Gemm g, const Sched& S, const Epi& E) {
;     ...
;             PG8_LDA(At, 1, 1); PG8_STAGE(PG8_SB(1, 0), b3, voffB); PG8_STAGE(PG8_SB(1, 1), b3 + hstep, voffB); PG8_STAGE(PG8_SA(1, 0), a3, voffA);
;             PG8_WAIT_V(8); PG8_WAIT_L(0); PG8_BAR; PG8_MMA(1, 0, At, B0); PG8_MMA(1, 1, At, B1); PG8_BAR; PG8_SCHED;
;         }
;         if (wr == 0) PG8_BAR;
	s_add_i32 s48, s81, s57
	v_lshl_add_u64 v[216:217], v[216:217], 0, s[18:19]
	s_mov_b32 m0, s48
	ds_read_b128 v[184:187], v173 offset:49152
	ds_read_b128 v[188:191], v173 offset:50176
	ds_read_b128 v[192:195], v173 offset:51200
	ds_read_b128 v[196:199], v173 offset:52224
	ds_read_b128 v[200:203], v173 offset:53248
	ds_read_b128 v[204:207], v173 offset:54272
	ds_read_b128 v[208:211], v173 offset:55296
	ds_read_b128 v[212:215], v173 offset:56320
	global_load_lds_dwordx4 v[216:217], off
	s_add_i32 m0, s48, 0x2000
	s_add_u32 s42, s42, 0x40080
	v_lshl_add_u64 v[216:217], v[218:219], 0, s[18:19]
	s_addc_u32 s43, s43, 0
	s_add_i32 s48, s82, s57
	global_load_lds_dwordx4 v[216:217], off
	v_lshl_add_u64 v[216:217], s[42:43], 0, v[130:131]
	s_mov_b32 m0, s48
	s_nop 0
	global_load_lds_dwordx4 v[216:217], off
	v_lshl_add_u64 v[216:217], s[42:43], 0, v[134:135]
	s_add_i32 m0, s48, 0x2000
	s_nop 0
	global_load_lds_dwordx4 v[216:217], off
	v_lshl_add_u64 v[216:217], v[220:221], 0, s[18:19]
	s_mov_b32 m0, s62
	s_nop 0
	global_load_lds_dwordx4 v[216:217], off
	v_lshl_add_u64 v[216:217], v[222:223], 0, s[18:19]
	s_mov_b32 m0, s63
	s_nop 0
	global_load_lds_dwordx4 v[216:217], off
	s_waitcnt vmcnt(8)
	s_waitcnt lgkmcnt(0)
	s_barrier
	s_waitcnt lgkmcnt(0)
	v_mfma_f32_16x16x32_bf16 v[60:63], v[144:147], v[184:187], v[60:63]
	v_mfma_f32_16x16x32_bf16 v[56:59], v[152:155], v[184:187], v[56:59]
	v_mfma_f32_16x16x32_bf16 v[44:47], v[144:147], v[192:195], v[44:47]
	v_mfma_f32_16x16x32_bf16 v[40:43], v[152:155], v[192:195], v[40:43]
	v_mfma_f32_16x16x32_bf16 v[28:31], v[144:147], v[200:203], v[28:31]
	v_mfma_f32_16x16x32_bf16 v[24:27], v[152:155], v[200:203], v[24:27]
	v_mfma_f32_16x16x32_bf16 v[12:15], v[144:147], v[208:211], v[12:15]
	v_mfma_f32_16x16x32_bf16 v[8:11], v[152:155], v[208:211], v[8:11]
	v_mfma_f32_16x16x32_bf16 v[60:63], v[148:151], v[188:191], v[60:63]
	v_mfma_f32_16x16x32_bf16 v[56:59], v[156:159], v[188:191], v[56:59]
	v_mfma_f32_16x16x32_bf16 v[44:47], v[148:151], v[196:199], v[44:47]
	v_mfma_f32_16x16x32_bf16 v[40:43], v[156:159], v[196:199], v[40:43]
	v_mfma_f32_16x16x32_bf16 v[28:31], v[148:151], v[204:207], v[28:31]
	v_mfma_f32_16x16x32_bf16 v[24:27], v[156:159], v[204:207], v[24:27]
	v_mfma_f32_16x16x32_bf16 v[12:15], v[148:151], v[212:215], v[12:15]
	v_mfma_f32_16x16x32_bf16 v[8:11], v[156:159], v[212:215], v[8:11]
	v_mfma_f32_16x16x32_bf16 v[52:55], v[160:163], v[184:187], v[52:55]
	v_mfma_f32_16x16x32_bf16 v[48:51], v[176:179], v[184:187], v[48:51]
	v_mfma_f32_16x16x32_bf16 v[36:39], v[160:163], v[192:195], v[36:39]
	v_mfma_f32_16x16x32_bf16 v[32:35], v[176:179], v[192:195], v[32:35]
	v_mfma_f32_16x16x32_bf16 v[20:23], v[160:163], v[200:203], v[20:23]
	v_mfma_f32_16x16x32_bf16 v[16:19], v[176:179], v[200:203], v[16:19]
	v_mfma_f32_16x16x32_bf16 v[4:7], v[160:163], v[208:211], v[4:7]
	v_mfma_f32_16x16x32_bf16 v[0:3], v[176:179], v[208:211], v[0:3]
	v_mfma_f32_16x16x32_bf16 v[52:55], v[164:167], v[188:191], v[52:55]
	v_mfma_f32_16x16x32_bf16 v[48:51], v[180:183], v[188:191], v[48:51]
	v_mfma_f32_16x16x32_bf16 v[36:39], v[164:167], v[196:199], v[36:39]
	v_mfma_f32_16x16x32_bf16 v[32:35], v[180:183], v[196:199], v[32:35]
	v_mfma_f32_16x16x32_bf16 v[20:23], v[164:167], v[204:207], v[20:23]
	v_mfma_f32_16x16x32_bf16 v[16:19], v[180:183], v[204:207], v[16:19]
	v_mfma_f32_16x16x32_bf16 v[4:7], v[164:167], v[212:215], v[4:7]
	v_mfma_f32_16x16x32_bf16 v[0:3], v[180:183], v[212:215], v[0:3]
	s_barrier
	s_add_i32 s80, s80, 2
	s_add_u32 s76, s76, 0x100
	s_addc_u32 s77, s77, 0
	s_add_u32 s40, s40, 0x100
	s_addc_u32 s41, s41, 0
	s_cmp_gt_u32 s80, 13
	s_cbranch_scc0 .LBB0_1980
	s_and_b64 vcc, exec, s[20:21]
	s_cbranch_vccz .LBB0_1983
	s_barrier

; DEVI int tid_() { int t = threadIdx.x; asm volatile("" : "+v"(t)); return t; }
; DEVI int bid_() { int t = blockIdx.x; asm volatile("" : "+s"(t)); return t; }
; DEVI int gdim_() { int t = gridDim.x; asm volatile("" : "+s"(t)); return t; }
; DEVI void ffn_fixup_panel(int pm, bf16_t* H, const float* cw, const float* cb, const float* tailg, const float* headpg, const float* headup) {
;     for (int it = tid_(); it < 4 * 2 * (DFF / 4); it += 512) {
;         const int j = (it % (DFF / 4)) * 4, be = it / (DFF / 4), e = be & 1, blk = pm * 4 + (be >> 1);
;         const int row = blk * 64 + e, t = row & (SEQ - 1);
; template <int PH>
; DEVI void run_phase(const Params& p, unsigned char* smem) {
;     ...
;             pg8::Gemm g{(const bf16_t*)(ws + WS_H), wbase + (size_t)16 * MiB / 2, MROWS, DM, DFF}; pg8::StaticOrder S; S.init(MROWS, DM, gdim_(), bid_());
;             pg8::Unit u;
;             for (int i = 0; S.next(i, u); ++i) ffn_fixup_panel(u.pm, (bf16_t*)(ws + WS_H), p.in[28] + (size_t)l * 3 * DFF, p.in[29] + (size_t)l * DFF, (const float*)(ws + WS_TAIL), (const float*)(ws + WS_HPG), (const float*)(ws + WS_HUP));
.Lsprio_sp21:
	s_add_u32 s6, s2, 0x10a00000
	s_mov_b32 s25, s89
	v_readlane_b32 s27, v249, 0
	s_addc_u32 s7, s3, 0
	s_ashr_i32 s33, s25, 31
	s_ashr_i32 s40, s27, 31
	s_add_u32 s4, s2, 0xa800000
	s_addc_u32 s5, s3, 0
	s_add_u32 s8, s2, 0xb300000
	s_addc_u32 s9, s3, 0
	v_readlane_b32 s56, v249, 37
	s_add_u32 s10, s2, 0xbe00000
	v_readlane_b32 s64, v249, 45
	v_readlane_b32 s65, v249, 46
	s_addc_u32 s11, s3, 0
	v_readlane_b32 s66, v249, 47
	v_readlane_b32 s67, v249, 48
	s_mov_b64 s[44:45], s[64:65]
	s_mov_b64 s[46:47], s[66:67]
	s_add_u32 s12, s44, 0x13400
	s_addc_u32 s13, s45, 0
	v_readlane_b32 s44, v249, 59
	s_mov_b32 s22, 0
	v_mov_b64_e32 v[20:21], 0x1ff
	s_movk_i32 s23, 0x1600
	s_mov_b32 s24, 0x2e8ba2e9
	s_movk_i32 s26, 0x2c00
	s_movk_i32 s28, 0x5800
	s_movk_i32 s29, 0x13ff
	v_mov_b32_e32 v28, 0
	v_readlane_b32 s45, v249, 60
	v_readlane_b32 s46, v249, 61
	v_readlane_b32 s47, v249, 62
	v_readlane_b32 s57, v249, 38
	v_readlane_b32 s58, v249, 39
	v_readlane_b32 s59, v249, 40
	v_readlane_b32 s60, v249, 41
	v_readlane_b32 s61, v249, 42
	v_readlane_b32 s62, v249, 43
	v_readlane_b32 s63, v249, 44
	v_readlane_b32 s68, v249, 49
	v_readlane_b32 s69, v249, 50
	v_readlane_b32 s70, v249, 51
	v_readlane_b32 s71, v249, 52
	s_branch .LBB0_2152

; DEVI int tid_() { int t = threadIdx.x; asm volatile("" : "+v"(t)); return t; }
; #define PG8_STAGE(bufoff, gbase, voff) do { _Pragma("unroll") for (int _i = 0; _i < 2; ++_i) \
;         __builtin_amdgcn_global_load_lds((const unsigned*)((const char*)(gbase) + (voff)[_i]), (LAS unsigned*)(lds + (bufoff) + ldsw + _i * 8192), 16, 0, 0); } while (0)
; #define PG8_WAIT_V(n) asm volatile("s_waitcnt vmcnt(" #n ")" ::: "memory")
; #define PG8_BAR __builtin_amdgcn_s_barrier()
; template <class Epi, class Sched>
; DEVI void gemm_phase(LAS unsigned char* lds, const Gemm g, const Sched& S, const Epi& E) {
;     const int tid = tid_(), wid = __builtin_amdgcn_readfirstlane(tid >> 6), lane = tid & 63, wr = wid >> 2, wc = wid & 3, fr = lane & 15, fq = lane >> 4;
;     const int K = g.K, nt = K / BK;
;     unsigned voffA[2], voffB[2];
; #pragma unroll
;     for (int i = 0; i < 2; ++i) { int R, C; stage_rc(tid * 16 + i * 8192, R, C); const int Rb = Epi::PERM ? ((R & ~31) + perm32(R & 31)) : R;
;         voffA[i] = (unsigned)(R * K + C) * 2u; voffB[i] = (unsigned)(Rb * K + C) * 2u; }
;     const size_t kstep = (size_t)(BK * 2);
;     const size_t hstep = (size_t)HALF * K * 2;
;     const size_t tstep = 2 * hstep;
;     const unsigned ldsw = (unsigned)wid * 1024u;
;     const int aoff = lds_byte(wr * 64 + fr, fq * 8), boff = lds_byte(wc * 32 + fr, fq * 8);
;     ...
;     Unit cur, nxt; int ui = 0;
;     if (!S.next(0, cur)) return;
;     f32x4 acc[2][2][4][2];
; #pragma unroll
;     for (int a = 0; a < 2; ++a)
; #pragma unroll
;         for (int b = 0; b < 2; ++b)
; #pragma unroll
;             for (int m = 0; m < 4; ++m)
; #pragma unroll
;                 for (int n = 0; n < 2; ++n) acc[a][b][m][n] = (f32x4){0.f, 0.f, 0.f, 0.f};
;     bf16x8 At[4][2], B0[2][2], B1[2][2];
;     const char* cA = (const char*)g.A + (size_t)cur.pm * tstep; const char* cB = (const char*)g.Bt + (size_t)cur.pn * tstep;
;     S.a_ready(cur);
;     PG8_STAGE(PG8_SB(0, 0), cB, voffB); PG8_STAGE(PG8_SB(0, 1), cB + hstep, voffB); PG8_STAGE(PG8_SA(0, 0), cA, voffA); PG8_STAGE(PG8_SA(0, 1), cA + hstep, voffA);
;     if (wr == 1) PG8_BAR;
;     PG8_WAIT_V(2); PG8_BAR;
;     PG8_STAGE(PG8_SB(1, 0), cB + kstep, voffB); PG8_STAGE(PG8_SA(1, 0), cA + kstep, voffA); PG8_STAGE(PG8_SB(1, 1), cB + hstep + kstep, voffB);
;     PG8_WAIT_V(6); PG8_BAR;
.Lsprio_sp22:
	s_cmpk_gt_i32 s33, 0x2ff
	v_readfirstlane_b32 s15, v8
	s_cbranch_scc1 .LBB0_2280
	v_lshlrev_b32_e32 v0, 4, v8
	v_add_u32_e32 v1, 0x2000, v0
	v_ashrrev_i32_e32 v2, 31, v1
	v_lshrrev_b32_e32 v2, 22, v2
	v_add_u32_e32 v2, v1, v2
	v_ashrrev_i32_e32 v9, 10, v2
	v_mul_i32_i24_e32 v2, 0x400, v9
	v_sub_u32_e32 v1, v1, v2
	v_lshrrev_b32_e32 v2, 4, v1
	v_bitop3_b32 v1, v2, v1, 32 bitop3:0x6c
	v_ashrrev_i32_e32 v2, 31, v1
	v_lshrrev_b32_e32 v2, 26, v2
	v_add_u32_e32 v2, v1, v2
	v_lshlrev_b32_e32 v3, 3, v9
	v_ashrrev_i32_e32 v10, 6, v2
	v_and_b32_e32 v3, -16, v3
	v_add_u32_e32 v3, v10, v3
	v_and_b32_e32 v4, 3, v10
	s_mov_b32 s2, 0x1fffe0
	v_lshrrev_b32_e32 v5, 2, v3
	v_lshlrev_b32_e32 v6, 1, v3
	v_and_b32_e32 v2, 0xc0, v2
	v_and_or_b32 v4, v3, s2, v4
	v_and_b32_e32 v5, 4, v5
	v_and_b32_e32 v6, 24, v6
	v_sub_u32_e32 v1, v1, v2
	v_mov_b32_e32 v2, 1
	v_or3_b32 v4, v4, v5, v6
	v_lshlrev_b32_e32 v5, 5, v9
	v_ashrrev_i16_sdwa v1, v2, sext(v1) dst_sel:DWORD dst_unused:UNUSED_PAD src0_sel:DWORD src1_sel:BYTE_0
	v_and_b32_e32 v5, 32, v5
	v_bfe_i32 v11, v1, 0, 16
	v_add_lshl_u32 v1, v5, v11, 1
	v_lshl_add_u32 v160, v4, 11, v1
	v_lshl_add_u32 v162, v3, 11, v1
	v_bfe_i32 v1, v8, 27, 1
	v_lshrrev_b32_e32 v1, 22, v1
	v_add_u32_e32 v1, v0, v1
	v_and_b32_e32 v1, 0xfffffc00, v1
	v_sub_u32_e32 v0, v0, v1
	v_lshrrev_b32_e32 v1, 4, v0
	v_bitop3_b32 v1, v1, v0, 32 bitop3:0x6c
	v_ashrrev_i32_e32 v0, 31, v0
	v_lshrrev_b32_e32 v0, 26, v0
	v_add_u32_e32 v0, v1, v0
	v_ashrrev_i32_e32 v12, 6, v0
	v_ashrrev_i32_e32 v0, 31, v8
	v_lshrrev_b32_e32 v0, 26, v0
	v_add_u32_e32 v0, v8, v0
	s_add_u32 s36, s0, 0x5200000
	v_ashrrev_i32_e32 v13, 6, v0
	s_addc_u32 s37, s1, 0
	v_lshlrev_b32_e32 v0, 3, v13
	s_add_u32 s38, s0, 0x6800000
	v_and_b32_e32 v0, -16, v0
	s_addc_u32 s39, s1, 0
	v_add_u32_e32 v0, v12, v0
	v_and_b32_e32 v3, 3, v12
	s_ashr_i32 s41, s33, 31
	v_and_or_b32 v3, v0, s2, v3
	s_lshr_b32 s2, s41, 29
	s_add_i32 s2, s33, s2
	s_ashr_i32 s12, s15, 6
	s_ashr_i32 s3, s2, 3
	s_and_b32 s2, s2, -8
	s_ashr_i32 s16, s15, 8
	s_lshl_b32 s40, s12, 10
	s_sub_i32 s2, s33, s2
	s_cmp_lt_i32 s2, 0
	s_movk_i32 s42, 0x61
	s_cselect_b32 s4, s42, 0x60
	s_mul_i32 s2, s4, s2
	s_add_i32 s2, s2, s3
	s_mul_hi_i32 s3, s2, 0x2aaaaaab
	s_lshr_b32 s4, s3, 31
	s_ashr_i32 s3, s3, 3
	s_add_i32 s3, s3, s4
	s_lshl_b32 s4, s3, 3
	s_mul_i32 s3, s3, 48
	s_sub_i32 s2, s2, s3
	s_bfe_i32 s3, s2, 0x80000
	s_bfe_u32 s3, s3, 0x3000c
	s_add_i32 s3, s2, s3
	s_bfe_i32 s5, s3, 0x80000
	s_and_b32 s3, s3, 0xf8
	v_lshrrev_b32_e32 v4, 2, v0
	v_lshlrev_b32_e32 v5, 1, v0
	s_sub_i32 s2, s2, s3
	v_and_b32_e32 v4, 4, v4
	v_and_b32_e32 v5, 24, v5
	s_sext_i32_i16 s5, s5
	s_sext_i32_i8 s2, s2
	v_or3_b32 v3, v3, v4, v5
	v_mul_i32_i24_e32 v5, 64, v12
	s_lshr_b32 s14, s5, 3
	s_add_i32 s26, s4, s2
	v_sub_u32_e32 v1, v1, v5
	s_ashr_i32 s27, s26, 31
	s_bfe_i64 s[4:5], s[14:15], 0x100000
	v_lshlrev_b32_e32 v4, 5, v13
	v_ashrrev_i16_sdwa v1, v2, sext(v1) dst_sel:DWORD dst_unused:UNUSED_PAD src0_sel:DWORD src1_sel:BYTE_0
	s_lshl_b64 s[2:3], s[26:27], 19
	s_lshl_b64 s[4:5], s[4:5], 19
	v_and_b32_e32 v4, 32, v4
	v_bfe_i32 v14, v1, 0, 16
	s_add_u32 s28, s36, s4
	v_add_lshl_u32 v1, v4, v14, 1
	s_addc_u32 s29, s37, s5
	s_add_i32 s27, s40, 0
	v_lshl_add_u32 v164, v3, 11, v1
	s_add_i32 m0, s27, 0x10000
	v_lshl_add_u32 v166, v0, 11, v1
	global_load_lds_dwordx4 v164, s[28:29]
	s_add_i32 m0, s27, 0x12000
	s_add_u32 s4, s28, 0x40000
	global_load_lds_dwordx4 v160, s[28:29]
	s_addc_u32 s5, s29, 0
	s_add_i32 m0, s27, 0x14000
	v_mov_b32_e32 v165, 0
	global_load_lds_dwordx4 v164, s[4:5]
	s_add_i32 m0, s27, 0x16000
	s_add_u32 s30, s38, s2
	s_addc_u32 s31, s39, s3
	s_add_i32 s43, s27, 0x2000
	global_load_lds_dwordx4 v160, s[4:5]
	s_mov_b32 m0, s27
	s_add_u32 s2, s30, 0x40000
	global_load_lds_dwordx4 v166, s[30:31]
	s_mov_b32 m0, s43
	s_addc_u32 s3, s31, 0
	s_add_i32 s48, s27, 0x4000
	global_load_lds_dwordx4 v162, s[30:31]
	s_mov_b32 m0, s48
	s_add_i32 s49, s27, 0x6000
	global_load_lds_dwordx4 v166, s[2:3]
	s_mov_b32 m0, s49
	v_mov_b32_e32 v161, v165
	global_load_lds_dwordx4 v162, s[2:3]
	v_mov_b32_e32 v167, v165
	v_mov_b32_e32 v163, v165
	s_cmp_eq_u32 s16, 1
	s_mov_b32 s50, 0
	v_lshl_add_u64 v[6:7], s[28:29], 0, v[164:165]
	v_lshl_add_u64 v[4:5], s[28:29], 0, v[160:161]
	v_lshl_add_u64 v[0:1], s[30:31], 0, v[166:167]
	s_cselect_b64 s[2:3], -1, 0
	s_cmp_lg_u32 s16, 1
	v_lshl_add_u64 v[2:3], s[30:31], 0, v[162:163]
	s_cbranch_scc1 .LBB0_2267
	s_barrier

; #define PG8_STAGE(bufoff, gbase, voff) do { _Pragma("unroll") for (int _i = 0; _i < 2; ++_i) \
;         __builtin_amdgcn_global_load_lds((const unsigned*)((const char*)(gbase) + (voff)[_i]), (LAS unsigned*)(lds + (bufoff) + ldsw + _i * 8192), 16, 0, 0); } while (0)
; #define PG8_LDA(dst, b, h) do { _Pragma("unroll") for (int m = 0; m < 4; ++m) _Pragma("unroll") for (int k = 0; k < 2; ++k) dst[m][k] = *(const LAS bf16x8*)(lds + PG8_SA(b, h) + aoff + m * 2048 + k * 1024); } while (0)
; #define PG8_LDB(dst, b, h) do { _Pragma("unroll") for (int n = 0; n < 2; ++n) _Pragma("unroll") for (int k = 0; k < 2; ++k) dst[n][k] = *(const LAS bf16x8*)(lds + PG8_SB(b, h) + boff + n * 2048 + k * 1024); } while (0)
; #define PG8_MMA(ai, bj, At, Bt) do { __builtin_amdgcn_s_setprio(1); _Pragma("unroll") for (int m = 0; m < 4; ++m) _Pragma("unroll") for (int n = 0; n < 2; ++n) _Pragma("unroll") for (int k = 0; k < 2; ++k) \
;         acc[ai][bj][m][n] = __builtin_amdgcn_mfma_f32_16x16x32_bf16(Bt[n][k], At[m][k], acc[ai][bj][m][n], 0, 0, 0); __builtin_amdgcn_s_setprio(0); } while (0)
; #define PG8_WAIT_V(n) asm volatile("s_waitcnt vmcnt(" #n ")" ::: "memory")
; #define PG8_WAIT_L(n) asm volatile("s_waitcnt lgkmcnt(" #n ")" ::: "memory")
; #define PG8_BAR __builtin_amdgcn_s_barrier()
; #define PG8_SCHED __builtin_amdgcn_sched_barrier(0)
; template <class Epi, class Sched>
; DEVI void gemm_phase(LAS unsigned char* lds, const Gemm g, const Sched& S, const Epi& E) {
;     ...
;         for (int t = 0; t < nt; t += 2) {
;             const bool last = (t == nt - 2);
;             const char* a1 = cA + (size_t)(t + 1) * kstep;
;             const char* a2 = last ? nA : cA + (size_t)(t + 2) * kstep; const char* b2 = last ? nB : cB + (size_t)(t + 2) * kstep;
;             const char* a3 = a2 + kstep; const char* b3 = b2 + kstep;
;             if (last && has_next) S.a_ready(nxt);
;             PG8_LDB(B0, 0, 0); PG8_LDB(B1, 0, 1); PG8_SCHED; PG8_LDA(At, 0, 0); PG8_STAGE(PG8_SA(1, 1), a1 + hstep, voffA);
;             PG8_WAIT_V(8); PG8_WAIT_L(0); PG8_BAR; PG8_MMA(0, 0, At, B0); PG8_MMA(0, 1, At, B1); PG8_BAR; PG8_SCHED;
;             PG8_LDA(At, 0, 1); PG8_STAGE(PG8_SB(0, 0), b2, voffB); PG8_STAGE(PG8_SB(0, 1), b2 + hstep, voffB); PG8_STAGE(PG8_SA(0, 0), a2, voffA);
;             PG8_WAIT_V(8); PG8_WAIT_L(0); PG8_BAR; PG8_MMA(1, 0, At, B0); PG8_MMA(1, 1, At, B1); PG8_BAR; PG8_SCHED;
.LBB0_2633:
	ds_read_b128 v[144:147], v171
	ds_read_b128 v[148:151], v171 offset:1024
	ds_read_b128 v[152:155], v171 offset:2048
	ds_read_b128 v[156:159], v171 offset:3072
	ds_read_b128 v[160:163], v172
	ds_read_b128 v[164:167], v172 offset:1024
	ds_read_b128 v[176:179], v172 offset:2048
	ds_read_b128 v[180:183], v172 offset:3072
	s_add_u32 s42, s40, 0xfffc0080
	s_addc_u32 s43, s41, -1
	s_cmp_eq_u32 s68, 12
	s_cselect_b32 s49, s29, s43
	s_cselect_b32 s48, s37, s42
	s_cselect_b32 s43, s27, s67
	s_cselect_b32 s42, s65, s66
	v_lshl_add_u64 v[216:217], s[40:41], 0, v[138:139]
	s_add_i32 m0, s39, 0xc000
	ds_read_b128 v[184:187], v173
	ds_read_b128 v[188:191], v173 offset:1024
	ds_read_b128 v[192:195], v173 offset:2048
	ds_read_b128 v[196:199], v173 offset:3072
	ds_read_b128 v[200:203], v173 offset:4096
	ds_read_b128 v[204:207], v173 offset:5120
	ds_read_b128 v[208:211], v173 offset:6144
	ds_read_b128 v[212:215], v173 offset:7168
	global_load_lds_dwordx4 v[216:217], off
	v_lshl_add_u64 v[216:217], s[40:41], 0, v[136:137]
	s_add_i32 m0, s39, 0xe000
	s_nop 0
	global_load_lds_dwordx4 v[216:217], off
	s_waitcnt vmcnt(8)
	s_waitcnt lgkmcnt(0)
	s_barrier
	s_waitcnt lgkmcnt(0)
	v_mfma_f32_16x16x32_bf16 v[124:127], v[144:147], v[184:187], v[124:127]
	v_mfma_f32_16x16x32_bf16 v[120:123], v[152:155], v[184:187], v[120:123]
	v_mfma_f32_16x16x32_bf16 v[108:111], v[144:147], v[192:195], v[108:111]
	v_mfma_f32_16x16x32_bf16 v[104:107], v[152:155], v[192:195], v[104:107]
	v_mfma_f32_16x16x32_bf16 v[92:95], v[144:147], v[200:203], v[92:95]
	v_mfma_f32_16x16x32_bf16 v[88:91], v[152:155], v[200:203], v[88:91]
	v_mfma_f32_16x16x32_bf16 v[76:79], v[144:147], v[208:211], v[76:79]
	v_mfma_f32_16x16x32_bf16 v[72:75], v[152:155], v[208:211], v[72:75]
	v_mfma_f32_16x16x32_bf16 v[124:127], v[148:151], v[188:191], v[124:127]
	v_mfma_f32_16x16x32_bf16 v[120:123], v[156:159], v[188:191], v[120:123]
	v_mfma_f32_16x16x32_bf16 v[108:111], v[148:151], v[196:199], v[108:111]
	v_mfma_f32_16x16x32_bf16 v[104:107], v[156:159], v[196:199], v[104:107]
	v_mfma_f32_16x16x32_bf16 v[92:95], v[148:151], v[204:207], v[92:95]
	v_mfma_f32_16x16x32_bf16 v[88:91], v[156:159], v[204:207], v[88:91]
	v_mfma_f32_16x16x32_bf16 v[76:79], v[148:151], v[212:215], v[76:79]
	v_mfma_f32_16x16x32_bf16 v[72:75], v[156:159], v[212:215], v[72:75]
	v_mfma_f32_16x16x32_bf16 v[116:119], v[160:163], v[184:187], v[116:119]
	v_mfma_f32_16x16x32_bf16 v[112:115], v[176:179], v[184:187], v[112:115]
	v_mfma_f32_16x16x32_bf16 v[100:103], v[160:163], v[192:195], v[100:103]
	v_mfma_f32_16x16x32_bf16 v[96:99], v[176:179], v[192:195], v[96:99]
	v_mfma_f32_16x16x32_bf16 v[84:87], v[160:163], v[200:203], v[84:87]
	v_mfma_f32_16x16x32_bf16 v[80:83], v[176:179], v[200:203], v[80:83]
	v_mfma_f32_16x16x32_bf16 v[68:71], v[160:163], v[208:211], v[68:71]
	v_mfma_f32_16x16x32_bf16 v[64:67], v[176:179], v[208:211], v[64:67]
	v_mfma_f32_16x16x32_bf16 v[116:119], v[164:167], v[188:191], v[116:119]
	v_mfma_f32_16x16x32_bf16 v[112:115], v[180:183], v[188:191], v[112:115]
	v_mfma_f32_16x16x32_bf16 v[100:103], v[164:167], v[196:199], v[100:103]
	v_mfma_f32_16x16x32_bf16 v[96:99], v[180:183], v[196:199], v[96:99]
	v_mfma_f32_16x16x32_bf16 v[84:87], v[164:167], v[204:207], v[84:87]
	v_mfma_f32_16x16x32_bf16 v[80:83], v[180:183], v[204:207], v[80:83]
	v_mfma_f32_16x16x32_bf16 v[68:71], v[164:167], v[212:215], v[68:71]
	v_mfma_f32_16x16x32_bf16 v[64:67], v[180:183], v[212:215], v[64:67]
	s_barrier
	s_add_i32 s69, s62, s53
	v_lshl_add_u64 v[216:217], s[42:43], 0, v[130:131]
	s_mov_b32 m0, s69
	ds_read_b128 v[184:187], v173 offset:16384
	ds_read_b128 v[188:191], v173 offset:17408
	ds_read_b128 v[192:195], v173 offset:18432
	ds_read_b128 v[196:199], v173 offset:19456
	ds_read_b128 v[200:203], v173 offset:20480
	ds_read_b128 v[204:207], v173 offset:21504
	ds_read_b128 v[208:211], v173 offset:22528
	ds_read_b128 v[212:215], v173 offset:23552
	global_load_lds_dwordx4 v[216:217], off
	s_add_i32 m0, s69, 0x2000
	s_add_u32 s70, s42, 0x40000
	v_lshl_add_u64 v[218:219], s[42:43], 0, v[134:135]
	s_addc_u32 s71, s43, 0
	s_add_i32 s69, s63, s53
	global_load_lds_dwordx4 v[218:219], off
	v_lshl_add_u64 v[220:221], s[70:71], 0, v[130:131]
	s_mov_b32 m0, s69
	v_lshl_add_u64 v[222:223], s[48:49], 0, v[132:133]
	global_load_lds_dwordx4 v[220:221], off
	v_lshl_add_u64 v[220:221], s[70:71], 0, v[134:135]
	s_add_i32 m0, s69, 0x2000
	s_nop 0
	global_load_lds_dwordx4 v[220:221], off
	v_lshl_add_u64 v[220:221], s[48:49], 0, v[128:129]
	s_mov_b32 m0, s39
	s_nop 0
	global_load_lds_dwordx4 v[220:221], off
	s_mov_b32 m0, s54
	s_nop 0
	global_load_lds_dwordx4 v[222:223], off
	s_waitcnt vmcnt(8)
	s_waitcnt lgkmcnt(0)
	s_barrier
; #define PG8_STAGE(bufoff, gbase, voff) do { _Pragma("unroll") for (int _i = 0; _i < 2; ++_i) \
;         __builtin_amdgcn_global_load_lds((const unsigned*)((const char*)(gbase) + (voff)[_i]), (LAS unsigned*)(lds + (bufoff) + ldsw + _i * 8192), 16, 0, 0); } while (0)
; #define PG8_LDA(dst, b, h) do { _Pragma("unroll") for (int m = 0; m < 4; ++m) _Pragma("unroll") for (int k = 0; k < 2; ++k) dst[m][k] = *(const LAS bf16x8*)(lds + PG8_SA(b, h) + aoff + m * 2048 + k * 1024); } while (0)
; #define PG8_LDB(dst, b, h) do { _Pragma("unroll") for (int n = 0; n < 2; ++n) _Pragma("unroll") for (int k = 0; k < 2; ++k) dst[n][k] = *(const LAS bf16x8*)(lds + PG8_SB(b, h) + boff + n * 2048 + k * 1024); } while (0)
; #define PG8_MMA(ai, bj, At, Bt) do { __builtin_amdgcn_s_setprio(1); _Pragma("unroll") for (int m = 0; m < 4; ++m) _Pragma("unroll") for (int n = 0; n < 2; ++n) _Pragma("unroll") for (int k = 0; k < 2; ++k) \
;         acc[ai][bj][m][n] = __builtin_amdgcn_mfma_f32_16x16x32_bf16(Bt[n][k], At[m][k], acc[ai][bj][m][n], 0, 0, 0); __builtin_amdgcn_s_setprio(0); } while (0)
; #define PG8_WAIT_V(n) asm volatile("s_waitcnt vmcnt(" #n ")" ::: "memory")
; #define PG8_WAIT_L(n) asm volatile("s_waitcnt lgkmcnt(" #n ")" ::: "memory")
; #define PG8_BAR __builtin_amdgcn_s_barrier()
; #define PG8_SCHED __builtin_amdgcn_sched_barrier(0)
; template <class Epi, class Sched>
; DEVI void gemm_phase(LAS unsigned char* lds, const Gemm g, const Sched& S, const Epi& E) {
;     ...
;             PG8_WAIT_V(8); PG8_WAIT_L(0); PG8_BAR; PG8_MMA(1, 0, At, B0); PG8_MMA(1, 1, At, B1); PG8_BAR; PG8_SCHED;
;             PG8_LDB(B0, 1, 0); PG8_LDB(B1, 1, 1); PG8_SCHED; PG8_LDA(At, 1, 0); PG8_STAGE(PG8_SA(0, 1), a2 + hstep, voffA);
;             PG8_WAIT_V(8); PG8_WAIT_L(0); PG8_BAR; PG8_MMA(0, 0, At, B0); PG8_MMA(0, 1, At, B1); PG8_BAR; PG8_SCHED;
	s_waitcnt lgkmcnt(0)
	v_mfma_f32_16x16x32_bf16 v[60:63], v[144:147], v[184:187], v[60:63]
	v_mfma_f32_16x16x32_bf16 v[56:59], v[152:155], v[184:187], v[56:59]
	v_mfma_f32_16x16x32_bf16 v[44:47], v[144:147], v[192:195], v[44:47]
	v_mfma_f32_16x16x32_bf16 v[40:43], v[152:155], v[192:195], v[40:43]
	v_mfma_f32_16x16x32_bf16 v[28:31], v[144:147], v[200:203], v[28:31]
	v_mfma_f32_16x16x32_bf16 v[24:27], v[152:155], v[200:203], v[24:27]
	v_mfma_f32_16x16x32_bf16 v[12:15], v[144:147], v[208:211], v[12:15]
	v_mfma_f32_16x16x32_bf16 v[8:11], v[152:155], v[208:211], v[8:11]
	v_mfma_f32_16x16x32_bf16 v[60:63], v[148:151], v[188:191], v[60:63]
	v_mfma_f32_16x16x32_bf16 v[56:59], v[156:159], v[188:191], v[56:59]
	v_mfma_f32_16x16x32_bf16 v[44:47], v[148:151], v[196:199], v[44:47]
	v_mfma_f32_16x16x32_bf16 v[40:43], v[156:159], v[196:199], v[40:43]
	v_mfma_f32_16x16x32_bf16 v[28:31], v[148:151], v[204:207], v[28:31]
	v_mfma_f32_16x16x32_bf16 v[24:27], v[156:159], v[204:207], v[24:27]
	v_mfma_f32_16x16x32_bf16 v[12:15], v[148:151], v[212:215], v[12:15]
	v_mfma_f32_16x16x32_bf16 v[8:11], v[156:159], v[212:215], v[8:11]
	v_mfma_f32_16x16x32_bf16 v[52:55], v[160:163], v[184:187], v[52:55]
	v_mfma_f32_16x16x32_bf16 v[48:51], v[176:179], v[184:187], v[48:51]
	v_mfma_f32_16x16x32_bf16 v[36:39], v[160:163], v[192:195], v[36:39]
	v_mfma_f32_16x16x32_bf16 v[32:35], v[176:179], v[192:195], v[32:35]
	v_mfma_f32_16x16x32_bf16 v[20:23], v[160:163], v[200:203], v[20:23]
	v_mfma_f32_16x16x32_bf16 v[16:19], v[176:179], v[200:203], v[16:19]
	v_mfma_f32_16x16x32_bf16 v[4:7], v[160:163], v[208:211], v[4:7]
	v_mfma_f32_16x16x32_bf16 v[0:3], v[176:179], v[208:211], v[0:3]
	v_mfma_f32_16x16x32_bf16 v[52:55], v[164:167], v[188:191], v[52:55]
	v_mfma_f32_16x16x32_bf16 v[48:51], v[180:183], v[188:191], v[48:51]
	v_mfma_f32_16x16x32_bf16 v[36:39], v[164:167], v[196:199], v[36:39]
	v_mfma_f32_16x16x32_bf16 v[32:35], v[180:183], v[196:199], v[32:35]
	v_mfma_f32_16x16x32_bf16 v[20:23], v[164:167], v[204:207], v[20:23]
	v_mfma_f32_16x16x32_bf16 v[16:19], v[180:183], v[204:207], v[16:19]
	v_mfma_f32_16x16x32_bf16 v[4:7], v[164:167], v[212:215], v[4:7]
	v_mfma_f32_16x16x32_bf16 v[0:3], v[180:183], v[212:215], v[0:3]
	s_barrier
	s_add_i32 s69, 0, 0x18000
	s_add_i32 s70, 0, 0x1c000
	v_add_u32_e32 v156, s69, v169
	v_add_u32_e32 v175, s70, v169
	ds_read_b128 v[144:147], v156
	ds_read_b128 v[148:151], v156 offset:1024
	ds_read_b128 v[152:155], v156 offset:2048
	ds_read_b128 v[156:159], v156 offset:3072
	ds_read_b128 v[160:163], v175
	ds_read_b128 v[164:167], v175 offset:1024
	ds_read_b128 v[176:179], v175 offset:2048
	ds_read_b128 v[180:183], v175 offset:3072
	s_add_u32 s48, s48, 0x40000
	s_addc_u32 s49, s49, 0
	s_mov_b32 m0, s55
	v_lshl_add_u64 v[224:225], s[48:49], 0, v[128:129]
	ds_read_b128 v[184:187], v173 offset:32768
	ds_read_b128 v[188:191], v173 offset:33792
	ds_read_b128 v[192:195], v173 offset:34816
	ds_read_b128 v[196:199], v173 offset:35840
	ds_read_b128 v[200:203], v173 offset:36864
	ds_read_b128 v[204:207], v173 offset:37888
	ds_read_b128 v[208:211], v173 offset:38912
	ds_read_b128 v[212:215], v173 offset:39936
	global_load_lds_dwordx4 v[224:225], off
	v_lshl_add_u64 v[224:225], s[48:49], 0, v[132:133]
	s_mov_b32 m0, s56
	s_nop 0
	global_load_lds_dwordx4 v[224:225], off
	s_waitcnt vmcnt(8)
	s_waitcnt lgkmcnt(0)
	s_barrier
	s_waitcnt lgkmcnt(0)
	v_mfma_f32_16x16x32_bf16 v[124:127], v[144:147], v[184:187], v[124:127]
	v_mfma_f32_16x16x32_bf16 v[120:123], v[152:155], v[184:187], v[120:123]
	v_mfma_f32_16x16x32_bf16 v[108:111], v[144:147], v[192:195], v[108:111]
	v_mfma_f32_16x16x32_bf16 v[104:107], v[152:155], v[192:195], v[104:107]
	v_mfma_f32_16x16x32_bf16 v[92:95], v[144:147], v[200:203], v[92:95]
	v_mfma_f32_16x16x32_bf16 v[88:91], v[152:155], v[200:203], v[88:91]
	v_mfma_f32_16x16x32_bf16 v[76:79], v[144:147], v[208:211], v[76:79]
	v_mfma_f32_16x16x32_bf16 v[72:75], v[152:155], v[208:211], v[72:75]
	v_mfma_f32_16x16x32_bf16 v[124:127], v[148:151], v[188:191], v[124:127]
	v_mfma_f32_16x16x32_bf16 v[120:123], v[156:159], v[188:191], v[120:123]
	v_mfma_f32_16x16x32_bf16 v[108:111], v[148:151], v[196:199], v[108:111]
	v_mfma_f32_16x16x32_bf16 v[104:107], v[156:159], v[196:199], v[104:107]
	v_mfma_f32_16x16x32_bf16 v[92:95], v[148:151], v[204:207], v[92:95]
	v_mfma_f32_16x16x32_bf16 v[88:91], v[156:159], v[204:207], v[88:91]
	v_mfma_f32_16x16x32_bf16 v[76:79], v[148:151], v[212:215], v[76:79]
	v_mfma_f32_16x16x32_bf16 v[72:75], v[156:159], v[212:215], v[72:75]
	v_mfma_f32_16x16x32_bf16 v[116:119], v[160:163], v[184:187], v[116:119]
	v_mfma_f32_16x16x32_bf16 v[112:115], v[176:179], v[184:187], v[112:115]
	v_mfma_f32_16x16x32_bf16 v[100:103], v[160:163], v[192:195], v[100:103]
	v_mfma_f32_16x16x32_bf16 v[96:99], v[176:179], v[192:195], v[96:99]
	v_mfma_f32_16x16x32_bf16 v[84:87], v[160:163], v[200:203], v[84:87]
	v_mfma_f32_16x16x32_bf16 v[80:83], v[176:179], v[200:203], v[80:83]
	v_mfma_f32_16x16x32_bf16 v[68:71], v[160:163], v[208:211], v[68:71]
	v_mfma_f32_16x16x32_bf16 v[64:67], v[176:179], v[208:211], v[64:67]
	v_mfma_f32_16x16x32_bf16 v[116:119], v[164:167], v[188:191], v[116:119]
	v_mfma_f32_16x16x32_bf16 v[112:115], v[180:183], v[188:191], v[112:115]
	v_mfma_f32_16x16x32_bf16 v[100:103], v[164:167], v[196:199], v[100:103]
	v_mfma_f32_16x16x32_bf16 v[96:99], v[180:183], v[196:199], v[96:99]
	v_mfma_f32_16x16x32_bf16 v[84:87], v[164:167], v[204:207], v[84:87]
	v_mfma_f32_16x16x32_bf16 v[80:83], v[180:183], v[204:207], v[80:83]
	v_mfma_f32_16x16x32_bf16 v[68:71], v[164:167], v[212:215], v[68:71]
	v_mfma_f32_16x16x32_bf16 v[64:67], v[180:183], v[212:215], v[64:67]
	s_barrier
; #define PG8_STAGE(bufoff, gbase, voff) do { _Pragma("unroll") for (int _i = 0; _i < 2; ++_i) \
;         __builtin_amdgcn_global_load_lds((const unsigned*)((const char*)(gbase) + (voff)[_i]), (LAS unsigned*)(lds + (bufoff) + ldsw + _i * 8192), 16, 0, 0); } while (0)
; #define PG8_LDA(dst, b, h) do { _Pragma("unroll") for (int m = 0; m < 4; ++m) _Pragma("unroll") for (int k = 0; k < 2; ++k) dst[m][k] = *(const LAS bf16x8*)(lds + PG8_SA(b, h) + aoff + m * 2048 + k * 1024); } while (0)
; #define PG8_MMA(ai, bj, At, Bt) do { __builtin_amdgcn_s_setprio(1); _Pragma("unroll") for (int m = 0; m < 4; ++m) _Pragma("unroll") for (int n = 0; n < 2; ++n) _Pragma("unroll") for (int k = 0; k < 2; ++k) \
;         acc[ai][bj][m][n] = __builtin_amdgcn_mfma_f32_16x16x32_bf16(Bt[n][k], At[m][k], acc[ai][bj][m][n], 0, 0, 0); __builtin_amdgcn_s_setprio(0); } while (0)
; #define PG8_WAIT_V(n) asm volatile("s_waitcnt vmcnt(" #n ")" ::: "memory")
; #define PG8_WAIT_L(n) asm volatile("s_waitcnt lgkmcnt(" #n ")" ::: "memory")
; #define PG8_BAR __builtin_amdgcn_s_barrier()
; #define PG8_SCHED __builtin_amdgcn_sched_barrier(0)
; template <class Epi, class Sched>
; DEVI void gemm_phase(LAS unsigned char* lds, const Gemm g, const Sched& S, const Epi& E) {
;     ...
;             PG8_LDA(At, 1, 1); PG8_STAGE(PG8_SB(1, 0), b3, voffB); PG8_STAGE(PG8_SB(1, 1), b3 + hstep, voffB); PG8_STAGE(PG8_SA(1, 0), a3, voffA);
;             PG8_WAIT_V(8); PG8_WAIT_L(0); PG8_BAR; PG8_MMA(1, 0, At, B0); PG8_MMA(1, 1, At, B1); PG8_BAR; PG8_SCHED;
;         }
;         if (wr == 0) PG8_BAR;
	s_add_i32 s48, s69, s53
	v_lshl_add_u64 v[216:217], v[216:217], 0, s[18:19]
	s_mov_b32 m0, s48
	ds_read_b128 v[184:187], v173 offset:49152
	ds_read_b128 v[188:191], v173 offset:50176
	ds_read_b128 v[192:195], v173 offset:51200
	ds_read_b128 v[196:199], v173 offset:52224
	ds_read_b128 v[200:203], v173 offset:53248
	ds_read_b128 v[204:207], v173 offset:54272
	ds_read_b128 v[208:211], v173 offset:55296
	ds_read_b128 v[212:215], v173 offset:56320
	global_load_lds_dwordx4 v[216:217], off
	s_add_i32 m0, s48, 0x2000
	s_add_u32 s42, s42, 0x40080
	v_lshl_add_u64 v[216:217], v[218:219], 0, s[18:19]
	s_addc_u32 s43, s43, 0
	s_add_i32 s48, s70, s53
	global_load_lds_dwordx4 v[216:217], off
	v_lshl_add_u64 v[216:217], s[42:43], 0, v[130:131]
	s_mov_b32 m0, s48
	s_nop 0
	global_load_lds_dwordx4 v[216:217], off
	v_lshl_add_u64 v[216:217], s[42:43], 0, v[134:135]
	s_add_i32 m0, s48, 0x2000
	s_nop 0
	global_load_lds_dwordx4 v[216:217], off
	v_lshl_add_u64 v[216:217], v[220:221], 0, s[18:19]
	s_mov_b32 m0, s58
	s_nop 0
	global_load_lds_dwordx4 v[216:217], off
	v_lshl_add_u64 v[216:217], v[222:223], 0, s[18:19]
	s_mov_b32 m0, s59
	s_nop 0
	global_load_lds_dwordx4 v[216:217], off
	s_waitcnt vmcnt(8)
	s_waitcnt lgkmcnt(0)
	s_barrier
	s_waitcnt lgkmcnt(0)
	v_mfma_f32_16x16x32_bf16 v[60:63], v[144:147], v[184:187], v[60:63]
	v_mfma_f32_16x16x32_bf16 v[56:59], v[152:155], v[184:187], v[56:59]
	v_mfma_f32_16x16x32_bf16 v[44:47], v[144:147], v[192:195], v[44:47]
	v_mfma_f32_16x16x32_bf16 v[40:43], v[152:155], v[192:195], v[40:43]
	v_mfma_f32_16x16x32_bf16 v[28:31], v[144:147], v[200:203], v[28:31]
	v_mfma_f32_16x16x32_bf16 v[24:27], v[152:155], v[200:203], v[24:27]
	v_mfma_f32_16x16x32_bf16 v[12:15], v[144:147], v[208:211], v[12:15]
	v_mfma_f32_16x16x32_bf16 v[8:11], v[152:155], v[208:211], v[8:11]
	v_mfma_f32_16x16x32_bf16 v[60:63], v[148:151], v[188:191], v[60:63]
	v_mfma_f32_16x16x32_bf16 v[56:59], v[156:159], v[188:191], v[56:59]
	v_mfma_f32_16x16x32_bf16 v[44:47], v[148:151], v[196:199], v[44:47]
	v_mfma_f32_16x16x32_bf16 v[40:43], v[156:159], v[196:199], v[40:43]
	v_mfma_f32_16x16x32_bf16 v[28:31], v[148:151], v[204:207], v[28:31]
	v_mfma_f32_16x16x32_bf16 v[24:27], v[156:159], v[204:207], v[24:27]
	v_mfma_f32_16x16x32_bf16 v[12:15], v[148:151], v[212:215], v[12:15]
	v_mfma_f32_16x16x32_bf16 v[8:11], v[156:159], v[212:215], v[8:11]
	v_mfma_f32_16x16x32_bf16 v[52:55], v[160:163], v[184:187], v[52:55]
	v_mfma_f32_16x16x32_bf16 v[48:51], v[176:179], v[184:187], v[48:51]
	v_mfma_f32_16x16x32_bf16 v[36:39], v[160:163], v[192:195], v[36:39]
	v_mfma_f32_16x16x32_bf16 v[32:35], v[176:179], v[192:195], v[32:35]
	v_mfma_f32_16x16x32_bf16 v[20:23], v[160:163], v[200:203], v[20:23]
	v_mfma_f32_16x16x32_bf16 v[16:19], v[176:179], v[200:203], v[16:19]
	v_mfma_f32_16x16x32_bf16 v[4:7], v[160:163], v[208:211], v[4:7]
	v_mfma_f32_16x16x32_bf16 v[0:3], v[176:179], v[208:211], v[0:3]
	v_mfma_f32_16x16x32_bf16 v[52:55], v[164:167], v[188:191], v[52:55]
	v_mfma_f32_16x16x32_bf16 v[48:51], v[180:183], v[188:191], v[48:51]
	v_mfma_f32_16x16x32_bf16 v[36:39], v[164:167], v[196:199], v[36:39]
	v_mfma_f32_16x16x32_bf16 v[32:35], v[180:183], v[196:199], v[32:35]
	v_mfma_f32_16x16x32_bf16 v[20:23], v[164:167], v[204:207], v[20:23]
	v_mfma_f32_16x16x32_bf16 v[16:19], v[180:183], v[204:207], v[16:19]
	v_mfma_f32_16x16x32_bf16 v[4:7], v[164:167], v[212:215], v[4:7]
	v_mfma_f32_16x16x32_bf16 v[0:3], v[180:183], v[212:215], v[0:3]
	s_barrier
	s_add_i32 s68, s68, 2
	s_add_u32 s66, s66, 0x100
	s_addc_u32 s67, s67, 0
	s_add_u32 s40, s40, 0x100
	s_addc_u32 s41, s41, 0
	s_cmp_gt_u32 s68, 13
	s_cbranch_scc0 .LBB0_2633
	s_and_b64 vcc, exec, s[20:21]
	s_cbranch_vccz .LBB0_2636
	s_barrier

; DEVI int bid_() { int t = blockIdx.x; asm volatile("" : "+s"(t)); return t; }
; DEVI int gdim_() { int t = gridDim.x; asm volatile("" : "+s"(t)); return t; }
;     DEVI bool next(int i, Unit& u) const {
;         const long L = (long)i * G + c; if (L >= nwg) return false;
;         int wgid = (int)L; { const int q = nwg / NXCD, r = nwg % NXCD, xcd = wgid % NXCD, off = wgid / NXCD; wgid = (xcd < r ? xcd * (q + 1) : r * (q + 1) + (xcd - r) * q) + off; }
;         const int nig = WGM * nN, gid = wgid / nig, fm = gid * WGM, gsz = (nM - fm) < WGM ? (nM - fm) : WGM;
;         u.pm = fm + ((wgid % nig) % gsz); u.pn = (wgid % nig) / gsz; return true;
; template <int PH>
; DEVI void run_phase(const Params& p, unsigned char* smem) {
;     ...
;             pg8::Gemm g{(const bf16_t*)(ws + WS_ZB), wbase + (size_t)5 * MiB / 2, MROWS, 2 * DFF, DM}; pg8::StaticOrder S; S.init(MROWS, 2 * DFF, gdim_(), bid_());
;             EpiFfn E{(bf16_t*)(ws + WS_H), stA, vec + 3072, vec + 3072 + 5632, p.in[28] + (size_t)l * 3 * DFF, p.in[29] + (size_t)l * DFF, (float*)(ws + WS_TAIL), (float*)(ws + WS_HPG), (float*)(ws + WS_HUP)};
;             pg8::gemm_phase<EpiFfn, pg8::StaticOrder>(lds, g, S, E);
.LBB0_2708:
	s_or_b64 exec, exec, s[0:1]
	s_mov_b64 s[2:3], s[96:97]
	s_mov_b32 s33, s89
	v_readlane_b32 s43, v249, 0
	s_waitcnt lgkmcnt(0)
	s_barrier
	v_readfirstlane_b32 s98, v242
	s_nop 3
	s_cmpk_lt_u32 s98, 0x100
	s_cbranch_scc1 .Lsprio_sp27
	s_setprio 1
.Lsprio_sp27:
	v_mov_b32_e32 v8, v242
	s_cmpk_lt_i32 s43, 0xb00
	s_cselect_b64 s[4:5], -1, 0
	s_cmpk_gt_i32 s43, 0xaff
	v_readfirstlane_b32 s6, v8
	s_cbranch_scc1 .LBB0_2710
	s_ashr_i32 s0, s43, 31
	s_lshr_b32 s0, s0, 29
	s_add_i32 s0, s43, s0
	s_ashr_i32 s1, s0, 3
	s_and_b32 s0, s0, -8
	s_sub_i32 s0, s43, s0
	s_cmp_lt_i32 s0, 0
	s_movk_i32 s7, 0x161
	s_cselect_b32 s7, s7, 0x160
	s_mul_i32 s0, s7, s0
	s_add_i32 s0, s0, s1
	s_mul_hi_i32 s1, s0, 0x2e8ba2e9
	s_lshr_b32 s7, s1, 31
	s_ashr_i32 s1, s1, 5
	s_add_i32 s1, s1, s7
	s_lshl_b32 s7, s1, 3
	s_mulk_i32 s1, 0xb0
	s_sub_i32 s0, s0, s1
	s_bfe_u32 s1, s0, 0x3001c
	s_add_i32 s1, s0, s1
	s_sext_i32_i16 s8, s1
	s_and_b32 s1, s1, 0xfff8
	s_sub_i32 s0, s0, s1
	s_sext_i32_i16 s0, s0
	s_add_i32 s10, s7, s0
	s_ashr_i32 s0, s8, 3

; #define PG8_STAGE(bufoff, gbase, voff) do { _Pragma("unroll") for (int _i = 0; _i < 2; ++_i) \
;         __builtin_amdgcn_global_load_lds((const unsigned*)((const char*)(gbase) + (voff)[_i]), (LAS unsigned*)(lds + (bufoff) + ldsw + _i * 8192), 16, 0, 0); } while (0)
; #define PG8_LDA(dst, b, h) do { _Pragma("unroll") for (int m = 0; m < 4; ++m) _Pragma("unroll") for (int k = 0; k < 2; ++k) dst[m][k] = *(const LAS bf16x8*)(lds + PG8_SA(b, h) + aoff + m * 2048 + k * 1024); } while (0)
; #define PG8_LDB(dst, b, h) do { _Pragma("unroll") for (int n = 0; n < 2; ++n) _Pragma("unroll") for (int k = 0; k < 2; ++k) dst[n][k] = *(const LAS bf16x8*)(lds + PG8_SB(b, h) + boff + n * 2048 + k * 1024); } while (0)
; #define PG8_MMA(ai, bj, At, Bt) do { __builtin_amdgcn_s_setprio(1); _Pragma("unroll") for (int m = 0; m < 4; ++m) _Pragma("unroll") for (int n = 0; n < 2; ++n) _Pragma("unroll") for (int k = 0; k < 2; ++k) \
;         acc[ai][bj][m][n] = __builtin_amdgcn_mfma_f32_16x16x32_bf16(Bt[n][k], At[m][k], acc[ai][bj][m][n], 0, 0, 0); __builtin_amdgcn_s_setprio(0); } while (0)
; #define PG8_WAIT_V(n) asm volatile("s_waitcnt vmcnt(" #n ")" ::: "memory")
; #define PG8_WAIT_L(n) asm volatile("s_waitcnt lgkmcnt(" #n ")" ::: "memory")
; #define PG8_BAR __builtin_amdgcn_s_barrier()
; #define PG8_SCHED __builtin_amdgcn_sched_barrier(0)
; template <class Epi, class Sched>
; DEVI void gemm_phase(LAS unsigned char* lds, const Gemm g, const Sched& S, const Epi& E) {
;     ...
;         for (int t = 0; t < nt; t += 2) {
;             const bool last = (t == nt - 2);
;             const char* a1 = cA + (size_t)(t + 1) * kstep;
;             const char* a2 = last ? nA : cA + (size_t)(t + 2) * kstep; const char* b2 = last ? nB : cB + (size_t)(t + 2) * kstep;
;             const char* a3 = a2 + kstep; const char* b3 = b2 + kstep;
;             if (last && has_next) S.a_ready(nxt);
;             PG8_LDB(B0, 0, 0); PG8_LDB(B1, 0, 1); PG8_SCHED; PG8_LDA(At, 0, 0); PG8_STAGE(PG8_SA(1, 1), a1 + hstep, voffA);
;             PG8_WAIT_V(8); PG8_WAIT_L(0); PG8_BAR; PG8_MMA(0, 0, At, B0); PG8_MMA(0, 1, At, B1); PG8_BAR; PG8_SCHED;
;             PG8_LDA(At, 0, 1); PG8_STAGE(PG8_SB(0, 0), b2, voffB); PG8_STAGE(PG8_SB(0, 1), b2 + hstep, voffB); PG8_STAGE(PG8_SA(0, 0), a2, voffA);
;             PG8_WAIT_V(8); PG8_WAIT_L(0); PG8_BAR; PG8_MMA(1, 0, At, B0); PG8_MMA(1, 1, At, B1); PG8_BAR; PG8_SCHED;
.LBB0_2719:
	ds_read_b128 v[112:115], v227
	ds_read_b128 v[116:119], v227 offset:1024
	ds_read_b128 v[120:123], v227 offset:2048
	ds_read_b128 v[124:127], v227 offset:3072
	ds_read_b128 v[128:131], v228
	ds_read_b128 v[136:139], v228 offset:1024
	ds_read_b128 v[140:143], v228 offset:2048
	ds_read_b128 v[144:147], v228 offset:3072
	s_add_u32 s48, s64, 0xfffc0080
	s_addc_u32 s49, s65, -1
	s_cmp_eq_u32 s85, 12
	s_cselect_b32 s51, s1, s49
	s_cselect_b32 s50, s11, s48
	s_cselect_b32 s49, s53, s57
	s_cselect_b32 s48, s55, s56
	v_lshl_add_u64 v[212:213], s[64:65], 0, v[178:179]
	s_add_i32 m0, s69, 0xc000
	ds_read_b128 v[160:163], v229
	ds_read_b128 v[184:187], v229 offset:1024
	ds_read_b128 v[188:191], v229 offset:2048
	ds_read_b128 v[192:195], v229 offset:3072
	ds_read_b128 v[196:199], v229 offset:4096
	ds_read_b128 v[200:203], v229 offset:5120
	ds_read_b128 v[204:207], v229 offset:6144
	ds_read_b128 v[208:211], v229 offset:7168
	global_load_lds_dwordx4 v[212:213], off
	v_lshl_add_u64 v[212:213], s[64:65], 0, v[176:177]
	s_add_i32 m0, s69, 0xe000
	s_nop 0
	global_load_lds_dwordx4 v[212:213], off
	s_waitcnt vmcnt(8)
	s_waitcnt lgkmcnt(0)
	s_barrier
	s_waitcnt lgkmcnt(0)
	v_mfma_f32_16x16x32_bf16 v[156:159], v[112:115], v[160:163], v[156:159]
	v_mfma_f32_16x16x32_bf16 v[60:63], v[120:123], v[160:163], v[60:63]
	v_mfma_f32_16x16x32_bf16 v[148:151], v[112:115], v[188:191], v[148:151]
	v_mfma_f32_16x16x32_bf16 v[52:55], v[120:123], v[188:191], v[52:55]
	v_mfma_f32_16x16x32_bf16 v[108:111], v[112:115], v[196:199], v[108:111]
	v_mfma_f32_16x16x32_bf16 v[44:47], v[120:123], v[196:199], v[44:47]
	v_mfma_f32_16x16x32_bf16 v[100:103], v[112:115], v[204:207], v[100:103]
	v_mfma_f32_16x16x32_bf16 v[36:39], v[120:123], v[204:207], v[36:39]
	v_mfma_f32_16x16x32_bf16 v[156:159], v[116:119], v[184:187], v[156:159]
	v_mfma_f32_16x16x32_bf16 v[60:63], v[124:127], v[184:187], v[60:63]
	v_mfma_f32_16x16x32_bf16 v[148:151], v[116:119], v[192:195], v[148:151]
	v_mfma_f32_16x16x32_bf16 v[52:55], v[124:127], v[192:195], v[52:55]
	v_mfma_f32_16x16x32_bf16 v[108:111], v[116:119], v[200:203], v[108:111]
	v_mfma_f32_16x16x32_bf16 v[44:47], v[124:127], v[200:203], v[44:47]
	v_mfma_f32_16x16x32_bf16 v[100:103], v[116:119], v[208:211], v[100:103]
	v_mfma_f32_16x16x32_bf16 v[36:39], v[124:127], v[208:211], v[36:39]
	v_mfma_f32_16x16x32_bf16 v[152:155], v[128:131], v[160:163], v[152:155]
	v_mfma_f32_16x16x32_bf16 v[56:59], v[140:143], v[160:163], v[56:59]
	v_mfma_f32_16x16x32_bf16 v[132:135], v[128:131], v[188:191], v[132:135]
	v_mfma_f32_16x16x32_bf16 v[48:51], v[140:143], v[188:191], v[48:51]
	v_mfma_f32_16x16x32_bf16 v[104:107], v[128:131], v[196:199], v[104:107]
	v_mfma_f32_16x16x32_bf16 v[40:43], v[140:143], v[196:199], v[40:43]
	v_mfma_f32_16x16x32_bf16 v[96:99], v[128:131], v[204:207], v[96:99]
	v_mfma_f32_16x16x32_bf16 v[32:35], v[140:143], v[204:207], v[32:35]
	v_mfma_f32_16x16x32_bf16 v[152:155], v[136:139], v[184:187], v[152:155]
	v_mfma_f32_16x16x32_bf16 v[56:59], v[144:147], v[184:187], v[56:59]
	v_mfma_f32_16x16x32_bf16 v[132:135], v[136:139], v[192:195], v[132:135]
	v_mfma_f32_16x16x32_bf16 v[48:51], v[144:147], v[192:195], v[48:51]
	v_mfma_f32_16x16x32_bf16 v[104:107], v[136:139], v[200:203], v[104:107]
	v_mfma_f32_16x16x32_bf16 v[40:43], v[144:147], v[200:203], v[40:43]
	v_mfma_f32_16x16x32_bf16 v[96:99], v[136:139], v[208:211], v[96:99]
	v_mfma_f32_16x16x32_bf16 v[32:35], v[144:147], v[208:211], v[32:35]
	s_barrier
	s_add_i32 s86, s79, s68
	v_lshl_add_u64 v[212:213], s[48:49], 0, v[166:167]
	s_mov_b32 m0, s86
	ds_read_b128 v[160:163], v229 offset:16384
	ds_read_b128 v[184:187], v229 offset:17408
	ds_read_b128 v[188:191], v229 offset:18432
	ds_read_b128 v[192:195], v229 offset:19456
	ds_read_b128 v[196:199], v229 offset:20480
	ds_read_b128 v[200:203], v229 offset:21504
	ds_read_b128 v[204:207], v229 offset:22528
	ds_read_b128 v[208:211], v229 offset:23552
	global_load_lds_dwordx4 v[212:213], off
	s_add_i32 m0, s86, 0x2000
	s_add_u32 s86, s48, 0x40000
	v_lshl_add_u64 v[214:215], s[48:49], 0, v[170:171]
	s_addc_u32 s87, s49, 0
	s_add_i32 s88, s80, s68
	global_load_lds_dwordx4 v[214:215], off
	v_lshl_add_u64 v[216:217], s[86:87], 0, v[166:167]
	s_mov_b32 m0, s88
	v_lshl_add_u64 v[218:219], s[50:51], 0, v[168:169]
	global_load_lds_dwordx4 v[216:217], off
	v_lshl_add_u64 v[216:217], s[86:87], 0, v[170:171]
	s_add_i32 m0, s88, 0x2000
	s_nop 0
	global_load_lds_dwordx4 v[216:217], off
	v_lshl_add_u64 v[216:217], s[50:51], 0, v[164:165]
	s_mov_b32 m0, s69
	s_nop 0
	global_load_lds_dwordx4 v[216:217], off
	s_mov_b32 m0, s70
	s_nop 0
	global_load_lds_dwordx4 v[218:219], off
	s_waitcnt vmcnt(8)
	s_waitcnt lgkmcnt(0)
	s_barrier
; #define PG8_STAGE(bufoff, gbase, voff) do { _Pragma("unroll") for (int _i = 0; _i < 2; ++_i) \
;         __builtin_amdgcn_global_load_lds((const unsigned*)((const char*)(gbase) + (voff)[_i]), (LAS unsigned*)(lds + (bufoff) + ldsw + _i * 8192), 16, 0, 0); } while (0)
; #define PG8_LDA(dst, b, h) do { _Pragma("unroll") for (int m = 0; m < 4; ++m) _Pragma("unroll") for (int k = 0; k < 2; ++k) dst[m][k] = *(const LAS bf16x8*)(lds + PG8_SA(b, h) + aoff + m * 2048 + k * 1024); } while (0)
; #define PG8_LDB(dst, b, h) do { _Pragma("unroll") for (int n = 0; n < 2; ++n) _Pragma("unroll") for (int k = 0; k < 2; ++k) dst[n][k] = *(const LAS bf16x8*)(lds + PG8_SB(b, h) + boff + n * 2048 + k * 1024); } while (0)
; #define PG8_MMA(ai, bj, At, Bt) do { __builtin_amdgcn_s_setprio(1); _Pragma("unroll") for (int m = 0; m < 4; ++m) _Pragma("unroll") for (int n = 0; n < 2; ++n) _Pragma("unroll") for (int k = 0; k < 2; ++k) \
;         acc[ai][bj][m][n] = __builtin_amdgcn_mfma_f32_16x16x32_bf16(Bt[n][k], At[m][k], acc[ai][bj][m][n], 0, 0, 0); __builtin_amdgcn_s_setprio(0); } while (0)
; #define PG8_WAIT_V(n) asm volatile("s_waitcnt vmcnt(" #n ")" ::: "memory")
; #define PG8_WAIT_L(n) asm volatile("s_waitcnt lgkmcnt(" #n ")" ::: "memory")
; #define PG8_BAR __builtin_amdgcn_s_barrier()
; #define PG8_SCHED __builtin_amdgcn_sched_barrier(0)
; template <class Epi, class Sched>
; DEVI void gemm_phase(LAS unsigned char* lds, const Gemm g, const Sched& S, const Epi& E) {
;     ...
;             PG8_WAIT_V(8); PG8_WAIT_L(0); PG8_BAR; PG8_MMA(1, 0, At, B0); PG8_MMA(1, 1, At, B1); PG8_BAR; PG8_SCHED;
;             PG8_LDB(B0, 1, 0); PG8_LDB(B1, 1, 1); PG8_SCHED; PG8_LDA(At, 1, 0); PG8_STAGE(PG8_SA(0, 1), a2 + hstep, voffA);
;             PG8_WAIT_V(8); PG8_WAIT_L(0); PG8_BAR; PG8_MMA(0, 0, At, B0); PG8_MMA(0, 1, At, B1); PG8_BAR; PG8_SCHED;
	s_waitcnt lgkmcnt(0)
	v_mfma_f32_16x16x32_bf16 v[92:95], v[112:115], v[160:163], v[92:95]
	v_mfma_f32_16x16x32_bf16 v[28:31], v[120:123], v[160:163], v[28:31]
	v_mfma_f32_16x16x32_bf16 v[84:87], v[112:115], v[188:191], v[84:87]
	v_mfma_f32_16x16x32_bf16 v[20:23], v[120:123], v[188:191], v[20:23]
	v_mfma_f32_16x16x32_bf16 v[76:79], v[112:115], v[196:199], v[76:79]
	v_mfma_f32_16x16x32_bf16 v[12:15], v[120:123], v[196:199], v[12:15]
	v_mfma_f32_16x16x32_bf16 v[68:71], v[112:115], v[204:207], v[68:71]
	v_mfma_f32_16x16x32_bf16 v[4:7], v[120:123], v[204:207], v[4:7]
	v_mfma_f32_16x16x32_bf16 v[92:95], v[116:119], v[184:187], v[92:95]
	v_mfma_f32_16x16x32_bf16 v[28:31], v[124:127], v[184:187], v[28:31]
	v_mfma_f32_16x16x32_bf16 v[84:87], v[116:119], v[192:195], v[84:87]
	v_mfma_f32_16x16x32_bf16 v[20:23], v[124:127], v[192:195], v[20:23]
	v_mfma_f32_16x16x32_bf16 v[76:79], v[116:119], v[200:203], v[76:79]
	v_mfma_f32_16x16x32_bf16 v[12:15], v[124:127], v[200:203], v[12:15]
	v_mfma_f32_16x16x32_bf16 v[68:71], v[116:119], v[208:211], v[68:71]
	v_mfma_f32_16x16x32_bf16 v[4:7], v[124:127], v[208:211], v[4:7]
	v_mfma_f32_16x16x32_bf16 v[88:91], v[128:131], v[160:163], v[88:91]
	v_mfma_f32_16x16x32_bf16 v[24:27], v[140:143], v[160:163], v[24:27]
	v_mfma_f32_16x16x32_bf16 v[80:83], v[128:131], v[188:191], v[80:83]
	v_mfma_f32_16x16x32_bf16 v[16:19], v[140:143], v[188:191], v[16:19]
	v_mfma_f32_16x16x32_bf16 v[72:75], v[128:131], v[196:199], v[72:75]
	v_mfma_f32_16x16x32_bf16 v[8:11], v[140:143], v[196:199], v[8:11]
	v_mfma_f32_16x16x32_bf16 v[64:67], v[128:131], v[204:207], v[64:67]
	v_mfma_f32_16x16x32_bf16 v[0:3], v[140:143], v[204:207], v[0:3]
	v_mfma_f32_16x16x32_bf16 v[88:91], v[136:139], v[184:187], v[88:91]
	v_mfma_f32_16x16x32_bf16 v[24:27], v[144:147], v[184:187], v[24:27]
	v_mfma_f32_16x16x32_bf16 v[80:83], v[136:139], v[192:195], v[80:83]
	v_mfma_f32_16x16x32_bf16 v[16:19], v[144:147], v[192:195], v[16:19]
	v_mfma_f32_16x16x32_bf16 v[72:75], v[136:139], v[200:203], v[72:75]
	v_mfma_f32_16x16x32_bf16 v[8:11], v[144:147], v[200:203], v[8:11]
	v_mfma_f32_16x16x32_bf16 v[64:67], v[136:139], v[208:211], v[64:67]
	v_mfma_f32_16x16x32_bf16 v[0:3], v[144:147], v[208:211], v[0:3]
	s_barrier
	s_add_i32 s86, 0, 0x18000
	s_add_i32 s87, 0, 0x1c000
	v_add_u32_e32 v124, s86, v173
	v_add_u32_e32 v144, s87, v173
	ds_read_b128 v[112:115], v124
	ds_read_b128 v[116:119], v124 offset:1024
	ds_read_b128 v[120:123], v124 offset:2048
	ds_read_b128 v[124:127], v124 offset:3072
	ds_read_b128 v[128:131], v144
	ds_read_b128 v[136:139], v144 offset:1024
	ds_read_b128 v[140:143], v144 offset:2048
	ds_read_b128 v[144:147], v144 offset:3072
	s_add_u32 s50, s50, 0x40000
	s_addc_u32 s51, s51, 0
	s_mov_b32 m0, s71
	v_lshl_add_u64 v[220:221], s[50:51], 0, v[164:165]
	ds_read_b128 v[160:163], v229 offset:32768
	ds_read_b128 v[184:187], v229 offset:33792
	ds_read_b128 v[188:191], v229 offset:34816
	ds_read_b128 v[192:195], v229 offset:35840
	ds_read_b128 v[196:199], v229 offset:36864
	ds_read_b128 v[200:203], v229 offset:37888
	ds_read_b128 v[204:207], v229 offset:38912
	ds_read_b128 v[208:211], v229 offset:39936
	global_load_lds_dwordx4 v[220:221], off
	v_lshl_add_u64 v[220:221], s[50:51], 0, v[168:169]
	s_mov_b32 m0, s72
	s_nop 0
	global_load_lds_dwordx4 v[220:221], off
	s_waitcnt vmcnt(8)
	s_waitcnt lgkmcnt(0)
	s_barrier
	s_waitcnt lgkmcnt(0)
	v_mfma_f32_16x16x32_bf16 v[156:159], v[112:115], v[160:163], v[156:159]
	v_mfma_f32_16x16x32_bf16 v[60:63], v[120:123], v[160:163], v[60:63]
	v_mfma_f32_16x16x32_bf16 v[148:151], v[112:115], v[188:191], v[148:151]
	v_mfma_f32_16x16x32_bf16 v[52:55], v[120:123], v[188:191], v[52:55]
	v_mfma_f32_16x16x32_bf16 v[108:111], v[112:115], v[196:199], v[108:111]
	v_mfma_f32_16x16x32_bf16 v[44:47], v[120:123], v[196:199], v[44:47]
	v_mfma_f32_16x16x32_bf16 v[100:103], v[112:115], v[204:207], v[100:103]
	v_mfma_f32_16x16x32_bf16 v[36:39], v[120:123], v[204:207], v[36:39]
	v_mfma_f32_16x16x32_bf16 v[156:159], v[116:119], v[184:187], v[156:159]
	v_mfma_f32_16x16x32_bf16 v[60:63], v[124:127], v[184:187], v[60:63]
	v_mfma_f32_16x16x32_bf16 v[148:151], v[116:119], v[192:195], v[148:151]
	v_mfma_f32_16x16x32_bf16 v[52:55], v[124:127], v[192:195], v[52:55]
	v_mfma_f32_16x16x32_bf16 v[108:111], v[116:119], v[200:203], v[108:111]
	v_mfma_f32_16x16x32_bf16 v[44:47], v[124:127], v[200:203], v[44:47]
	v_mfma_f32_16x16x32_bf16 v[100:103], v[116:119], v[208:211], v[100:103]
	v_mfma_f32_16x16x32_bf16 v[36:39], v[124:127], v[208:211], v[36:39]
	v_mfma_f32_16x16x32_bf16 v[152:155], v[128:131], v[160:163], v[152:155]
	v_mfma_f32_16x16x32_bf16 v[56:59], v[140:143], v[160:163], v[56:59]
	v_mfma_f32_16x16x32_bf16 v[132:135], v[128:131], v[188:191], v[132:135]
	v_mfma_f32_16x16x32_bf16 v[48:51], v[140:143], v[188:191], v[48:51]
	v_mfma_f32_16x16x32_bf16 v[104:107], v[128:131], v[196:199], v[104:107]
	v_mfma_f32_16x16x32_bf16 v[40:43], v[140:143], v[196:199], v[40:43]
	v_mfma_f32_16x16x32_bf16 v[96:99], v[128:131], v[204:207], v[96:99]
	v_mfma_f32_16x16x32_bf16 v[32:35], v[140:143], v[204:207], v[32:35]
	v_mfma_f32_16x16x32_bf16 v[152:155], v[136:139], v[184:187], v[152:155]
	v_mfma_f32_16x16x32_bf16 v[56:59], v[144:147], v[184:187], v[56:59]
	v_mfma_f32_16x16x32_bf16 v[132:135], v[136:139], v[192:195], v[132:135]
	v_mfma_f32_16x16x32_bf16 v[48:51], v[144:147], v[192:195], v[48:51]
	v_mfma_f32_16x16x32_bf16 v[104:107], v[136:139], v[200:203], v[104:107]
	v_mfma_f32_16x16x32_bf16 v[40:43], v[144:147], v[200:203], v[40:43]
	v_mfma_f32_16x16x32_bf16 v[96:99], v[136:139], v[208:211], v[96:99]
	v_mfma_f32_16x16x32_bf16 v[32:35], v[144:147], v[208:211], v[32:35]
	s_barrier
; #define PG8_STAGE(bufoff, gbase, voff) do { _Pragma("unroll") for (int _i = 0; _i < 2; ++_i) \
;         __builtin_amdgcn_global_load_lds((const unsigned*)((const char*)(gbase) + (voff)[_i]), (LAS unsigned*)(lds + (bufoff) + ldsw + _i * 8192), 16, 0, 0); } while (0)
; #define PG8_LDA(dst, b, h) do { _Pragma("unroll") for (int m = 0; m < 4; ++m) _Pragma("unroll") for (int k = 0; k < 2; ++k) dst[m][k] = *(const LAS bf16x8*)(lds + PG8_SA(b, h) + aoff + m * 2048 + k * 1024); } while (0)
; #define PG8_MMA(ai, bj, At, Bt) do { __builtin_amdgcn_s_setprio(1); _Pragma("unroll") for (int m = 0; m < 4; ++m) _Pragma("unroll") for (int n = 0; n < 2; ++n) _Pragma("unroll") for (int k = 0; k < 2; ++k) \
;         acc[ai][bj][m][n] = __builtin_amdgcn_mfma_f32_16x16x32_bf16(Bt[n][k], At[m][k], acc[ai][bj][m][n], 0, 0, 0); __builtin_amdgcn_s_setprio(0); } while (0)
; #define PG8_WAIT_V(n) asm volatile("s_waitcnt vmcnt(" #n ")" ::: "memory")
; #define PG8_WAIT_L(n) asm volatile("s_waitcnt lgkmcnt(" #n ")" ::: "memory")
; #define PG8_BAR __builtin_amdgcn_s_barrier()
; #define PG8_SCHED __builtin_amdgcn_sched_barrier(0)
; template <class Epi, class Sched>
; DEVI void gemm_phase(LAS unsigned char* lds, const Gemm g, const Sched& S, const Epi& E) {
;     ...
;             PG8_LDA(At, 1, 1); PG8_STAGE(PG8_SB(1, 0), b3, voffB); PG8_STAGE(PG8_SB(1, 1), b3 + hstep, voffB); PG8_STAGE(PG8_SA(1, 0), a3, voffA);
;             PG8_WAIT_V(8); PG8_WAIT_L(0); PG8_BAR; PG8_MMA(1, 0, At, B0); PG8_MMA(1, 1, At, B1); PG8_BAR; PG8_SCHED;
;         }
;         if (wr == 0) PG8_BAR;
	s_add_i32 s50, s86, s68
	v_lshl_add_u64 v[212:213], v[212:213], 0, s[34:35]
	s_mov_b32 m0, s50
	ds_read_b128 v[160:163], v229 offset:49152
	ds_read_b128 v[184:187], v229 offset:50176
	ds_read_b128 v[188:191], v229 offset:51200
	ds_read_b128 v[192:195], v229 offset:52224
	ds_read_b128 v[196:199], v229 offset:53248
	ds_read_b128 v[200:203], v229 offset:54272
	ds_read_b128 v[204:207], v229 offset:55296
	ds_read_b128 v[208:211], v229 offset:56320
	global_load_lds_dwordx4 v[212:213], off
	s_add_i32 m0, s50, 0x2000
	s_add_u32 s48, s48, 0x40080
	v_lshl_add_u64 v[212:213], v[214:215], 0, s[34:35]
	s_addc_u32 s49, s49, 0
	s_add_i32 s50, s87, s68
	global_load_lds_dwordx4 v[212:213], off
	v_lshl_add_u64 v[212:213], s[48:49], 0, v[166:167]
	s_mov_b32 m0, s50
	s_nop 0
	global_load_lds_dwordx4 v[212:213], off
	v_lshl_add_u64 v[212:213], s[48:49], 0, v[170:171]
	s_add_i32 m0, s50, 0x2000
	s_nop 0
	global_load_lds_dwordx4 v[212:213], off
	v_lshl_add_u64 v[212:213], v[216:217], 0, s[34:35]
	s_mov_b32 m0, s75
	s_nop 0
	global_load_lds_dwordx4 v[212:213], off
	v_lshl_add_u64 v[212:213], v[218:219], 0, s[34:35]
	s_mov_b32 m0, s76
	s_nop 0
	global_load_lds_dwordx4 v[212:213], off
	s_waitcnt vmcnt(8)
	s_waitcnt lgkmcnt(0)
	s_barrier
	s_waitcnt lgkmcnt(0)
	v_mfma_f32_16x16x32_bf16 v[92:95], v[112:115], v[160:163], v[92:95]
	v_mfma_f32_16x16x32_bf16 v[28:31], v[120:123], v[160:163], v[28:31]
	v_mfma_f32_16x16x32_bf16 v[84:87], v[112:115], v[188:191], v[84:87]
	v_mfma_f32_16x16x32_bf16 v[20:23], v[120:123], v[188:191], v[20:23]
	v_mfma_f32_16x16x32_bf16 v[76:79], v[112:115], v[196:199], v[76:79]
	v_mfma_f32_16x16x32_bf16 v[12:15], v[120:123], v[196:199], v[12:15]
	v_mfma_f32_16x16x32_bf16 v[68:71], v[112:115], v[204:207], v[68:71]
	v_mfma_f32_16x16x32_bf16 v[4:7], v[120:123], v[204:207], v[4:7]
	v_mfma_f32_16x16x32_bf16 v[92:95], v[116:119], v[184:187], v[92:95]
	v_mfma_f32_16x16x32_bf16 v[28:31], v[124:127], v[184:187], v[28:31]
	v_mfma_f32_16x16x32_bf16 v[84:87], v[116:119], v[192:195], v[84:87]
	v_mfma_f32_16x16x32_bf16 v[20:23], v[124:127], v[192:195], v[20:23]
	v_mfma_f32_16x16x32_bf16 v[76:79], v[116:119], v[200:203], v[76:79]
	v_mfma_f32_16x16x32_bf16 v[12:15], v[124:127], v[200:203], v[12:15]
	v_mfma_f32_16x16x32_bf16 v[68:71], v[116:119], v[208:211], v[68:71]
	v_mfma_f32_16x16x32_bf16 v[4:7], v[124:127], v[208:211], v[4:7]
	v_mfma_f32_16x16x32_bf16 v[88:91], v[128:131], v[160:163], v[88:91]
	v_mfma_f32_16x16x32_bf16 v[24:27], v[140:143], v[160:163], v[24:27]
	v_mfma_f32_16x16x32_bf16 v[80:83], v[128:131], v[188:191], v[80:83]
	v_mfma_f32_16x16x32_bf16 v[16:19], v[140:143], v[188:191], v[16:19]
	v_mfma_f32_16x16x32_bf16 v[72:75], v[128:131], v[196:199], v[72:75]
	v_mfma_f32_16x16x32_bf16 v[8:11], v[140:143], v[196:199], v[8:11]
	v_mfma_f32_16x16x32_bf16 v[64:67], v[128:131], v[204:207], v[64:67]
	v_mfma_f32_16x16x32_bf16 v[0:3], v[140:143], v[204:207], v[0:3]
	v_mfma_f32_16x16x32_bf16 v[88:91], v[136:139], v[184:187], v[88:91]
	v_mfma_f32_16x16x32_bf16 v[24:27], v[144:147], v[184:187], v[24:27]
	v_mfma_f32_16x16x32_bf16 v[80:83], v[136:139], v[192:195], v[80:83]
	v_mfma_f32_16x16x32_bf16 v[16:19], v[144:147], v[192:195], v[16:19]
	v_mfma_f32_16x16x32_bf16 v[72:75], v[136:139], v[200:203], v[72:75]
	v_mfma_f32_16x16x32_bf16 v[8:11], v[144:147], v[200:203], v[8:11]
	v_mfma_f32_16x16x32_bf16 v[64:67], v[136:139], v[208:211], v[64:67]
	v_mfma_f32_16x16x32_bf16 v[0:3], v[144:147], v[208:211], v[0:3]
	s_barrier
	s_add_i32 s85, s85, 2
	s_add_u32 s56, s56, 0x100
	s_addc_u32 s57, s57, 0
	s_add_u32 s64, s64, 0x100
	s_addc_u32 s65, s65, 0
	s_cmp_gt_u32 s85, 13
	s_cbranch_scc0 .LBB0_2719
	s_and_b64 vcc, exec, s[36:37]
	s_cbranch_vccz .LBB0_2722
	s_barrier

; #define LAS __attribute__((address_space(3)))
; #define PG8_WAIT_V(n) asm volatile("s_waitcnt vmcnt(" #n ")" ::: "memory")
; #define PG8_BAR __builtin_amdgcn_s_barrier()
; DEVI unsigned xb_xcc_id() { return (unsigned)__builtin_amdgcn_s_getreg((3 << 11) | 20) & 0xFu; }
; template <class Epi, class Sched>
; DEVI void gemm_phase(LAS unsigned char* lds, const Gemm g, const Sched& S, const Epi& E) {
;     ...
;     PG8_WAIT_V(0);
;     PG8_BAR;
; DEVI void xcd_barrier(unsigned* bar, volatile LAS unsigned* st) {
;     asm volatile("s_waitcnt vmcnt(0)" ::: "memory");
;     __syncthreads();
;     if (threadIdx.x == 0) {
;         const unsigned x = xb_xcc_id();
;         __builtin_amdgcn_s_waitcnt(0);
;         unsigned nloc = st[0], nx = st[1];
;         if (nloc == 0u) { xcd_barrier_complete(bar, x, nloc, nx); st[0] = nloc; st[1] = nx; }
.LBB0_2750:
	s_waitcnt vmcnt(0)
	s_waitcnt lgkmcnt(0)
	s_setprio 0
	s_barrier
	s_mov_b64 s[0:1], exec
	v_readlane_b32 s2, v249, 53
	v_readlane_b32 s3, v249, 54
	s_and_b64 s[2:3], s[0:1], s[2:3]
	s_mov_b64 exec, s[2:3]
	s_cbranch_execz .LBB0_2802
	s_add_i32 s3, 0, 0x26ff0
	v_mov_b32_e32 v0, s3
	s_getreg_b32 s2, hwreg(HW_REG_XCC_ID, 0, 4)
	s_waitcnt vmcnt(0) expcnt(0) lgkmcnt(0)
	ds_read_b32 v2, v0
	s_add_i32 s3, 0, 0x26ff4
	v_mov_b32_e32 v0, s3
	ds_read_b32 v0, v0
	s_and_b32 s33, s2, 15
	s_waitcnt lgkmcnt(1)
	v_cmp_ne_u32_e32 vcc, 0, v2
	s_cbranch_vccnz .LBB0_2766
	s_add_u32 s2, s96, 0x6fc200
	s_addc_u32 s3, s97, 0
	s_add_u32 s4, s96, 0x6fc400
	s_addc_u32 s5, s97, 0
	s_add_u32 s6, s96, 0x6fc500
	s_addc_u32 s7, s97, 0
	s_add_u32 s8, s96, 0x6fc600
	s_addc_u32 s9, s97, 0
	s_add_u32 s10, s96, 0x6fc700
	s_addc_u32 s11, s97, 0
	s_add_u32 s14, s96, 0x6fc800
	s_addc_u32 s15, s97, 0
	s_add_u32 s16, s96, 0x6fc900
	s_addc_u32 s17, s97, 0
	s_add_u32 s18, s96, 0x6fca00
	s_addc_u32 s19, s97, 0
	s_add_u32 s20, s96, 0x6fcb00
	s_addc_u32 s21, s97, 0
	s_add_u32 s22, s96, 0x6fcc00
	s_addc_u32 s23, s97, 0
	s_add_u32 s24, s96, 0x6fcd00
	s_addc_u32 s25, s97, 0
	s_add_u32 s26, s96, 0x6fce00
	s_addc_u32 s27, s97, 0
	s_add_u32 s28, s96, 0x6fcf00
	s_addc_u32 s29, s97, 0
	s_add_u32 s30, s96, 0x6fd000
	s_addc_u32 s31, s97, 0
	s_add_u32 s34, s96, 0x6fd100
	s_addc_u32 s35, s97, 0
	s_add_u32 s36, s96, 0x6fd200
	s_addc_u32 s37, s97, 0
	s_add_u32 s38, s96, 0x6fd300
	s_addc_u32 s39, s97, 0
	s_mov_b32 s50, 1
	v_mov_b32_e32 v16, 0
	s_branch .LBB0_2754

; DEVI int tid_() { int t = threadIdx.x; asm volatile("" : "+v"(t)); return t; }
; DEVI int bid_() { int t = blockIdx.x; asm volatile("" : "+s"(t)); return t; }
; DEVI int gdim_() { int t = gridDim.x; asm volatile("" : "+s"(t)); return t; }
; DEVI void ffn_fixup_panel(int pm, bf16_t* H, const float* cw, const float* cb, const float* tailg, const float* headpg, const float* headup) {
;     for (int it = tid_(); it < 4 * 2 * (DFF / 4); it += 512) {
;         const int j = (it % (DFF / 4)) * 4, be = it / (DFF / 4), e = be & 1, blk = pm * 4 + (be >> 1);
;         const int row = blk * 64 + e, t = row & (SEQ - 1);
; template <int PH>
; DEVI void run_phase(const Params& p, unsigned char* smem) {
;     ...
;             pg8::Gemm g{(const bf16_t*)(ws + WS_H), wbase + (size_t)16 * MiB / 2, MROWS, DM, DFF}; pg8::StaticOrder S; S.init(MROWS, DM, gdim_(), bid_());
;             pg8::Unit u;
;             for (int i = 0; S.next(i, u); ++i) ffn_fixup_panel(u.pm, (bf16_t*)(ws + WS_H), p.in[28] + (size_t)l * 3 * DFF, p.in[29] + (size_t)l * DFF, (const float*)(ws + WS_TAIL), (const float*)(ws + WS_HPG), (const float*)(ws + WS_HUP));
.LBB0_2802:
	s_or_b64 exec, exec, s[0:1]
	s_mov_b64 s[0:1], s[96:97]
	s_waitcnt lgkmcnt(0)
	s_barrier
	v_readfirstlane_b32 s98, v242
	s_nop 3
	s_cmpk_lt_u32 s98, 0x100
	s_cbranch_scc1 .Lsprio_sp28
	s_setprio 1
.Lsprio_sp28:
	s_add_u32 s6, s0, 0x10a00000
	s_mov_b32 s23, s89
	v_readlane_b32 s25, v249, 0
	s_addc_u32 s7, s1, 0
	s_ashr_i32 s33, s23, 31
	s_ashr_i32 s38, s25, 31
	s_add_u32 s2, s0, 0xa800000
	s_addc_u32 s3, s1, 0
	s_add_u32 s4, s0, 0xb300000
	s_addc_u32 s5, s1, 0
	s_add_u32 s8, s0, 0xbe00000
	v_readlane_b32 s40, v249, 37
	s_addc_u32 s9, s1, 0
	v_readlane_b32 s44, v249, 41
	v_readlane_b32 s45, v249, 42
	v_readlane_b32 s46, v249, 43
	v_readlane_b32 s47, v249, 44
	v_readlane_b32 s48, v249, 45
	v_readlane_b32 s49, v249, 46
	s_add_u32 s10, s48, 0x1b800
	v_readlane_b32 s44, v249, 59
	s_addc_u32 s11, s49, 0
	s_mov_b32 s22, 0
	v_mov_b64_e32 v[20:21], 0x1ff
	s_movk_i32 s24, 0x1600
	s_mov_b32 s26, 0x2e8ba2e9
	s_movk_i32 s27, 0x2c00
	s_movk_i32 s28, 0x5800
	s_movk_i32 s29, 0x13ff
	v_mov_b32_e32 v28, 0
	v_readlane_b32 s45, v249, 60
	v_readlane_b32 s46, v249, 61
	v_readlane_b32 s47, v249, 62
	v_readlane_b32 s41, v249, 38
	v_readlane_b32 s42, v249, 39
	v_readlane_b32 s43, v249, 40
	v_readlane_b32 s50, v249, 47
	v_readlane_b32 s51, v249, 48
	v_readlane_b32 s52, v249, 49
	v_readlane_b32 s53, v249, 50
	v_readlane_b32 s54, v249, 51
	v_readlane_b32 s55, v249, 52
	s_branch .LBB0_2805

; #define PG8_STAGE(bufoff, gbase, voff) do { _Pragma("unroll") for (int _i = 0; _i < 2; ++_i) \
;         __builtin_amdgcn_global_load_lds((const unsigned*)((const char*)(gbase) + (voff)[_i]), (LAS unsigned*)(lds + (bufoff) + ldsw + _i * 8192), 16, 0, 0); } while (0)
; #define PG8_LDA(dst, b, h) do { _Pragma("unroll") for (int m = 0; m < 4; ++m) _Pragma("unroll") for (int k = 0; k < 2; ++k) dst[m][k] = *(const LAS bf16x8*)(lds + PG8_SA(b, h) + aoff + m * 2048 + k * 1024); } while (0)
; #define PG8_LDB(dst, b, h) do { _Pragma("unroll") for (int n = 0; n < 2; ++n) _Pragma("unroll") for (int k = 0; k < 2; ++k) dst[n][k] = *(const LAS bf16x8*)(lds + PG8_SB(b, h) + boff + n * 2048 + k * 1024); } while (0)
; #define PG8_MMA(ai, bj, At, Bt) do { __builtin_amdgcn_s_setprio(1); _Pragma("unroll") for (int m = 0; m < 4; ++m) _Pragma("unroll") for (int n = 0; n < 2; ++n) _Pragma("unroll") for (int k = 0; k < 2; ++k) \
;         acc[ai][bj][m][n] = __builtin_amdgcn_mfma_f32_16x16x32_bf16(Bt[n][k], At[m][k], acc[ai][bj][m][n], 0, 0, 0); __builtin_amdgcn_s_setprio(0); } while (0)
; #define PG8_WAIT_V(n) asm volatile("s_waitcnt vmcnt(" #n ")" ::: "memory")
; #define PG8_WAIT_L(n) asm volatile("s_waitcnt lgkmcnt(" #n ")" ::: "memory")
; #define PG8_BAR __builtin_amdgcn_s_barrier()
; #define PG8_SCHED __builtin_amdgcn_sched_barrier(0)
; template <class Epi, class Sched>
; DEVI void gemm_phase(LAS unsigned char* lds, const Gemm g, const Sched& S, const Epi& E) {
;     ...
;         for (int t = 0; t < nt; t += 2) {
;             const bool last = (t == nt - 2);
;             const char* a1 = cA + (size_t)(t + 1) * kstep;
;             const char* a2 = last ? nA : cA + (size_t)(t + 2) * kstep; const char* b2 = last ? nB : cB + (size_t)(t + 2) * kstep;
;             const char* a3 = a2 + kstep; const char* b3 = b2 + kstep;
;             if (last && has_next) S.a_ready(nxt);
;             PG8_LDB(B0, 0, 0); PG8_LDB(B1, 0, 1); PG8_SCHED; PG8_LDA(At, 0, 0); PG8_STAGE(PG8_SA(1, 1), a1 + hstep, voffA);
;             PG8_WAIT_V(8); PG8_WAIT_L(0); PG8_BAR; PG8_MMA(0, 0, At, B0); PG8_MMA(0, 1, At, B1); PG8_BAR; PG8_SCHED;
;             PG8_LDA(At, 0, 1); PG8_STAGE(PG8_SB(0, 0), b2, voffB); PG8_STAGE(PG8_SB(0, 1), b2 + hstep, voffB); PG8_STAGE(PG8_SA(0, 0), a2, voffA);
;             PG8_WAIT_V(8); PG8_WAIT_L(0); PG8_BAR; PG8_MMA(1, 0, At, B0); PG8_MMA(1, 1, At, B1); PG8_BAR; PG8_SCHED;
.LBB0_2842:
	ds_read_b128 v[144:147], v163
	ds_read_b128 v[148:151], v163 offset:1024
	ds_read_b128 v[152:155], v163 offset:2048
	ds_read_b128 v[156:159], v163 offset:3072
	ds_read_b128 v[168:171], v164
	ds_read_b128 v[172:175], v164 offset:1024
	ds_read_b128 v[176:179], v164 offset:2048
	ds_read_b128 v[180:183], v164 offset:3072
	s_add_u32 s30, s28, 0x100
	s_addc_u32 s31, s29, 0
	s_cmp_eq_u32 s62, 40
	s_cselect_b32 s37, s1, s31
	s_cselect_b32 s36, s0, s30
	s_cselect_b32 s35, s27, s61
	s_cselect_b32 s34, s26, s60
	v_lshl_add_u64 v[216:217], s[28:29], 0, v[138:139]
	s_add_i32 m0, s42, 0xc000
	ds_read_b128 v[184:187], v165
	ds_read_b128 v[188:191], v165 offset:1024
	ds_read_b128 v[192:195], v165 offset:2048
	ds_read_b128 v[196:199], v165 offset:3072
	ds_read_b128 v[200:203], v165 offset:4096
	ds_read_b128 v[204:207], v165 offset:5120
	ds_read_b128 v[208:211], v165 offset:6144
	ds_read_b128 v[212:215], v165 offset:7168
	global_load_lds_dwordx4 v[216:217], off
	v_lshl_add_u64 v[216:217], s[28:29], 0, v[136:137]
	s_add_i32 m0, s42, 0xe000
	s_nop 0
	global_load_lds_dwordx4 v[216:217], off
	s_waitcnt vmcnt(8)
	s_waitcnt lgkmcnt(0)
	s_barrier
	s_waitcnt lgkmcnt(0)
	v_mfma_f32_16x16x32_bf16 v[124:127], v[144:147], v[184:187], v[124:127]
	v_mfma_f32_16x16x32_bf16 v[120:123], v[152:155], v[184:187], v[120:123]
	v_mfma_f32_16x16x32_bf16 v[108:111], v[144:147], v[192:195], v[108:111]
	v_mfma_f32_16x16x32_bf16 v[104:107], v[152:155], v[192:195], v[104:107]
	v_mfma_f32_16x16x32_bf16 v[92:95], v[144:147], v[200:203], v[92:95]
	v_mfma_f32_16x16x32_bf16 v[88:91], v[152:155], v[200:203], v[88:91]
	v_mfma_f32_16x16x32_bf16 v[76:79], v[144:147], v[208:211], v[76:79]
	v_mfma_f32_16x16x32_bf16 v[72:75], v[152:155], v[208:211], v[72:75]
	v_mfma_f32_16x16x32_bf16 v[124:127], v[148:151], v[188:191], v[124:127]
	v_mfma_f32_16x16x32_bf16 v[120:123], v[156:159], v[188:191], v[120:123]
	v_mfma_f32_16x16x32_bf16 v[108:111], v[148:151], v[196:199], v[108:111]
	v_mfma_f32_16x16x32_bf16 v[104:107], v[156:159], v[196:199], v[104:107]
	v_mfma_f32_16x16x32_bf16 v[92:95], v[148:151], v[204:207], v[92:95]
	v_mfma_f32_16x16x32_bf16 v[88:91], v[156:159], v[204:207], v[88:91]
	v_mfma_f32_16x16x32_bf16 v[76:79], v[148:151], v[212:215], v[76:79]
	v_mfma_f32_16x16x32_bf16 v[72:75], v[156:159], v[212:215], v[72:75]
	v_mfma_f32_16x16x32_bf16 v[116:119], v[168:171], v[184:187], v[116:119]
	v_mfma_f32_16x16x32_bf16 v[112:115], v[176:179], v[184:187], v[112:115]
	v_mfma_f32_16x16x32_bf16 v[100:103], v[168:171], v[192:195], v[100:103]
	v_mfma_f32_16x16x32_bf16 v[96:99], v[176:179], v[192:195], v[96:99]
	v_mfma_f32_16x16x32_bf16 v[84:87], v[168:171], v[200:203], v[84:87]
	v_mfma_f32_16x16x32_bf16 v[80:83], v[176:179], v[200:203], v[80:83]
	v_mfma_f32_16x16x32_bf16 v[68:71], v[168:171], v[208:211], v[68:71]
	v_mfma_f32_16x16x32_bf16 v[64:67], v[176:179], v[208:211], v[64:67]
	v_mfma_f32_16x16x32_bf16 v[116:119], v[172:175], v[188:191], v[116:119]
	v_mfma_f32_16x16x32_bf16 v[112:115], v[180:183], v[188:191], v[112:115]
	v_mfma_f32_16x16x32_bf16 v[100:103], v[172:175], v[196:199], v[100:103]
	v_mfma_f32_16x16x32_bf16 v[96:99], v[180:183], v[196:199], v[96:99]
	v_mfma_f32_16x16x32_bf16 v[84:87], v[172:175], v[204:207], v[84:87]
	v_mfma_f32_16x16x32_bf16 v[80:83], v[180:183], v[204:207], v[80:83]
	v_mfma_f32_16x16x32_bf16 v[68:71], v[172:175], v[212:215], v[68:71]
	v_mfma_f32_16x16x32_bf16 v[64:67], v[180:183], v[212:215], v[64:67]
	s_barrier
	s_add_i32 s28, s53, s41
	v_lshl_add_u64 v[216:217], s[34:35], 0, v[130:131]
	s_mov_b32 m0, s28
	ds_read_b128 v[184:187], v165 offset:16384
	ds_read_b128 v[188:191], v165 offset:17408
	ds_read_b128 v[192:195], v165 offset:18432
	ds_read_b128 v[196:199], v165 offset:19456
	ds_read_b128 v[200:203], v165 offset:20480
	ds_read_b128 v[204:207], v165 offset:21504
	ds_read_b128 v[208:211], v165 offset:22528
	ds_read_b128 v[212:215], v165 offset:23552
	global_load_lds_dwordx4 v[216:217], off
	s_add_i32 m0, s28, 0x2000
	s_add_u32 s28, s34, 0xb0000
	v_lshl_add_u64 v[218:219], s[34:35], 0, v[134:135]
	s_addc_u32 s29, s35, 0
	s_add_i32 s63, s54, s41
	global_load_lds_dwordx4 v[218:219], off
	v_lshl_add_u64 v[220:221], s[28:29], 0, v[130:131]
	s_mov_b32 m0, s63
	v_lshl_add_u64 v[222:223], s[36:37], 0, v[132:133]
	global_load_lds_dwordx4 v[220:221], off
	v_lshl_add_u64 v[220:221], s[28:29], 0, v[134:135]
	s_add_i32 m0, s63, 0x2000
	s_nop 0
	global_load_lds_dwordx4 v[220:221], off
	v_lshl_add_u64 v[220:221], s[36:37], 0, v[128:129]
	s_mov_b32 m0, s42
	s_nop 0
	global_load_lds_dwordx4 v[220:221], off
	s_mov_b32 m0, s43
	s_nop 0
	global_load_lds_dwordx4 v[222:223], off
	s_waitcnt vmcnt(8)
	s_waitcnt lgkmcnt(0)
	s_barrier
; #define PG8_STAGE(bufoff, gbase, voff) do { _Pragma("unroll") for (int _i = 0; _i < 2; ++_i) \
;         __builtin_amdgcn_global_load_lds((const unsigned*)((const char*)(gbase) + (voff)[_i]), (LAS unsigned*)(lds + (bufoff) + ldsw + _i * 8192), 16, 0, 0); } while (0)
; #define PG8_LDA(dst, b, h) do { _Pragma("unroll") for (int m = 0; m < 4; ++m) _Pragma("unroll") for (int k = 0; k < 2; ++k) dst[m][k] = *(const LAS bf16x8*)(lds + PG8_SA(b, h) + aoff + m * 2048 + k * 1024); } while (0)
; #define PG8_LDB(dst, b, h) do { _Pragma("unroll") for (int n = 0; n < 2; ++n) _Pragma("unroll") for (int k = 0; k < 2; ++k) dst[n][k] = *(const LAS bf16x8*)(lds + PG8_SB(b, h) + boff + n * 2048 + k * 1024); } while (0)
; #define PG8_MMA(ai, bj, At, Bt) do { __builtin_amdgcn_s_setprio(1); _Pragma("unroll") for (int m = 0; m < 4; ++m) _Pragma("unroll") for (int n = 0; n < 2; ++n) _Pragma("unroll") for (int k = 0; k < 2; ++k) \
;         acc[ai][bj][m][n] = __builtin_amdgcn_mfma_f32_16x16x32_bf16(Bt[n][k], At[m][k], acc[ai][bj][m][n], 0, 0, 0); __builtin_amdgcn_s_setprio(0); } while (0)
; #define PG8_WAIT_V(n) asm volatile("s_waitcnt vmcnt(" #n ")" ::: "memory")
; #define PG8_WAIT_L(n) asm volatile("s_waitcnt lgkmcnt(" #n ")" ::: "memory")
; #define PG8_BAR __builtin_amdgcn_s_barrier()
; #define PG8_SCHED __builtin_amdgcn_sched_barrier(0)
; template <class Epi, class Sched>
; DEVI void gemm_phase(LAS unsigned char* lds, const Gemm g, const Sched& S, const Epi& E) {
;     ...
;             PG8_WAIT_V(8); PG8_WAIT_L(0); PG8_BAR; PG8_MMA(1, 0, At, B0); PG8_MMA(1, 1, At, B1); PG8_BAR; PG8_SCHED;
;             PG8_LDB(B0, 1, 0); PG8_LDB(B1, 1, 1); PG8_SCHED; PG8_LDA(At, 1, 0); PG8_STAGE(PG8_SA(0, 1), a2 + hstep, voffA);
;             PG8_WAIT_V(8); PG8_WAIT_L(0); PG8_BAR; PG8_MMA(0, 0, At, B0); PG8_MMA(0, 1, At, B1); PG8_BAR; PG8_SCHED;
	s_waitcnt lgkmcnt(0)
	v_mfma_f32_16x16x32_bf16 v[60:63], v[144:147], v[184:187], v[60:63]
	v_mfma_f32_16x16x32_bf16 v[56:59], v[152:155], v[184:187], v[56:59]
	v_mfma_f32_16x16x32_bf16 v[44:47], v[144:147], v[192:195], v[44:47]
	v_mfma_f32_16x16x32_bf16 v[40:43], v[152:155], v[192:195], v[40:43]
	v_mfma_f32_16x16x32_bf16 v[28:31], v[144:147], v[200:203], v[28:31]
	v_mfma_f32_16x16x32_bf16 v[24:27], v[152:155], v[200:203], v[24:27]
	v_mfma_f32_16x16x32_bf16 v[12:15], v[144:147], v[208:211], v[12:15]
	v_mfma_f32_16x16x32_bf16 v[8:11], v[152:155], v[208:211], v[8:11]
	v_mfma_f32_16x16x32_bf16 v[60:63], v[148:151], v[188:191], v[60:63]
	v_mfma_f32_16x16x32_bf16 v[56:59], v[156:159], v[188:191], v[56:59]
	v_mfma_f32_16x16x32_bf16 v[44:47], v[148:151], v[196:199], v[44:47]
	v_mfma_f32_16x16x32_bf16 v[40:43], v[156:159], v[196:199], v[40:43]
	v_mfma_f32_16x16x32_bf16 v[28:31], v[148:151], v[204:207], v[28:31]
	v_mfma_f32_16x16x32_bf16 v[24:27], v[156:159], v[204:207], v[24:27]
	v_mfma_f32_16x16x32_bf16 v[12:15], v[148:151], v[212:215], v[12:15]
	v_mfma_f32_16x16x32_bf16 v[8:11], v[156:159], v[212:215], v[8:11]
	v_mfma_f32_16x16x32_bf16 v[52:55], v[168:171], v[184:187], v[52:55]
	v_mfma_f32_16x16x32_bf16 v[48:51], v[176:179], v[184:187], v[48:51]
	v_mfma_f32_16x16x32_bf16 v[36:39], v[168:171], v[192:195], v[36:39]
	v_mfma_f32_16x16x32_bf16 v[32:35], v[176:179], v[192:195], v[32:35]
	v_mfma_f32_16x16x32_bf16 v[20:23], v[168:171], v[200:203], v[20:23]
	v_mfma_f32_16x16x32_bf16 v[16:19], v[176:179], v[200:203], v[16:19]
	v_mfma_f32_16x16x32_bf16 v[4:7], v[168:171], v[208:211], v[4:7]
	v_mfma_f32_16x16x32_bf16 v[0:3], v[176:179], v[208:211], v[0:3]
	v_mfma_f32_16x16x32_bf16 v[52:55], v[172:175], v[188:191], v[52:55]
	v_mfma_f32_16x16x32_bf16 v[48:51], v[180:183], v[188:191], v[48:51]
	v_mfma_f32_16x16x32_bf16 v[36:39], v[172:175], v[196:199], v[36:39]
	v_mfma_f32_16x16x32_bf16 v[32:35], v[180:183], v[196:199], v[32:35]
	v_mfma_f32_16x16x32_bf16 v[20:23], v[172:175], v[204:207], v[20:23]
	v_mfma_f32_16x16x32_bf16 v[16:19], v[180:183], v[204:207], v[16:19]
	v_mfma_f32_16x16x32_bf16 v[4:7], v[172:175], v[212:215], v[4:7]
	v_mfma_f32_16x16x32_bf16 v[0:3], v[180:183], v[212:215], v[0:3]
	s_barrier
	s_add_i32 s63, 0, 0x18000
	s_add_i32 s64, 0, 0x1c000
	v_add_u32_e32 v156, s63, v161
	v_add_u32_e32 v167, s64, v161
	ds_read_b128 v[144:147], v156
	ds_read_b128 v[148:151], v156 offset:1024
	ds_read_b128 v[152:155], v156 offset:2048
	ds_read_b128 v[156:159], v156 offset:3072
	ds_read_b128 v[168:171], v167
	ds_read_b128 v[172:175], v167 offset:1024
	ds_read_b128 v[176:179], v167 offset:2048
	ds_read_b128 v[180:183], v167 offset:3072
	s_add_u32 s28, s36, 0xb0000
	s_addc_u32 s29, s37, 0
	s_mov_b32 m0, s48
	v_lshl_add_u64 v[224:225], s[28:29], 0, v[128:129]
	ds_read_b128 v[184:187], v165 offset:32768
	ds_read_b128 v[188:191], v165 offset:33792
	ds_read_b128 v[192:195], v165 offset:34816
	ds_read_b128 v[196:199], v165 offset:35840
	ds_read_b128 v[200:203], v165 offset:36864
	ds_read_b128 v[204:207], v165 offset:37888
	ds_read_b128 v[208:211], v165 offset:38912
	ds_read_b128 v[212:215], v165 offset:39936
	global_load_lds_dwordx4 v[224:225], off
	v_lshl_add_u64 v[224:225], s[28:29], 0, v[132:133]
	s_mov_b32 m0, s49
	s_nop 0
	global_load_lds_dwordx4 v[224:225], off
	s_waitcnt vmcnt(8)
	s_waitcnt lgkmcnt(0)
	s_barrier
	s_waitcnt lgkmcnt(0)
	v_mfma_f32_16x16x32_bf16 v[124:127], v[144:147], v[184:187], v[124:127]
	v_mfma_f32_16x16x32_bf16 v[120:123], v[152:155], v[184:187], v[120:123]
	v_mfma_f32_16x16x32_bf16 v[108:111], v[144:147], v[192:195], v[108:111]
	v_mfma_f32_16x16x32_bf16 v[104:107], v[152:155], v[192:195], v[104:107]
	v_mfma_f32_16x16x32_bf16 v[92:95], v[144:147], v[200:203], v[92:95]
	v_mfma_f32_16x16x32_bf16 v[88:91], v[152:155], v[200:203], v[88:91]
	v_mfma_f32_16x16x32_bf16 v[76:79], v[144:147], v[208:211], v[76:79]
	v_mfma_f32_16x16x32_bf16 v[72:75], v[152:155], v[208:211], v[72:75]
	v_mfma_f32_16x16x32_bf16 v[124:127], v[148:151], v[188:191], v[124:127]
	v_mfma_f32_16x16x32_bf16 v[120:123], v[156:159], v[188:191], v[120:123]
	v_mfma_f32_16x16x32_bf16 v[108:111], v[148:151], v[196:199], v[108:111]
	v_mfma_f32_16x16x32_bf16 v[104:107], v[156:159], v[196:199], v[104:107]
	v_mfma_f32_16x16x32_bf16 v[92:95], v[148:151], v[204:207], v[92:95]
	v_mfma_f32_16x16x32_bf16 v[88:91], v[156:159], v[204:207], v[88:91]
	v_mfma_f32_16x16x32_bf16 v[76:79], v[148:151], v[212:215], v[76:79]
	v_mfma_f32_16x16x32_bf16 v[72:75], v[156:159], v[212:215], v[72:75]
	v_mfma_f32_16x16x32_bf16 v[116:119], v[168:171], v[184:187], v[116:119]
	v_mfma_f32_16x16x32_bf16 v[112:115], v[176:179], v[184:187], v[112:115]
	v_mfma_f32_16x16x32_bf16 v[100:103], v[168:171], v[192:195], v[100:103]
	v_mfma_f32_16x16x32_bf16 v[96:99], v[176:179], v[192:195], v[96:99]
	v_mfma_f32_16x16x32_bf16 v[84:87], v[168:171], v[200:203], v[84:87]
	v_mfma_f32_16x16x32_bf16 v[80:83], v[176:179], v[200:203], v[80:83]
	v_mfma_f32_16x16x32_bf16 v[68:71], v[168:171], v[208:211], v[68:71]
	v_mfma_f32_16x16x32_bf16 v[64:67], v[176:179], v[208:211], v[64:67]
	v_mfma_f32_16x16x32_bf16 v[116:119], v[172:175], v[188:191], v[116:119]
	v_mfma_f32_16x16x32_bf16 v[112:115], v[180:183], v[188:191], v[112:115]
	v_mfma_f32_16x16x32_bf16 v[100:103], v[172:175], v[196:199], v[100:103]
	v_mfma_f32_16x16x32_bf16 v[96:99], v[180:183], v[196:199], v[96:99]
	v_mfma_f32_16x16x32_bf16 v[84:87], v[172:175], v[204:207], v[84:87]
	v_mfma_f32_16x16x32_bf16 v[80:83], v[180:183], v[204:207], v[80:83]
	v_mfma_f32_16x16x32_bf16 v[68:71], v[172:175], v[212:215], v[68:71]
	v_mfma_f32_16x16x32_bf16 v[64:67], v[180:183], v[212:215], v[64:67]
	s_barrier
; #define PG8_STAGE(bufoff, gbase, voff) do { _Pragma("unroll") for (int _i = 0; _i < 2; ++_i) \
;         __builtin_amdgcn_global_load_lds((const unsigned*)((const char*)(gbase) + (voff)[_i]), (LAS unsigned*)(lds + (bufoff) + ldsw + _i * 8192), 16, 0, 0); } while (0)
; #define PG8_LDA(dst, b, h) do { _Pragma("unroll") for (int m = 0; m < 4; ++m) _Pragma("unroll") for (int k = 0; k < 2; ++k) dst[m][k] = *(const LAS bf16x8*)(lds + PG8_SA(b, h) + aoff + m * 2048 + k * 1024); } while (0)
; #define PG8_MMA(ai, bj, At, Bt) do { __builtin_amdgcn_s_setprio(1); _Pragma("unroll") for (int m = 0; m < 4; ++m) _Pragma("unroll") for (int n = 0; n < 2; ++n) _Pragma("unroll") for (int k = 0; k < 2; ++k) \
;         acc[ai][bj][m][n] = __builtin_amdgcn_mfma_f32_16x16x32_bf16(Bt[n][k], At[m][k], acc[ai][bj][m][n], 0, 0, 0); __builtin_amdgcn_s_setprio(0); } while (0)
; #define PG8_WAIT_V(n) asm volatile("s_waitcnt vmcnt(" #n ")" ::: "memory")
; #define PG8_WAIT_L(n) asm volatile("s_waitcnt lgkmcnt(" #n ")" ::: "memory")
; #define PG8_BAR __builtin_amdgcn_s_barrier()
; #define PG8_SCHED __builtin_amdgcn_sched_barrier(0)
; template <class Epi, class Sched>
; DEVI void gemm_phase(LAS unsigned char* lds, const Gemm g, const Sched& S, const Epi& E) {
;     ...
;             PG8_LDA(At, 1, 1); PG8_STAGE(PG8_SB(1, 0), b3, voffB); PG8_STAGE(PG8_SB(1, 1), b3 + hstep, voffB); PG8_STAGE(PG8_SA(1, 0), a3, voffA);
;             PG8_WAIT_V(8); PG8_WAIT_L(0); PG8_BAR; PG8_MMA(1, 0, At, B0); PG8_MMA(1, 1, At, B1); PG8_BAR; PG8_SCHED;
;         }
;         if (wr == 0) PG8_BAR;
	s_add_i32 s28, s63, s41
	v_lshl_add_u64 v[216:217], v[216:217], 0, s[18:19]
	s_mov_b32 m0, s28
	ds_read_b128 v[184:187], v165 offset:49152
	ds_read_b128 v[188:191], v165 offset:50176
	ds_read_b128 v[192:195], v165 offset:51200
	ds_read_b128 v[196:199], v165 offset:52224
	ds_read_b128 v[200:203], v165 offset:53248
	ds_read_b128 v[204:207], v165 offset:54272
	ds_read_b128 v[208:211], v165 offset:55296
	ds_read_b128 v[212:215], v165 offset:56320
	global_load_lds_dwordx4 v[216:217], off
	s_add_i32 m0, s28, 0x2000
	s_add_u32 s28, s34, 0xb0080
	v_lshl_add_u64 v[216:217], v[218:219], 0, s[18:19]
	s_addc_u32 s29, s35, 0
	s_add_i32 s34, s64, s41
	global_load_lds_dwordx4 v[216:217], off
	v_lshl_add_u64 v[216:217], s[28:29], 0, v[130:131]
	s_mov_b32 m0, s34
	s_nop 0
	global_load_lds_dwordx4 v[216:217], off
	v_lshl_add_u64 v[216:217], s[28:29], 0, v[134:135]
	s_add_i32 m0, s34, 0x2000
	s_nop 0
	global_load_lds_dwordx4 v[216:217], off
	v_lshl_add_u64 v[216:217], v[220:221], 0, s[18:19]
	s_mov_b32 m0, s51
	s_nop 0
	global_load_lds_dwordx4 v[216:217], off
	v_lshl_add_u64 v[216:217], v[222:223], 0, s[18:19]
	s_mov_b32 m0, s52
	s_nop 0
	global_load_lds_dwordx4 v[216:217], off
	s_waitcnt vmcnt(8)
	s_waitcnt lgkmcnt(0)
	s_barrier
	s_waitcnt lgkmcnt(0)
	v_mfma_f32_16x16x32_bf16 v[60:63], v[144:147], v[184:187], v[60:63]
	v_mfma_f32_16x16x32_bf16 v[56:59], v[152:155], v[184:187], v[56:59]
	v_mfma_f32_16x16x32_bf16 v[44:47], v[144:147], v[192:195], v[44:47]
	v_mfma_f32_16x16x32_bf16 v[40:43], v[152:155], v[192:195], v[40:43]
	v_mfma_f32_16x16x32_bf16 v[28:31], v[144:147], v[200:203], v[28:31]
	v_mfma_f32_16x16x32_bf16 v[24:27], v[152:155], v[200:203], v[24:27]
	v_mfma_f32_16x16x32_bf16 v[12:15], v[144:147], v[208:211], v[12:15]
	v_mfma_f32_16x16x32_bf16 v[8:11], v[152:155], v[208:211], v[8:11]
	v_mfma_f32_16x16x32_bf16 v[60:63], v[148:151], v[188:191], v[60:63]
	v_mfma_f32_16x16x32_bf16 v[56:59], v[156:159], v[188:191], v[56:59]
	v_mfma_f32_16x16x32_bf16 v[44:47], v[148:151], v[196:199], v[44:47]
	v_mfma_f32_16x16x32_bf16 v[40:43], v[156:159], v[196:199], v[40:43]
	v_mfma_f32_16x16x32_bf16 v[28:31], v[148:151], v[204:207], v[28:31]
	v_mfma_f32_16x16x32_bf16 v[24:27], v[156:159], v[204:207], v[24:27]
	v_mfma_f32_16x16x32_bf16 v[12:15], v[148:151], v[212:215], v[12:15]
	v_mfma_f32_16x16x32_bf16 v[8:11], v[156:159], v[212:215], v[8:11]
	v_mfma_f32_16x16x32_bf16 v[52:55], v[168:171], v[184:187], v[52:55]
	v_mfma_f32_16x16x32_bf16 v[48:51], v[176:179], v[184:187], v[48:51]
	v_mfma_f32_16x16x32_bf16 v[36:39], v[168:171], v[192:195], v[36:39]
	v_mfma_f32_16x16x32_bf16 v[32:35], v[176:179], v[192:195], v[32:35]
	v_mfma_f32_16x16x32_bf16 v[20:23], v[168:171], v[200:203], v[20:23]
	v_mfma_f32_16x16x32_bf16 v[16:19], v[176:179], v[200:203], v[16:19]
	v_mfma_f32_16x16x32_bf16 v[4:7], v[168:171], v[208:211], v[4:7]
	v_mfma_f32_16x16x32_bf16 v[0:3], v[176:179], v[208:211], v[0:3]
	v_mfma_f32_16x16x32_bf16 v[52:55], v[172:175], v[188:191], v[52:55]
	v_mfma_f32_16x16x32_bf16 v[48:51], v[180:183], v[188:191], v[48:51]
	v_mfma_f32_16x16x32_bf16 v[36:39], v[172:175], v[196:199], v[36:39]
	v_mfma_f32_16x16x32_bf16 v[32:35], v[180:183], v[196:199], v[32:35]
	v_mfma_f32_16x16x32_bf16 v[20:23], v[172:175], v[204:207], v[20:23]
	v_mfma_f32_16x16x32_bf16 v[16:19], v[180:183], v[204:207], v[16:19]
	v_mfma_f32_16x16x32_bf16 v[4:7], v[172:175], v[212:215], v[4:7]
	v_mfma_f32_16x16x32_bf16 v[0:3], v[180:183], v[212:215], v[0:3]
	s_barrier
	s_add_i32 s62, s62, 2
	s_add_u32 s60, s60, 0x100
	s_addc_u32 s61, s61, 0
	s_cmp_gt_u32 s62, 41
	s_mov_b64 s[28:29], s[30:31]
	s_cbranch_scc0 .LBB0_2842
	s_and_b64 vcc, exec, s[20:21]
	s_cbranch_vccz .LBB0_2845
	s_barrier
